# gdnout: z-gate loads batched + DPP row sums; diffpost: unrolled with prefetch; merge epilogue: gate loads hoisted; solve rows interleaved; stagger on GEMM/MIX phases only
# speedup vs baseline: 1.0384x; 1.0133x over previous
; __global__ void __launch_bounds__(256, 2) mega(Params p, int ph_lo, int ph_hi) {
;     ...
;   for (int ph = ph_lo; ph < ph_hi; ++ph) {
;     if (ph > ph_lo) xcd_barrier(xb);
;     if (ph_hi < 0) cg::this_grid().sync();
;     run_phase(p, ph, lds, &s_item);
.LBB0_74:
	s_mov_b64 s[92:93], 0
	s_bitcmp1_b32 s56, 8
	s_cbranch_scc0 .Lno_stagger
	s_mov_b32 s98, 0x696d2da4
	s_mov_b32 s99, 0x1b4b
	s_bitcmp1_b64 s[98:99], s19
	s_cbranch_scc0 .Lno_stagger
	s_sleep 38

; DI f32x4 mfma16(bf16x8 a, bf16x8 b, f32x4 c) { return __builtin_amdgcn_mfma_f32_16x16x32_bf16(a, b, c, 0, 0, 0); }
; template <int NI>
; DI void gemm_kloop(f32x4 (&acc)[4][NI], const bf16_t* __restrict__ A, int lda, const bf16_t* __restrict__ B, int ldb, int K, bf16_t* sA, bf16_t* sB) {
;     ...
;   for (int kt = 0; kt < nk; ++kt) {
;     __syncthreads();
; #pragma unroll
;     for (int i = 0; i < 4; ++i) { int c = tid + 256 * i, row = c >> 3, kc = (c & 7) * 8; *(bf16x8*)(sA + row * 72 + kc) = ra[i]; }
; #pragma unroll
;     for (int i = 0; i < NB; ++i) { int c = tid + 256 * i, row = c >> 3, kc = (c & 7) * 8; *(bf16x8*)(sB + row * 72 + kc) = rb[i]; }
;     __syncthreads();
;     if (kt + 1 < nk) {
;       const int k0 = (kt + 1) * 64;
; #pragma unroll
;       for (int i = 0; i < 4; ++i) { int c = tid + 256 * i, row = c >> 3, kc = (c & 7) * 8; ra[i] = *(const bf16x8*)(A + (size_t)row * lda + k0 + kc); }
; #pragma unroll
;       for (int i = 0; i < NB; ++i) { int c = tid + 256 * i, row = c >> 3, kc = (c & 7) * 8; rb[i] = *(const bf16x8*)(B + (size_t)row * ldb + k0 + kc); }
;     }
;     __builtin_amdgcn_s_setprio(1);
; #pragma unroll
;     for (int ks = 0; ks < 2; ++ks) {
;       bf16x8 af[4];
; #pragma unroll
;       for (int mi = 0; mi < 4; ++mi) af[mi] = *(const bf16x8*)(sA + (wr * 64 + mi * 16 + lr) * 72 + ks * 32 + lq * 8);
; #pragma unroll
;       for (int nh = 0; nh < NI / 4; ++nh) {
;         bf16x8 bfr[4];
; #pragma unroll
;         for (int ni = 0; ni < 4; ++ni) bfr[ni] = *(const bf16x8*)(sB + (wc * (NI * 16) + (nh * 4 + ni) * 16 + lr) * 72 + ks * 32 + lq * 8);
; #pragma unroll
;         for (int mi = 0; mi < 4; ++mi)
; #pragma unroll
;           for (int ni = 0; ni < 4; ++ni) acc[mi][nh * 4 + ni] = mfma16(bfr[ni], af[mi], acc[mi][nh * 4 + ni]);
;       }
;     }
;     __builtin_amdgcn_s_setprio(0);
;   }
.LBB0_234:
	s_barrier
	s_waitcnt vmcnt(0)
	ds_write_b128 v147, v[30:33]
	ds_write_b128 v148, v[26:29]
	ds_write_b128 v149, v[22:25]
	ds_write_b128 v150, v[18:21]
	ds_write_b128 v147, v[14:17] offset:18432
	ds_write_b128 v148, v[10:13] offset:18432
	ds_write_b128 v149, v[6:9] offset:18432
	ds_write_b128 v150, v[2:5] offset:18432
	v_lshl_add_u64 v[2:3], v[130:131], 0, s[24:25]
	v_lshl_add_u64 v[4:5], v[132:133], 0, s[24:25]
	s_waitcnt lgkmcnt(0)
	s_barrier
	global_load_dwordx4 v[30:33], v[2:3], off
	global_load_dwordx4 v[26:29], v[4:5], off
	v_lshl_add_u64 v[2:3], v[134:135], 0, s[24:25]
	v_lshl_add_u64 v[4:5], v[136:137], 0, s[24:25]
	global_load_dwordx4 v[22:25], v[2:3], off
	global_load_dwordx4 v[18:21], v[4:5], off
	v_lshl_add_u64 v[2:3], v[138:139], 0, s[24:25]
	v_lshl_add_u64 v[4:5], v[140:141], 0, s[24:25]
	global_load_dwordx4 v[14:17], v[2:3], off
	global_load_dwordx4 v[10:13], v[4:5], off
	v_lshl_add_u64 v[2:3], v[142:143], 0, s[24:25]
	v_lshl_add_u64 v[4:5], v[144:145], 0, s[24:25]
	global_load_dwordx4 v[6:9], v[2:3], off
	s_nop 0
	global_load_dwordx4 v[2:5], v[4:5], off
	s_setprio 1
	ds_read_b128 v[152:155], v146 offset:18432
	ds_read_b128 v[156:159], v0
	ds_read_b128 v[160:163], v146 offset:20736
	ds_read_b128 v[164:167], v146 offset:23040
	ds_read_b128 v[168:171], v146 offset:25344
	s_waitcnt lgkmcnt(3)
	v_mfma_f32_16x16x32_bf16 v[38:41], v[152:155], v[156:159], v[38:41]
	s_waitcnt lgkmcnt(2)
	v_mfma_f32_16x16x32_bf16 v[82:85], v[160:163], v[156:159], v[82:85]
	s_waitcnt lgkmcnt(1)
	v_mfma_f32_16x16x32_bf16 v[78:81], v[164:167], v[156:159], v[78:81]
	s_waitcnt lgkmcnt(0)
	v_mfma_f32_16x16x32_bf16 v[74:77], v[168:171], v[156:159], v[74:77]
	ds_read_b128 v[156:159], v0 offset:2304
	s_waitcnt lgkmcnt(0)
	v_mfma_f32_16x16x32_bf16 v[70:73], v[152:155], v[156:159], v[70:73]
	v_mfma_f32_16x16x32_bf16 v[62:65], v[160:163], v[156:159], v[62:65]
	v_mfma_f32_16x16x32_bf16 v[54:57], v[164:167], v[156:159], v[54:57]
	v_mfma_f32_16x16x32_bf16 v[46:49], v[168:171], v[156:159], v[46:49]
	ds_read_b128 v[156:159], v0 offset:4608
	s_waitcnt lgkmcnt(0)
	v_mfma_f32_16x16x32_bf16 v[66:69], v[152:155], v[156:159], v[66:69]
	v_mfma_f32_16x16x32_bf16 v[58:61], v[160:163], v[156:159], v[58:61]
	v_mfma_f32_16x16x32_bf16 v[50:53], v[164:167], v[156:159], v[50:53]
	v_mfma_f32_16x16x32_bf16 v[42:45], v[168:171], v[156:159], v[42:45]
	ds_read_b128 v[156:159], v0 offset:6912
	s_waitcnt lgkmcnt(0)
	v_mfma_f32_16x16x32_bf16 v[94:97], v[152:155], v[156:159], v[94:97]
	ds_read_b128 v[152:155], v146 offset:18496
	v_mfma_f32_16x16x32_bf16 v[90:93], v[160:163], v[156:159], v[90:93]
	ds_read_b128 v[160:163], v146 offset:20800
	v_mfma_f32_16x16x32_bf16 v[86:89], v[164:167], v[156:159], v[86:89]
	ds_read_b128 v[164:167], v146 offset:23104
	v_mfma_f32_16x16x32_bf16 v[34:37], v[168:171], v[156:159], v[34:37]
	ds_read_b128 v[168:171], v146 offset:25408
	ds_read_b128 v[156:159], v0 offset:64
	s_waitcnt lgkmcnt(0)
	v_mfma_f32_16x16x32_bf16 v[38:41], v[152:155], v[156:159], v[38:41]
	v_mfma_f32_16x16x32_bf16 v[82:85], v[160:163], v[156:159], v[82:85]
	v_mfma_f32_16x16x32_bf16 v[78:81], v[164:167], v[156:159], v[78:81]
	v_mfma_f32_16x16x32_bf16 v[74:77], v[168:171], v[156:159], v[74:77]
	ds_read_b128 v[156:159], v0 offset:2368
	s_waitcnt lgkmcnt(0)
	v_mfma_f32_16x16x32_bf16 v[70:73], v[152:155], v[156:159], v[70:73]
	v_mfma_f32_16x16x32_bf16 v[62:65], v[160:163], v[156:159], v[62:65]
	v_mfma_f32_16x16x32_bf16 v[54:57], v[164:167], v[156:159], v[54:57]
	v_mfma_f32_16x16x32_bf16 v[46:49], v[168:171], v[156:159], v[46:49]
	ds_read_b128 v[156:159], v0 offset:4672
	s_waitcnt lgkmcnt(0)
	v_mfma_f32_16x16x32_bf16 v[66:69], v[152:155], v[156:159], v[66:69]
	v_mfma_f32_16x16x32_bf16 v[58:61], v[160:163], v[156:159], v[58:61]
	v_mfma_f32_16x16x32_bf16 v[50:53], v[164:167], v[156:159], v[50:53]
	v_mfma_f32_16x16x32_bf16 v[42:45], v[168:171], v[156:159], v[42:45]
	ds_read_b128 v[156:159], v0 offset:6976
	s_waitcnt lgkmcnt(0)
	v_mfma_f32_16x16x32_bf16 v[94:97], v[152:155], v[156:159], v[94:97]
	v_mfma_f32_16x16x32_bf16 v[90:93], v[160:163], v[156:159], v[90:93]
	v_mfma_f32_16x16x32_bf16 v[86:89], v[164:167], v[156:159], v[86:89]
	v_mfma_f32_16x16x32_bf16 v[34:37], v[168:171], v[156:159], v[34:37]
	s_setprio 0
	s_add_u32 s24, s24, 0x80
	s_addc_u32 s25, s25, 0
	s_cmpk_lg_i32 s24, 0x380
	s_cbranch_scc1 .LBB0_234
	s_barrier
	s_waitcnt vmcnt(7)
	ds_write_b128 v147, v[30:33]
	s_waitcnt vmcnt(6)
	ds_write_b128 v148, v[26:29]
	s_waitcnt vmcnt(5)
	ds_write_b128 v149, v[22:25]
	s_waitcnt vmcnt(4)
	ds_write_b128 v150, v[18:21]
	s_waitcnt vmcnt(3)
	ds_write_b128 v147, v[14:17] offset:18432
	s_waitcnt vmcnt(2)
	ds_write_b128 v148, v[10:13] offset:18432
	s_waitcnt vmcnt(1)
	ds_write_b128 v149, v[6:9] offset:18432
	s_waitcnt vmcnt(0)
	ds_write_b128 v150, v[2:5] offset:18432
	s_waitcnt lgkmcnt(0)
	s_barrier
; DI f32x4 mfma16(bf16x8 a, bf16x8 b, f32x4 c) { return __builtin_amdgcn_mfma_f32_16x16x32_bf16(a, b, c, 0, 0, 0); }
; template <int NI>
; DI void gemm_kloop(f32x4 (&acc)[4][NI], const bf16_t* __restrict__ A, int lda, const bf16_t* __restrict__ B, int ldb, int K, bf16_t* sA, bf16_t* sB) {
;     ...
; #pragma unroll
;     for (int ks = 0; ks < 2; ++ks) {
;       bf16x8 af[4];
; #pragma unroll
;       for (int mi = 0; mi < 4; ++mi) af[mi] = *(const bf16x8*)(sA + (wr * 64 + mi * 16 + lr) * 72 + ks * 32 + lq * 8);
; #pragma unroll
;       for (int nh = 0; nh < NI / 4; ++nh) {
;         bf16x8 bfr[4];
; #pragma unroll
;         for (int ni = 0; ni < 4; ++ni) bfr[ni] = *(const bf16x8*)(sB + (wc * (NI * 16) + (nh * 4 + ni) * 16 + lr) * 72 + ks * 32 + lq * 8);
; #pragma unroll
;         for (int mi = 0; mi < 4; ++mi)
; #pragma unroll
;           for (int ni = 0; ni < 4; ++ni) acc[mi][nh * 4 + ni] = mfma16(bfr[ni], af[mi], acc[mi][nh * 4 + ni]);
;       }
;     }
	s_setprio 1
	ds_read_b128 v[2:5], v146 offset:18432
	ds_read_b128 v[6:9], v0
	ds_read_b128 v[14:17], v146 offset:20736
	ds_read_b128 v[22:25], v146 offset:23040
	ds_read_b128 v[30:33], v146 offset:25344
	s_waitcnt lgkmcnt(3)
	v_mfma_f32_16x16x32_bf16 v[10:13], v[2:5], v[6:9], v[38:41]
	ds_read_b128 v[142:145], v146 offset:23104
	s_nop 1
	ds_read_b128 v[38:41], v0 offset:2304
	s_waitcnt lgkmcnt(4)
	v_mfma_f32_16x16x32_bf16 v[18:21], v[14:17], v[6:9], v[82:85]
	s_waitcnt lgkmcnt(3)
	v_mfma_f32_16x16x32_bf16 v[26:29], v[22:25], v[6:9], v[78:81]
	s_waitcnt lgkmcnt(2)
	v_mfma_f32_16x16x32_bf16 v[6:9], v[30:33], v[6:9], v[74:77]
	s_waitcnt lgkmcnt(0)
	v_mfma_f32_16x16x32_bf16 v[70:73], v[2:5], v[38:41], v[70:73]
	v_mfma_f32_16x16x32_bf16 v[74:77], v[14:17], v[38:41], v[62:65]
	v_mfma_f32_16x16x32_bf16 v[78:81], v[22:25], v[38:41], v[54:57]
	v_mfma_f32_16x16x32_bf16 v[82:85], v[30:33], v[38:41], v[46:49]
	ds_read_b128 v[38:41], v0 offset:4608
	s_waitcnt lgkmcnt(0)
	v_mfma_f32_16x16x32_bf16 v[66:69], v[2:5], v[38:41], v[66:69]
	v_mfma_f32_16x16x32_bf16 v[130:133], v[14:17], v[38:41], v[58:61]
	v_mfma_f32_16x16x32_bf16 v[134:137], v[22:25], v[38:41], v[50:53]
	v_mfma_f32_16x16x32_bf16 v[138:141], v[30:33], v[38:41], v[42:45]
	ds_read_b128 v[38:41], v0 offset:6912
	s_waitcnt lgkmcnt(0)
	v_mfma_f32_16x16x32_bf16 v[90:93], v[14:17], v[38:41], v[90:93]
	ds_read_b128 v[14:17], v146 offset:18496
	v_mfma_f32_16x16x32_bf16 v[86:89], v[22:25], v[38:41], v[86:89]
	ds_read_b128 v[22:25], v0 offset:64
	s_waitcnt lgkmcnt(0)
	v_mfma_f32_16x16x32_bf16 v[62:65], v[14:17], v[22:25], v[10:13]
	s_nop 2
	ds_read_b128 v[10:13], v146 offset:20800
	ds_read_b128 v[146:149], v146 offset:25408
	s_waitcnt lgkmcnt(0)
	v_mfma_f32_16x16x32_bf16 v[50:53], v[146:149], v[22:25], v[6:9]
	s_nop 2
	ds_read_b128 v[6:9], v0 offset:2368
	v_mfma_f32_16x16x32_bf16 v[2:5], v[2:5], v[38:41], v[94:97]
	v_mfma_f32_16x16x32_bf16 v[94:97], v[30:33], v[38:41], v[34:37]
	s_waitcnt lgkmcnt(0)
	v_mfma_f32_16x16x32_bf16 v[46:49], v[14:17], v[6:9], v[70:73]
	v_mfma_f32_16x16x32_bf16 v[42:45], v[10:13], v[6:9], v[74:77]
	v_mfma_f32_16x16x32_bf16 v[38:41], v[142:145], v[6:9], v[78:81]
	v_mfma_f32_16x16x32_bf16 v[34:37], v[146:149], v[6:9], v[82:85]
	ds_read_b128 v[6:9], v0 offset:4672
	s_waitcnt lgkmcnt(0)
	v_mfma_f32_16x16x32_bf16 v[30:33], v[14:17], v[6:9], v[66:69]
	s_nop 2
	ds_read_b128 v[66:69], v0 offset:6976
	v_mfma_f32_16x16x32_bf16 v[58:61], v[10:13], v[22:25], v[18:21]
	v_mfma_f32_16x16x32_bf16 v[54:57], v[142:145], v[22:25], v[26:29]
	v_mfma_f32_16x16x32_bf16 v[26:29], v[10:13], v[6:9], v[130:133]
	v_mfma_f32_16x16x32_bf16 v[22:25], v[142:145], v[6:9], v[134:137]
	v_mfma_f32_16x16x32_bf16 v[18:21], v[146:149], v[6:9], v[138:141]
	s_waitcnt lgkmcnt(0)
; DI unsigned pk2(float lo, float hi) { f32x2_t v; v[0] = lo; v[1] = hi; bf16x2_t b = __builtin_convertvector(v, bf16x2_t); return __builtin_bit_cast(unsigned, b); }
; DI float bflo(unsigned u) { return __uint_as_float(u << 16); }
; DI float bfhi(unsigned u) { return __uint_as_float(u & 0xffff0000u); }
; DI float sigmoidf_(float x) { return 1.f / (1.f + __expf(-x)); }
; DI void merge_item(const Params& p, int l, int item, bf16_t* lds) {
;     ...
;     EPI_LOOP({
;       u32x2 g = *(const u32x2*)(RG + (size_t)t * 3072 + br * 1024 + n0 + cl);
;       f32x4 o; o[0] = sigmoidf_(bflo(g.x)) * v[0]; o[1] = sigmoidf_(bfhi(g.x)) * v[1]; o[2] = sigmoidf_(bflo(g.y)) * v[2]; o[3] = sigmoidf_(bfhi(g.y)) * v[3];
;       if (br > 0) { u32x2 pm = mg[mi][ni]; o[0] += bflo(pm.x); o[1] += bfhi(pm.x); o[2] += bflo(pm.y); o[3] += bfhi(pm.y); }
;       u32x2 pk; pk.x = pk2(o[0], o[1]); pk.y = pk2(o[2], o[3]);
;       mg[mi][ni] = pk;
	v_mfma_f32_16x16x32_bf16 v[14:17], v[14:17], v[66:69], v[2:5]
	v_mfma_f32_16x16x32_bf16 v[10:13], v[10:13], v[66:69], v[90:93]
	v_mfma_f32_16x16x32_bf16 v[6:9], v[142:145], v[66:69], v[86:89]
	v_mfma_f32_16x16x32_bf16 v[2:5], v[146:149], v[66:69], v[94:97]
	s_setprio 0
	v_mov_b32_e32 v0, v201
	v_mov_b32_e32 v67, v201
	s_lshl_b32 s4, s63, 11
	v_ashrrev_i32_e32 v66, 1, v67
	v_and_b32_e32 v66, 0xffffffc0, v66
	v_add_u32_e32 v66, s46, v66
	v_and_or_b32 v66, v0, 15, v66
	v_lshrrev_b32_e32 v0, 2, v0
	s_add_u32 s24, s47, s4
	v_and_b32_e32 v0, 12, v0
	s_addc_u32 s25, s48, 0
	v_and_or_b32 v0, v67, 64, v0
	v_mov_b64_e32 v[68:69], s[24:25]
	v_mad_i64_i32 v[68:69], s[4:5], v66, s8, v[68:69]
	v_lshlrev_b32_e32 v0, 1, v0
	v_lshl_add_u64 v[68:69], v[68:69], 0, v[0:1]
	global_load_dwordx2 v[172:173], v[68:69], off
	global_load_dwordx2 v[174:175], v[68:69], off offset:32
	global_load_dwordx2 v[176:177], v[68:69], off offset:64
	global_load_dwordx2 v[178:179], v[68:69], off offset:96
	v_or_b32_e32 v206, 16, v66
	v_mov_b64_e32 v[208:209], s[24:25]
	v_mad_i64_i32 v[208:209], s[98:99], v206, s8, v[208:209]
	v_lshl_add_u64 v[208:209], v[208:209], 0, v[0:1]
	global_load_dwordx2 v[180:181], v[208:209], off
	global_load_dwordx2 v[182:183], v[208:209], off offset:32
	global_load_dwordx2 v[184:185], v[208:209], off offset:64
	global_load_dwordx2 v[186:187], v[208:209], off offset:96
	v_or_b32_e32 v206, 32, v66
	v_mov_b64_e32 v[208:209], s[24:25]
	v_mad_i64_i32 v[208:209], s[98:99], v206, s8, v[208:209]
	v_lshl_add_u64 v[208:209], v[208:209], 0, v[0:1]
	global_load_dwordx2 v[188:189], v[208:209], off
	global_load_dwordx2 v[190:191], v[208:209], off offset:32
	global_load_dwordx2 v[192:193], v[208:209], off offset:64
	global_load_dwordx2 v[194:195], v[208:209], off offset:96
	v_or_b32_e32 v206, 48, v66
	v_mov_b64_e32 v[208:209], s[24:25]
	v_mad_i64_i32 v[208:209], s[98:99], v206, s8, v[208:209]
	v_lshl_add_u64 v[208:209], v[208:209], 0, v[0:1]
	global_load_dwordx2 v[196:197], v[208:209], off
	global_load_dwordx2 v[198:199], v[208:209], off offset:32
	global_load_dwordx2 v[202:203], v[208:209], off offset:64
	global_load_dwordx2 v[204:205], v[208:209], off offset:96
	s_cmp_lg_u32 s63, 0
	s_cselect_b64 s[26:27], -1, 0
	s_cmp_eq_u32 s63, 0
	s_waitcnt vmcnt(15)
	v_mov_b32_e32 v72, v172
	v_mov_b32_e32 v73, v173
	v_lshlrev_b32_e32 v67, 16, v72
	v_mul_f32_e32 v67, 0xbfb8aa3b, v67
	v_exp_f32_e32 v70, v67
	v_and_b32_e32 v67, 0xffff0000, v72
	v_mul_f32_e32 v67, 0xbfb8aa3b, v67
	v_exp_f32_e32 v71, v67
	s_nop 0
	v_pk_add_f32 v[70:71], v[70:71], 1.0 op_sel_hi:[1,0]
	s_nop 0
	v_div_scale_f32 v67, s[4:5], v71, v71, 1.0
	v_rcp_f32_e32 v72, v67
	s_nop 0
	v_fma_f32 v74, -v67, v72, 1.0
	v_fmac_f32_e32 v72, v74, v72
	v_div_scale_f32 v74, vcc, 1.0, v71, 1.0
	v_mul_f32_e32 v75, v74, v72
	v_fma_f32 v76, -v67, v75, v74
	v_fmac_f32_e32 v75, v76, v72
	v_fma_f32 v67, -v67, v75, v74
	v_div_fmas_f32 v67, v67, v72, v75
	v_div_fixup_f32 v71, v67, v71, 1.0
	v_div_scale_f32 v67, s[4:5], v70, v70, 1.0
	v_rcp_f32_e32 v72, v67
	s_nop 0
	v_fma_f32 v74, -v67, v72, 1.0
	v_fmac_f32_e32 v72, v74, v72
	v_div_scale_f32 v74, vcc, 1.0, v70, 1.0
	v_mul_f32_e32 v75, v74, v72
	v_fma_f32 v76, -v67, v75, v74
	v_fmac_f32_e32 v75, v76, v72
	v_fma_f32 v67, -v67, v75, v74
	v_div_fmas_f32 v67, v67, v72, v75
	v_div_fixup_f32 v70, v67, v70, 1.0
	v_pk_mul_f32 v[70:71], v[62:63], v[70:71]
	v_lshlrev_b32_e32 v62, 16, v73
	v_and_b32_e32 v63, 0xffff0000, v73
	v_mul_f32_e32 v62, 0xbfb8aa3b, v62
	v_mul_f32_e32 v63, 0xbfb8aa3b, v63
	v_exp_f32_e32 v62, v62
	v_exp_f32_e32 v63, v63
	s_nop 0
	v_pk_add_f32 v[62:63], v[62:63], 1.0 op_sel_hi:[1,0]
	s_nop 0
	v_div_scale_f32 v67, s[4:5], v63, v63, 1.0
	v_rcp_f32_e32 v72, v67
	s_nop 0
	v_fma_f32 v73, -v67, v72, 1.0
	v_fmac_f32_e32 v72, v73, v72
	v_div_scale_f32 v73, vcc, 1.0, v63, 1.0
	v_mul_f32_e32 v74, v73, v72
	v_fma_f32 v75, -v67, v74, v73
	v_fmac_f32_e32 v74, v75, v72
	v_fma_f32 v67, -v67, v74, v73
	v_div_fmas_f32 v67, v67, v72, v74
	v_div_fixup_f32 v63, v67, v63, 1.0
	v_div_scale_f32 v67, s[4:5], v62, v62, 1.0
	v_rcp_f32_e32 v72, v67
	s_nop 0
	v_fma_f32 v73, -v67, v72, 1.0
	v_fmac_f32_e32 v72, v73, v72
	v_div_scale_f32 v73, vcc, 1.0, v62, 1.0
	v_mul_f32_e32 v74, v73, v72
	v_fma_f32 v75, -v67, v74, v73
	v_fmac_f32_e32 v74, v75, v72
	v_fma_f32 v67, -v67, v74, v73
	v_div_fmas_f32 v67, v67, v72, v74
	v_div_fixup_f32 v62, v67, v62, 1.0
	v_pk_mul_f32 v[64:65], v[64:65], v[62:63]
	s_cbranch_scc1 .LBB0_237
	v_lshlrev_b32_e32 v62, 16, v128
	v_and_b32_e32 v63, 0xffff0000, v128
	v_pk_add_f32 v[70:71], v[70:71], v[62:63]
	v_lshlrev_b32_e32 v62, 16, v129
	v_and_b32_e32 v63, 0xffff0000, v129
	v_pk_add_f32 v[64:65], v[64:65], v[62:63]

; DI unsigned pk2(float lo, float hi) { f32x2_t v; v[0] = lo; v[1] = hi; bf16x2_t b = __builtin_convertvector(v, bf16x2_t); return __builtin_bit_cast(unsigned, b); }
; DI float bflo(unsigned u) { return __uint_as_float(u << 16); }
; DI float bfhi(unsigned u) { return __uint_as_float(u & 0xffff0000u); }
; DI float sigmoidf_(float x) { return 1.f / (1.f + __expf(-x)); }
; DI void merge_item(const Params& p, int l, int item, bf16_t* lds) {
;     ...
;     EPI_LOOP({
;       u32x2 g = *(const u32x2*)(RG + (size_t)t * 3072 + br * 1024 + n0 + cl);
;       f32x4 o; o[0] = sigmoidf_(bflo(g.x)) * v[0]; o[1] = sigmoidf_(bfhi(g.x)) * v[1]; o[2] = sigmoidf_(bflo(g.y)) * v[2]; o[3] = sigmoidf_(bfhi(g.y)) * v[3];
;       if (br > 0) { u32x2 pm = mg[mi][ni]; o[0] += bflo(pm.x); o[1] += bfhi(pm.x); o[2] += bflo(pm.y); o[3] += bfhi(pm.y); }
;       u32x2 pk; pk.x = pk2(o[0], o[1]); pk.y = pk2(o[2], o[3]);
;       mg[mi][ni] = pk;
.LBB0_239:
	s_waitcnt vmcnt(14)
	v_mov_b32_e32 v64, v174
	v_mov_b32_e32 v65, v175
	v_lshlrev_b32_e32 v67, 16, v64
	v_and_b32_e32 v64, 0xffff0000, v64
	v_mul_f32_e32 v67, 0xbfb8aa3b, v67
	v_mul_f32_e32 v64, 0xbfb8aa3b, v64
	v_exp_f32_e32 v70, v67
	v_exp_f32_e32 v71, v64
	s_nop 0
	v_pk_add_f32 v[70:71], v[70:71], 1.0 op_sel_hi:[1,0]
	s_nop 0
	v_div_scale_f32 v64, s[4:5], v71, v71, 1.0
	v_rcp_f32_e32 v67, v64
	s_nop 0
	v_fma_f32 v72, -v64, v67, 1.0
	v_fmac_f32_e32 v67, v72, v67
	v_div_scale_f32 v72, vcc, 1.0, v71, 1.0
	v_mul_f32_e32 v73, v72, v67
	v_fma_f32 v74, -v64, v73, v72
	v_fmac_f32_e32 v73, v74, v67
	v_fma_f32 v64, -v64, v73, v72
	v_div_fmas_f32 v64, v64, v67, v73
	v_div_fixup_f32 v71, v64, v71, 1.0
	v_div_scale_f32 v64, s[4:5], v70, v70, 1.0
	v_rcp_f32_e32 v67, v64
	s_nop 0
	v_fma_f32 v72, -v64, v67, 1.0
	v_fmac_f32_e32 v67, v72, v67
	v_div_scale_f32 v72, vcc, 1.0, v70, 1.0
	v_mul_f32_e32 v73, v72, v67
	v_fma_f32 v74, -v64, v73, v72
	v_fmac_f32_e32 v73, v74, v67
	v_fma_f32 v64, -v64, v73, v72
	v_div_fmas_f32 v64, v64, v67, v73
	v_div_fixup_f32 v70, v64, v70, 1.0
	v_lshlrev_b32_e32 v64, 16, v65
	v_and_b32_e32 v65, 0xffff0000, v65
	v_mul_f32_e32 v64, 0xbfb8aa3b, v64
	v_mul_f32_e32 v65, 0xbfb8aa3b, v65
	v_exp_f32_e32 v64, v64
	v_exp_f32_e32 v65, v65
	v_pk_mul_f32 v[58:59], v[58:59], v[70:71]
	v_pk_add_f32 v[64:65], v[64:65], 1.0 op_sel_hi:[1,0]
	s_nop 0
	v_div_scale_f32 v67, s[4:5], v65, v65, 1.0
	v_rcp_f32_e32 v70, v67
	s_nop 0
	v_fma_f32 v71, -v67, v70, 1.0
	v_fmac_f32_e32 v70, v71, v70
	v_div_scale_f32 v71, vcc, 1.0, v65, 1.0
	v_mul_f32_e32 v72, v71, v70
	v_fma_f32 v73, -v67, v72, v71
	v_fmac_f32_e32 v72, v73, v70
	v_fma_f32 v67, -v67, v72, v71
	v_div_fmas_f32 v67, v67, v70, v72
	v_div_fixup_f32 v65, v67, v65, 1.0
	v_div_scale_f32 v67, s[4:5], v64, v64, 1.0
	v_rcp_f32_e32 v70, v67
	s_nop 0
	v_fma_f32 v71, -v67, v70, 1.0
	v_fmac_f32_e32 v70, v71, v70
	v_div_scale_f32 v71, vcc, 1.0, v64, 1.0
	v_mul_f32_e32 v72, v71, v70
	v_fma_f32 v73, -v67, v72, v71
	v_fmac_f32_e32 v72, v73, v70
	v_fma_f32 v67, -v67, v72, v71
	v_div_fmas_f32 v67, v67, v70, v72
	v_div_fixup_f32 v64, v67, v64, 1.0
	v_pk_mul_f32 v[60:61], v[60:61], v[64:65]
	v_cndmask_b32_e64 v64, 0, 1, s[26:27]
	v_cmp_ne_u32_e64 s[38:39], 1, v64
	s_andn2_b64 vcc, exec, s[26:27]
	s_cbranch_vccnz .LBB0_241
	v_lshlrev_b32_e32 v64, 16, v126
	v_and_b32_e32 v65, 0xffff0000, v126
	v_pk_add_f32 v[58:59], v[58:59], v[64:65]
	v_lshlrev_b32_e32 v64, 16, v127
	v_and_b32_e32 v65, 0xffff0000, v127
	v_pk_add_f32 v[60:61], v[60:61], v[64:65]

; DI unsigned pk2(float lo, float hi) { f32x2_t v; v[0] = lo; v[1] = hi; bf16x2_t b = __builtin_convertvector(v, bf16x2_t); return __builtin_bit_cast(unsigned, b); }
; DI float bflo(unsigned u) { return __uint_as_float(u << 16); }
; DI float bfhi(unsigned u) { return __uint_as_float(u & 0xffff0000u); }
; DI float sigmoidf_(float x) { return 1.f / (1.f + __expf(-x)); }
; DI void merge_item(const Params& p, int l, int item, bf16_t* lds) {
;     ...
;     EPI_LOOP({
;       u32x2 g = *(const u32x2*)(RG + (size_t)t * 3072 + br * 1024 + n0 + cl);
;       f32x4 o; o[0] = sigmoidf_(bflo(g.x)) * v[0]; o[1] = sigmoidf_(bfhi(g.x)) * v[1]; o[2] = sigmoidf_(bflo(g.y)) * v[2]; o[3] = sigmoidf_(bfhi(g.y)) * v[3];
;       if (br > 0) { u32x2 pm = mg[mi][ni]; o[0] += bflo(pm.x); o[1] += bfhi(pm.x); o[2] += bflo(pm.y); o[3] += bfhi(pm.y); }
;       u32x2 pk; pk.x = pk2(o[0], o[1]); pk.y = pk2(o[2], o[3]);
;       mg[mi][ni] = pk;
.LBB0_243:
	s_waitcnt vmcnt(13)
	v_mov_b32_e32 v58, v176
	v_mov_b32_e32 v59, v177
	v_lshlrev_b32_e32 v60, 16, v58
	v_and_b32_e32 v58, 0xffff0000, v58
	v_mul_f32_e32 v60, 0xbfb8aa3b, v60
	v_mul_f32_e32 v58, 0xbfb8aa3b, v58
	v_exp_f32_e32 v60, v60
	v_exp_f32_e32 v61, v58
	s_nop 0
	v_pk_add_f32 v[60:61], v[60:61], 1.0 op_sel_hi:[1,0]
	s_nop 0
	v_div_scale_f32 v58, s[4:5], v61, v61, 1.0
	v_rcp_f32_e32 v64, v58
	s_nop 0
	v_fma_f32 v65, -v58, v64, 1.0
	v_fmac_f32_e32 v64, v65, v64
	v_div_scale_f32 v65, vcc, 1.0, v61, 1.0
	v_mul_f32_e32 v67, v65, v64
	v_fma_f32 v70, -v58, v67, v65
	v_fmac_f32_e32 v67, v70, v64
	v_fma_f32 v58, -v58, v67, v65
	v_div_fmas_f32 v58, v58, v64, v67
	v_div_fixup_f32 v61, v58, v61, 1.0
	v_div_scale_f32 v58, s[4:5], v60, v60, 1.0
	v_rcp_f32_e32 v64, v58
	s_nop 0
	v_fma_f32 v65, -v58, v64, 1.0
	v_fmac_f32_e32 v64, v65, v64
	v_div_scale_f32 v65, vcc, 1.0, v60, 1.0
	v_mul_f32_e32 v67, v65, v64
	v_fma_f32 v70, -v58, v67, v65
	v_fmac_f32_e32 v67, v70, v64
	v_fma_f32 v58, -v58, v67, v65
	v_div_fmas_f32 v58, v58, v64, v67
	v_div_fixup_f32 v60, v58, v60, 1.0
	v_lshlrev_b32_e32 v58, 16, v59
	v_and_b32_e32 v59, 0xffff0000, v59
	v_mul_f32_e32 v58, 0xbfb8aa3b, v58
	v_mul_f32_e32 v59, 0xbfb8aa3b, v59
	v_exp_f32_e32 v58, v58
	v_exp_f32_e32 v59, v59
	v_pk_mul_f32 v[54:55], v[54:55], v[60:61]
	v_pk_add_f32 v[58:59], v[58:59], 1.0 op_sel_hi:[1,0]
	s_nop 0
	v_div_scale_f32 v60, s[4:5], v59, v59, 1.0
	v_rcp_f32_e32 v61, v60
	s_nop 0
	v_fma_f32 v64, -v60, v61, 1.0
	v_fmac_f32_e32 v61, v64, v61
	v_div_scale_f32 v64, vcc, 1.0, v59, 1.0
	v_mul_f32_e32 v65, v64, v61
	v_fma_f32 v67, -v60, v65, v64
	v_fmac_f32_e32 v65, v67, v61
	v_fma_f32 v60, -v60, v65, v64
	v_div_fmas_f32 v60, v60, v61, v65
	v_div_fixup_f32 v59, v60, v59, 1.0
	v_div_scale_f32 v60, s[4:5], v58, v58, 1.0
	v_rcp_f32_e32 v61, v60
	s_nop 0
	v_fma_f32 v64, -v60, v61, 1.0
	v_fmac_f32_e32 v61, v64, v61
	v_div_scale_f32 v64, vcc, 1.0, v58, 1.0
	v_mul_f32_e32 v65, v64, v61
	v_fma_f32 v67, -v60, v65, v64
	v_fmac_f32_e32 v65, v67, v61
	v_fma_f32 v60, -v60, v65, v64
	v_div_fmas_f32 v60, v60, v61, v65
	v_div_fixup_f32 v58, v60, v58, 1.0
	v_pk_mul_f32 v[56:57], v[56:57], v[58:59]
	s_and_b64 vcc, exec, s[38:39]
	s_cbranch_vccnz .LBB0_245
	v_lshlrev_b32_e32 v58, 16, v122
	v_and_b32_e32 v59, 0xffff0000, v122
	v_pk_add_f32 v[54:55], v[54:55], v[58:59]
	v_lshlrev_b32_e32 v58, 16, v123
	v_and_b32_e32 v59, 0xffff0000, v123
	v_pk_add_f32 v[56:57], v[56:57], v[58:59]

; DI unsigned pk2(float lo, float hi) { f32x2_t v; v[0] = lo; v[1] = hi; bf16x2_t b = __builtin_convertvector(v, bf16x2_t); return __builtin_bit_cast(unsigned, b); }
; DI float bflo(unsigned u) { return __uint_as_float(u << 16); }
; DI float bfhi(unsigned u) { return __uint_as_float(u & 0xffff0000u); }
; DI float sigmoidf_(float x) { return 1.f / (1.f + __expf(-x)); }
; DI void merge_item(const Params& p, int l, int item, bf16_t* lds) {
;     ...
;     EPI_LOOP({
;       u32x2 g = *(const u32x2*)(RG + (size_t)t * 3072 + br * 1024 + n0 + cl);
;       f32x4 o; o[0] = sigmoidf_(bflo(g.x)) * v[0]; o[1] = sigmoidf_(bfhi(g.x)) * v[1]; o[2] = sigmoidf_(bflo(g.y)) * v[2]; o[3] = sigmoidf_(bfhi(g.y)) * v[3];
;       if (br > 0) { u32x2 pm = mg[mi][ni]; o[0] += bflo(pm.x); o[1] += bfhi(pm.x); o[2] += bflo(pm.y); o[3] += bfhi(pm.y); }
;       u32x2 pk; pk.x = pk2(o[0], o[1]); pk.y = pk2(o[2], o[3]);
;       mg[mi][ni] = pk;
.LBB0_247:
	s_waitcnt vmcnt(12)
	v_mov_b32_e32 v54, v178
	v_mov_b32_e32 v55, v179
	v_lshlrev_b32_e32 v56, 16, v54
	v_and_b32_e32 v54, 0xffff0000, v54
	v_mul_f32_e32 v56, 0xbfb8aa3b, v56
	v_mul_f32_e32 v54, 0xbfb8aa3b, v54
	v_exp_f32_e32 v56, v56
	v_exp_f32_e32 v57, v54
	s_nop 0
	v_pk_add_f32 v[56:57], v[56:57], 1.0 op_sel_hi:[1,0]
	s_nop 0
	v_div_scale_f32 v54, s[4:5], v57, v57, 1.0
	v_rcp_f32_e32 v58, v54
	s_nop 0
	v_fma_f32 v59, -v54, v58, 1.0
	v_fmac_f32_e32 v58, v59, v58
	v_div_scale_f32 v59, vcc, 1.0, v57, 1.0
	v_mul_f32_e32 v60, v59, v58
	v_fma_f32 v61, -v54, v60, v59
	v_fmac_f32_e32 v60, v61, v58
	v_fma_f32 v54, -v54, v60, v59
	v_div_fmas_f32 v54, v54, v58, v60
	v_div_fixup_f32 v57, v54, v57, 1.0
	v_div_scale_f32 v54, s[4:5], v56, v56, 1.0
	v_rcp_f32_e32 v58, v54
	s_nop 0
	v_fma_f32 v59, -v54, v58, 1.0
	v_fmac_f32_e32 v58, v59, v58
	v_div_scale_f32 v59, vcc, 1.0, v56, 1.0
	v_mul_f32_e32 v60, v59, v58
	v_fma_f32 v61, -v54, v60, v59
	v_fmac_f32_e32 v60, v61, v58
	v_fma_f32 v54, -v54, v60, v59
	v_div_fmas_f32 v54, v54, v58, v60
	v_div_fixup_f32 v56, v54, v56, 1.0
	v_lshlrev_b32_e32 v54, 16, v55
	v_and_b32_e32 v55, 0xffff0000, v55
	v_mul_f32_e32 v54, 0xbfb8aa3b, v54
	v_mul_f32_e32 v55, 0xbfb8aa3b, v55
	v_exp_f32_e32 v54, v54
	v_exp_f32_e32 v55, v55
	v_pk_mul_f32 v[50:51], v[50:51], v[56:57]
	v_pk_add_f32 v[54:55], v[54:55], 1.0 op_sel_hi:[1,0]
	s_nop 0
	v_div_scale_f32 v56, s[4:5], v55, v55, 1.0
	v_rcp_f32_e32 v57, v56
	s_nop 0
	v_fma_f32 v58, -v56, v57, 1.0
	v_fmac_f32_e32 v57, v58, v57
	v_div_scale_f32 v58, vcc, 1.0, v55, 1.0
	v_mul_f32_e32 v59, v58, v57
	v_fma_f32 v60, -v56, v59, v58
	v_fmac_f32_e32 v59, v60, v57
	v_fma_f32 v56, -v56, v59, v58
	v_div_fmas_f32 v56, v56, v57, v59
	v_div_fixup_f32 v55, v56, v55, 1.0
	v_div_scale_f32 v56, s[4:5], v54, v54, 1.0
	v_rcp_f32_e32 v57, v56
	s_nop 0
	v_fma_f32 v58, -v56, v57, 1.0
	v_fmac_f32_e32 v57, v58, v57
	v_div_scale_f32 v58, vcc, 1.0, v54, 1.0
	v_mul_f32_e32 v59, v58, v57
	v_fma_f32 v60, -v56, v59, v58
	v_fmac_f32_e32 v59, v60, v57
	v_fma_f32 v56, -v56, v59, v58
	v_div_fmas_f32 v56, v56, v57, v59
	v_div_fixup_f32 v54, v56, v54, 1.0
	v_pk_mul_f32 v[52:53], v[52:53], v[54:55]
	s_and_b64 vcc, exec, s[38:39]
	s_cbranch_vccnz .LBB0_249
	v_lshlrev_b32_e32 v54, 16, v120
	v_and_b32_e32 v55, 0xffff0000, v120
	v_pk_add_f32 v[50:51], v[50:51], v[54:55]
	v_lshlrev_b32_e32 v54, 16, v121
	v_and_b32_e32 v55, 0xffff0000, v121
	v_pk_add_f32 v[52:53], v[52:53], v[54:55]

; DI unsigned pk2(float lo, float hi) { f32x2_t v; v[0] = lo; v[1] = hi; bf16x2_t b = __builtin_convertvector(v, bf16x2_t); return __builtin_bit_cast(unsigned, b); }
; DI float bflo(unsigned u) { return __uint_as_float(u << 16); }
; DI float bfhi(unsigned u) { return __uint_as_float(u & 0xffff0000u); }
; DI float sigmoidf_(float x) { return 1.f / (1.f + __expf(-x)); }
; DI void merge_item(const Params& p, int l, int item, bf16_t* lds) {
;     ...
;     EPI_LOOP({
;       u32x2 g = *(const u32x2*)(RG + (size_t)t * 3072 + br * 1024 + n0 + cl);
;       f32x4 o; o[0] = sigmoidf_(bflo(g.x)) * v[0]; o[1] = sigmoidf_(bfhi(g.x)) * v[1]; o[2] = sigmoidf_(bflo(g.y)) * v[2]; o[3] = sigmoidf_(bfhi(g.y)) * v[3];
;       if (br > 0) { u32x2 pm = mg[mi][ni]; o[0] += bflo(pm.x); o[1] += bfhi(pm.x); o[2] += bflo(pm.y); o[3] += bfhi(pm.y); }
;       u32x2 pk; pk.x = pk2(o[0], o[1]); pk.y = pk2(o[2], o[3]);
;       mg[mi][ni] = pk;
.LBB0_251:
	v_or_b32_e32 v52, 16, v66
	v_mov_b64_e32 v[50:51], s[24:25]
	v_mad_i64_i32 v[50:51], s[4:5], v52, s8, v[50:51]
	v_lshl_add_u64 v[50:51], v[50:51], 0, v[0:1]
	s_waitcnt vmcnt(11)
	v_mov_b32_e32 v56, v180
	v_mov_b32_e32 v57, v181
	v_lshlrev_b32_e32 v53, 16, v56
	v_mul_f32_e32 v53, 0xbfb8aa3b, v53
	v_exp_f32_e32 v54, v53
	v_and_b32_e32 v53, 0xffff0000, v56
	v_mul_f32_e32 v53, 0xbfb8aa3b, v53
	v_exp_f32_e32 v55, v53
	s_nop 0
	v_pk_add_f32 v[54:55], v[54:55], 1.0 op_sel_hi:[1,0]
	s_nop 0
	v_div_scale_f32 v53, s[4:5], v55, v55, 1.0
	v_rcp_f32_e32 v56, v53
	s_nop 0
	v_fma_f32 v58, -v53, v56, 1.0
	v_fmac_f32_e32 v56, v58, v56
	v_div_scale_f32 v58, vcc, 1.0, v55, 1.0
	v_mul_f32_e32 v59, v58, v56
	v_fma_f32 v60, -v53, v59, v58
	v_fmac_f32_e32 v59, v60, v56
	v_fma_f32 v53, -v53, v59, v58
	v_div_fmas_f32 v53, v53, v56, v59
	v_div_fixup_f32 v55, v53, v55, 1.0
	v_div_scale_f32 v53, s[4:5], v54, v54, 1.0
	v_rcp_f32_e32 v56, v53
	s_nop 0
	v_fma_f32 v58, -v53, v56, 1.0
	v_fmac_f32_e32 v56, v58, v56
	v_div_scale_f32 v58, vcc, 1.0, v54, 1.0
	v_mul_f32_e32 v59, v58, v56
	v_fma_f32 v60, -v53, v59, v58
	v_fmac_f32_e32 v59, v60, v56
	v_fma_f32 v53, -v53, v59, v58
	v_div_fmas_f32 v53, v53, v56, v59
	v_div_fixup_f32 v54, v53, v54, 1.0
	v_pk_mul_f32 v[54:55], v[46:47], v[54:55]
	v_lshlrev_b32_e32 v46, 16, v57
	v_and_b32_e32 v47, 0xffff0000, v57
	v_mul_f32_e32 v46, 0xbfb8aa3b, v46
	v_mul_f32_e32 v47, 0xbfb8aa3b, v47
	v_exp_f32_e32 v46, v46
	v_exp_f32_e32 v47, v47
	s_nop 0
	v_pk_add_f32 v[46:47], v[46:47], 1.0 op_sel_hi:[1,0]
	s_nop 0
	v_div_scale_f32 v53, s[4:5], v47, v47, 1.0
	v_rcp_f32_e32 v56, v53
	s_nop 0
	v_fma_f32 v57, -v53, v56, 1.0
	v_fmac_f32_e32 v56, v57, v56
	v_div_scale_f32 v57, vcc, 1.0, v47, 1.0
	v_mul_f32_e32 v58, v57, v56
	v_fma_f32 v59, -v53, v58, v57
	v_fmac_f32_e32 v58, v59, v56
	v_fma_f32 v53, -v53, v58, v57
	v_div_fmas_f32 v53, v53, v56, v58
	v_div_fixup_f32 v47, v53, v47, 1.0
	v_div_scale_f32 v53, s[4:5], v46, v46, 1.0
	v_rcp_f32_e32 v56, v53
	s_nop 0
	v_fma_f32 v57, -v53, v56, 1.0
	v_fmac_f32_e32 v56, v57, v56
	v_div_scale_f32 v57, vcc, 1.0, v46, 1.0
	v_mul_f32_e32 v58, v57, v56
	v_fma_f32 v59, -v53, v58, v57
	v_fmac_f32_e32 v58, v59, v56
	v_fma_f32 v53, -v53, v58, v57
	v_div_fmas_f32 v53, v53, v56, v58
	v_div_fixup_f32 v46, v53, v46, 1.0
	v_pk_mul_f32 v[48:49], v[48:49], v[46:47]
	s_and_b64 vcc, exec, s[38:39]
	s_cbranch_vccnz .LBB0_253
	v_lshlrev_b32_e32 v46, 16, v124
	v_and_b32_e32 v47, 0xffff0000, v124
	v_pk_add_f32 v[54:55], v[54:55], v[46:47]
	v_lshlrev_b32_e32 v46, 16, v125
	v_and_b32_e32 v47, 0xffff0000, v125
	v_pk_add_f32 v[48:49], v[48:49], v[46:47]

; DI unsigned pk2(float lo, float hi) { f32x2_t v; v[0] = lo; v[1] = hi; bf16x2_t b = __builtin_convertvector(v, bf16x2_t); return __builtin_bit_cast(unsigned, b); }
; DI float bflo(unsigned u) { return __uint_as_float(u << 16); }
; DI float bfhi(unsigned u) { return __uint_as_float(u & 0xffff0000u); }
; DI float sigmoidf_(float x) { return 1.f / (1.f + __expf(-x)); }
; DI void merge_item(const Params& p, int l, int item, bf16_t* lds) {
;     ...
;     EPI_LOOP({
;       u32x2 g = *(const u32x2*)(RG + (size_t)t * 3072 + br * 1024 + n0 + cl);
;       f32x4 o; o[0] = sigmoidf_(bflo(g.x)) * v[0]; o[1] = sigmoidf_(bfhi(g.x)) * v[1]; o[2] = sigmoidf_(bflo(g.y)) * v[2]; o[3] = sigmoidf_(bfhi(g.y)) * v[3];
;       if (br > 0) { u32x2 pm = mg[mi][ni]; o[0] += bflo(pm.x); o[1] += bfhi(pm.x); o[2] += bflo(pm.y); o[3] += bfhi(pm.y); }
;       u32x2 pk; pk.x = pk2(o[0], o[1]); pk.y = pk2(o[2], o[3]);
;       mg[mi][ni] = pk;
.LBB0_255:
	s_waitcnt vmcnt(10)
	v_mov_b32_e32 v48, v182
	v_mov_b32_e32 v49, v183
	v_lshlrev_b32_e32 v52, 16, v48
	v_and_b32_e32 v48, 0xffff0000, v48
	v_mul_f32_e32 v52, 0xbfb8aa3b, v52
	v_mul_f32_e32 v48, 0xbfb8aa3b, v48
	v_exp_f32_e32 v52, v52
	v_exp_f32_e32 v53, v48
	s_nop 0
	v_pk_add_f32 v[52:53], v[52:53], 1.0 op_sel_hi:[1,0]
	s_nop 0
	v_div_scale_f32 v48, s[4:5], v53, v53, 1.0
	v_rcp_f32_e32 v54, v48
	s_nop 0
	v_fma_f32 v55, -v48, v54, 1.0
	v_fmac_f32_e32 v54, v55, v54
	v_div_scale_f32 v55, vcc, 1.0, v53, 1.0
	v_mul_f32_e32 v56, v55, v54
	v_fma_f32 v57, -v48, v56, v55
	v_fmac_f32_e32 v56, v57, v54
	v_fma_f32 v48, -v48, v56, v55
	v_div_fmas_f32 v48, v48, v54, v56
	v_div_fixup_f32 v53, v48, v53, 1.0
	v_div_scale_f32 v48, s[4:5], v52, v52, 1.0
	v_rcp_f32_e32 v54, v48
	s_nop 0
	v_fma_f32 v55, -v48, v54, 1.0
	v_fmac_f32_e32 v54, v55, v54
	v_div_scale_f32 v55, vcc, 1.0, v52, 1.0
	v_mul_f32_e32 v56, v55, v54
	v_fma_f32 v57, -v48, v56, v55
	v_fmac_f32_e32 v56, v57, v54
	v_fma_f32 v48, -v48, v56, v55
	v_div_fmas_f32 v48, v48, v54, v56
	v_div_fixup_f32 v52, v48, v52, 1.0
	v_lshlrev_b32_e32 v48, 16, v49
	v_and_b32_e32 v49, 0xffff0000, v49
	v_mul_f32_e32 v48, 0xbfb8aa3b, v48
	v_mul_f32_e32 v49, 0xbfb8aa3b, v49
	v_exp_f32_e32 v48, v48
	v_exp_f32_e32 v49, v49
	v_pk_mul_f32 v[42:43], v[42:43], v[52:53]
	v_pk_add_f32 v[48:49], v[48:49], 1.0 op_sel_hi:[1,0]
	s_nop 0
	v_div_scale_f32 v52, s[4:5], v49, v49, 1.0
	v_rcp_f32_e32 v53, v52
	s_nop 0
	v_fma_f32 v54, -v52, v53, 1.0
	v_fmac_f32_e32 v53, v54, v53
	v_div_scale_f32 v54, vcc, 1.0, v49, 1.0
	v_mul_f32_e32 v55, v54, v53
	v_fma_f32 v56, -v52, v55, v54
	v_fmac_f32_e32 v55, v56, v53
	v_fma_f32 v52, -v52, v55, v54
	v_div_fmas_f32 v52, v52, v53, v55
	v_div_fixup_f32 v49, v52, v49, 1.0
	v_div_scale_f32 v52, s[4:5], v48, v48, 1.0
	v_rcp_f32_e32 v53, v52
	s_nop 0
	v_fma_f32 v54, -v52, v53, 1.0
	v_fmac_f32_e32 v53, v54, v53
	v_div_scale_f32 v54, vcc, 1.0, v48, 1.0
	v_mul_f32_e32 v55, v54, v53
	v_fma_f32 v56, -v52, v55, v54
	v_fmac_f32_e32 v55, v56, v53
	v_fma_f32 v52, -v52, v55, v54
	v_div_fmas_f32 v52, v52, v53, v55
	v_div_fixup_f32 v48, v52, v48, 1.0
	v_pk_mul_f32 v[44:45], v[44:45], v[48:49]
	s_and_b64 vcc, exec, s[38:39]
	s_cbranch_vccnz .LBB0_257
	v_lshlrev_b32_e32 v48, 16, v118
	v_and_b32_e32 v49, 0xffff0000, v118
	v_pk_add_f32 v[42:43], v[42:43], v[48:49]
	v_lshlrev_b32_e32 v48, 16, v119
	v_and_b32_e32 v49, 0xffff0000, v119
	v_pk_add_f32 v[44:45], v[44:45], v[48:49]

; DI unsigned pk2(float lo, float hi) { f32x2_t v; v[0] = lo; v[1] = hi; bf16x2_t b = __builtin_convertvector(v, bf16x2_t); return __builtin_bit_cast(unsigned, b); }
; DI float bflo(unsigned u) { return __uint_as_float(u << 16); }
; DI float bfhi(unsigned u) { return __uint_as_float(u & 0xffff0000u); }
; DI float sigmoidf_(float x) { return 1.f / (1.f + __expf(-x)); }
; DI void merge_item(const Params& p, int l, int item, bf16_t* lds) {
;     ...
;     EPI_LOOP({
;       u32x2 g = *(const u32x2*)(RG + (size_t)t * 3072 + br * 1024 + n0 + cl);
;       f32x4 o; o[0] = sigmoidf_(bflo(g.x)) * v[0]; o[1] = sigmoidf_(bfhi(g.x)) * v[1]; o[2] = sigmoidf_(bflo(g.y)) * v[2]; o[3] = sigmoidf_(bfhi(g.y)) * v[3];
;       if (br > 0) { u32x2 pm = mg[mi][ni]; o[0] += bflo(pm.x); o[1] += bfhi(pm.x); o[2] += bflo(pm.y); o[3] += bfhi(pm.y); }
;       u32x2 pk; pk.x = pk2(o[0], o[1]); pk.y = pk2(o[2], o[3]);
;       mg[mi][ni] = pk;
.LBB0_259:
	s_waitcnt vmcnt(9)
	v_mov_b32_e32 v42, v184
	v_mov_b32_e32 v43, v185
	v_lshlrev_b32_e32 v44, 16, v42
	v_and_b32_e32 v42, 0xffff0000, v42
	v_mul_f32_e32 v44, 0xbfb8aa3b, v44
	v_mul_f32_e32 v42, 0xbfb8aa3b, v42
	v_exp_f32_e32 v44, v44
	v_exp_f32_e32 v45, v42
	s_nop 0
	v_pk_add_f32 v[44:45], v[44:45], 1.0 op_sel_hi:[1,0]
	s_nop 0
	v_div_scale_f32 v42, s[4:5], v45, v45, 1.0
	v_rcp_f32_e32 v48, v42
	s_nop 0
	v_fma_f32 v49, -v42, v48, 1.0
	v_fmac_f32_e32 v48, v49, v48
	v_div_scale_f32 v49, vcc, 1.0, v45, 1.0
	v_mul_f32_e32 v52, v49, v48
	v_fma_f32 v53, -v42, v52, v49
	v_fmac_f32_e32 v52, v53, v48
	v_fma_f32 v42, -v42, v52, v49
	v_div_fmas_f32 v42, v42, v48, v52
	v_div_fixup_f32 v45, v42, v45, 1.0
	v_div_scale_f32 v42, s[4:5], v44, v44, 1.0
	v_rcp_f32_e32 v48, v42
	s_nop 0
	v_fma_f32 v49, -v42, v48, 1.0
	v_fmac_f32_e32 v48, v49, v48
	v_div_scale_f32 v49, vcc, 1.0, v44, 1.0
	v_mul_f32_e32 v52, v49, v48
	v_fma_f32 v53, -v42, v52, v49
	v_fmac_f32_e32 v52, v53, v48
	v_fma_f32 v42, -v42, v52, v49
	v_div_fmas_f32 v42, v42, v48, v52
	v_div_fixup_f32 v44, v42, v44, 1.0
	v_lshlrev_b32_e32 v42, 16, v43
	v_and_b32_e32 v43, 0xffff0000, v43
	v_mul_f32_e32 v42, 0xbfb8aa3b, v42
	v_mul_f32_e32 v43, 0xbfb8aa3b, v43
	v_exp_f32_e32 v42, v42
	v_exp_f32_e32 v43, v43
	v_pk_mul_f32 v[38:39], v[38:39], v[44:45]
	v_pk_add_f32 v[42:43], v[42:43], 1.0 op_sel_hi:[1,0]
	s_nop 0
	v_div_scale_f32 v44, s[4:5], v43, v43, 1.0
	v_rcp_f32_e32 v45, v44
	s_nop 0
	v_fma_f32 v48, -v44, v45, 1.0
	v_fmac_f32_e32 v45, v48, v45
	v_div_scale_f32 v48, vcc, 1.0, v43, 1.0
	v_mul_f32_e32 v49, v48, v45
	v_fma_f32 v52, -v44, v49, v48
	v_fmac_f32_e32 v49, v52, v45
	v_fma_f32 v44, -v44, v49, v48
	v_div_fmas_f32 v44, v44, v45, v49
	v_div_fixup_f32 v43, v44, v43, 1.0
	v_div_scale_f32 v44, s[4:5], v42, v42, 1.0
	v_rcp_f32_e32 v45, v44
	s_nop 0
	v_fma_f32 v48, -v44, v45, 1.0
	v_fmac_f32_e32 v45, v48, v45
	v_div_scale_f32 v48, vcc, 1.0, v42, 1.0
	v_mul_f32_e32 v49, v48, v45
	v_fma_f32 v52, -v44, v49, v48
	v_fmac_f32_e32 v49, v52, v45
	v_fma_f32 v44, -v44, v49, v48
	v_div_fmas_f32 v44, v44, v45, v49
	v_div_fixup_f32 v42, v44, v42, 1.0
	v_pk_mul_f32 v[40:41], v[40:41], v[42:43]
	s_and_b64 vcc, exec, s[38:39]
	s_cbranch_vccnz .LBB0_261
	v_lshlrev_b32_e32 v42, 16, v114
	v_and_b32_e32 v43, 0xffff0000, v114
	v_pk_add_f32 v[38:39], v[38:39], v[42:43]
	v_lshlrev_b32_e32 v42, 16, v115
	v_and_b32_e32 v43, 0xffff0000, v115
	v_pk_add_f32 v[40:41], v[40:41], v[42:43]

; DI unsigned pk2(float lo, float hi) { f32x2_t v; v[0] = lo; v[1] = hi; bf16x2_t b = __builtin_convertvector(v, bf16x2_t); return __builtin_bit_cast(unsigned, b); }
; DI float bflo(unsigned u) { return __uint_as_float(u << 16); }
; DI float bfhi(unsigned u) { return __uint_as_float(u & 0xffff0000u); }
; DI float sigmoidf_(float x) { return 1.f / (1.f + __expf(-x)); }
; DI void merge_item(const Params& p, int l, int item, bf16_t* lds) {
;     ...
;     EPI_LOOP({
;       u32x2 g = *(const u32x2*)(RG + (size_t)t * 3072 + br * 1024 + n0 + cl);
;       f32x4 o; o[0] = sigmoidf_(bflo(g.x)) * v[0]; o[1] = sigmoidf_(bfhi(g.x)) * v[1]; o[2] = sigmoidf_(bflo(g.y)) * v[2]; o[3] = sigmoidf_(bfhi(g.y)) * v[3];
;       if (br > 0) { u32x2 pm = mg[mi][ni]; o[0] += bflo(pm.x); o[1] += bfhi(pm.x); o[2] += bflo(pm.y); o[3] += bfhi(pm.y); }
;       u32x2 pk; pk.x = pk2(o[0], o[1]); pk.y = pk2(o[2], o[3]);
;       mg[mi][ni] = pk;
.LBB0_263:
	s_waitcnt vmcnt(8)
	v_mov_b32_e32 v38, v186
	v_mov_b32_e32 v39, v187
	v_lshlrev_b32_e32 v40, 16, v38
	v_and_b32_e32 v38, 0xffff0000, v38
	v_mul_f32_e32 v40, 0xbfb8aa3b, v40
	v_mul_f32_e32 v38, 0xbfb8aa3b, v38
	v_exp_f32_e32 v40, v40
	v_exp_f32_e32 v41, v38
	s_nop 0
	v_pk_add_f32 v[40:41], v[40:41], 1.0 op_sel_hi:[1,0]
	s_nop 0
	v_div_scale_f32 v38, s[4:5], v41, v41, 1.0
	v_rcp_f32_e32 v42, v38
	s_nop 0
	v_fma_f32 v43, -v38, v42, 1.0
	v_fmac_f32_e32 v42, v43, v42
	v_div_scale_f32 v43, vcc, 1.0, v41, 1.0
	v_mul_f32_e32 v44, v43, v42
	v_fma_f32 v45, -v38, v44, v43
	v_fmac_f32_e32 v44, v45, v42
	v_fma_f32 v38, -v38, v44, v43
	v_div_fmas_f32 v38, v38, v42, v44
	v_div_fixup_f32 v41, v38, v41, 1.0
	v_div_scale_f32 v38, s[4:5], v40, v40, 1.0
	v_rcp_f32_e32 v42, v38
	s_nop 0
	v_fma_f32 v43, -v38, v42, 1.0
	v_fmac_f32_e32 v42, v43, v42
	v_div_scale_f32 v43, vcc, 1.0, v40, 1.0
	v_mul_f32_e32 v44, v43, v42
	v_fma_f32 v45, -v38, v44, v43
	v_fmac_f32_e32 v44, v45, v42
	v_fma_f32 v38, -v38, v44, v43
	v_div_fmas_f32 v38, v38, v42, v44
	v_div_fixup_f32 v40, v38, v40, 1.0
	v_lshlrev_b32_e32 v38, 16, v39
	v_and_b32_e32 v39, 0xffff0000, v39
	v_mul_f32_e32 v38, 0xbfb8aa3b, v38
	v_mul_f32_e32 v39, 0xbfb8aa3b, v39
	v_exp_f32_e32 v38, v38
	v_exp_f32_e32 v39, v39
	v_pk_mul_f32 v[34:35], v[34:35], v[40:41]
	v_pk_add_f32 v[38:39], v[38:39], 1.0 op_sel_hi:[1,0]
	s_nop 0
	v_div_scale_f32 v40, s[4:5], v39, v39, 1.0
	v_rcp_f32_e32 v41, v40
	s_nop 0
	v_fma_f32 v42, -v40, v41, 1.0
	v_fmac_f32_e32 v41, v42, v41
	v_div_scale_f32 v42, vcc, 1.0, v39, 1.0
	v_mul_f32_e32 v43, v42, v41
	v_fma_f32 v44, -v40, v43, v42
	v_fmac_f32_e32 v43, v44, v41
	v_fma_f32 v40, -v40, v43, v42
	v_div_fmas_f32 v40, v40, v41, v43
	v_div_fixup_f32 v39, v40, v39, 1.0
	v_div_scale_f32 v40, s[4:5], v38, v38, 1.0
	v_rcp_f32_e32 v41, v40
	s_nop 0
	v_fma_f32 v42, -v40, v41, 1.0
	v_fmac_f32_e32 v41, v42, v41
	v_div_scale_f32 v42, vcc, 1.0, v38, 1.0
	v_mul_f32_e32 v43, v42, v41
	v_fma_f32 v44, -v40, v43, v42
	v_fmac_f32_e32 v43, v44, v41
	v_fma_f32 v40, -v40, v43, v42
	v_div_fmas_f32 v40, v40, v41, v43
	v_div_fixup_f32 v38, v40, v38, 1.0
	v_pk_mul_f32 v[36:37], v[36:37], v[38:39]
	s_and_b64 vcc, exec, s[38:39]
	s_cbranch_vccnz .LBB0_265
	v_lshlrev_b32_e32 v38, 16, v112
	v_and_b32_e32 v39, 0xffff0000, v112
	v_pk_add_f32 v[34:35], v[34:35], v[38:39]
	v_lshlrev_b32_e32 v38, 16, v113
	v_and_b32_e32 v39, 0xffff0000, v113
	v_pk_add_f32 v[36:37], v[36:37], v[38:39]

; DI unsigned pk2(float lo, float hi) { f32x2_t v; v[0] = lo; v[1] = hi; bf16x2_t b = __builtin_convertvector(v, bf16x2_t); return __builtin_bit_cast(unsigned, b); }
; DI float bflo(unsigned u) { return __uint_as_float(u << 16); }
; DI float bfhi(unsigned u) { return __uint_as_float(u & 0xffff0000u); }
; DI float sigmoidf_(float x) { return 1.f / (1.f + __expf(-x)); }
; DI void merge_item(const Params& p, int l, int item, bf16_t* lds) {
;     ...
;     EPI_LOOP({
;       u32x2 g = *(const u32x2*)(RG + (size_t)t * 3072 + br * 1024 + n0 + cl);
;       f32x4 o; o[0] = sigmoidf_(bflo(g.x)) * v[0]; o[1] = sigmoidf_(bfhi(g.x)) * v[1]; o[2] = sigmoidf_(bflo(g.y)) * v[2]; o[3] = sigmoidf_(bfhi(g.y)) * v[3];
;       if (br > 0) { u32x2 pm = mg[mi][ni]; o[0] += bflo(pm.x); o[1] += bfhi(pm.x); o[2] += bflo(pm.y); o[3] += bfhi(pm.y); }
;       u32x2 pk; pk.x = pk2(o[0], o[1]); pk.y = pk2(o[2], o[3]);
;       mg[mi][ni] = pk;
.LBB0_267:
	v_or_b32_e32 v36, 32, v66
	v_mov_b64_e32 v[34:35], s[24:25]
	v_mad_i64_i32 v[34:35], s[4:5], v36, s8, v[34:35]
	v_lshl_add_u64 v[34:35], v[34:35], 0, v[0:1]
	s_waitcnt vmcnt(7)
	v_mov_b32_e32 v40, v188
	v_mov_b32_e32 v41, v189
	v_lshlrev_b32_e32 v37, 16, v40
	v_mul_f32_e32 v37, 0xbfb8aa3b, v37
	v_exp_f32_e32 v38, v37
	v_and_b32_e32 v37, 0xffff0000, v40
	v_mul_f32_e32 v37, 0xbfb8aa3b, v37
	v_exp_f32_e32 v39, v37
	s_nop 0
	v_pk_add_f32 v[38:39], v[38:39], 1.0 op_sel_hi:[1,0]
	s_nop 0
	v_div_scale_f32 v37, s[4:5], v39, v39, 1.0
	v_rcp_f32_e32 v40, v37
	s_nop 0
	v_fma_f32 v42, -v37, v40, 1.0
	v_fmac_f32_e32 v40, v42, v40
	v_div_scale_f32 v42, vcc, 1.0, v39, 1.0
	v_mul_f32_e32 v43, v42, v40
	v_fma_f32 v44, -v37, v43, v42
	v_fmac_f32_e32 v43, v44, v40
	v_fma_f32 v37, -v37, v43, v42
	v_div_fmas_f32 v37, v37, v40, v43
	v_div_fixup_f32 v39, v37, v39, 1.0
	v_div_scale_f32 v37, s[4:5], v38, v38, 1.0
	v_rcp_f32_e32 v40, v37
	s_nop 0
	v_fma_f32 v42, -v37, v40, 1.0
	v_fmac_f32_e32 v40, v42, v40
	v_div_scale_f32 v42, vcc, 1.0, v38, 1.0
	v_mul_f32_e32 v43, v42, v40
	v_fma_f32 v44, -v37, v43, v42
	v_fmac_f32_e32 v43, v44, v40
	v_fma_f32 v37, -v37, v43, v42
	v_div_fmas_f32 v37, v37, v40, v43
	v_div_fixup_f32 v38, v37, v38, 1.0
	v_pk_mul_f32 v[38:39], v[30:31], v[38:39]
	v_lshlrev_b32_e32 v30, 16, v41
	v_and_b32_e32 v31, 0xffff0000, v41
	v_mul_f32_e32 v30, 0xbfb8aa3b, v30
	v_mul_f32_e32 v31, 0xbfb8aa3b, v31
	v_exp_f32_e32 v30, v30
	v_exp_f32_e32 v31, v31
	s_nop 0
	v_pk_add_f32 v[30:31], v[30:31], 1.0 op_sel_hi:[1,0]
	s_nop 0
	v_div_scale_f32 v37, s[4:5], v31, v31, 1.0
	v_rcp_f32_e32 v40, v37
	s_nop 0
	v_fma_f32 v41, -v37, v40, 1.0
	v_fmac_f32_e32 v40, v41, v40
	v_div_scale_f32 v41, vcc, 1.0, v31, 1.0
	v_mul_f32_e32 v42, v41, v40
	v_fma_f32 v43, -v37, v42, v41
	v_fmac_f32_e32 v42, v43, v40
	v_fma_f32 v37, -v37, v42, v41
	v_div_fmas_f32 v37, v37, v40, v42
	v_div_fixup_f32 v31, v37, v31, 1.0
	v_div_scale_f32 v37, s[4:5], v30, v30, 1.0
	v_rcp_f32_e32 v40, v37
	s_nop 0
	v_fma_f32 v41, -v37, v40, 1.0
	v_fmac_f32_e32 v40, v41, v40
	v_div_scale_f32 v41, vcc, 1.0, v30, 1.0
	v_mul_f32_e32 v42, v41, v40
	v_fma_f32 v43, -v37, v42, v41
	v_fmac_f32_e32 v42, v43, v40
	v_fma_f32 v37, -v37, v42, v41
	v_div_fmas_f32 v37, v37, v40, v42
	v_div_fixup_f32 v30, v37, v30, 1.0
	v_pk_mul_f32 v[32:33], v[32:33], v[30:31]
	s_and_b64 vcc, exec, s[38:39]
	s_cbranch_vccnz .LBB0_269
	v_lshlrev_b32_e32 v30, 16, v116
	v_and_b32_e32 v31, 0xffff0000, v116
	v_pk_add_f32 v[38:39], v[38:39], v[30:31]
	v_lshlrev_b32_e32 v30, 16, v117
	v_and_b32_e32 v31, 0xffff0000, v117
	v_pk_add_f32 v[32:33], v[32:33], v[30:31]

; DI unsigned pk2(float lo, float hi) { f32x2_t v; v[0] = lo; v[1] = hi; bf16x2_t b = __builtin_convertvector(v, bf16x2_t); return __builtin_bit_cast(unsigned, b); }
; DI float bflo(unsigned u) { return __uint_as_float(u << 16); }
; DI float bfhi(unsigned u) { return __uint_as_float(u & 0xffff0000u); }
; DI float sigmoidf_(float x) { return 1.f / (1.f + __expf(-x)); }
; DI void merge_item(const Params& p, int l, int item, bf16_t* lds) {
;     ...
;     EPI_LOOP({
;       u32x2 g = *(const u32x2*)(RG + (size_t)t * 3072 + br * 1024 + n0 + cl);
;       f32x4 o; o[0] = sigmoidf_(bflo(g.x)) * v[0]; o[1] = sigmoidf_(bfhi(g.x)) * v[1]; o[2] = sigmoidf_(bflo(g.y)) * v[2]; o[3] = sigmoidf_(bfhi(g.y)) * v[3];
;       if (br > 0) { u32x2 pm = mg[mi][ni]; o[0] += bflo(pm.x); o[1] += bfhi(pm.x); o[2] += bflo(pm.y); o[3] += bfhi(pm.y); }
;       u32x2 pk; pk.x = pk2(o[0], o[1]); pk.y = pk2(o[2], o[3]);
;       mg[mi][ni] = pk;
.LBB0_271:
	s_waitcnt vmcnt(6)
	v_mov_b32_e32 v32, v190
	v_mov_b32_e32 v33, v191
	v_lshlrev_b32_e32 v36, 16, v32
	v_and_b32_e32 v32, 0xffff0000, v32
	v_mul_f32_e32 v36, 0xbfb8aa3b, v36
	v_mul_f32_e32 v32, 0xbfb8aa3b, v32
	v_exp_f32_e32 v36, v36
	v_exp_f32_e32 v37, v32
	s_nop 0
	v_pk_add_f32 v[36:37], v[36:37], 1.0 op_sel_hi:[1,0]
	s_nop 0
	v_div_scale_f32 v32, s[4:5], v37, v37, 1.0
	v_rcp_f32_e32 v38, v32
	s_nop 0
	v_fma_f32 v39, -v32, v38, 1.0
	v_fmac_f32_e32 v38, v39, v38
	v_div_scale_f32 v39, vcc, 1.0, v37, 1.0
	v_mul_f32_e32 v40, v39, v38
	v_fma_f32 v41, -v32, v40, v39
	v_fmac_f32_e32 v40, v41, v38
	v_fma_f32 v32, -v32, v40, v39
	v_div_fmas_f32 v32, v32, v38, v40
	v_div_fixup_f32 v37, v32, v37, 1.0
	v_div_scale_f32 v32, s[4:5], v36, v36, 1.0
	v_rcp_f32_e32 v38, v32
	s_nop 0
	v_fma_f32 v39, -v32, v38, 1.0
	v_fmac_f32_e32 v38, v39, v38
	v_div_scale_f32 v39, vcc, 1.0, v36, 1.0
	v_mul_f32_e32 v40, v39, v38
	v_fma_f32 v41, -v32, v40, v39
	v_fmac_f32_e32 v40, v41, v38
	v_fma_f32 v32, -v32, v40, v39
	v_div_fmas_f32 v32, v32, v38, v40
	v_div_fixup_f32 v36, v32, v36, 1.0
	v_lshlrev_b32_e32 v32, 16, v33
	v_and_b32_e32 v33, 0xffff0000, v33
	v_mul_f32_e32 v32, 0xbfb8aa3b, v32
	v_mul_f32_e32 v33, 0xbfb8aa3b, v33
	v_exp_f32_e32 v32, v32
	v_exp_f32_e32 v33, v33
	v_pk_mul_f32 v[26:27], v[26:27], v[36:37]
	v_pk_add_f32 v[32:33], v[32:33], 1.0 op_sel_hi:[1,0]
	s_nop 0
	v_div_scale_f32 v36, s[4:5], v33, v33, 1.0
	v_rcp_f32_e32 v37, v36
	s_nop 0
	v_fma_f32 v38, -v36, v37, 1.0
	v_fmac_f32_e32 v37, v38, v37
	v_div_scale_f32 v38, vcc, 1.0, v33, 1.0
	v_mul_f32_e32 v39, v38, v37
	v_fma_f32 v40, -v36, v39, v38
	v_fmac_f32_e32 v39, v40, v37
	v_fma_f32 v36, -v36, v39, v38
	v_div_fmas_f32 v36, v36, v37, v39
	v_div_fixup_f32 v33, v36, v33, 1.0
	v_div_scale_f32 v36, s[4:5], v32, v32, 1.0
	v_rcp_f32_e32 v37, v36
	s_nop 0
	v_fma_f32 v38, -v36, v37, 1.0
	v_fmac_f32_e32 v37, v38, v37
	v_div_scale_f32 v38, vcc, 1.0, v32, 1.0
	v_mul_f32_e32 v39, v38, v37
	v_fma_f32 v40, -v36, v39, v38
	v_fmac_f32_e32 v39, v40, v37
	v_fma_f32 v36, -v36, v39, v38
	v_div_fmas_f32 v36, v36, v37, v39
	v_div_fixup_f32 v32, v36, v32, 1.0
	v_pk_mul_f32 v[28:29], v[28:29], v[32:33]
	s_and_b64 vcc, exec, s[38:39]
	s_cbranch_vccnz .LBB0_273
	v_lshlrev_b32_e32 v32, 16, v110
	v_and_b32_e32 v33, 0xffff0000, v110
	v_pk_add_f32 v[26:27], v[26:27], v[32:33]
	v_lshlrev_b32_e32 v32, 16, v111
	v_and_b32_e32 v33, 0xffff0000, v111
	v_pk_add_f32 v[28:29], v[28:29], v[32:33]

; DI unsigned pk2(float lo, float hi) { f32x2_t v; v[0] = lo; v[1] = hi; bf16x2_t b = __builtin_convertvector(v, bf16x2_t); return __builtin_bit_cast(unsigned, b); }
; DI float bflo(unsigned u) { return __uint_as_float(u << 16); }
; DI float bfhi(unsigned u) { return __uint_as_float(u & 0xffff0000u); }
; DI float sigmoidf_(float x) { return 1.f / (1.f + __expf(-x)); }
; DI void merge_item(const Params& p, int l, int item, bf16_t* lds) {
;     ...
;     EPI_LOOP({
;       u32x2 g = *(const u32x2*)(RG + (size_t)t * 3072 + br * 1024 + n0 + cl);
;       f32x4 o; o[0] = sigmoidf_(bflo(g.x)) * v[0]; o[1] = sigmoidf_(bfhi(g.x)) * v[1]; o[2] = sigmoidf_(bflo(g.y)) * v[2]; o[3] = sigmoidf_(bfhi(g.y)) * v[3];
;       if (br > 0) { u32x2 pm = mg[mi][ni]; o[0] += bflo(pm.x); o[1] += bfhi(pm.x); o[2] += bflo(pm.y); o[3] += bfhi(pm.y); }
;       u32x2 pk; pk.x = pk2(o[0], o[1]); pk.y = pk2(o[2], o[3]);
;       mg[mi][ni] = pk;
.LBB0_275:
	s_waitcnt vmcnt(5)
	v_mov_b32_e32 v26, v192
	v_mov_b32_e32 v27, v193
	v_lshlrev_b32_e32 v28, 16, v26
	v_and_b32_e32 v26, 0xffff0000, v26
	v_mul_f32_e32 v28, 0xbfb8aa3b, v28
	v_mul_f32_e32 v26, 0xbfb8aa3b, v26
	v_exp_f32_e32 v28, v28
	v_exp_f32_e32 v29, v26
	s_nop 0
	v_pk_add_f32 v[28:29], v[28:29], 1.0 op_sel_hi:[1,0]
	s_nop 0
	v_div_scale_f32 v26, s[4:5], v29, v29, 1.0
	v_rcp_f32_e32 v32, v26
	s_nop 0
	v_fma_f32 v33, -v26, v32, 1.0
	v_fmac_f32_e32 v32, v33, v32
	v_div_scale_f32 v33, vcc, 1.0, v29, 1.0
	v_mul_f32_e32 v36, v33, v32
	v_fma_f32 v37, -v26, v36, v33
	v_fmac_f32_e32 v36, v37, v32
	v_fma_f32 v26, -v26, v36, v33
	v_div_fmas_f32 v26, v26, v32, v36
	v_div_fixup_f32 v29, v26, v29, 1.0
	v_div_scale_f32 v26, s[4:5], v28, v28, 1.0
	v_rcp_f32_e32 v32, v26
	s_nop 0
	v_fma_f32 v33, -v26, v32, 1.0
	v_fmac_f32_e32 v32, v33, v32
	v_div_scale_f32 v33, vcc, 1.0, v28, 1.0
	v_mul_f32_e32 v36, v33, v32
	v_fma_f32 v37, -v26, v36, v33
	v_fmac_f32_e32 v36, v37, v32
	v_fma_f32 v26, -v26, v36, v33
	v_div_fmas_f32 v26, v26, v32, v36
	v_div_fixup_f32 v28, v26, v28, 1.0
	v_lshlrev_b32_e32 v26, 16, v27
	v_and_b32_e32 v27, 0xffff0000, v27
	v_mul_f32_e32 v26, 0xbfb8aa3b, v26
	v_mul_f32_e32 v27, 0xbfb8aa3b, v27
	v_exp_f32_e32 v26, v26
	v_exp_f32_e32 v27, v27
	v_pk_mul_f32 v[22:23], v[22:23], v[28:29]
	v_pk_add_f32 v[26:27], v[26:27], 1.0 op_sel_hi:[1,0]
	s_nop 0
	v_div_scale_f32 v28, s[4:5], v27, v27, 1.0
	v_rcp_f32_e32 v29, v28
	s_nop 0
	v_fma_f32 v32, -v28, v29, 1.0
	v_fmac_f32_e32 v29, v32, v29
	v_div_scale_f32 v32, vcc, 1.0, v27, 1.0
	v_mul_f32_e32 v33, v32, v29
	v_fma_f32 v36, -v28, v33, v32
	v_fmac_f32_e32 v33, v36, v29
	v_fma_f32 v28, -v28, v33, v32
	v_div_fmas_f32 v28, v28, v29, v33
	v_div_fixup_f32 v27, v28, v27, 1.0
	v_div_scale_f32 v28, s[4:5], v26, v26, 1.0
	v_rcp_f32_e32 v29, v28
	s_nop 0
	v_fma_f32 v32, -v28, v29, 1.0
	v_fmac_f32_e32 v29, v32, v29
	v_div_scale_f32 v32, vcc, 1.0, v26, 1.0
	v_mul_f32_e32 v33, v32, v29
	v_fma_f32 v36, -v28, v33, v32
	v_fmac_f32_e32 v33, v36, v29
	v_fma_f32 v28, -v28, v33, v32
	v_div_fmas_f32 v28, v28, v29, v33
	v_div_fixup_f32 v26, v28, v26, 1.0
	v_pk_mul_f32 v[24:25], v[24:25], v[26:27]
	s_and_b64 vcc, exec, s[38:39]
	s_cbranch_vccnz .LBB0_277
	v_lshlrev_b32_e32 v26, 16, v106
	v_and_b32_e32 v27, 0xffff0000, v106
	v_pk_add_f32 v[22:23], v[22:23], v[26:27]
	v_lshlrev_b32_e32 v26, 16, v107
	v_and_b32_e32 v27, 0xffff0000, v107
	v_pk_add_f32 v[24:25], v[24:25], v[26:27]

; DI unsigned pk2(float lo, float hi) { f32x2_t v; v[0] = lo; v[1] = hi; bf16x2_t b = __builtin_convertvector(v, bf16x2_t); return __builtin_bit_cast(unsigned, b); }
; DI float bflo(unsigned u) { return __uint_as_float(u << 16); }
; DI float bfhi(unsigned u) { return __uint_as_float(u & 0xffff0000u); }
; DI float sigmoidf_(float x) { return 1.f / (1.f + __expf(-x)); }
; DI void merge_item(const Params& p, int l, int item, bf16_t* lds) {
;     ...
;     EPI_LOOP({
;       u32x2 g = *(const u32x2*)(RG + (size_t)t * 3072 + br * 1024 + n0 + cl);
;       f32x4 o; o[0] = sigmoidf_(bflo(g.x)) * v[0]; o[1] = sigmoidf_(bfhi(g.x)) * v[1]; o[2] = sigmoidf_(bflo(g.y)) * v[2]; o[3] = sigmoidf_(bfhi(g.y)) * v[3];
;       if (br > 0) { u32x2 pm = mg[mi][ni]; o[0] += bflo(pm.x); o[1] += bfhi(pm.x); o[2] += bflo(pm.y); o[3] += bfhi(pm.y); }
;       u32x2 pk; pk.x = pk2(o[0], o[1]); pk.y = pk2(o[2], o[3]);
;       mg[mi][ni] = pk;
.LBB0_279:
	s_waitcnt vmcnt(4)
	v_mov_b32_e32 v22, v194
	v_mov_b32_e32 v23, v195
	v_lshlrev_b32_e32 v24, 16, v22
	v_and_b32_e32 v22, 0xffff0000, v22
	v_mul_f32_e32 v24, 0xbfb8aa3b, v24
	v_mul_f32_e32 v22, 0xbfb8aa3b, v22
	v_exp_f32_e32 v24, v24
	v_exp_f32_e32 v25, v22
	s_nop 0
	v_pk_add_f32 v[24:25], v[24:25], 1.0 op_sel_hi:[1,0]
	s_nop 0
	v_div_scale_f32 v22, s[4:5], v25, v25, 1.0
	v_rcp_f32_e32 v26, v22
	s_nop 0
	v_fma_f32 v27, -v22, v26, 1.0
	v_fmac_f32_e32 v26, v27, v26
	v_div_scale_f32 v27, vcc, 1.0, v25, 1.0
	v_mul_f32_e32 v28, v27, v26
	v_fma_f32 v29, -v22, v28, v27
	v_fmac_f32_e32 v28, v29, v26
	v_fma_f32 v22, -v22, v28, v27
	v_div_fmas_f32 v22, v22, v26, v28
	v_div_fixup_f32 v25, v22, v25, 1.0
	v_div_scale_f32 v22, s[4:5], v24, v24, 1.0
	v_rcp_f32_e32 v26, v22
	s_nop 0
	v_fma_f32 v27, -v22, v26, 1.0
	v_fmac_f32_e32 v26, v27, v26
	v_div_scale_f32 v27, vcc, 1.0, v24, 1.0
	v_mul_f32_e32 v28, v27, v26
	v_fma_f32 v29, -v22, v28, v27
	v_fmac_f32_e32 v28, v29, v26
	v_fma_f32 v22, -v22, v28, v27
	v_div_fmas_f32 v22, v22, v26, v28
	v_div_fixup_f32 v24, v22, v24, 1.0
	v_lshlrev_b32_e32 v22, 16, v23
	v_and_b32_e32 v23, 0xffff0000, v23
	v_mul_f32_e32 v22, 0xbfb8aa3b, v22
	v_mul_f32_e32 v23, 0xbfb8aa3b, v23
	v_exp_f32_e32 v22, v22
	v_exp_f32_e32 v23, v23
	v_pk_mul_f32 v[18:19], v[18:19], v[24:25]
	v_pk_add_f32 v[22:23], v[22:23], 1.0 op_sel_hi:[1,0]
	s_nop 0
	v_div_scale_f32 v24, s[4:5], v23, v23, 1.0
	v_rcp_f32_e32 v25, v24
	s_nop 0
	v_fma_f32 v26, -v24, v25, 1.0
	v_fmac_f32_e32 v25, v26, v25
	v_div_scale_f32 v26, vcc, 1.0, v23, 1.0
	v_mul_f32_e32 v27, v26, v25
	v_fma_f32 v28, -v24, v27, v26
	v_fmac_f32_e32 v27, v28, v25
	v_fma_f32 v24, -v24, v27, v26
	v_div_fmas_f32 v24, v24, v25, v27
	v_div_fixup_f32 v23, v24, v23, 1.0
	v_div_scale_f32 v24, s[4:5], v22, v22, 1.0
	v_rcp_f32_e32 v25, v24
	s_nop 0
	v_fma_f32 v26, -v24, v25, 1.0
	v_fmac_f32_e32 v25, v26, v25
	v_div_scale_f32 v26, vcc, 1.0, v22, 1.0
	v_mul_f32_e32 v27, v26, v25
	v_fma_f32 v28, -v24, v27, v26
	v_fmac_f32_e32 v27, v28, v25
	v_fma_f32 v24, -v24, v27, v26
	v_div_fmas_f32 v24, v24, v25, v27
	v_div_fixup_f32 v22, v24, v22, 1.0
	v_pk_mul_f32 v[20:21], v[20:21], v[22:23]
	s_and_b64 vcc, exec, s[38:39]
	s_cbranch_vccnz .LBB0_281
	v_lshlrev_b32_e32 v22, 16, v104
	v_and_b32_e32 v23, 0xffff0000, v104
	v_pk_add_f32 v[18:19], v[18:19], v[22:23]
	v_lshlrev_b32_e32 v22, 16, v105
	v_and_b32_e32 v23, 0xffff0000, v105
	v_pk_add_f32 v[20:21], v[20:21], v[22:23]

; DI unsigned pk2(float lo, float hi) { f32x2_t v; v[0] = lo; v[1] = hi; bf16x2_t b = __builtin_convertvector(v, bf16x2_t); return __builtin_bit_cast(unsigned, b); }
; DI float bflo(unsigned u) { return __uint_as_float(u << 16); }
; DI float bfhi(unsigned u) { return __uint_as_float(u & 0xffff0000u); }
; DI float sigmoidf_(float x) { return 1.f / (1.f + __expf(-x)); }
; DI void merge_item(const Params& p, int l, int item, bf16_t* lds) {
;     ...
;     EPI_LOOP({
;       u32x2 g = *(const u32x2*)(RG + (size_t)t * 3072 + br * 1024 + n0 + cl);
;       f32x4 o; o[0] = sigmoidf_(bflo(g.x)) * v[0]; o[1] = sigmoidf_(bfhi(g.x)) * v[1]; o[2] = sigmoidf_(bflo(g.y)) * v[2]; o[3] = sigmoidf_(bfhi(g.y)) * v[3];
;       if (br > 0) { u32x2 pm = mg[mi][ni]; o[0] += bflo(pm.x); o[1] += bfhi(pm.x); o[2] += bflo(pm.y); o[3] += bfhi(pm.y); }
;       u32x2 pk; pk.x = pk2(o[0], o[1]); pk.y = pk2(o[2], o[3]);
;       mg[mi][ni] = pk;
.LBB0_283:
	v_or_b32_e32 v20, 48, v66
	v_mov_b64_e32 v[18:19], s[24:25]
	v_mad_i64_i32 v[18:19], s[4:5], v20, s8, v[18:19]
	v_lshl_add_u64 v[18:19], v[18:19], 0, v[0:1]
	s_waitcnt vmcnt(3)
	v_mov_b32_e32 v24, v196
	v_mov_b32_e32 v25, v197
	v_lshlrev_b32_e32 v21, 16, v24
	v_mul_f32_e32 v21, 0xbfb8aa3b, v21
	v_exp_f32_e32 v22, v21
	v_and_b32_e32 v21, 0xffff0000, v24
	v_mul_f32_e32 v21, 0xbfb8aa3b, v21
	v_exp_f32_e32 v23, v21
	s_nop 0
	v_pk_add_f32 v[22:23], v[22:23], 1.0 op_sel_hi:[1,0]
	s_nop 0
	v_div_scale_f32 v21, s[4:5], v23, v23, 1.0
	v_rcp_f32_e32 v24, v21
	s_nop 0
	v_fma_f32 v26, -v21, v24, 1.0
	v_fmac_f32_e32 v24, v26, v24
	v_div_scale_f32 v26, vcc, 1.0, v23, 1.0
	v_mul_f32_e32 v27, v26, v24
	v_fma_f32 v28, -v21, v27, v26
	v_fmac_f32_e32 v27, v28, v24
	v_fma_f32 v21, -v21, v27, v26
	v_div_fmas_f32 v21, v21, v24, v27
	v_div_fixup_f32 v23, v21, v23, 1.0
	v_div_scale_f32 v21, s[4:5], v22, v22, 1.0
	v_rcp_f32_e32 v24, v21
	s_nop 0
	v_fma_f32 v26, -v21, v24, 1.0
	v_fmac_f32_e32 v24, v26, v24
	v_div_scale_f32 v26, vcc, 1.0, v22, 1.0
	v_mul_f32_e32 v27, v26, v24
	v_fma_f32 v28, -v21, v27, v26
	v_fmac_f32_e32 v27, v28, v24
	v_fma_f32 v21, -v21, v27, v26
	v_div_fmas_f32 v21, v21, v24, v27
	v_div_fixup_f32 v22, v21, v22, 1.0
	v_pk_mul_f32 v[22:23], v[14:15], v[22:23]
	v_lshlrev_b32_e32 v14, 16, v25
	v_and_b32_e32 v15, 0xffff0000, v25
	v_mul_f32_e32 v14, 0xbfb8aa3b, v14
	v_mul_f32_e32 v15, 0xbfb8aa3b, v15
	v_exp_f32_e32 v14, v14
	v_exp_f32_e32 v15, v15
	s_nop 0
	v_pk_add_f32 v[14:15], v[14:15], 1.0 op_sel_hi:[1,0]
	s_nop 0
	v_div_scale_f32 v21, s[4:5], v15, v15, 1.0
	v_rcp_f32_e32 v24, v21
	s_nop 0
	v_fma_f32 v25, -v21, v24, 1.0
	v_fmac_f32_e32 v24, v25, v24
	v_div_scale_f32 v25, vcc, 1.0, v15, 1.0
	v_mul_f32_e32 v26, v25, v24
	v_fma_f32 v27, -v21, v26, v25
	v_fmac_f32_e32 v26, v27, v24
	v_fma_f32 v21, -v21, v26, v25
	v_div_fmas_f32 v21, v21, v24, v26
	v_div_fixup_f32 v15, v21, v15, 1.0
	v_div_scale_f32 v21, s[4:5], v14, v14, 1.0
	v_rcp_f32_e32 v24, v21
	s_nop 0
	v_fma_f32 v25, -v21, v24, 1.0
	v_fmac_f32_e32 v24, v25, v24
	v_div_scale_f32 v25, vcc, 1.0, v14, 1.0
	v_mul_f32_e32 v26, v25, v24
	v_fma_f32 v27, -v21, v26, v25
	v_fmac_f32_e32 v26, v27, v24
	v_fma_f32 v21, -v21, v26, v25
	v_div_fmas_f32 v21, v21, v24, v26
	v_div_fixup_f32 v14, v21, v14, 1.0
	v_pk_mul_f32 v[16:17], v[16:17], v[14:15]
	s_and_b64 vcc, exec, s[38:39]
	s_cbranch_vccnz .LBB0_285
	v_lshlrev_b32_e32 v14, 16, v108
	v_and_b32_e32 v15, 0xffff0000, v108
	v_pk_add_f32 v[22:23], v[22:23], v[14:15]
	v_lshlrev_b32_e32 v14, 16, v109
	v_and_b32_e32 v15, 0xffff0000, v109
	v_pk_add_f32 v[16:17], v[16:17], v[14:15]

; DI unsigned pk2(float lo, float hi) { f32x2_t v; v[0] = lo; v[1] = hi; bf16x2_t b = __builtin_convertvector(v, bf16x2_t); return __builtin_bit_cast(unsigned, b); }
; DI float bflo(unsigned u) { return __uint_as_float(u << 16); }
; DI float bfhi(unsigned u) { return __uint_as_float(u & 0xffff0000u); }
; DI float sigmoidf_(float x) { return 1.f / (1.f + __expf(-x)); }
; DI void merge_item(const Params& p, int l, int item, bf16_t* lds) {
;     ...
;     EPI_LOOP({
;       u32x2 g = *(const u32x2*)(RG + (size_t)t * 3072 + br * 1024 + n0 + cl);
;       f32x4 o; o[0] = sigmoidf_(bflo(g.x)) * v[0]; o[1] = sigmoidf_(bfhi(g.x)) * v[1]; o[2] = sigmoidf_(bflo(g.y)) * v[2]; o[3] = sigmoidf_(bfhi(g.y)) * v[3];
;       if (br > 0) { u32x2 pm = mg[mi][ni]; o[0] += bflo(pm.x); o[1] += bfhi(pm.x); o[2] += bflo(pm.y); o[3] += bfhi(pm.y); }
;       u32x2 pk; pk.x = pk2(o[0], o[1]); pk.y = pk2(o[2], o[3]);
;       mg[mi][ni] = pk;
.LBB0_287:
	s_waitcnt vmcnt(2)
	v_mov_b32_e32 v16, v198
	v_mov_b32_e32 v17, v199
	v_lshlrev_b32_e32 v20, 16, v16
	v_and_b32_e32 v16, 0xffff0000, v16
	v_mul_f32_e32 v20, 0xbfb8aa3b, v20
	v_mul_f32_e32 v16, 0xbfb8aa3b, v16
	v_exp_f32_e32 v20, v20
	v_exp_f32_e32 v21, v16
	s_nop 0
	v_pk_add_f32 v[20:21], v[20:21], 1.0 op_sel_hi:[1,0]
	s_nop 0
	v_div_scale_f32 v16, s[4:5], v21, v21, 1.0
	v_rcp_f32_e32 v22, v16
	s_nop 0
	v_fma_f32 v23, -v16, v22, 1.0
	v_fmac_f32_e32 v22, v23, v22
	v_div_scale_f32 v23, vcc, 1.0, v21, 1.0
	v_mul_f32_e32 v24, v23, v22
	v_fma_f32 v25, -v16, v24, v23
	v_fmac_f32_e32 v24, v25, v22
	v_fma_f32 v16, -v16, v24, v23
	v_div_fmas_f32 v16, v16, v22, v24
	v_div_fixup_f32 v21, v16, v21, 1.0
	v_div_scale_f32 v16, s[4:5], v20, v20, 1.0
	v_rcp_f32_e32 v22, v16
	s_nop 0
	v_fma_f32 v23, -v16, v22, 1.0
	v_fmac_f32_e32 v22, v23, v22
	v_div_scale_f32 v23, vcc, 1.0, v20, 1.0
	v_mul_f32_e32 v24, v23, v22
	v_fma_f32 v25, -v16, v24, v23
	v_fmac_f32_e32 v24, v25, v22
	v_fma_f32 v16, -v16, v24, v23
	v_div_fmas_f32 v16, v16, v22, v24
	v_div_fixup_f32 v20, v16, v20, 1.0
	v_lshlrev_b32_e32 v16, 16, v17
	v_and_b32_e32 v17, 0xffff0000, v17
	v_mul_f32_e32 v16, 0xbfb8aa3b, v16
	v_mul_f32_e32 v17, 0xbfb8aa3b, v17
	v_exp_f32_e32 v16, v16
	v_exp_f32_e32 v17, v17
	v_pk_mul_f32 v[10:11], v[10:11], v[20:21]
	v_pk_add_f32 v[16:17], v[16:17], 1.0 op_sel_hi:[1,0]
	s_nop 0
	v_div_scale_f32 v20, s[4:5], v17, v17, 1.0
	v_rcp_f32_e32 v21, v20
	s_nop 0
	v_fma_f32 v22, -v20, v21, 1.0
	v_fmac_f32_e32 v21, v22, v21
	v_div_scale_f32 v22, vcc, 1.0, v17, 1.0
	v_mul_f32_e32 v23, v22, v21
	v_fma_f32 v24, -v20, v23, v22
	v_fmac_f32_e32 v23, v24, v21
	v_fma_f32 v20, -v20, v23, v22
	v_div_fmas_f32 v20, v20, v21, v23
	v_div_fixup_f32 v17, v20, v17, 1.0
	v_div_scale_f32 v20, s[4:5], v16, v16, 1.0
	v_rcp_f32_e32 v21, v20
	s_nop 0
	v_fma_f32 v22, -v20, v21, 1.0
	v_fmac_f32_e32 v21, v22, v21
	v_div_scale_f32 v22, vcc, 1.0, v16, 1.0
	v_mul_f32_e32 v23, v22, v21
	v_fma_f32 v24, -v20, v23, v22
	v_fmac_f32_e32 v23, v24, v21
	v_fma_f32 v20, -v20, v23, v22
	v_div_fmas_f32 v20, v20, v21, v23
	v_div_fixup_f32 v16, v20, v16, 1.0
	v_pk_mul_f32 v[12:13], v[12:13], v[16:17]
	s_and_b64 vcc, exec, s[38:39]
	s_cbranch_vccnz .LBB0_289
	v_lshlrev_b32_e32 v16, 16, v102
	v_and_b32_e32 v17, 0xffff0000, v102
	v_pk_add_f32 v[10:11], v[10:11], v[16:17]
	v_lshlrev_b32_e32 v16, 16, v103
	v_and_b32_e32 v17, 0xffff0000, v103
	v_pk_add_f32 v[12:13], v[12:13], v[16:17]

; DI unsigned pk2(float lo, float hi) { f32x2_t v; v[0] = lo; v[1] = hi; bf16x2_t b = __builtin_convertvector(v, bf16x2_t); return __builtin_bit_cast(unsigned, b); }
; DI float bflo(unsigned u) { return __uint_as_float(u << 16); }
; DI float bfhi(unsigned u) { return __uint_as_float(u & 0xffff0000u); }
; DI float sigmoidf_(float x) { return 1.f / (1.f + __expf(-x)); }
; DI void merge_item(const Params& p, int l, int item, bf16_t* lds) {
;     ...
;     EPI_LOOP({
;       u32x2 g = *(const u32x2*)(RG + (size_t)t * 3072 + br * 1024 + n0 + cl);
;       f32x4 o; o[0] = sigmoidf_(bflo(g.x)) * v[0]; o[1] = sigmoidf_(bfhi(g.x)) * v[1]; o[2] = sigmoidf_(bflo(g.y)) * v[2]; o[3] = sigmoidf_(bfhi(g.y)) * v[3];
;       if (br > 0) { u32x2 pm = mg[mi][ni]; o[0] += bflo(pm.x); o[1] += bfhi(pm.x); o[2] += bflo(pm.y); o[3] += bfhi(pm.y); }
;       u32x2 pk; pk.x = pk2(o[0], o[1]); pk.y = pk2(o[2], o[3]);
;       mg[mi][ni] = pk;
.LBB0_291:
	s_waitcnt vmcnt(1)
	v_mov_b32_e32 v10, v202
	v_mov_b32_e32 v11, v203
	v_lshlrev_b32_e32 v12, 16, v10
	v_and_b32_e32 v10, 0xffff0000, v10
	v_mul_f32_e32 v12, 0xbfb8aa3b, v12
	v_mul_f32_e32 v10, 0xbfb8aa3b, v10
	v_exp_f32_e32 v12, v12
	v_exp_f32_e32 v13, v10
	s_nop 0
	v_pk_add_f32 v[12:13], v[12:13], 1.0 op_sel_hi:[1,0]
	s_nop 0
	v_div_scale_f32 v10, s[4:5], v13, v13, 1.0
	v_rcp_f32_e32 v16, v10
	s_nop 0
	v_fma_f32 v17, -v10, v16, 1.0
	v_fmac_f32_e32 v16, v17, v16
	v_div_scale_f32 v17, vcc, 1.0, v13, 1.0
	v_mul_f32_e32 v20, v17, v16
	v_fma_f32 v21, -v10, v20, v17
	v_fmac_f32_e32 v20, v21, v16
	v_fma_f32 v10, -v10, v20, v17
	v_div_fmas_f32 v10, v10, v16, v20
	v_div_fixup_f32 v13, v10, v13, 1.0
	v_div_scale_f32 v10, s[4:5], v12, v12, 1.0
	v_rcp_f32_e32 v16, v10
	s_nop 0
	v_fma_f32 v17, -v10, v16, 1.0
	v_fmac_f32_e32 v16, v17, v16
	v_div_scale_f32 v17, vcc, 1.0, v12, 1.0
	v_mul_f32_e32 v20, v17, v16
	v_fma_f32 v21, -v10, v20, v17
	v_fmac_f32_e32 v20, v21, v16
	v_fma_f32 v10, -v10, v20, v17
	v_div_fmas_f32 v10, v10, v16, v20
	v_div_fixup_f32 v12, v10, v12, 1.0
	v_lshlrev_b32_e32 v10, 16, v11
	v_and_b32_e32 v11, 0xffff0000, v11
	v_mul_f32_e32 v10, 0xbfb8aa3b, v10
	v_mul_f32_e32 v11, 0xbfb8aa3b, v11
	v_exp_f32_e32 v10, v10
	v_exp_f32_e32 v11, v11
	v_pk_mul_f32 v[6:7], v[6:7], v[12:13]
	v_pk_add_f32 v[10:11], v[10:11], 1.0 op_sel_hi:[1,0]
	s_nop 0
	v_div_scale_f32 v12, s[4:5], v11, v11, 1.0
	v_rcp_f32_e32 v13, v12
	s_nop 0
	v_fma_f32 v16, -v12, v13, 1.0
	v_fmac_f32_e32 v13, v16, v13
	v_div_scale_f32 v16, vcc, 1.0, v11, 1.0
	v_mul_f32_e32 v17, v16, v13
	v_fma_f32 v20, -v12, v17, v16
	v_fmac_f32_e32 v17, v20, v13
	v_fma_f32 v12, -v12, v17, v16
	v_div_fmas_f32 v12, v12, v13, v17
	v_div_fixup_f32 v11, v12, v11, 1.0
	v_div_scale_f32 v12, s[4:5], v10, v10, 1.0
	v_rcp_f32_e32 v13, v12
	s_nop 0
	v_fma_f32 v16, -v12, v13, 1.0
	v_fmac_f32_e32 v13, v16, v13
	v_div_scale_f32 v16, vcc, 1.0, v10, 1.0
	v_mul_f32_e32 v17, v16, v13
	v_fma_f32 v20, -v12, v17, v16
	v_fmac_f32_e32 v17, v20, v13
	v_fma_f32 v12, -v12, v17, v16
	v_div_fmas_f32 v12, v12, v13, v17
	v_div_fixup_f32 v10, v12, v10, 1.0
	v_pk_mul_f32 v[8:9], v[8:9], v[10:11]
	s_and_b64 vcc, exec, s[38:39]
	s_cbranch_vccnz .LBB0_293
	v_lshlrev_b32_e32 v10, 16, v100
	v_and_b32_e32 v11, 0xffff0000, v100
	v_pk_add_f32 v[6:7], v[6:7], v[10:11]
	v_lshlrev_b32_e32 v10, 16, v101
	v_and_b32_e32 v11, 0xffff0000, v101
	v_pk_add_f32 v[8:9], v[8:9], v[10:11]

; DI unsigned pk2(float lo, float hi) { f32x2_t v; v[0] = lo; v[1] = hi; bf16x2_t b = __builtin_convertvector(v, bf16x2_t); return __builtin_bit_cast(unsigned, b); }
; DI float bflo(unsigned u) { return __uint_as_float(u << 16); }
; DI float bfhi(unsigned u) { return __uint_as_float(u & 0xffff0000u); }
; DI float sigmoidf_(float x) { return 1.f / (1.f + __expf(-x)); }
; DI void merge_item(const Params& p, int l, int item, bf16_t* lds) {
;     ...
;     EPI_LOOP({
;       u32x2 g = *(const u32x2*)(RG + (size_t)t * 3072 + br * 1024 + n0 + cl);
;       f32x4 o; o[0] = sigmoidf_(bflo(g.x)) * v[0]; o[1] = sigmoidf_(bfhi(g.x)) * v[1]; o[2] = sigmoidf_(bflo(g.y)) * v[2]; o[3] = sigmoidf_(bfhi(g.y)) * v[3];
;       if (br > 0) { u32x2 pm = mg[mi][ni]; o[0] += bflo(pm.x); o[1] += bfhi(pm.x); o[2] += bflo(pm.y); o[3] += bfhi(pm.y); }
;       u32x2 pk; pk.x = pk2(o[0], o[1]); pk.y = pk2(o[2], o[3]);
;       mg[mi][ni] = pk;
.LBB0_295:
	s_waitcnt vmcnt(0)
	v_mov_b32_e32 v6, v204
	v_mov_b32_e32 v7, v205
	v_lshlrev_b32_e32 v8, 16, v6
	v_and_b32_e32 v6, 0xffff0000, v6
	v_mul_f32_e32 v8, 0xbfb8aa3b, v8
	v_mul_f32_e32 v6, 0xbfb8aa3b, v6
	v_exp_f32_e32 v8, v8
	v_exp_f32_e32 v9, v6
	s_nop 0
	v_pk_add_f32 v[8:9], v[8:9], 1.0 op_sel_hi:[1,0]
	s_nop 0
	v_div_scale_f32 v6, s[4:5], v9, v9, 1.0
	v_rcp_f32_e32 v10, v6
	s_nop 0
	v_fma_f32 v11, -v6, v10, 1.0
	v_fmac_f32_e32 v10, v11, v10
	v_div_scale_f32 v11, vcc, 1.0, v9, 1.0
	v_mul_f32_e32 v12, v11, v10
	v_fma_f32 v13, -v6, v12, v11
	v_fmac_f32_e32 v12, v13, v10
	v_fma_f32 v6, -v6, v12, v11
	v_div_fmas_f32 v6, v6, v10, v12
	v_div_fixup_f32 v9, v6, v9, 1.0
	v_div_scale_f32 v6, s[4:5], v8, v8, 1.0
	v_rcp_f32_e32 v10, v6
	s_nop 0
	v_fma_f32 v11, -v6, v10, 1.0
	v_fmac_f32_e32 v10, v11, v10
	v_div_scale_f32 v11, vcc, 1.0, v8, 1.0
	v_mul_f32_e32 v12, v11, v10
	v_fma_f32 v13, -v6, v12, v11
	v_fmac_f32_e32 v12, v13, v10
	v_fma_f32 v6, -v6, v12, v11
	v_div_fmas_f32 v6, v6, v10, v12
	v_div_fixup_f32 v8, v6, v8, 1.0
	v_lshlrev_b32_e32 v6, 16, v7
	v_and_b32_e32 v7, 0xffff0000, v7
	v_mul_f32_e32 v6, 0xbfb8aa3b, v6
	v_mul_f32_e32 v7, 0xbfb8aa3b, v7
	v_exp_f32_e32 v6, v6
	v_exp_f32_e32 v7, v7
	v_pk_mul_f32 v[2:3], v[2:3], v[8:9]
	v_pk_add_f32 v[6:7], v[6:7], 1.0 op_sel_hi:[1,0]
	s_nop 0
	v_div_scale_f32 v8, s[4:5], v7, v7, 1.0
	v_rcp_f32_e32 v9, v8
	s_nop 0
	v_fma_f32 v10, -v8, v9, 1.0
	v_fmac_f32_e32 v9, v10, v9
	v_div_scale_f32 v10, vcc, 1.0, v7, 1.0
	v_mul_f32_e32 v11, v10, v9
	v_fma_f32 v12, -v8, v11, v10
	v_fmac_f32_e32 v11, v12, v9
	v_fma_f32 v8, -v8, v11, v10
	v_div_fmas_f32 v8, v8, v9, v11
	v_div_fixup_f32 v7, v8, v7, 1.0
	v_div_scale_f32 v8, s[4:5], v6, v6, 1.0
	v_rcp_f32_e32 v9, v8
	s_nop 0
	v_fma_f32 v10, -v8, v9, 1.0
	v_fmac_f32_e32 v9, v10, v9
	v_div_scale_f32 v10, vcc, 1.0, v6, 1.0
	v_mul_f32_e32 v11, v10, v9
	v_fma_f32 v12, -v8, v11, v10
	v_fmac_f32_e32 v11, v12, v9
	v_fma_f32 v8, -v8, v11, v10
	v_div_fmas_f32 v8, v8, v9, v11
	v_div_fixup_f32 v6, v8, v6, 1.0
	v_pk_mul_f32 v[4:5], v[4:5], v[6:7]
	s_and_b64 vcc, exec, s[38:39]
	s_cbranch_vccnz .LBB0_297
	v_lshlrev_b32_e32 v6, 16, v98
	v_and_b32_e32 v7, 0xffff0000, v98
	v_pk_add_f32 v[2:3], v[2:3], v[6:7]
	v_lshlrev_b32_e32 v6, 16, v99
	v_and_b32_e32 v7, 0xffff0000, v99
	v_pk_add_f32 v[4:5], v[4:5], v[6:7]

; DI float bf2f(unsigned h) { return __uint_as_float(h << 16); }
; DI bf16_t f2bf(float f) { return (bf16_t)(pk2(f, 0.f) & 0xffffu); }
; DI float siluf_(float x) { return x / (1.f + __expf(-x)); }
; DI void gdnout_item(const Params& p, int l, int item, float* red  ) {
;     ...
;   __syncthreads();
; #pragma unroll
;   for (int mi = 0; mi < 4; ++mi)
; #pragma unroll
;     for (int r = 0; r < 4; ++r) {
;       const int tk = mi * 16 + lq * 4 + r;
;       const float rstd = rsqrtf((red[tk] + red[64 + tk] + red[128 + tk] + red[192 + tk]) * (1.f / 128.f) + EPS);
; #pragma unroll
;       for (int j = 0; j < 2; ++j) {
;         const int col = (2 * wid + j) * 16 + lr;
;         const size_t idx = (size_t)(t0 + tk) * 512 + h * 128 + col;
;         OC[idx] = f2bf(O[mi][j][r] * rstd * p.onw[l * 128 + col] * siluf_(bf2f(RZ[idx])));
;       }
;     }
.LBB0_304:
	s_or_b64 exec, exec, s[36:37]
	v_lshrrev_b32_e32 v0, 2, v65
	s_lshl_b32 s18, s30, 4
	v_and_b32_e32 v54, 12, v0
	s_and_b32 s19, s18, 0xffffffc0
	v_or_b32_e32 v46, s19, v54
	s_lshl_b32 s17, s30, 7
	v_ashrrev_i32_e32 v47, 31, v46
	v_lshl_or_b32 v42, v66, 5, v64
	s_and_b32 s17, s17, 0x180
	v_lshlrev_b64 v[60:61], 9, v[46:47]
	v_ashrrev_i32_e32 v43, 31, v42
	v_or_b32_e32 v60, s17, v60
	s_waitcnt lgkmcnt(0)
	v_lshl_add_u64 v[34:35], v[60:61], 0, v[42:43]
	v_lshlrev_b64 v[64:65], 1, v[34:35]
	v_lshl_add_u64 v[34:35], s[26:27], 0, v[64:65]
	s_barrier
	global_load_ushort v102, v[34:35], off
	global_load_ushort v103, v[34:35], off offset:32
	global_load_ushort v104, v[34:35], off offset:1024
	global_load_ushort v105, v[34:35], off offset:1056
	global_load_ushort v106, v[34:35], off offset:2048
	global_load_ushort v107, v[34:35], off offset:2080
	global_load_ushort v108, v[34:35], off offset:3072
	global_load_ushort v109, v[34:35], off offset:3104
	s_mov_b64 s[98:99], 0x4000
	v_lshl_add_u64 v[134:135], v[34:35], 0, s[98:99]
	global_load_ushort v110, v[134:135], off
	global_load_ushort v111, v[134:135], off offset:32
	global_load_ushort v112, v[134:135], off offset:1024
	global_load_ushort v113, v[134:135], off offset:1056
	global_load_ushort v114, v[134:135], off offset:2048
	global_load_ushort v115, v[134:135], off offset:2080
	global_load_ushort v116, v[134:135], off offset:3072
	global_load_ushort v117, v[134:135], off offset:3104
	v_lshl_add_u64 v[134:135], v[134:135], 0, s[98:99]
	global_load_ushort v118, v[134:135], off
	global_load_ushort v119, v[134:135], off offset:32
	global_load_ushort v120, v[134:135], off offset:1024
	global_load_ushort v121, v[134:135], off offset:1056
	global_load_ushort v122, v[134:135], off offset:2048
	global_load_ushort v123, v[134:135], off offset:2080
	global_load_ushort v124, v[134:135], off offset:3072
	global_load_ushort v125, v[134:135], off offset:3104
	v_lshl_add_u64 v[134:135], v[134:135], 0, s[98:99]
	global_load_ushort v126, v[134:135], off
	global_load_ushort v127, v[134:135], off offset:32
	global_load_ushort v128, v[134:135], off offset:1024
	global_load_ushort v129, v[134:135], off offset:1056
	global_load_ushort v130, v[134:135], off offset:2048
	global_load_ushort v131, v[134:135], off offset:2080
	global_load_ushort v132, v[134:135], off offset:3072
	global_load_ushort v133, v[134:135], off offset:3104
	v_add_u32_e32 v34, s4, v42
	v_ashrrev_i32_e32 v35, 31, v34
	v_lshl_add_u64 v[66:67], v[34:35], 2, s[72:73]
	global_load_dword v0, v[66:67], off
	global_load_dword v136, v[66:67], off offset:64
	v_lshlrev_b32_e32 v55, 2, v54
	ds_read_b128 v[34:37], v55
	ds_read_b128 v[38:41], v55 offset:256
	ds_read_b128 v[50:53], v55 offset:512
	ds_read_b128 v[56:59], v55 offset:768
	s_mov_b32 s34, 0x358637bd
	v_mov_b64_e32 v[48:49], s[34:35]
	s_waitcnt lgkmcnt(2)
	v_pk_add_f32 v[34:35], v[34:35], v[38:39]
	s_brev_b32 s34, 60
	s_waitcnt lgkmcnt(1)
	v_pk_add_f32 v[34:35], v[34:35], v[50:51]
	v_or_b32_e32 v44, 16, v42
	s_waitcnt lgkmcnt(0)
	v_pk_add_f32 v[34:35], v[34:35], v[56:57]
	v_ashrrev_i32_e32 v45, 31, v44
	v_pk_fma_f32 v[34:35], v[34:35], s[34:35], v[48:49] op_sel_hi:[1,0,0]
	v_lshl_add_u64 v[60:61], v[60:61], 0, v[44:45]
	v_mul_f32_e32 v38, 0x4b800000, v34
	v_cmp_gt_f32_e32 vcc, s58, v34
	v_lshlrev_b64 v[60:61], 1, v[60:61]
	v_lshl_add_u64 v[64:65], s[28:29], 0, v[64:65]
	v_cndmask_b32_e32 v34, v34, v38, vcc
	v_rsq_f32_e32 v34, v34
	v_lshl_add_u64 v[68:69], s[26:27], 0, v[60:61]
	s_waitcnt vmcnt(0)
	v_mov_b32_e32 v47, v102
	v_lshlrev_b32_e32 v38, 16, v47
	v_mul_f32_e32 v39, 0xbfb8aa3b, v38
	v_exp_f32_e32 v39, v39
	v_mul_f32_e32 v47, 0x45800000, v34
	v_cndmask_b32_e32 v34, v34, v47, vcc
	v_mul_f32_e32 v30, v30, v34
	v_add_f32_e32 v39, 1.0, v39
	v_div_scale_f32 v47, s[36:37], v39, v39, v38
	v_rcp_f32_e32 v50, v47
	v_div_scale_f32 v51, vcc, v38, v39, v38
	v_mul_f32_e32 v30, v0, v30
	v_fma_f32 v56, -v47, v50, 1.0
	v_fmac_f32_e32 v50, v56, v50
	v_mul_f32_e32 v56, v51, v50
	v_fma_f32 v57, -v47, v56, v51
	v_fmac_f32_e32 v56, v57, v50
	v_fma_f32 v47, -v47, v56, v51
	v_div_fmas_f32 v47, v47, v50, v56
	v_div_fixup_f32 v38, v47, v39, v38
	v_mul_f32_e32 v30, v38, v30
	v_cvt_pk_bf16_f32 v30, v30, s0
	global_store_short v[64:65], v30, off
	v_mov_b32_e32 v30, v103
	s_nop 0
	v_mov_b32_e32 v47, v136
	v_lshl_add_u64 v[56:57], s[28:29], 0, v[60:61]
	v_mul_f32_e32 v26, v26, v34
	v_or_b32_e32 v38, 1, v46
	v_ashrrev_i32_e32 v39, 31, v38
	v_lshlrev_b64 v[38:39], 9, v[38:39]
	v_or_b32_e32 v38, s17, v38
	v_lshl_add_u64 v[50:51], v[38:39], 0, v[42:43]
	v_lshlrev_b64 v[50:51], 1, v[50:51]
	v_lshl_add_u64 v[38:39], v[38:39], 0, v[44:45]
	v_lshlrev_b64 v[38:39], 1, v[38:39]
	v_lshlrev_b32_e32 v30, 16, v30
	v_mul_f32_e32 v60, 0xbfb8aa3b, v30
	v_exp_f32_e32 v64, v60
	v_mul_f32_e32 v26, v47, v26
	v_lshl_add_u64 v[60:61], s[26:27], 0, v[50:51]
	v_lshl_add_u64 v[50:51], s[28:29], 0, v[50:51]
	v_add_f32_e32 v34, 1.0, v64
	v_div_scale_f32 v64, s[36:37], v34, v34, v30
	v_rcp_f32_e32 v65, v64
	v_div_scale_f32 v66, vcc, v30, v34, v30
	v_fma_f32 v67, -v64, v65, 1.0
	v_fmac_f32_e32 v65, v67, v65
	v_mul_f32_e32 v67, v66, v65
	v_fma_f32 v68, -v64, v67, v66
	v_fmac_f32_e32 v67, v68, v65
	v_fma_f32 v64, -v64, v67, v66
	v_div_fmas_f32 v64, v64, v65, v67
	v_div_fixup_f32 v30, v64, v34, v30
	v_mul_f32_e32 v26, v26, v30
	v_cvt_pk_bf16_f32 v26, v26, s0
	global_store_short v[56:57], v26, off
	v_mov_b32_e32 v26, v104
	v_mul_f32_e32 v30, 0x4b800000, v35
	v_cmp_gt_f32_e32 vcc, s58, v35
	v_lshl_add_u64 v[56:57], s[26:27], 0, v[38:39]
	v_lshl_add_u64 v[38:39], s[28:29], 0, v[38:39]
	v_cndmask_b32_e32 v30, v35, v30, vcc
	v_rsq_f32_e32 v30, v30
; DI float bf2f(unsigned h) { return __uint_as_float(h << 16); }
; DI bf16_t f2bf(float f) { return (bf16_t)(pk2(f, 0.f) & 0xffffu); }
; DI float siluf_(float x) { return x / (1.f + __expf(-x)); }
; DI void gdnout_item(const Params& p, int l, int item, float* red  ) {
;     ...
; #pragma unroll
;   for (int mi = 0; mi < 4; ++mi)
; #pragma unroll
;     for (int r = 0; r < 4; ++r) {
;       const int tk = mi * 16 + lq * 4 + r;
;       const float rstd = rsqrtf((red[tk] + red[64 + tk] + red[128 + tk] + red[192 + tk]) * (1.f / 128.f) + EPS);
; #pragma unroll
;       for (int j = 0; j < 2; ++j) {
;         const int col = (2 * wid + j) * 16 + lr;
;         const size_t idx = (size_t)(t0 + tk) * 512 + h * 128 + col;
;         OC[idx] = f2bf(O[mi][j][r] * rstd * p.onw[l * 128 + col] * siluf_(bf2f(RZ[idx])));
;       }
;     }
	v_lshlrev_b32_e32 v26, 16, v26
	v_mul_f32_e32 v34, 0xbfb8aa3b, v26
	v_exp_f32_e32 v34, v34
	v_mul_f32_e32 v35, 0x45800000, v30
	v_cndmask_b32_e32 v60, v30, v35, vcc
	v_mul_f32_e32 v30, v31, v60
	v_add_f32_e32 v31, 1.0, v34
	v_div_scale_f32 v34, s[36:37], v31, v31, v26
	v_rcp_f32_e32 v35, v34
	v_div_scale_f32 v61, vcc, v26, v31, v26
	v_mul_f32_e32 v30, v0, v30
	v_fma_f32 v64, -v34, v35, 1.0
	v_fmac_f32_e32 v35, v64, v35
	v_mul_f32_e32 v64, v61, v35
	v_fma_f32 v65, -v34, v64, v61
	v_fmac_f32_e32 v64, v65, v35
	v_fma_f32 v34, -v34, v64, v61
	v_div_fmas_f32 v34, v34, v35, v64
	v_div_fixup_f32 v26, v34, v31, v26
	v_mul_f32_e32 v26, v26, v30
	v_cvt_pk_bf16_f32 v26, v26, s0
	global_store_short v[50:51], v26, off
	v_mov_b32_e32 v26, v105
	v_mul_f32_e32 v27, v27, v60
	v_or_b32_e32 v30, 2, v46
	v_ashrrev_i32_e32 v31, 31, v30
	v_lshlrev_b64 v[30:31], 9, v[30:31]
	v_or_b32_e32 v30, s17, v30
	v_mul_f32_e32 v27, v47, v27
	v_lshl_add_u64 v[34:35], v[30:31], 0, v[42:43]
	v_lshlrev_b64 v[34:35], 1, v[34:35]
	v_lshlrev_b32_e32 v26, 16, v26
	v_mul_f32_e32 v50, 0xbfb8aa3b, v26
	v_exp_f32_e32 v56, v50
	v_lshl_add_u64 v[50:51], s[26:27], 0, v[34:35]
	v_lshl_add_u64 v[34:35], s[28:29], 0, v[34:35]
	v_add_f32_e32 v56, 1.0, v56
	v_div_scale_f32 v57, s[36:37], v56, v56, v26
	v_rcp_f32_e32 v60, v57
	v_div_scale_f32 v61, vcc, v26, v56, v26
	v_fma_f32 v64, -v57, v60, 1.0
	v_fmac_f32_e32 v60, v64, v60
	v_mul_f32_e32 v64, v61, v60
	v_fma_f32 v65, -v57, v64, v61
	v_fmac_f32_e32 v64, v65, v60
	v_fma_f32 v57, -v57, v64, v61
	v_div_fmas_f32 v57, v57, v60, v64
	v_div_fixup_f32 v26, v57, v56, v26
	v_mul_f32_e32 v26, v27, v26
	v_cvt_pk_bf16_f32 v26, v26, s0
	global_store_short v[38:39], v26, off
	v_mov_b32_e32 v38, v106
	v_lshl_add_u64 v[26:27], v[30:31], 0, v[44:45]
	v_pk_add_f32 v[30:31], v[36:37], v[40:41]
	v_lshlrev_b64 v[26:27], 1, v[26:27]
	v_pk_add_f32 v[30:31], v[30:31], v[52:53]
	v_lshl_add_u64 v[36:37], s[26:27], 0, v[26:27]
	v_pk_add_f32 v[30:31], v[30:31], v[58:59]
	v_lshl_add_u64 v[26:27], s[28:29], 0, v[26:27]
	v_pk_fma_f32 v[30:31], v[30:31], s[34:35], v[48:49] op_sel_hi:[1,0,0]
	v_lshlrev_b32_e32 v38, 16, v38
	v_mul_f32_e32 v39, 0x4b800000, v30
	v_cmp_gt_f32_e32 vcc, s58, v30
	s_nop 1
	v_cndmask_b32_e32 v30, v30, v39, vcc
	v_mul_f32_e32 v39, 0xbfb8aa3b, v38
	v_rsq_f32_e32 v30, v30
	v_exp_f32_e32 v39, v39
	v_mul_f32_e32 v40, 0x45800000, v30
	v_add_f32_e32 v39, 1.0, v39
	v_cndmask_b32_e32 v30, v30, v40, vcc
	v_div_scale_f32 v40, s[36:37], v39, v39, v38
	v_rcp_f32_e32 v41, v40
	v_div_scale_f32 v50, vcc, v38, v39, v38
	v_mul_f32_e32 v32, v32, v30
	v_fma_f32 v51, -v40, v41, 1.0
	v_fmac_f32_e32 v41, v51, v41
	v_mul_f32_e32 v51, v50, v41
	v_fma_f32 v52, -v40, v51, v50
	v_fmac_f32_e32 v51, v52, v41
	v_fma_f32 v40, -v40, v51, v50
	v_div_fmas_f32 v40, v40, v41, v51
	v_mul_f32_e32 v32, v0, v32
	v_div_fixup_f32 v38, v40, v39, v38
	v_mul_f32_e32 v32, v38, v32
	v_cvt_pk_bf16_f32 v32, v32, s0
	global_store_short v[34:35], v32, off
	v_mov_b32_e32 v32, v107
	v_mul_f32_e32 v28, v28, v30
	v_or_b32_e32 v34, 3, v46
	v_ashrrev_i32_e32 v35, 31, v34
	v_lshlrev_b64 v[34:35], 9, v[34:35]
	v_or_b32_e32 v34, s17, v34
	v_mul_f32_e32 v28, v47, v28
	v_lshl_add_u64 v[36:37], v[34:35], 0, v[42:43]
	v_lshlrev_b64 v[36:37], 1, v[36:37]
	v_lshlrev_b32_e32 v32, 16, v32
	v_mul_f32_e32 v38, 0xbfb8aa3b, v32
	v_exp_f32_e32 v40, v38
	v_lshl_add_u64 v[38:39], s[26:27], 0, v[36:37]
	v_add_f32_e32 v30, 1.0, v40
	v_div_scale_f32 v40, s[36:37], v30, v30, v32
	v_rcp_f32_e32 v41, v40
	v_div_scale_f32 v50, vcc, v32, v30, v32
	v_fma_f32 v51, -v40, v41, 1.0
	v_fmac_f32_e32 v41, v51, v41
	v_mul_f32_e32 v51, v50, v41
	v_fma_f32 v52, -v40, v51, v50
	v_fmac_f32_e32 v51, v52, v41
	v_fma_f32 v40, -v40, v51, v50
	v_div_fmas_f32 v40, v40, v41, v51
	v_div_fixup_f32 v30, v40, v30, v32
	v_mul_f32_e32 v28, v28, v30
	v_cvt_pk_bf16_f32 v28, v28, s0
	global_store_short v[26:27], v28, off
	v_mov_b32_e32 v28, v108
	v_mul_f32_e32 v30, 0x4b800000, v31
	v_cmp_gt_f32_e32 vcc, s58, v31
	v_lshl_add_u64 v[26:27], v[34:35], 0, v[44:45]
	v_lshlrev_b64 v[26:27], 1, v[26:27]
	v_cndmask_b32_e32 v30, v31, v30, vcc
	v_rsq_f32_e32 v30, v30
	v_lshl_add_u64 v[34:35], s[28:29], 0, v[36:37]
	v_lshl_add_u64 v[36:37], s[26:27], 0, v[26:27]
	v_lshl_add_u64 v[26:27], s[28:29], 0, v[26:27]
	v_mul_f32_e32 v32, 0x45800000, v30
	v_cndmask_b32_e32 v32, v30, v32, vcc
	v_mul_f32_e32 v30, v33, v32
	v_mul_f32_e32 v30, v0, v30
	v_mul_f32_e32 v29, v29, v32
	v_mul_f32_e32 v29, v47, v29
	v_lshlrev_b32_e32 v28, 16, v28
	v_mul_f32_e32 v31, 0xbfb8aa3b, v28
	v_exp_f32_e32 v31, v31
	s_nop 0
	v_add_f32_e32 v31, 1.0, v31
	v_div_scale_f32 v33, s[36:37], v31, v31, v28
	v_rcp_f32_e32 v38, v33
	v_div_scale_f32 v39, vcc, v28, v31, v28
	v_fma_f32 v40, -v33, v38, 1.0
	v_fmac_f32_e32 v38, v40, v38
	v_mul_f32_e32 v40, v39, v38
	v_fma_f32 v41, -v33, v40, v39
	v_fmac_f32_e32 v40, v41, v38
	v_fma_f32 v33, -v33, v40, v39
	v_div_fmas_f32 v33, v33, v38, v40
	v_div_fixup_f32 v28, v33, v31, v28
	v_mul_f32_e32 v28, v28, v30
	v_cvt_pk_bf16_f32 v28, v28, s0
	global_store_short v[34:35], v28, off
	v_mov_b32_e32 v28, v109
	v_or_b32_e32 v30, 16, v46
	v_ashrrev_i32_e32 v31, 31, v30
	v_lshlrev_b64 v[52:53], 9, v[30:31]
	v_or_b32_e32 v52, s17, v52
	v_lshl_add_u64 v[30:31], v[52:53], 0, v[42:43]
	v_lshlrev_b64 v[50:51], 1, v[30:31]
	v_lshl_add_u64 v[52:53], v[52:53], 0, v[44:45]
	v_lshlrev_b64 v[52:53], 1, v[52:53]
	v_lshlrev_b32_e32 v28, 16, v28
	v_mul_f32_e32 v30, 0xbfb8aa3b, v28
	v_exp_f32_e32 v33, v30
	v_lshl_add_u64 v[30:31], s[26:27], 0, v[50:51]
	v_add_f32_e32 v32, 1.0, v33
	v_div_scale_f32 v33, s[36:37], v32, v32, v28
	v_rcp_f32_e32 v34, v33
	v_div_scale_f32 v35, vcc, v28, v32, v28
	v_fma_f32 v36, -v33, v34, 1.0
	v_fmac_f32_e32 v34, v36, v34
	v_mul_f32_e32 v36, v35, v34
	v_fma_f32 v37, -v33, v36, v35
	v_fmac_f32_e32 v36, v37, v34
	v_fma_f32 v33, -v33, v36, v35
	v_div_fmas_f32 v33, v33, v34, v36
	v_div_fixup_f32 v28, v33, v32, v28
	v_mul_f32_e32 v28, v29, v28
	v_cvt_pk_bf16_f32 v28, v28, s0
	global_store_short v[26:27], v28, off
	v_mov_b32_e32 v56, v110
	ds_read_b128 v[26:29], v55 offset:64
	ds_read_b128 v[30:33], v55 offset:320
	ds_read_b128 v[34:37], v55 offset:576
	ds_read_b128 v[38:41], v55 offset:832
	s_waitcnt lgkmcnt(2)
; DI float bf2f(unsigned h) { return __uint_as_float(h << 16); }
; DI bf16_t f2bf(float f) { return (bf16_t)(pk2(f, 0.f) & 0xffffu); }
; DI float siluf_(float x) { return x / (1.f + __expf(-x)); }
; DI void gdnout_item(const Params& p, int l, int item, float* red  ) {
;     ...
; #pragma unroll
;   for (int mi = 0; mi < 4; ++mi)
; #pragma unroll
;     for (int r = 0; r < 4; ++r) {
;       const int tk = mi * 16 + lq * 4 + r;
;       const float rstd = rsqrtf((red[tk] + red[64 + tk] + red[128 + tk] + red[192 + tk]) * (1.f / 128.f) + EPS);
; #pragma unroll
;       for (int j = 0; j < 2; ++j) {
;         const int col = (2 * wid + j) * 16 + lr;
;         const size_t idx = (size_t)(t0 + tk) * 512 + h * 128 + col;
;         OC[idx] = f2bf(O[mi][j][r] * rstd * p.onw[l * 128 + col] * siluf_(bf2f(RZ[idx])));
;       }
;     }
	v_pk_add_f32 v[26:27], v[26:27], v[30:31]
	s_waitcnt lgkmcnt(1)
	v_pk_add_f32 v[26:27], v[26:27], v[34:35]
	v_lshl_add_u64 v[30:31], s[28:29], 0, v[50:51]
	s_waitcnt lgkmcnt(0)
	v_pk_add_f32 v[26:27], v[26:27], v[38:39]
	v_lshl_add_u64 v[50:51], s[26:27], 0, v[52:53]
	v_pk_fma_f32 v[26:27], v[26:27], s[34:35], v[48:49] op_sel_hi:[1,0,0]
	s_nop 0
	v_mul_f32_e32 v34, 0x4b800000, v26
	v_cmp_gt_f32_e32 vcc, s58, v26
	s_nop 1
	v_cndmask_b32_e32 v26, v26, v34, vcc
	v_rsq_f32_e32 v26, v26
	v_lshlrev_b32_e32 v34, 16, v56
	v_mul_f32_e32 v35, 0xbfb8aa3b, v34
	v_exp_f32_e32 v35, v35
	v_mul_f32_e32 v38, 0x45800000, v26
	v_cndmask_b32_e32 v26, v26, v38, vcc
	v_mul_f32_e32 v22, v22, v26
	v_add_f32_e32 v35, 1.0, v35
	v_div_scale_f32 v38, s[36:37], v35, v35, v34
	v_rcp_f32_e32 v39, v38
	v_div_scale_f32 v56, vcc, v34, v35, v34
	v_mul_f32_e32 v22, v0, v22
	v_fma_f32 v57, -v38, v39, 1.0
	v_fmac_f32_e32 v39, v57, v39
	v_mul_f32_e32 v57, v56, v39
	v_fma_f32 v58, -v38, v57, v56
	v_fmac_f32_e32 v57, v58, v39
	v_fma_f32 v38, -v38, v57, v56
	v_div_fmas_f32 v38, v38, v39, v57
	v_div_fixup_f32 v34, v38, v35, v34
	v_mul_f32_e32 v22, v34, v22
	v_cvt_pk_bf16_f32 v22, v22, s0
	global_store_short v[30:31], v22, off
	v_mov_b32_e32 v22, v111
	v_mul_f32_e32 v18, v18, v26
	v_or_b32_e32 v30, 17, v46
	v_ashrrev_i32_e32 v31, 31, v30
	v_lshlrev_b64 v[30:31], 9, v[30:31]
	v_or_b32_e32 v30, s17, v30
	v_mul_f32_e32 v18, v47, v18
	v_lshl_add_u64 v[34:35], v[30:31], 0, v[42:43]
	v_lshlrev_b64 v[34:35], 1, v[34:35]
	v_lshl_add_u64 v[50:51], s[26:27], 0, v[34:35]
	v_lshl_add_u64 v[30:31], v[30:31], 0, v[44:45]
	v_lshlrev_b64 v[30:31], 1, v[30:31]
	v_lshl_add_u64 v[34:35], s[28:29], 0, v[34:35]
	v_lshlrev_b32_e32 v22, 16, v22
	v_mul_f32_e32 v38, 0xbfb8aa3b, v22
	v_exp_f32_e32 v56, v38
	v_lshl_add_u64 v[38:39], s[28:29], 0, v[52:53]
	v_add_f32_e32 v26, 1.0, v56
	v_div_scale_f32 v52, s[36:37], v26, v26, v22
	v_rcp_f32_e32 v53, v52
	v_div_scale_f32 v56, vcc, v22, v26, v22
	v_fma_f32 v57, -v52, v53, 1.0
	v_fmac_f32_e32 v53, v57, v53
	v_mul_f32_e32 v57, v56, v53
	v_fma_f32 v58, -v52, v57, v56
	v_fmac_f32_e32 v57, v58, v53
	v_fma_f32 v52, -v52, v57, v56
	v_div_fmas_f32 v52, v52, v53, v57
	v_div_fixup_f32 v22, v52, v26, v22
	v_mul_f32_e32 v18, v18, v22
	v_cvt_pk_bf16_f32 v18, v18, s0
	global_store_short v[38:39], v18, off
	v_mov_b32_e32 v18, v112
	v_mul_f32_e32 v22, 0x4b800000, v27
	v_cmp_gt_f32_e32 vcc, s58, v27
	v_lshl_add_u64 v[38:39], s[26:27], 0, v[30:31]
	v_lshl_add_u64 v[30:31], s[28:29], 0, v[30:31]
	v_cndmask_b32_e32 v22, v27, v22, vcc
	v_rsq_f32_e32 v22, v22
	v_lshlrev_b32_e32 v18, 16, v18
	v_mul_f32_e32 v26, 0xbfb8aa3b, v18
	v_exp_f32_e32 v26, v26
	v_mul_f32_e32 v27, 0x45800000, v22
	v_cndmask_b32_e32 v50, v22, v27, vcc
	v_mul_f32_e32 v22, v23, v50
	v_add_f32_e32 v23, 1.0, v26
	v_div_scale_f32 v26, s[36:37], v23, v23, v18
	v_rcp_f32_e32 v27, v26
	v_div_scale_f32 v51, vcc, v18, v23, v18
	v_mul_f32_e32 v22, v0, v22
	v_fma_f32 v52, -v26, v27, 1.0
	v_fmac_f32_e32 v27, v52, v27
	v_mul_f32_e32 v52, v51, v27
	v_fma_f32 v53, -v26, v52, v51
	v_fmac_f32_e32 v52, v53, v27
	v_fma_f32 v26, -v26, v52, v51
	v_div_fmas_f32 v26, v26, v27, v52
	v_div_fixup_f32 v18, v26, v23, v18
	v_mul_f32_e32 v18, v18, v22
	v_cvt_pk_bf16_f32 v18, v18, s0
	global_store_short v[34:35], v18, off
	v_mov_b32_e32 v18, v113
	v_mul_f32_e32 v19, v19, v50
	v_or_b32_e32 v22, 18, v46
	v_ashrrev_i32_e32 v23, 31, v22
	v_lshlrev_b64 v[22:23], 9, v[22:23]
	v_or_b32_e32 v22, s17, v22
	v_mul_f32_e32 v19, v47, v19
	v_lshl_add_u64 v[26:27], v[22:23], 0, v[42:43]
	v_lshlrev_b64 v[26:27], 1, v[26:27]
	v_lshlrev_b32_e32 v18, 16, v18
	v_mul_f32_e32 v34, 0xbfb8aa3b, v18
	v_exp_f32_e32 v38, v34
	v_lshl_add_u64 v[34:35], s[26:27], 0, v[26:27]
	v_lshl_add_u64 v[26:27], s[28:29], 0, v[26:27]
	v_add_f32_e32 v38, 1.0, v38
	v_div_scale_f32 v39, s[36:37], v38, v38, v18
	v_rcp_f32_e32 v50, v39
	v_div_scale_f32 v51, vcc, v18, v38, v18
	v_fma_f32 v52, -v39, v50, 1.0
	v_fmac_f32_e32 v50, v52, v50
	v_mul_f32_e32 v52, v51, v50
	v_fma_f32 v53, -v39, v52, v51
	v_fmac_f32_e32 v52, v53, v50
	v_fma_f32 v39, -v39, v52, v51
	v_div_fmas_f32 v39, v39, v50, v52
	v_div_fixup_f32 v18, v39, v38, v18
	v_mul_f32_e32 v18, v19, v18
	v_cvt_pk_bf16_f32 v18, v18, s0
	global_store_short v[30:31], v18, off
	v_mov_b32_e32 v30, v114
	v_lshl_add_u64 v[18:19], v[22:23], 0, v[44:45]
	v_pk_add_f32 v[22:23], v[28:29], v[32:33]
	v_lshlrev_b64 v[18:19], 1, v[18:19]
	v_pk_add_f32 v[22:23], v[22:23], v[36:37]
	v_lshl_add_u64 v[28:29], s[26:27], 0, v[18:19]
	v_pk_add_f32 v[22:23], v[22:23], v[40:41]
	v_lshl_add_u64 v[18:19], s[28:29], 0, v[18:19]
	v_pk_fma_f32 v[22:23], v[22:23], s[34:35], v[48:49] op_sel_hi:[1,0,0]
	v_lshlrev_b32_e32 v30, 16, v30
	v_mul_f32_e32 v31, 0x4b800000, v22
	v_cmp_gt_f32_e32 vcc, s58, v22
	s_nop 1
	v_cndmask_b32_e32 v22, v22, v31, vcc
	v_mul_f32_e32 v31, 0xbfb8aa3b, v30
	v_rsq_f32_e32 v22, v22
	v_exp_f32_e32 v31, v31
	v_mul_f32_e32 v32, 0x45800000, v22
	v_add_f32_e32 v31, 1.0, v31
	v_cndmask_b32_e32 v22, v22, v32, vcc
	v_div_scale_f32 v32, s[36:37], v31, v31, v30
	v_rcp_f32_e32 v33, v32
	v_div_scale_f32 v34, vcc, v30, v31, v30
	v_mul_f32_e32 v24, v24, v22
	v_fma_f32 v35, -v32, v33, 1.0
	v_fmac_f32_e32 v33, v35, v33
	v_mul_f32_e32 v35, v34, v33
	v_fma_f32 v36, -v32, v35, v34
	v_fmac_f32_e32 v35, v36, v33
	v_fma_f32 v32, -v32, v35, v34
	v_div_fmas_f32 v32, v32, v33, v35
	v_mul_f32_e32 v24, v0, v24
	v_div_fixup_f32 v30, v32, v31, v30
	v_mul_f32_e32 v24, v30, v24
	v_cvt_pk_bf16_f32 v24, v24, s0
	global_store_short v[26:27], v24, off
	v_mov_b32_e32 v24, v115
	v_mul_f32_e32 v20, v20, v22
	v_or_b32_e32 v26, 19, v46
	v_ashrrev_i32_e32 v27, 31, v26
; DI float bf2f(unsigned h) { return __uint_as_float(h << 16); }
; DI bf16_t f2bf(float f) { return (bf16_t)(pk2(f, 0.f) & 0xffffu); }
; DI float siluf_(float x) { return x / (1.f + __expf(-x)); }
; DI void gdnout_item(const Params& p, int l, int item, float* red  ) {
;     ...
; #pragma unroll
;   for (int mi = 0; mi < 4; ++mi)
; #pragma unroll
;     for (int r = 0; r < 4; ++r) {
;       const int tk = mi * 16 + lq * 4 + r;
;       const float rstd = rsqrtf((red[tk] + red[64 + tk] + red[128 + tk] + red[192 + tk]) * (1.f / 128.f) + EPS);
; #pragma unroll
;       for (int j = 0; j < 2; ++j) {
;         const int col = (2 * wid + j) * 16 + lr;
;         const size_t idx = (size_t)(t0 + tk) * 512 + h * 128 + col;
;         OC[idx] = f2bf(O[mi][j][r] * rstd * p.onw[l * 128 + col] * siluf_(bf2f(RZ[idx])));
;       }
;     }
	v_lshlrev_b64 v[26:27], 9, v[26:27]
	v_or_b32_e32 v26, s17, v26
	v_mul_f32_e32 v20, v47, v20
	v_lshl_add_u64 v[28:29], v[26:27], 0, v[42:43]
	v_lshlrev_b64 v[28:29], 1, v[28:29]
	v_lshlrev_b32_e32 v24, 16, v24
	v_mul_f32_e32 v30, 0xbfb8aa3b, v24
	v_exp_f32_e32 v32, v30
	v_lshl_add_u64 v[30:31], s[26:27], 0, v[28:29]
	v_add_f32_e32 v22, 1.0, v32
	v_div_scale_f32 v32, s[36:37], v22, v22, v24
	v_rcp_f32_e32 v33, v32
	v_div_scale_f32 v34, vcc, v24, v22, v24
	v_fma_f32 v35, -v32, v33, 1.0
	v_fmac_f32_e32 v33, v35, v33
	v_mul_f32_e32 v35, v34, v33
	v_fma_f32 v36, -v32, v35, v34
	v_fmac_f32_e32 v35, v36, v33
	v_fma_f32 v32, -v32, v35, v34
	v_div_fmas_f32 v32, v32, v33, v35
	v_div_fixup_f32 v22, v32, v22, v24
	v_mul_f32_e32 v20, v20, v22
	v_cvt_pk_bf16_f32 v20, v20, s0
	global_store_short v[18:19], v20, off
	v_mov_b32_e32 v20, v116
	v_mul_f32_e32 v22, 0x4b800000, v23
	v_cmp_gt_f32_e32 vcc, s58, v23
	v_lshl_add_u64 v[18:19], v[26:27], 0, v[44:45]
	v_lshlrev_b64 v[18:19], 1, v[18:19]
	v_cndmask_b32_e32 v22, v23, v22, vcc
	v_rsq_f32_e32 v22, v22
	v_lshl_add_u64 v[26:27], s[28:29], 0, v[28:29]
	v_lshl_add_u64 v[28:29], s[26:27], 0, v[18:19]
	v_lshl_add_u64 v[18:19], s[28:29], 0, v[18:19]
	v_mul_f32_e32 v24, 0x45800000, v22
	v_cndmask_b32_e32 v24, v22, v24, vcc
	v_mul_f32_e32 v22, v25, v24
	v_mul_f32_e32 v22, v0, v22
	v_mul_f32_e32 v21, v21, v24
	v_mul_f32_e32 v21, v47, v21
	v_lshlrev_b32_e32 v20, 16, v20
	v_mul_f32_e32 v23, 0xbfb8aa3b, v20
	v_exp_f32_e32 v23, v23
	s_nop 0
	v_add_f32_e32 v23, 1.0, v23
	v_div_scale_f32 v25, s[36:37], v23, v23, v20
	v_rcp_f32_e32 v30, v25
	v_div_scale_f32 v31, vcc, v20, v23, v20
	v_fma_f32 v32, -v25, v30, 1.0
	v_fmac_f32_e32 v30, v32, v30
	v_mul_f32_e32 v32, v31, v30
	v_fma_f32 v33, -v25, v32, v31
	v_fmac_f32_e32 v32, v33, v30
	v_fma_f32 v25, -v25, v32, v31
	v_div_fmas_f32 v25, v25, v30, v32
	v_div_fixup_f32 v20, v25, v23, v20
	v_mul_f32_e32 v20, v20, v22
	v_cvt_pk_bf16_f32 v20, v20, s0
	global_store_short v[26:27], v20, off
	v_mov_b32_e32 v20, v117
	v_or_b32_e32 v22, 32, v46
	v_ashrrev_i32_e32 v23, 31, v22
	v_lshlrev_b64 v[34:35], 9, v[22:23]
	v_or_b32_e32 v34, s17, v34
	v_lshl_add_u64 v[22:23], v[34:35], 0, v[42:43]
	v_lshlrev_b64 v[36:37], 1, v[22:23]
	v_lshl_add_u64 v[34:35], v[34:35], 0, v[44:45]
	v_lshlrev_b64 v[34:35], 1, v[34:35]
	v_lshlrev_b32_e32 v20, 16, v20
	v_mul_f32_e32 v22, 0xbfb8aa3b, v20
	v_exp_f32_e32 v25, v22
	v_lshl_add_u64 v[22:23], s[26:27], 0, v[36:37]
	v_add_f32_e32 v24, 1.0, v25
	v_div_scale_f32 v25, s[36:37], v24, v24, v20
	v_rcp_f32_e32 v26, v25
	v_div_scale_f32 v27, vcc, v20, v24, v20
	v_fma_f32 v28, -v25, v26, 1.0
	v_fmac_f32_e32 v26, v28, v26
	v_mul_f32_e32 v28, v27, v26
	v_fma_f32 v29, -v25, v28, v27
	v_fmac_f32_e32 v28, v29, v26
	v_fma_f32 v25, -v25, v28, v27
	v_div_fmas_f32 v25, v25, v26, v28
	v_div_fixup_f32 v20, v25, v24, v20
	v_mul_f32_e32 v20, v21, v20
	v_cvt_pk_bf16_f32 v20, v20, s0
	global_store_short v[18:19], v20, off
	v_mov_b32_e32 v38, v118
	ds_read_b128 v[18:21], v55 offset:128
	ds_read_b128 v[22:25], v55 offset:384
	ds_read_b128 v[26:29], v55 offset:640
	ds_read_b128 v[30:33], v55 offset:896
	s_waitcnt lgkmcnt(2)
	v_pk_add_f32 v[18:19], v[18:19], v[22:23]
	s_waitcnt lgkmcnt(1)
	v_pk_add_f32 v[18:19], v[18:19], v[26:27]
	v_lshl_add_u64 v[22:23], s[28:29], 0, v[36:37]
	s_waitcnt lgkmcnt(0)
	v_pk_add_f32 v[18:19], v[18:19], v[30:31]
	v_lshl_add_u64 v[36:37], s[26:27], 0, v[34:35]
	v_pk_fma_f32 v[18:19], v[18:19], s[34:35], v[48:49] op_sel_hi:[1,0,0]
	s_nop 0
	v_mul_f32_e32 v26, 0x4b800000, v18
	v_cmp_gt_f32_e32 vcc, s58, v18
	s_nop 1
	v_cndmask_b32_e32 v18, v18, v26, vcc
	v_rsq_f32_e32 v18, v18
	v_lshlrev_b32_e32 v26, 16, v38
	v_mul_f32_e32 v27, 0xbfb8aa3b, v26
	v_exp_f32_e32 v27, v27
	v_mul_f32_e32 v30, 0x45800000, v18
	v_cndmask_b32_e32 v18, v18, v30, vcc
	v_mul_f32_e32 v14, v14, v18
	v_add_f32_e32 v27, 1.0, v27
	v_div_scale_f32 v30, s[36:37], v27, v27, v26
	v_rcp_f32_e32 v31, v30
	v_div_scale_f32 v38, vcc, v26, v27, v26
	v_mul_f32_e32 v14, v0, v14
	v_fma_f32 v39, -v30, v31, 1.0
	v_fmac_f32_e32 v31, v39, v31
	v_mul_f32_e32 v39, v38, v31
	v_fma_f32 v40, -v30, v39, v38
	v_fmac_f32_e32 v39, v40, v31
	v_fma_f32 v30, -v30, v39, v38
	v_div_fmas_f32 v30, v30, v31, v39
	v_div_fixup_f32 v26, v30, v27, v26
	v_mul_f32_e32 v14, v26, v14
	v_cvt_pk_bf16_f32 v14, v14, s0
	global_store_short v[22:23], v14, off
	v_mov_b32_e32 v14, v119
	v_mul_f32_e32 v10, v10, v18
	v_or_b32_e32 v22, 33, v46
	v_ashrrev_i32_e32 v23, 31, v22
	v_lshlrev_b64 v[22:23], 9, v[22:23]
	v_or_b32_e32 v22, s17, v22
	v_mul_f32_e32 v10, v47, v10
	v_lshl_add_u64 v[26:27], v[22:23], 0, v[42:43]
	v_lshlrev_b64 v[26:27], 1, v[26:27]
	v_lshl_add_u64 v[22:23], v[22:23], 0, v[44:45]
	v_lshlrev_b64 v[22:23], 1, v[22:23]
	v_lshlrev_b32_e32 v14, 16, v14
	v_mul_f32_e32 v30, 0xbfb8aa3b, v14
	v_exp_f32_e32 v36, v30
	v_lshl_add_u64 v[30:31], s[28:29], 0, v[34:35]
	v_lshl_add_u64 v[34:35], s[26:27], 0, v[26:27]
	v_lshl_add_u64 v[26:27], s[28:29], 0, v[26:27]
	v_add_f32_e32 v18, 1.0, v36
	v_div_scale_f32 v36, s[36:37], v18, v18, v14
	v_rcp_f32_e32 v37, v36
	v_div_scale_f32 v38, vcc, v14, v18, v14
	v_fma_f32 v39, -v36, v37, 1.0
	v_fmac_f32_e32 v37, v39, v37
	v_mul_f32_e32 v39, v38, v37
	v_fma_f32 v40, -v36, v39, v38
	v_fmac_f32_e32 v39, v40, v37
	v_fma_f32 v36, -v36, v39, v38
	v_div_fmas_f32 v36, v36, v37, v39
	v_div_fixup_f32 v14, v36, v18, v14
	v_mul_f32_e32 v10, v10, v14
	v_cvt_pk_bf16_f32 v10, v10, s0
	global_store_short v[30:31], v10, off
	v_mov_b32_e32 v10, v120
	v_mul_f32_e32 v14, 0x4b800000, v19
	v_cmp_gt_f32_e32 vcc, s58, v19
	v_lshl_add_u64 v[30:31], s[26:27], 0, v[22:23]
	v_lshl_add_u64 v[22:23], s[28:29], 0, v[22:23]
; DI float bf2f(unsigned h) { return __uint_as_float(h << 16); }
; DI bf16_t f2bf(float f) { return (bf16_t)(pk2(f, 0.f) & 0xffffu); }
; DI float siluf_(float x) { return x / (1.f + __expf(-x)); }
; DI void gdnout_item(const Params& p, int l, int item, float* red  ) {
;     ...
; #pragma unroll
;   for (int mi = 0; mi < 4; ++mi)
; #pragma unroll
;     for (int r = 0; r < 4; ++r) {
;       const int tk = mi * 16 + lq * 4 + r;
;       const float rstd = rsqrtf((red[tk] + red[64 + tk] + red[128 + tk] + red[192 + tk]) * (1.f / 128.f) + EPS);
; #pragma unroll
;       for (int j = 0; j < 2; ++j) {
;         const int col = (2 * wid + j) * 16 + lr;
;         const size_t idx = (size_t)(t0 + tk) * 512 + h * 128 + col;
;         OC[idx] = f2bf(O[mi][j][r] * rstd * p.onw[l * 128 + col] * siluf_(bf2f(RZ[idx])));
;       }
;     }
	v_cndmask_b32_e32 v14, v19, v14, vcc
	v_rsq_f32_e32 v14, v14
	v_lshlrev_b32_e32 v10, 16, v10
	v_mul_f32_e32 v18, 0xbfb8aa3b, v10
	v_exp_f32_e32 v18, v18
	v_mul_f32_e32 v19, 0x45800000, v14
	v_cndmask_b32_e32 v34, v14, v19, vcc
	v_mul_f32_e32 v14, v15, v34
	v_add_f32_e32 v15, 1.0, v18
	v_div_scale_f32 v18, s[36:37], v15, v15, v10
	v_rcp_f32_e32 v19, v18
	v_div_scale_f32 v35, vcc, v10, v15, v10
	v_mul_f32_e32 v14, v0, v14
	v_fma_f32 v36, -v18, v19, 1.0
	v_fmac_f32_e32 v19, v36, v19
	v_mul_f32_e32 v36, v35, v19
	v_fma_f32 v37, -v18, v36, v35
	v_fmac_f32_e32 v36, v37, v19
	v_fma_f32 v18, -v18, v36, v35
	v_div_fmas_f32 v18, v18, v19, v36
	v_div_fixup_f32 v10, v18, v15, v10
	v_mul_f32_e32 v10, v10, v14
	v_cvt_pk_bf16_f32 v10, v10, s0
	global_store_short v[26:27], v10, off
	v_mov_b32_e32 v10, v121
	v_mul_f32_e32 v11, v11, v34
	v_or_b32_e32 v14, 34, v46
	v_ashrrev_i32_e32 v15, 31, v14
	v_lshlrev_b64 v[14:15], 9, v[14:15]
	v_or_b32_e32 v14, s17, v14
	v_mul_f32_e32 v11, v47, v11
	v_lshl_add_u64 v[18:19], v[14:15], 0, v[42:43]
	v_lshlrev_b64 v[18:19], 1, v[18:19]
	v_lshlrev_b32_e32 v10, 16, v10
	v_mul_f32_e32 v26, 0xbfb8aa3b, v10
	v_exp_f32_e32 v30, v26
	v_lshl_add_u64 v[26:27], s[26:27], 0, v[18:19]
	v_lshl_add_u64 v[18:19], s[28:29], 0, v[18:19]
	v_add_f32_e32 v30, 1.0, v30
	v_div_scale_f32 v31, s[36:37], v30, v30, v10
	v_rcp_f32_e32 v34, v31
	v_div_scale_f32 v35, vcc, v10, v30, v10
	v_fma_f32 v36, -v31, v34, 1.0
	v_fmac_f32_e32 v34, v36, v34
	v_mul_f32_e32 v36, v35, v34
	v_fma_f32 v37, -v31, v36, v35
	v_fmac_f32_e32 v36, v37, v34
	v_fma_f32 v31, -v31, v36, v35
	v_div_fmas_f32 v31, v31, v34, v36
	v_div_fixup_f32 v10, v31, v30, v10
	v_mul_f32_e32 v10, v11, v10
	v_cvt_pk_bf16_f32 v10, v10, s0
	global_store_short v[22:23], v10, off
	v_mov_b32_e32 v22, v122
	v_lshl_add_u64 v[10:11], v[14:15], 0, v[44:45]
	v_pk_add_f32 v[14:15], v[20:21], v[24:25]
	v_lshlrev_b64 v[10:11], 1, v[10:11]
	v_pk_add_f32 v[14:15], v[14:15], v[28:29]
	v_lshl_add_u64 v[20:21], s[26:27], 0, v[10:11]
	v_pk_add_f32 v[14:15], v[14:15], v[32:33]
	v_lshl_add_u64 v[10:11], s[28:29], 0, v[10:11]
	v_pk_fma_f32 v[14:15], v[14:15], s[34:35], v[48:49] op_sel_hi:[1,0,0]
	v_lshlrev_b32_e32 v22, 16, v22
	v_mul_f32_e32 v23, 0x4b800000, v14
	v_cmp_gt_f32_e32 vcc, s58, v14
	s_nop 1
	v_cndmask_b32_e32 v14, v14, v23, vcc
	v_mul_f32_e32 v23, 0xbfb8aa3b, v22
	v_rsq_f32_e32 v14, v14
	v_exp_f32_e32 v23, v23
	v_mul_f32_e32 v24, 0x45800000, v14
	v_add_f32_e32 v23, 1.0, v23
	v_cndmask_b32_e32 v14, v14, v24, vcc
	v_div_scale_f32 v24, s[36:37], v23, v23, v22
	v_rcp_f32_e32 v25, v24
	v_div_scale_f32 v26, vcc, v22, v23, v22
	v_mul_f32_e32 v16, v16, v14
	v_fma_f32 v27, -v24, v25, 1.0
	v_fmac_f32_e32 v25, v27, v25
	v_mul_f32_e32 v27, v26, v25
	v_fma_f32 v28, -v24, v27, v26
	v_fmac_f32_e32 v27, v28, v25
	v_fma_f32 v24, -v24, v27, v26
	v_div_fmas_f32 v24, v24, v25, v27
	v_mul_f32_e32 v16, v0, v16
	v_div_fixup_f32 v22, v24, v23, v22
	v_mul_f32_e32 v16, v22, v16
	v_cvt_pk_bf16_f32 v16, v16, s0
	global_store_short v[18:19], v16, off
	v_mov_b32_e32 v16, v123
	v_mul_f32_e32 v12, v12, v14
	v_or_b32_e32 v18, 35, v46
	v_ashrrev_i32_e32 v19, 31, v18
	v_lshlrev_b64 v[18:19], 9, v[18:19]
	v_or_b32_e32 v18, s17, v18
	v_mul_f32_e32 v12, v47, v12
	v_lshl_add_u64 v[20:21], v[18:19], 0, v[42:43]
	v_lshlrev_b64 v[20:21], 1, v[20:21]
	v_lshlrev_b32_e32 v16, 16, v16
	v_mul_f32_e32 v22, 0xbfb8aa3b, v16
	v_exp_f32_e32 v24, v22
	v_lshl_add_u64 v[22:23], s[26:27], 0, v[20:21]
	v_add_f32_e32 v14, 1.0, v24
	v_div_scale_f32 v24, s[36:37], v14, v14, v16
	v_rcp_f32_e32 v25, v24
	v_div_scale_f32 v26, vcc, v16, v14, v16
	v_fma_f32 v27, -v24, v25, 1.0
	v_fmac_f32_e32 v25, v27, v25
	v_mul_f32_e32 v27, v26, v25
	v_fma_f32 v28, -v24, v27, v26
	v_fmac_f32_e32 v27, v28, v25
	v_fma_f32 v24, -v24, v27, v26
	v_div_fmas_f32 v24, v24, v25, v27
	v_div_fixup_f32 v14, v24, v14, v16
	v_mul_f32_e32 v12, v12, v14
	v_cvt_pk_bf16_f32 v12, v12, s0
	global_store_short v[10:11], v12, off
	v_mov_b32_e32 v12, v124
	v_mul_f32_e32 v14, 0x4b800000, v15
	v_cmp_gt_f32_e32 vcc, s58, v15
	v_lshl_add_u64 v[10:11], v[18:19], 0, v[44:45]
	v_lshlrev_b64 v[10:11], 1, v[10:11]
	v_cndmask_b32_e32 v14, v15, v14, vcc
	v_rsq_f32_e32 v14, v14
	v_lshl_add_u64 v[18:19], s[28:29], 0, v[20:21]
	v_lshl_add_u64 v[20:21], s[26:27], 0, v[10:11]
	v_lshl_add_u64 v[10:11], s[28:29], 0, v[10:11]
	v_mul_f32_e32 v16, 0x45800000, v14
	v_cndmask_b32_e32 v16, v14, v16, vcc
	v_mul_f32_e32 v14, v17, v16
	v_mul_f32_e32 v14, v0, v14
	v_mul_f32_e32 v13, v13, v16
	v_mul_f32_e32 v13, v47, v13
	v_lshlrev_b32_e32 v12, 16, v12
	v_mul_f32_e32 v15, 0xbfb8aa3b, v12
	v_exp_f32_e32 v15, v15
	s_nop 0
	v_add_f32_e32 v15, 1.0, v15
	v_div_scale_f32 v17, s[36:37], v15, v15, v12
	v_rcp_f32_e32 v22, v17
	v_div_scale_f32 v23, vcc, v12, v15, v12
	v_fma_f32 v24, -v17, v22, 1.0
	v_fmac_f32_e32 v22, v24, v22
	v_mul_f32_e32 v24, v23, v22
	v_fma_f32 v25, -v17, v24, v23
	v_fmac_f32_e32 v24, v25, v22
	v_fma_f32 v17, -v17, v24, v23
	v_div_fmas_f32 v17, v17, v22, v24
	v_div_fixup_f32 v12, v17, v15, v12
	v_mul_f32_e32 v12, v12, v14
	v_cvt_pk_bf16_f32 v12, v12, s0
	global_store_short v[18:19], v12, off
	v_mov_b32_e32 v12, v125
	v_or_b32_e32 v14, 48, v46
	v_ashrrev_i32_e32 v15, 31, v14
	v_lshlrev_b64 v[28:29], 9, v[14:15]
	v_or_b32_e32 v28, s17, v28
	v_lshl_add_u64 v[14:15], v[28:29], 0, v[42:43]
	v_lshlrev_b64 v[26:27], 1, v[14:15]
	v_lshl_add_u64 v[28:29], v[28:29], 0, v[44:45]
	v_lshlrev_b64 v[28:29], 1, v[28:29]
	v_lshlrev_b32_e32 v12, 16, v12
	v_mul_f32_e32 v14, 0xbfb8aa3b, v12
	v_exp_f32_e32 v17, v14
	v_lshl_add_u64 v[14:15], s[26:27], 0, v[26:27]
	v_add_f32_e32 v16, 1.0, v17
	v_div_scale_f32 v17, s[36:37], v16, v16, v12
	v_rcp_f32_e32 v18, v17
	v_div_scale_f32 v19, vcc, v12, v16, v12
	v_fma_f32 v20, -v17, v18, 1.0
	v_fmac_f32_e32 v18, v20, v18
	v_mul_f32_e32 v20, v19, v18
	v_fma_f32 v21, -v17, v20, v19
	v_fmac_f32_e32 v20, v21, v18
	v_fma_f32 v17, -v17, v20, v19
	v_div_fmas_f32 v17, v17, v18, v20
	v_div_fixup_f32 v12, v17, v16, v12
	v_mul_f32_e32 v12, v13, v12
	v_cvt_pk_bf16_f32 v12, v12, s0
	global_store_short v[10:11], v12, off
	v_mov_b32_e32 v30, v126
	ds_read_b128 v[10:13], v55 offset:192
	ds_read_b128 v[14:17], v55 offset:448
	ds_read_b128 v[18:21], v55 offset:704
	ds_read_b128 v[22:25], v55 offset:960
	s_waitcnt lgkmcnt(2)
; DI float bf2f(unsigned h) { return __uint_as_float(h << 16); }
; DI bf16_t f2bf(float f) { return (bf16_t)(pk2(f, 0.f) & 0xffffu); }
; DI float siluf_(float x) { return x / (1.f + __expf(-x)); }
; DI void gdnout_item(const Params& p, int l, int item, float* red  ) {
;     ...
; #pragma unroll
;   for (int mi = 0; mi < 4; ++mi)
; #pragma unroll
;     for (int r = 0; r < 4; ++r) {
;       const int tk = mi * 16 + lq * 4 + r;
;       const float rstd = rsqrtf((red[tk] + red[64 + tk] + red[128 + tk] + red[192 + tk]) * (1.f / 128.f) + EPS);
; #pragma unroll
;       for (int j = 0; j < 2; ++j) {
;         const int col = (2 * wid + j) * 16 + lr;
;         const size_t idx = (size_t)(t0 + tk) * 512 + h * 128 + col;
;         OC[idx] = f2bf(O[mi][j][r] * rstd * p.onw[l * 128 + col] * siluf_(bf2f(RZ[idx])));
;       }
;     }
	v_pk_add_f32 v[10:11], v[10:11], v[14:15]
	s_waitcnt lgkmcnt(1)
	v_pk_add_f32 v[10:11], v[10:11], v[18:19]
	v_lshl_add_u64 v[14:15], s[28:29], 0, v[26:27]
	s_waitcnt lgkmcnt(0)
	v_pk_add_f32 v[10:11], v[10:11], v[22:23]
	v_lshl_add_u64 v[26:27], s[26:27], 0, v[28:29]
	v_pk_fma_f32 v[10:11], v[10:11], s[34:35], v[48:49] op_sel_hi:[1,0,0]
	s_nop 0
	v_mul_f32_e32 v18, 0x4b800000, v10
	v_cmp_gt_f32_e32 vcc, s58, v10
	s_nop 1
	v_cndmask_b32_e32 v10, v10, v18, vcc
	v_rsq_f32_e32 v10, v10
	v_lshlrev_b32_e32 v18, 16, v30
	v_mul_f32_e32 v19, 0xbfb8aa3b, v18
	v_exp_f32_e32 v19, v19
	v_mul_f32_e32 v22, 0x45800000, v10
	v_cndmask_b32_e32 v10, v10, v22, vcc
	v_mul_f32_e32 v6, v6, v10
	v_add_f32_e32 v19, 1.0, v19
	v_div_scale_f32 v22, s[36:37], v19, v19, v18
	v_rcp_f32_e32 v23, v22
	v_div_scale_f32 v30, vcc, v18, v19, v18
	v_mul_f32_e32 v6, v0, v6
	v_fma_f32 v31, -v22, v23, 1.0
	v_fmac_f32_e32 v23, v31, v23
	v_mul_f32_e32 v31, v30, v23
	v_fma_f32 v32, -v22, v31, v30
	v_fmac_f32_e32 v31, v32, v23
	v_fma_f32 v22, -v22, v31, v30
	v_div_fmas_f32 v22, v22, v23, v31
	v_div_fixup_f32 v18, v22, v19, v18
	v_mul_f32_e32 v6, v18, v6
	v_cvt_pk_bf16_f32 v6, v6, s0
	global_store_short v[14:15], v6, off
	v_mov_b32_e32 v6, v127
	v_mul_f32_e32 v2, v2, v10
	v_or_b32_e32 v30, s18, v54
	v_or_b32_e32 v14, 49, v30
	v_ashrrev_i32_e32 v15, 31, v14
	v_lshlrev_b64 v[14:15], 9, v[14:15]
	v_or_b32_e32 v14, s17, v14
	v_mul_f32_e32 v2, v47, v2
	v_lshl_add_u64 v[18:19], v[14:15], 0, v[42:43]
	v_lshlrev_b64 v[18:19], 1, v[18:19]
	v_lshl_add_u64 v[26:27], s[26:27], 0, v[18:19]
	v_lshl_add_u64 v[14:15], v[14:15], 0, v[44:45]
	v_lshlrev_b64 v[14:15], 1, v[14:15]
	v_lshl_add_u64 v[18:19], s[28:29], 0, v[18:19]
	v_lshlrev_b32_e32 v6, 16, v6
	v_mul_f32_e32 v22, 0xbfb8aa3b, v6
	v_exp_f32_e32 v31, v22
	v_lshl_add_u64 v[22:23], s[28:29], 0, v[28:29]
	v_add_f32_e32 v10, 1.0, v31
	v_div_scale_f32 v28, s[18:19], v10, v10, v6
	v_rcp_f32_e32 v29, v28
	v_div_scale_f32 v31, vcc, v6, v10, v6
	v_fma_f32 v32, -v28, v29, 1.0
	v_fmac_f32_e32 v29, v32, v29
	v_mul_f32_e32 v32, v31, v29
	v_fma_f32 v33, -v28, v32, v31
	v_fmac_f32_e32 v32, v33, v29
	v_fma_f32 v28, -v28, v32, v31
	v_div_fmas_f32 v28, v28, v29, v32
	v_div_fixup_f32 v6, v28, v10, v6
	v_mul_f32_e32 v2, v2, v6
	v_cvt_pk_bf16_f32 v2, v2, s0
	global_store_short v[22:23], v2, off
	v_mov_b32_e32 v2, v128
	v_mul_f32_e32 v6, 0x4b800000, v11
	v_cmp_gt_f32_e32 vcc, s58, v11
	v_lshl_add_u64 v[22:23], s[26:27], 0, v[14:15]
	v_lshl_add_u64 v[14:15], s[28:29], 0, v[14:15]
	v_cndmask_b32_e32 v6, v11, v6, vcc
	v_rsq_f32_e32 v6, v6
	v_lshlrev_b32_e32 v2, 16, v2
	v_mul_f32_e32 v10, 0xbfb8aa3b, v2
	v_exp_f32_e32 v10, v10
	v_mul_f32_e32 v11, 0x45800000, v6
	v_cndmask_b32_e32 v26, v6, v11, vcc
	v_mul_f32_e32 v6, v7, v26
	v_add_f32_e32 v7, 1.0, v10
	v_div_scale_f32 v10, s[18:19], v7, v7, v2
	v_rcp_f32_e32 v11, v10
	v_div_scale_f32 v27, vcc, v2, v7, v2
	v_mul_f32_e32 v6, v0, v6
	v_fma_f32 v28, -v10, v11, 1.0
	v_fmac_f32_e32 v11, v28, v11
	v_mul_f32_e32 v28, v27, v11
	v_fma_f32 v29, -v10, v28, v27
	v_fmac_f32_e32 v28, v29, v11
	v_fma_f32 v10, -v10, v28, v27
	v_div_fmas_f32 v10, v10, v11, v28
	v_div_fixup_f32 v2, v10, v7, v2
	v_mul_f32_e32 v2, v2, v6
	v_cvt_pk_bf16_f32 v2, v2, s0
	global_store_short v[18:19], v2, off
	v_mov_b32_e32 v2, v129
	v_mul_f32_e32 v3, v3, v26
	v_or_b32_e32 v6, 50, v46
	v_ashrrev_i32_e32 v7, 31, v6
	v_lshlrev_b64 v[6:7], 9, v[6:7]
	v_or_b32_e32 v6, s17, v6
	v_mul_f32_e32 v3, v47, v3
	v_lshl_add_u64 v[10:11], v[6:7], 0, v[42:43]
	v_lshlrev_b64 v[10:11], 1, v[10:11]
	v_lshlrev_b32_e32 v2, 16, v2
	v_mul_f32_e32 v18, 0xbfb8aa3b, v2
	v_exp_f32_e32 v22, v18
	v_lshl_add_u64 v[18:19], s[26:27], 0, v[10:11]
	v_lshl_add_u64 v[10:11], s[28:29], 0, v[10:11]
	v_add_f32_e32 v22, 1.0, v22
	v_div_scale_f32 v23, s[18:19], v22, v22, v2
	v_rcp_f32_e32 v26, v23
	v_div_scale_f32 v27, vcc, v2, v22, v2
	v_fma_f32 v28, -v23, v26, 1.0
	v_fmac_f32_e32 v26, v28, v26
	v_mul_f32_e32 v28, v27, v26
	v_fma_f32 v29, -v23, v28, v27
	v_fmac_f32_e32 v28, v29, v26
; DI float bf2f(unsigned h) { return __uint_as_float(h << 16); }
; DI bf16_t f2bf(float f) { return (bf16_t)(pk2(f, 0.f) & 0xffffu); }
; DI float siluf_(float x) { return x / (1.f + __expf(-x)); }
; DI void gdnout_item(const Params& p, int l, int item, float* red  ) {
;     ...
; #pragma unroll
;   for (int mi = 0; mi < 4; ++mi)
; #pragma unroll
;     for (int r = 0; r < 4; ++r) {
;       const int tk = mi * 16 + lq * 4 + r;
;       const float rstd = rsqrtf((red[tk] + red[64 + tk] + red[128 + tk] + red[192 + tk]) * (1.f / 128.f) + EPS);
; #pragma unroll
;       for (int j = 0; j < 2; ++j) {
;         const int col = (2 * wid + j) * 16 + lr;
;         const size_t idx = (size_t)(t0 + tk) * 512 + h * 128 + col;
;         OC[idx] = f2bf(O[mi][j][r] * rstd * p.onw[l * 128 + col] * siluf_(bf2f(RZ[idx])));
;       }
;     }
	v_fma_f32 v23, -v23, v28, v27
	v_div_fmas_f32 v23, v23, v26, v28
	v_div_fixup_f32 v2, v23, v22, v2
	v_mul_f32_e32 v2, v3, v2
	v_cvt_pk_bf16_f32 v2, v2, s0
	global_store_short v[14:15], v2, off
	v_mov_b32_e32 v14, v130
	v_lshl_add_u64 v[2:3], v[6:7], 0, v[44:45]
	v_pk_add_f32 v[6:7], v[12:13], v[16:17]
	v_lshlrev_b64 v[2:3], 1, v[2:3]
	v_pk_add_f32 v[6:7], v[6:7], v[20:21]
	v_lshl_add_u64 v[12:13], s[26:27], 0, v[2:3]
	v_pk_add_f32 v[6:7], v[6:7], v[24:25]
	v_lshl_add_u64 v[2:3], s[28:29], 0, v[2:3]
	v_pk_fma_f32 v[6:7], v[6:7], s[34:35], v[48:49] op_sel_hi:[1,0,0]
	v_lshlrev_b32_e32 v14, 16, v14
	v_mul_f32_e32 v15, 0x4b800000, v6
	v_cmp_gt_f32_e32 vcc, s58, v6
	s_nop 1
	v_cndmask_b32_e32 v6, v6, v15, vcc
	v_mul_f32_e32 v15, 0xbfb8aa3b, v14
	v_rsq_f32_e32 v6, v6
	v_exp_f32_e32 v15, v15
	v_mul_f32_e32 v16, 0x45800000, v6
	v_add_f32_e32 v15, 1.0, v15
	v_cndmask_b32_e32 v6, v6, v16, vcc
	v_div_scale_f32 v16, s[18:19], v15, v15, v14
	v_rcp_f32_e32 v17, v16
	v_div_scale_f32 v18, vcc, v14, v15, v14
	v_mul_f32_e32 v8, v8, v6
	v_fma_f32 v19, -v16, v17, 1.0
	v_fmac_f32_e32 v17, v19, v17
	v_mul_f32_e32 v19, v18, v17
	v_fma_f32 v20, -v16, v19, v18
	v_fmac_f32_e32 v19, v20, v17
	v_fma_f32 v16, -v16, v19, v18
	v_div_fmas_f32 v16, v16, v17, v19
	v_mul_f32_e32 v8, v0, v8
	v_div_fixup_f32 v14, v16, v15, v14
	v_mul_f32_e32 v8, v14, v8
	v_cvt_pk_bf16_f32 v8, v8, s0
	global_store_short v[10:11], v8, off
	v_mov_b32_e32 v8, v131
	v_mul_f32_e32 v4, v4, v6
	v_or_b32_e32 v10, 51, v30
	v_ashrrev_i32_e32 v11, 31, v10
	v_lshlrev_b64 v[10:11], 9, v[10:11]
	v_or_b32_e32 v10, s17, v10
	v_mul_f32_e32 v4, v47, v4
	v_lshl_add_u64 v[12:13], v[10:11], 0, v[42:43]
	v_lshlrev_b64 v[12:13], 1, v[12:13]
	v_lshlrev_b32_e32 v8, 16, v8
	v_mul_f32_e32 v14, 0xbfb8aa3b, v8
	v_exp_f32_e32 v16, v14
	v_lshl_add_u64 v[14:15], s[26:27], 0, v[12:13]
	v_add_f32_e32 v6, 1.0, v16
	v_div_scale_f32 v16, s[18:19], v6, v6, v8
	v_rcp_f32_e32 v17, v16
	v_div_scale_f32 v18, vcc, v8, v6, v8
	v_fma_f32 v19, -v16, v17, 1.0
	v_fmac_f32_e32 v17, v19, v17
	v_mul_f32_e32 v19, v18, v17
	v_fma_f32 v20, -v16, v19, v18
	v_fmac_f32_e32 v19, v20, v17
	v_fma_f32 v16, -v16, v19, v18
	v_div_fmas_f32 v16, v16, v17, v19
	v_div_fixup_f32 v6, v16, v6, v8
	v_mul_f32_e32 v4, v4, v6
	v_cvt_pk_bf16_f32 v4, v4, s0
	global_store_short v[2:3], v4, off
	v_mov_b32_e32 v4, v132
	v_mul_f32_e32 v6, 0x4b800000, v7
	v_cmp_gt_f32_e32 vcc, s58, v7
	v_lshl_add_u64 v[2:3], v[10:11], 0, v[44:45]
	v_lshlrev_b64 v[2:3], 1, v[2:3]
	v_cndmask_b32_e32 v6, v7, v6, vcc
	v_rsq_f32_e32 v6, v6
	v_lshl_add_u64 v[10:11], s[28:29], 0, v[12:13]
	v_lshl_add_u64 v[12:13], s[26:27], 0, v[2:3]
	v_lshl_add_u64 v[2:3], s[28:29], 0, v[2:3]
	v_mul_f32_e32 v8, 0x45800000, v6
	v_cndmask_b32_e32 v6, v6, v8, vcc
	v_mul_f32_e32 v8, v9, v6
	v_mul_f32_e32 v0, v0, v8
	v_mul_f32_e32 v5, v5, v6
	v_mul_f32_e32 v5, v47, v5
	v_lshlrev_b32_e32 v4, 16, v4
	v_mul_f32_e32 v7, 0xbfb8aa3b, v4
	v_exp_f32_e32 v7, v7
	s_nop 0
	v_add_f32_e32 v7, 1.0, v7
	v_div_scale_f32 v9, s[18:19], v7, v7, v4
	v_rcp_f32_e32 v14, v9
	v_div_scale_f32 v8, vcc, v4, v7, v4
	v_fma_f32 v15, -v9, v14, 1.0
	v_fmac_f32_e32 v14, v15, v14
	v_mul_f32_e32 v15, v8, v14
	v_fma_f32 v16, -v9, v15, v8
	v_fmac_f32_e32 v15, v16, v14
	v_fma_f32 v8, -v9, v15, v8
	v_div_fmas_f32 v8, v8, v14, v15
	v_div_fixup_f32 v4, v8, v7, v4
	v_mul_f32_e32 v0, v4, v0
	v_cvt_pk_bf16_f32 v0, v0, s0
	global_store_short v[10:11], v0, off
	v_mov_b32_e32 v0, v133
	v_lshlrev_b32_e32 v0, 16, v0
	v_mul_f32_e32 v4, 0xbfb8aa3b, v0
	v_exp_f32_e32 v4, v4
	s_nop 0
	v_add_f32_e32 v4, 1.0, v4
	v_div_scale_f32 v6, s[18:19], v4, v4, v0
	v_rcp_f32_e32 v7, v6
	v_div_scale_f32 v8, vcc, v0, v4, v0
	v_fma_f32 v9, -v6, v7, 1.0
	v_fmac_f32_e32 v7, v9, v7
	v_mul_f32_e32 v9, v8, v7
	v_fma_f32 v10, -v6, v9, v8
	v_fmac_f32_e32 v9, v10, v7
	v_fma_f32 v6, -v6, v9, v8
	v_div_fmas_f32 v6, v6, v7, v9
	v_div_fixup_f32 v0, v6, v4, v0
	v_mul_f32_e32 v0, v5, v0
	v_cvt_pk_bf16_f32 v0, v0, s0
	global_store_short v[2:3], v0, off

; DI float bflo(unsigned u) { return __uint_as_float(u << 16); }
; DI float bfhi(unsigned u) { return __uint_as_float(u & 0xffff0000u); }
; DI void diffpost_item(const Params& p, int l, int item) {
;     ...
;   for (int rr = 0; rr < 16; ++rr) {
;     const int t = item * 64 + wid * 16 + rr;
;     u32x4 a = *(const u32x4*)(D1 + (size_t)t * 512 + lane * 8), b = *(const u32x4*)(D2 + (size_t)t * 512 + lane * 8);
;     unsigned aw[4] = {a.x, a.y, a.z, a.w}, bw[4] = {b.x, b.y, b.z, b.w};
;     float o[8]; float ss = 0.f;
; #pragma unroll
;     for (int j = 0; j < 4; ++j) { o[2 * j] = bflo(aw[j]) - lam * bflo(bw[j]); o[2 * j + 1] = bfhi(aw[j]) - lam * bfhi(bw[j]); ss += o[2 * j] * o[2 * j] + o[2 * j + 1] * o[2 * j + 1]; }
;     ss += __shfl_xor(ss, 1); ss += __shfl_xor(ss, 2); ss += __shfl_xor(ss, 4); ss += __shfl_xor(ss, 8);
.LBB0_308:
	v_add_u32_e32 v30, 0, v0
	v_ashrrev_i32_e32 v31, 31, v30
	v_lshlrev_b64 v[32:33], 10, v[30:31]
	v_lshl_add_u64 v[34:35], v[12:13], 0, v[32:33]
	v_lshl_add_u64 v[32:33], v[14:15], 0, v[32:33]
	global_load_dwordx4 v[80:83], v[34:35], off
	global_load_dwordx4 v[84:87], v[32:33], off
	v_add_u32_e32 v30, 1, v0
	v_ashrrev_i32_e32 v31, 31, v30
	v_lshlrev_b64 v[32:33], 10, v[30:31]
	v_lshl_add_u64 v[34:35], v[12:13], 0, v[32:33]
	v_lshl_add_u64 v[32:33], v[14:15], 0, v[32:33]
	global_load_dwordx4 v[88:91], v[34:35], off
	global_load_dwordx4 v[92:95], v[32:33], off
	v_add_u32_e32 v30, 2, v0
	v_ashrrev_i32_e32 v31, 31, v30
	v_lshlrev_b64 v[32:33], 10, v[30:31]
	v_lshl_add_u64 v[34:35], v[12:13], 0, v[32:33]
	v_lshl_add_u64 v[32:33], v[14:15], 0, v[32:33]
	global_load_dwordx4 v[102:105], v[34:35], off
	global_load_dwordx4 v[106:109], v[32:33], off
	v_add_u32_e32 v30, 3, v0
	v_ashrrev_i32_e32 v31, 31, v30
	v_lshlrev_b64 v[32:33], 10, v[30:31]
	v_lshl_add_u64 v[34:35], v[12:13], 0, v[32:33]
	v_lshl_add_u64 v[32:33], v[14:15], 0, v[32:33]
	global_load_dwordx4 v[110:113], v[34:35], off
	global_load_dwordx4 v[114:117], v[32:33], off
	v_add_u32_e32 v30, 4, v0
	v_ashrrev_i32_e32 v31, 31, v30
	v_lshlrev_b64 v[32:33], 10, v[30:31]
	v_lshl_add_u64 v[34:35], v[12:13], 0, v[32:33]
	v_lshl_add_u64 v[32:33], v[14:15], 0, v[32:33]
	global_load_dwordx4 v[118:121], v[34:35], off
	global_load_dwordx4 v[122:125], v[32:33], off
	v_add_u32_e32 v30, 5, v0
	v_ashrrev_i32_e32 v31, 31, v30
	v_lshlrev_b64 v[32:33], 10, v[30:31]
	v_lshl_add_u64 v[34:35], v[12:13], 0, v[32:33]
	v_lshl_add_u64 v[32:33], v[14:15], 0, v[32:33]
	global_load_dwordx4 v[126:129], v[34:35], off
	global_load_dwordx4 v[130:133], v[32:33], off
	v_add_u32_e32 v30, 6, v0
	v_ashrrev_i32_e32 v31, 31, v30
	v_lshlrev_b64 v[32:33], 10, v[30:31]
	v_lshl_add_u64 v[34:35], v[12:13], 0, v[32:33]
	v_lshl_add_u64 v[32:33], v[14:15], 0, v[32:33]
	global_load_dwordx4 v[134:137], v[34:35], off
	global_load_dwordx4 v[138:141], v[32:33], off
	v_add_u32_e32 v30, 7, v0
	v_ashrrev_i32_e32 v31, 31, v30
	v_lshlrev_b64 v[32:33], 10, v[30:31]
	v_lshl_add_u64 v[34:35], v[12:13], 0, v[32:33]
	v_lshl_add_u64 v[32:33], v[14:15], 0, v[32:33]
	global_load_dwordx4 v[142:145], v[34:35], off
	global_load_dwordx4 v[146:149], v[32:33], off
	v_add_u32_e32 v30, 8, v0
	v_ashrrev_i32_e32 v31, 31, v30
	v_lshlrev_b64 v[32:33], 10, v[30:31]
	v_lshl_add_u64 v[34:35], v[12:13], 0, v[32:33]
	v_lshl_add_u64 v[32:33], v[14:15], 0, v[32:33]
	global_load_dwordx4 v[150:153], v[34:35], off
	global_load_dwordx4 v[154:157], v[32:33], off
	v_add_u32_e32 v30, 9, v0
	v_ashrrev_i32_e32 v31, 31, v30
	v_lshlrev_b64 v[32:33], 10, v[30:31]
	v_lshl_add_u64 v[34:35], v[12:13], 0, v[32:33]
	v_lshl_add_u64 v[32:33], v[14:15], 0, v[32:33]
	global_load_dwordx4 v[158:161], v[34:35], off
	global_load_dwordx4 v[162:165], v[32:33], off
	v_add_u32_e32 v30, 10, v0
	v_ashrrev_i32_e32 v31, 31, v30
	v_lshlrev_b64 v[32:33], 10, v[30:31]
	v_lshl_add_u64 v[34:35], v[12:13], 0, v[32:33]
	v_lshl_add_u64 v[32:33], v[14:15], 0, v[32:33]
	global_load_dwordx4 v[166:169], v[34:35], off
	global_load_dwordx4 v[170:173], v[32:33], off
	v_add_u32_e32 v30, 11, v0
	v_ashrrev_i32_e32 v31, 31, v30
	v_lshlrev_b64 v[32:33], 10, v[30:31]
	v_lshl_add_u64 v[34:35], v[12:13], 0, v[32:33]
	v_lshl_add_u64 v[32:33], v[14:15], 0, v[32:33]
	global_load_dwordx4 v[174:177], v[34:35], off
	global_load_dwordx4 v[178:181], v[32:33], off
	v_add_u32_e32 v30, 12, v0
	v_ashrrev_i32_e32 v31, 31, v30
	v_lshlrev_b64 v[32:33], 10, v[30:31]
	v_lshl_add_u64 v[34:35], v[12:13], 0, v[32:33]
	v_lshl_add_u64 v[32:33], v[14:15], 0, v[32:33]
	global_load_dwordx4 v[182:185], v[34:35], off
	global_load_dwordx4 v[186:189], v[32:33], off
	v_add_u32_e32 v30, 13, v0
	v_ashrrev_i32_e32 v31, 31, v30
	v_lshlrev_b64 v[32:33], 10, v[30:31]
	v_lshl_add_u64 v[34:35], v[12:13], 0, v[32:33]
	v_lshl_add_u64 v[32:33], v[14:15], 0, v[32:33]
	global_load_dwordx4 v[190:193], v[34:35], off
	global_load_dwordx4 v[194:197], v[32:33], off
	s_waitcnt vmcnt(26)
	v_mov_b32_e32 v22, v80
	v_mov_b32_e32 v23, v81
	v_mov_b32_e32 v24, v82
	v_mov_b32_e32 v25, v83
	v_mov_b32_e32 v26, v84
	v_mov_b32_e32 v27, v85
	v_mov_b32_e32 v28, v86
	v_mov_b32_e32 v29, v87
	v_add_u32_e32 v30, 0, v0
	v_lshlrev_b32_e32 v32, 16, v25
	v_and_b32_e32 v33, 0xffff0000, v25
	v_lshlrev_b32_e32 v34, 16, v29
	v_and_b32_e32 v35, 0xffff0000, v29
	v_pk_fma_f32 v[32:33], v[10:11], v[34:35], v[32:33] neg_lo:[1,0,0] neg_hi:[1,0,0]
	v_lshlrev_b32_e32 v34, 16, v24
	v_and_b32_e32 v35, 0xffff0000, v24
	v_lshlrev_b32_e32 v24, 16, v28
	v_and_b32_e32 v25, 0xffff0000, v28
	v_pk_fma_f32 v[24:25], v[10:11], v[24:25], v[34:35] neg_lo:[1,0,0] neg_hi:[1,0,0]
	v_mov_b32_e32 v28, v32
	v_mov_b32_e32 v29, v24
	v_pk_mul_f32 v[28:29], v[28:29], v[28:29]
	v_mov_b32_e32 v34, v33
	v_mov_b32_e32 v35, v25
	v_pk_fma_f32 v[28:29], v[34:35], v[34:35], v[28:29]
	v_lshlrev_b32_e32 v34, 16, v23
	v_and_b32_e32 v35, 0xffff0000, v23
	v_lshlrev_b32_e32 v36, 16, v27
	v_and_b32_e32 v37, 0xffff0000, v27
	v_pk_fma_f32 v[34:35], v[10:11], v[36:37], v[34:35] neg_lo:[1,0,0] neg_hi:[1,0,0]
	v_lshlrev_b32_e32 v36, 16, v22
	v_and_b32_e32 v37, 0xffff0000, v22
	v_lshlrev_b32_e32 v22, 16, v26
	v_and_b32_e32 v23, 0xffff0000, v26
	v_pk_fma_f32 v[22:23], v[10:11], v[22:23], v[36:37] neg_lo:[1,0,0] neg_hi:[1,0,0]
	v_mov_b32_e32 v27, v34
	v_mov_b32_e32 v26, v22
	v_pk_mul_f32 v[26:27], v[26:27], v[26:27]
	v_mov_b32_e32 v36, v23
	v_mov_b32_e32 v37, v35
	v_pk_fma_f32 v[26:27], v[36:37], v[36:37], v[26:27]
	s_nop 0
	v_add_f32_e32 v26, v26, v27
	v_add_f32_e32 v26, v29, v26
	v_add_f32_e32 v26, v28, v26
	s_nop 1
; DI unsigned pk2(float lo, float hi) { f32x2_t v; v[0] = lo; v[1] = hi; bf16x2_t b = __builtin_convertvector(v, bf16x2_t); return __builtin_bit_cast(unsigned, b); }
; DI float bflo(unsigned u) { return __uint_as_float(u << 16); }
; DI float bfhi(unsigned u) { return __uint_as_float(u & 0xffff0000u); }
; DI void diffpost_item(const Params& p, int l, int item) {
;     ...
;   for (int rr = 0; rr < 16; ++rr) {
;     const int t = item * 64 + wid * 16 + rr;
;     u32x4 a = *(const u32x4*)(D1 + (size_t)t * 512 + lane * 8), b = *(const u32x4*)(D2 + (size_t)t * 512 + lane * 8);
;     unsigned aw[4] = {a.x, a.y, a.z, a.w}, bw[4] = {b.x, b.y, b.z, b.w};
;     float o[8]; float ss = 0.f;
; #pragma unroll
;     for (int j = 0; j < 4; ++j) { o[2 * j] = bflo(aw[j]) - lam * bflo(bw[j]); o[2 * j + 1] = bfhi(aw[j]) - lam * bfhi(bw[j]); ss += o[2 * j] * o[2 * j] + o[2 * j + 1] * o[2 * j + 1]; }
;     ss += __shfl_xor(ss, 1); ss += __shfl_xor(ss, 2); ss += __shfl_xor(ss, 4); ss += __shfl_xor(ss, 8);
;     const float rs = rsqrtf(ss * (1.f / 128.f) + EPS) * (1.f - lambda_init);
;     u32x4 ov; ov.x = pk2(o[0] * rs * w0[0], o[1] * rs * w0[1]); ov.y = pk2(o[2] * rs * w0[2], o[3] * rs * w0[3]);
;     ov.z = pk2(o[4] * rs * w1[0], o[5] * rs * w1[1]); ov.w = pk2(o[6] * rs * w1[2], o[7] * rs * w1[3]);
;     *(u32x4*)(RA + (size_t)t * 1536 + lane * 8) = ov;
;   }
	v_add_f32_dpp v26, v26, v26 quad_perm:[1,0,3,2] row_mask:0xf bank_mask:0xf
	s_nop 1
	v_add_f32_dpp v26, v26, v26 quad_perm:[2,3,0,1] row_mask:0xf bank_mask:0xf
	s_nop 1
	v_add_f32_dpp v26, v26, v26 row_half_mirror row_mask:0xf bank_mask:0xf
	s_nop 1
	v_add_f32_dpp v26, v26, v26 row_mirror row_mask:0xf bank_mask:0xf
	v_fmamk_f32 v26, v26, 0x3c000000, v200
	v_cmp_gt_f32_e32 vcc, s58, v26
	v_mul_f32_e32 v27, 0x4b800000, v26
	s_nop 0
	v_cndmask_b32_e32 v26, v26, v27, vcc
	v_rsq_f32_e32 v26, v26
	s_nop 0
	v_mul_f32_e32 v27, 0x45800000, v26
	v_cndmask_b32_e32 v26, v26, v27, vcc
	v_mul_f32_e32 v26, v63, v26
	v_pk_mul_f32 v[22:23], v[22:23], v[26:27] op_sel_hi:[1,0]
	v_pk_mul_f32 v[28:29], v[34:35], v[26:27] op_sel_hi:[1,0]
	v_pk_mul_f32 v[24:25], v[24:25], v[26:27] op_sel_hi:[1,0]
	v_pk_mul_f32 v[26:27], v[32:33], v[26:27] op_sel_hi:[1,0]
	v_pk_mul_f32 v[22:23], v[2:3], v[22:23]
	v_pk_mul_f32 v[28:29], v[4:5], v[28:29]
	v_pk_mul_f32 v[24:25], v[6:7], v[24:25]
	v_pk_mul_f32 v[26:27], v[8:9], v[26:27]
	v_cvt_pk_bf16_f32 v22, v22, v23
	v_cvt_pk_bf16_f32 v23, v28, v29
	v_cvt_pk_bf16_f32 v24, v24, v25
	v_cvt_pk_bf16_f32 v25, v26, v27
	v_mad_i64_i32 v[26:27], s[18:19], v30, s57, v[16:17]
	global_store_dwordx4 v[26:27], v[22:25], off
	s_nop 1
	v_add_u32_e32 v30, 14, v0
	v_ashrrev_i32_e32 v31, 31, v30
	v_lshlrev_b64 v[32:33], 10, v[30:31]
	v_lshl_add_u64 v[34:35], v[12:13], 0, v[32:33]
	v_lshl_add_u64 v[32:33], v[14:15], 0, v[32:33]
	global_load_dwordx4 v[80:83], v[34:35], off
	global_load_dwordx4 v[84:87], v[32:33], off
	s_waitcnt vmcnt(27)
	v_mov_b32_e32 v22, v88
	v_mov_b32_e32 v23, v89
	v_mov_b32_e32 v24, v90
	v_mov_b32_e32 v25, v91
	v_mov_b32_e32 v26, v92
	v_mov_b32_e32 v27, v93
	v_mov_b32_e32 v28, v94
	v_mov_b32_e32 v29, v95
	v_add_u32_e32 v30, 1, v0
	v_lshlrev_b32_e32 v32, 16, v25
	v_and_b32_e32 v33, 0xffff0000, v25
	v_lshlrev_b32_e32 v34, 16, v29
	v_and_b32_e32 v35, 0xffff0000, v29
	v_pk_fma_f32 v[32:33], v[10:11], v[34:35], v[32:33] neg_lo:[1,0,0] neg_hi:[1,0,0]
	v_lshlrev_b32_e32 v34, 16, v24
	v_and_b32_e32 v35, 0xffff0000, v24
	v_lshlrev_b32_e32 v24, 16, v28
	v_and_b32_e32 v25, 0xffff0000, v28
	v_pk_fma_f32 v[24:25], v[10:11], v[24:25], v[34:35] neg_lo:[1,0,0] neg_hi:[1,0,0]
	v_mov_b32_e32 v28, v32
	v_mov_b32_e32 v29, v24
	v_pk_mul_f32 v[28:29], v[28:29], v[28:29]
	v_mov_b32_e32 v34, v33
	v_mov_b32_e32 v35, v25
	v_pk_fma_f32 v[28:29], v[34:35], v[34:35], v[28:29]
	v_lshlrev_b32_e32 v34, 16, v23
	v_and_b32_e32 v35, 0xffff0000, v23
	v_lshlrev_b32_e32 v36, 16, v27
	v_and_b32_e32 v37, 0xffff0000, v27
	v_pk_fma_f32 v[34:35], v[10:11], v[36:37], v[34:35] neg_lo:[1,0,0] neg_hi:[1,0,0]
	v_lshlrev_b32_e32 v36, 16, v22
	v_and_b32_e32 v37, 0xffff0000, v22
	v_lshlrev_b32_e32 v22, 16, v26
	v_and_b32_e32 v23, 0xffff0000, v26
	v_pk_fma_f32 v[22:23], v[10:11], v[22:23], v[36:37] neg_lo:[1,0,0] neg_hi:[1,0,0]
	v_mov_b32_e32 v27, v34
	v_mov_b32_e32 v26, v22
	v_pk_mul_f32 v[26:27], v[26:27], v[26:27]
	v_mov_b32_e32 v36, v23
	v_mov_b32_e32 v37, v35
	v_pk_fma_f32 v[26:27], v[36:37], v[36:37], v[26:27]
	s_nop 0
	v_add_f32_e32 v26, v26, v27
	v_add_f32_e32 v26, v29, v26
	v_add_f32_e32 v26, v28, v26
	s_nop 1
	v_add_f32_dpp v26, v26, v26 quad_perm:[1,0,3,2] row_mask:0xf bank_mask:0xf
	s_nop 1
	v_add_f32_dpp v26, v26, v26 quad_perm:[2,3,0,1] row_mask:0xf bank_mask:0xf
	s_nop 1
	v_add_f32_dpp v26, v26, v26 row_half_mirror row_mask:0xf bank_mask:0xf
	s_nop 1
	v_add_f32_dpp v26, v26, v26 row_mirror row_mask:0xf bank_mask:0xf
	v_fmamk_f32 v26, v26, 0x3c000000, v200
	v_cmp_gt_f32_e32 vcc, s58, v26
	v_mul_f32_e32 v27, 0x4b800000, v26
	s_nop 0
	v_cndmask_b32_e32 v26, v26, v27, vcc
	v_rsq_f32_e32 v26, v26
	s_nop 0
	v_mul_f32_e32 v27, 0x45800000, v26
	v_cndmask_b32_e32 v26, v26, v27, vcc
	v_mul_f32_e32 v26, v63, v26
	v_pk_mul_f32 v[22:23], v[22:23], v[26:27] op_sel_hi:[1,0]
	v_pk_mul_f32 v[28:29], v[34:35], v[26:27] op_sel_hi:[1,0]
	v_pk_mul_f32 v[24:25], v[24:25], v[26:27] op_sel_hi:[1,0]
	v_pk_mul_f32 v[26:27], v[32:33], v[26:27] op_sel_hi:[1,0]
	v_pk_mul_f32 v[22:23], v[2:3], v[22:23]
	v_pk_mul_f32 v[28:29], v[4:5], v[28:29]
	v_pk_mul_f32 v[24:25], v[6:7], v[24:25]
	v_pk_mul_f32 v[26:27], v[8:9], v[26:27]
	v_cvt_pk_bf16_f32 v22, v22, v23
	v_cvt_pk_bf16_f32 v23, v28, v29
	v_cvt_pk_bf16_f32 v24, v24, v25
	v_cvt_pk_bf16_f32 v25, v26, v27
	v_mad_i64_i32 v[26:27], s[18:19], v30, s57, v[16:17]
	global_store_dwordx4 v[26:27], v[22:25], off
	s_nop 1
	v_add_u32_e32 v30, 15, v0
	v_ashrrev_i32_e32 v31, 31, v30
	v_lshlrev_b64 v[32:33], 10, v[30:31]
	v_lshl_add_u64 v[34:35], v[12:13], 0, v[32:33]
	v_lshl_add_u64 v[32:33], v[14:15], 0, v[32:33]
	global_load_dwordx4 v[88:91], v[34:35], off
	global_load_dwordx4 v[92:95], v[32:33], off
	s_waitcnt vmcnt(28)
; DI unsigned pk2(float lo, float hi) { f32x2_t v; v[0] = lo; v[1] = hi; bf16x2_t b = __builtin_convertvector(v, bf16x2_t); return __builtin_bit_cast(unsigned, b); }
; DI float bflo(unsigned u) { return __uint_as_float(u << 16); }
; DI float bfhi(unsigned u) { return __uint_as_float(u & 0xffff0000u); }
; DI void diffpost_item(const Params& p, int l, int item) {
;     ...
;   for (int rr = 0; rr < 16; ++rr) {
;     const int t = item * 64 + wid * 16 + rr;
;     u32x4 a = *(const u32x4*)(D1 + (size_t)t * 512 + lane * 8), b = *(const u32x4*)(D2 + (size_t)t * 512 + lane * 8);
;     unsigned aw[4] = {a.x, a.y, a.z, a.w}, bw[4] = {b.x, b.y, b.z, b.w};
;     float o[8]; float ss = 0.f;
; #pragma unroll
;     for (int j = 0; j < 4; ++j) { o[2 * j] = bflo(aw[j]) - lam * bflo(bw[j]); o[2 * j + 1] = bfhi(aw[j]) - lam * bfhi(bw[j]); ss += o[2 * j] * o[2 * j] + o[2 * j + 1] * o[2 * j + 1]; }
;     ss += __shfl_xor(ss, 1); ss += __shfl_xor(ss, 2); ss += __shfl_xor(ss, 4); ss += __shfl_xor(ss, 8);
;     const float rs = rsqrtf(ss * (1.f / 128.f) + EPS) * (1.f - lambda_init);
;     u32x4 ov; ov.x = pk2(o[0] * rs * w0[0], o[1] * rs * w0[1]); ov.y = pk2(o[2] * rs * w0[2], o[3] * rs * w0[3]);
;     ov.z = pk2(o[4] * rs * w1[0], o[5] * rs * w1[1]); ov.w = pk2(o[6] * rs * w1[2], o[7] * rs * w1[3]);
;     *(u32x4*)(RA + (size_t)t * 1536 + lane * 8) = ov;
;   }
	v_mov_b32_e32 v22, v102
	v_mov_b32_e32 v23, v103
	v_mov_b32_e32 v24, v104
	v_mov_b32_e32 v25, v105
	v_mov_b32_e32 v26, v106
	v_mov_b32_e32 v27, v107
	v_mov_b32_e32 v28, v108
	v_mov_b32_e32 v29, v109
	v_add_u32_e32 v30, 2, v0
	v_lshlrev_b32_e32 v32, 16, v25
	v_and_b32_e32 v33, 0xffff0000, v25
	v_lshlrev_b32_e32 v34, 16, v29
	v_and_b32_e32 v35, 0xffff0000, v29
	v_pk_fma_f32 v[32:33], v[10:11], v[34:35], v[32:33] neg_lo:[1,0,0] neg_hi:[1,0,0]
	v_lshlrev_b32_e32 v34, 16, v24
	v_and_b32_e32 v35, 0xffff0000, v24
	v_lshlrev_b32_e32 v24, 16, v28
	v_and_b32_e32 v25, 0xffff0000, v28
	v_pk_fma_f32 v[24:25], v[10:11], v[24:25], v[34:35] neg_lo:[1,0,0] neg_hi:[1,0,0]
	v_mov_b32_e32 v28, v32
	v_mov_b32_e32 v29, v24
	v_pk_mul_f32 v[28:29], v[28:29], v[28:29]
	v_mov_b32_e32 v34, v33
	v_mov_b32_e32 v35, v25
	v_pk_fma_f32 v[28:29], v[34:35], v[34:35], v[28:29]
	v_lshlrev_b32_e32 v34, 16, v23
	v_and_b32_e32 v35, 0xffff0000, v23
	v_lshlrev_b32_e32 v36, 16, v27
	v_and_b32_e32 v37, 0xffff0000, v27
	v_pk_fma_f32 v[34:35], v[10:11], v[36:37], v[34:35] neg_lo:[1,0,0] neg_hi:[1,0,0]
	v_lshlrev_b32_e32 v36, 16, v22
	v_and_b32_e32 v37, 0xffff0000, v22
	v_lshlrev_b32_e32 v22, 16, v26
	v_and_b32_e32 v23, 0xffff0000, v26
	v_pk_fma_f32 v[22:23], v[10:11], v[22:23], v[36:37] neg_lo:[1,0,0] neg_hi:[1,0,0]
	v_mov_b32_e32 v27, v34
	v_mov_b32_e32 v26, v22
	v_pk_mul_f32 v[26:27], v[26:27], v[26:27]
	v_mov_b32_e32 v36, v23
	v_mov_b32_e32 v37, v35
	v_pk_fma_f32 v[26:27], v[36:37], v[36:37], v[26:27]
	s_nop 0
	v_add_f32_e32 v26, v26, v27
	v_add_f32_e32 v26, v29, v26
	v_add_f32_e32 v26, v28, v26
	s_nop 1
	v_add_f32_dpp v26, v26, v26 quad_perm:[1,0,3,2] row_mask:0xf bank_mask:0xf
	s_nop 1
	v_add_f32_dpp v26, v26, v26 quad_perm:[2,3,0,1] row_mask:0xf bank_mask:0xf
	s_nop 1
	v_add_f32_dpp v26, v26, v26 row_half_mirror row_mask:0xf bank_mask:0xf
	s_nop 1
	v_add_f32_dpp v26, v26, v26 row_mirror row_mask:0xf bank_mask:0xf
	v_fmamk_f32 v26, v26, 0x3c000000, v200
	v_cmp_gt_f32_e32 vcc, s58, v26
	v_mul_f32_e32 v27, 0x4b800000, v26
	s_nop 0
	v_cndmask_b32_e32 v26, v26, v27, vcc
	v_rsq_f32_e32 v26, v26
	s_nop 0
	v_mul_f32_e32 v27, 0x45800000, v26
	v_cndmask_b32_e32 v26, v26, v27, vcc
	v_mul_f32_e32 v26, v63, v26
	v_pk_mul_f32 v[22:23], v[22:23], v[26:27] op_sel_hi:[1,0]
	v_pk_mul_f32 v[28:29], v[34:35], v[26:27] op_sel_hi:[1,0]
	v_pk_mul_f32 v[24:25], v[24:25], v[26:27] op_sel_hi:[1,0]
	v_pk_mul_f32 v[26:27], v[32:33], v[26:27] op_sel_hi:[1,0]
	v_pk_mul_f32 v[22:23], v[2:3], v[22:23]
	v_pk_mul_f32 v[28:29], v[4:5], v[28:29]
	v_pk_mul_f32 v[24:25], v[6:7], v[24:25]
	v_pk_mul_f32 v[26:27], v[8:9], v[26:27]
	v_cvt_pk_bf16_f32 v22, v22, v23
	v_cvt_pk_bf16_f32 v23, v28, v29
	v_cvt_pk_bf16_f32 v24, v24, v25
	v_cvt_pk_bf16_f32 v25, v26, v27
	v_mad_i64_i32 v[26:27], s[18:19], v30, s57, v[16:17]
	global_store_dwordx4 v[26:27], v[22:25], off
	s_nop 1
	s_waitcnt vmcnt(27)
	v_mov_b32_e32 v22, v110
	v_mov_b32_e32 v23, v111
	v_mov_b32_e32 v24, v112
	v_mov_b32_e32 v25, v113
	v_mov_b32_e32 v26, v114
	v_mov_b32_e32 v27, v115
	v_mov_b32_e32 v28, v116
	v_mov_b32_e32 v29, v117
	v_add_u32_e32 v30, 3, v0
	v_lshlrev_b32_e32 v32, 16, v25
	v_and_b32_e32 v33, 0xffff0000, v25
	v_lshlrev_b32_e32 v34, 16, v29
	v_and_b32_e32 v35, 0xffff0000, v29
	v_pk_fma_f32 v[32:33], v[10:11], v[34:35], v[32:33] neg_lo:[1,0,0] neg_hi:[1,0,0]
	v_lshlrev_b32_e32 v34, 16, v24
	v_and_b32_e32 v35, 0xffff0000, v24
	v_lshlrev_b32_e32 v24, 16, v28
	v_and_b32_e32 v25, 0xffff0000, v28
	v_pk_fma_f32 v[24:25], v[10:11], v[24:25], v[34:35] neg_lo:[1,0,0] neg_hi:[1,0,0]
	v_mov_b32_e32 v28, v32
	v_mov_b32_e32 v29, v24
	v_pk_mul_f32 v[28:29], v[28:29], v[28:29]
	v_mov_b32_e32 v34, v33
	v_mov_b32_e32 v35, v25
	v_pk_fma_f32 v[28:29], v[34:35], v[34:35], v[28:29]
	v_lshlrev_b32_e32 v34, 16, v23
	v_and_b32_e32 v35, 0xffff0000, v23
	v_lshlrev_b32_e32 v36, 16, v27
	v_and_b32_e32 v37, 0xffff0000, v27
	v_pk_fma_f32 v[34:35], v[10:11], v[36:37], v[34:35] neg_lo:[1,0,0] neg_hi:[1,0,0]
	v_lshlrev_b32_e32 v36, 16, v22
	v_and_b32_e32 v37, 0xffff0000, v22
	v_lshlrev_b32_e32 v22, 16, v26
	v_and_b32_e32 v23, 0xffff0000, v26
	v_pk_fma_f32 v[22:23], v[10:11], v[22:23], v[36:37] neg_lo:[1,0,0] neg_hi:[1,0,0]
	v_mov_b32_e32 v27, v34
	v_mov_b32_e32 v26, v22
	v_pk_mul_f32 v[26:27], v[26:27], v[26:27]
	v_mov_b32_e32 v36, v23
	v_mov_b32_e32 v37, v35
	v_pk_fma_f32 v[26:27], v[36:37], v[36:37], v[26:27]
	s_nop 0
	v_add_f32_e32 v26, v26, v27
	v_add_f32_e32 v26, v29, v26
	v_add_f32_e32 v26, v28, v26
	s_nop 1
	v_add_f32_dpp v26, v26, v26 quad_perm:[1,0,3,2] row_mask:0xf bank_mask:0xf
	s_nop 1
	v_add_f32_dpp v26, v26, v26 quad_perm:[2,3,0,1] row_mask:0xf bank_mask:0xf
	s_nop 1
	v_add_f32_dpp v26, v26, v26 row_half_mirror row_mask:0xf bank_mask:0xf
	s_nop 1
	v_add_f32_dpp v26, v26, v26 row_mirror row_mask:0xf bank_mask:0xf
	v_fmamk_f32 v26, v26, 0x3c000000, v200
	v_cmp_gt_f32_e32 vcc, s58, v26
	v_mul_f32_e32 v27, 0x4b800000, v26
	s_nop 0
	v_cndmask_b32_e32 v26, v26, v27, vcc
	v_rsq_f32_e32 v26, v26
	s_nop 0
	v_mul_f32_e32 v27, 0x45800000, v26
	v_cndmask_b32_e32 v26, v26, v27, vcc
	v_mul_f32_e32 v26, v63, v26
	v_pk_mul_f32 v[22:23], v[22:23], v[26:27] op_sel_hi:[1,0]
	v_pk_mul_f32 v[28:29], v[34:35], v[26:27] op_sel_hi:[1,0]
	v_pk_mul_f32 v[24:25], v[24:25], v[26:27] op_sel_hi:[1,0]
	v_pk_mul_f32 v[26:27], v[32:33], v[26:27] op_sel_hi:[1,0]
	v_pk_mul_f32 v[22:23], v[2:3], v[22:23]
	v_pk_mul_f32 v[28:29], v[4:5], v[28:29]
	v_pk_mul_f32 v[24:25], v[6:7], v[24:25]
	v_pk_mul_f32 v[26:27], v[8:9], v[26:27]
	v_cvt_pk_bf16_f32 v22, v22, v23
	v_cvt_pk_bf16_f32 v23, v28, v29
	v_cvt_pk_bf16_f32 v24, v24, v25
	v_cvt_pk_bf16_f32 v25, v26, v27
	v_mad_i64_i32 v[26:27], s[18:19], v30, s57, v[16:17]
	global_store_dwordx4 v[26:27], v[22:25], off
	s_nop 1
	s_waitcnt vmcnt(26)
; DI unsigned pk2(float lo, float hi) { f32x2_t v; v[0] = lo; v[1] = hi; bf16x2_t b = __builtin_convertvector(v, bf16x2_t); return __builtin_bit_cast(unsigned, b); }
; DI float bflo(unsigned u) { return __uint_as_float(u << 16); }
; DI float bfhi(unsigned u) { return __uint_as_float(u & 0xffff0000u); }
; DI void diffpost_item(const Params& p, int l, int item) {
;     ...
;   for (int rr = 0; rr < 16; ++rr) {
;     const int t = item * 64 + wid * 16 + rr;
;     u32x4 a = *(const u32x4*)(D1 + (size_t)t * 512 + lane * 8), b = *(const u32x4*)(D2 + (size_t)t * 512 + lane * 8);
;     unsigned aw[4] = {a.x, a.y, a.z, a.w}, bw[4] = {b.x, b.y, b.z, b.w};
;     float o[8]; float ss = 0.f;
; #pragma unroll
;     for (int j = 0; j < 4; ++j) { o[2 * j] = bflo(aw[j]) - lam * bflo(bw[j]); o[2 * j + 1] = bfhi(aw[j]) - lam * bfhi(bw[j]); ss += o[2 * j] * o[2 * j] + o[2 * j + 1] * o[2 * j + 1]; }
;     ss += __shfl_xor(ss, 1); ss += __shfl_xor(ss, 2); ss += __shfl_xor(ss, 4); ss += __shfl_xor(ss, 8);
;     const float rs = rsqrtf(ss * (1.f / 128.f) + EPS) * (1.f - lambda_init);
;     u32x4 ov; ov.x = pk2(o[0] * rs * w0[0], o[1] * rs * w0[1]); ov.y = pk2(o[2] * rs * w0[2], o[3] * rs * w0[3]);
;     ov.z = pk2(o[4] * rs * w1[0], o[5] * rs * w1[1]); ov.w = pk2(o[6] * rs * w1[2], o[7] * rs * w1[3]);
;     *(u32x4*)(RA + (size_t)t * 1536 + lane * 8) = ov;
;   }
	v_mov_b32_e32 v22, v118
	v_mov_b32_e32 v23, v119
	v_mov_b32_e32 v24, v120
	v_mov_b32_e32 v25, v121
	v_mov_b32_e32 v26, v122
	v_mov_b32_e32 v27, v123
	v_mov_b32_e32 v28, v124
	v_mov_b32_e32 v29, v125
	v_add_u32_e32 v30, 4, v0
	v_lshlrev_b32_e32 v32, 16, v25
	v_and_b32_e32 v33, 0xffff0000, v25
	v_lshlrev_b32_e32 v34, 16, v29
	v_and_b32_e32 v35, 0xffff0000, v29
	v_pk_fma_f32 v[32:33], v[10:11], v[34:35], v[32:33] neg_lo:[1,0,0] neg_hi:[1,0,0]
	v_lshlrev_b32_e32 v34, 16, v24
	v_and_b32_e32 v35, 0xffff0000, v24
	v_lshlrev_b32_e32 v24, 16, v28
	v_and_b32_e32 v25, 0xffff0000, v28
	v_pk_fma_f32 v[24:25], v[10:11], v[24:25], v[34:35] neg_lo:[1,0,0] neg_hi:[1,0,0]
	v_mov_b32_e32 v28, v32
	v_mov_b32_e32 v29, v24
	v_pk_mul_f32 v[28:29], v[28:29], v[28:29]
	v_mov_b32_e32 v34, v33
	v_mov_b32_e32 v35, v25
	v_pk_fma_f32 v[28:29], v[34:35], v[34:35], v[28:29]
	v_lshlrev_b32_e32 v34, 16, v23
	v_and_b32_e32 v35, 0xffff0000, v23
	v_lshlrev_b32_e32 v36, 16, v27
	v_and_b32_e32 v37, 0xffff0000, v27
	v_pk_fma_f32 v[34:35], v[10:11], v[36:37], v[34:35] neg_lo:[1,0,0] neg_hi:[1,0,0]
	v_lshlrev_b32_e32 v36, 16, v22
	v_and_b32_e32 v37, 0xffff0000, v22
	v_lshlrev_b32_e32 v22, 16, v26
	v_and_b32_e32 v23, 0xffff0000, v26
	v_pk_fma_f32 v[22:23], v[10:11], v[22:23], v[36:37] neg_lo:[1,0,0] neg_hi:[1,0,0]
	v_mov_b32_e32 v27, v34
	v_mov_b32_e32 v26, v22
	v_pk_mul_f32 v[26:27], v[26:27], v[26:27]
	v_mov_b32_e32 v36, v23
	v_mov_b32_e32 v37, v35
	v_pk_fma_f32 v[26:27], v[36:37], v[36:37], v[26:27]
	s_nop 0
	v_add_f32_e32 v26, v26, v27
	v_add_f32_e32 v26, v29, v26
	v_add_f32_e32 v26, v28, v26
	s_nop 1
	v_add_f32_dpp v26, v26, v26 quad_perm:[1,0,3,2] row_mask:0xf bank_mask:0xf
	s_nop 1
	v_add_f32_dpp v26, v26, v26 quad_perm:[2,3,0,1] row_mask:0xf bank_mask:0xf
	s_nop 1
	v_add_f32_dpp v26, v26, v26 row_half_mirror row_mask:0xf bank_mask:0xf
	s_nop 1
	v_add_f32_dpp v26, v26, v26 row_mirror row_mask:0xf bank_mask:0xf
	v_fmamk_f32 v26, v26, 0x3c000000, v200
	v_cmp_gt_f32_e32 vcc, s58, v26
	v_mul_f32_e32 v27, 0x4b800000, v26
	s_nop 0
	v_cndmask_b32_e32 v26, v26, v27, vcc
	v_rsq_f32_e32 v26, v26
	s_nop 0
	v_mul_f32_e32 v27, 0x45800000, v26
	v_cndmask_b32_e32 v26, v26, v27, vcc
	v_mul_f32_e32 v26, v63, v26
	v_pk_mul_f32 v[22:23], v[22:23], v[26:27] op_sel_hi:[1,0]
	v_pk_mul_f32 v[28:29], v[34:35], v[26:27] op_sel_hi:[1,0]
	v_pk_mul_f32 v[24:25], v[24:25], v[26:27] op_sel_hi:[1,0]
	v_pk_mul_f32 v[26:27], v[32:33], v[26:27] op_sel_hi:[1,0]
	v_pk_mul_f32 v[22:23], v[2:3], v[22:23]
	v_pk_mul_f32 v[28:29], v[4:5], v[28:29]
	v_pk_mul_f32 v[24:25], v[6:7], v[24:25]
	v_pk_mul_f32 v[26:27], v[8:9], v[26:27]
	v_cvt_pk_bf16_f32 v22, v22, v23
	v_cvt_pk_bf16_f32 v23, v28, v29
	v_cvt_pk_bf16_f32 v24, v24, v25
	v_cvt_pk_bf16_f32 v25, v26, v27
	v_mad_i64_i32 v[26:27], s[18:19], v30, s57, v[16:17]
	global_store_dwordx4 v[26:27], v[22:25], off
	s_nop 1
	s_waitcnt vmcnt(25)
	v_mov_b32_e32 v22, v126
	v_mov_b32_e32 v23, v127
	v_mov_b32_e32 v24, v128
	v_mov_b32_e32 v25, v129
	v_mov_b32_e32 v26, v130
	v_mov_b32_e32 v27, v131
	v_mov_b32_e32 v28, v132
	v_mov_b32_e32 v29, v133
	v_add_u32_e32 v30, 5, v0
	v_lshlrev_b32_e32 v32, 16, v25
	v_and_b32_e32 v33, 0xffff0000, v25
	v_lshlrev_b32_e32 v34, 16, v29
	v_and_b32_e32 v35, 0xffff0000, v29
	v_pk_fma_f32 v[32:33], v[10:11], v[34:35], v[32:33] neg_lo:[1,0,0] neg_hi:[1,0,0]
	v_lshlrev_b32_e32 v34, 16, v24
	v_and_b32_e32 v35, 0xffff0000, v24
	v_lshlrev_b32_e32 v24, 16, v28
	v_and_b32_e32 v25, 0xffff0000, v28
	v_pk_fma_f32 v[24:25], v[10:11], v[24:25], v[34:35] neg_lo:[1,0,0] neg_hi:[1,0,0]
	v_mov_b32_e32 v28, v32
	v_mov_b32_e32 v29, v24
	v_pk_mul_f32 v[28:29], v[28:29], v[28:29]
	v_mov_b32_e32 v34, v33
	v_mov_b32_e32 v35, v25
	v_pk_fma_f32 v[28:29], v[34:35], v[34:35], v[28:29]
	v_lshlrev_b32_e32 v34, 16, v23
	v_and_b32_e32 v35, 0xffff0000, v23
	v_lshlrev_b32_e32 v36, 16, v27
	v_and_b32_e32 v37, 0xffff0000, v27
	v_pk_fma_f32 v[34:35], v[10:11], v[36:37], v[34:35] neg_lo:[1,0,0] neg_hi:[1,0,0]
	v_lshlrev_b32_e32 v36, 16, v22
	v_and_b32_e32 v37, 0xffff0000, v22
	v_lshlrev_b32_e32 v22, 16, v26
	v_and_b32_e32 v23, 0xffff0000, v26
	v_pk_fma_f32 v[22:23], v[10:11], v[22:23], v[36:37] neg_lo:[1,0,0] neg_hi:[1,0,0]
	v_mov_b32_e32 v27, v34
	v_mov_b32_e32 v26, v22
	v_pk_mul_f32 v[26:27], v[26:27], v[26:27]
	v_mov_b32_e32 v36, v23
	v_mov_b32_e32 v37, v35
	v_pk_fma_f32 v[26:27], v[36:37], v[36:37], v[26:27]
	s_nop 0
	v_add_f32_e32 v26, v26, v27
	v_add_f32_e32 v26, v29, v26
	v_add_f32_e32 v26, v28, v26
	s_nop 1
	v_add_f32_dpp v26, v26, v26 quad_perm:[1,0,3,2] row_mask:0xf bank_mask:0xf
	s_nop 1
	v_add_f32_dpp v26, v26, v26 quad_perm:[2,3,0,1] row_mask:0xf bank_mask:0xf
	s_nop 1
	v_add_f32_dpp v26, v26, v26 row_half_mirror row_mask:0xf bank_mask:0xf
	s_nop 1
	v_add_f32_dpp v26, v26, v26 row_mirror row_mask:0xf bank_mask:0xf
	v_fmamk_f32 v26, v26, 0x3c000000, v200
	v_cmp_gt_f32_e32 vcc, s58, v26
	v_mul_f32_e32 v27, 0x4b800000, v26
	s_nop 0
	v_cndmask_b32_e32 v26, v26, v27, vcc
	v_rsq_f32_e32 v26, v26
	s_nop 0
	v_mul_f32_e32 v27, 0x45800000, v26
	v_cndmask_b32_e32 v26, v26, v27, vcc
	v_mul_f32_e32 v26, v63, v26
	v_pk_mul_f32 v[22:23], v[22:23], v[26:27] op_sel_hi:[1,0]
	v_pk_mul_f32 v[28:29], v[34:35], v[26:27] op_sel_hi:[1,0]
	v_pk_mul_f32 v[24:25], v[24:25], v[26:27] op_sel_hi:[1,0]
	v_pk_mul_f32 v[26:27], v[32:33], v[26:27] op_sel_hi:[1,0]
	v_pk_mul_f32 v[22:23], v[2:3], v[22:23]
	v_pk_mul_f32 v[28:29], v[4:5], v[28:29]
	v_pk_mul_f32 v[24:25], v[6:7], v[24:25]
	v_pk_mul_f32 v[26:27], v[8:9], v[26:27]
	v_cvt_pk_bf16_f32 v22, v22, v23
	v_cvt_pk_bf16_f32 v23, v28, v29
	v_cvt_pk_bf16_f32 v24, v24, v25
	v_cvt_pk_bf16_f32 v25, v26, v27
	v_mad_i64_i32 v[26:27], s[18:19], v30, s57, v[16:17]
	global_store_dwordx4 v[26:27], v[22:25], off
	s_nop 1
	s_waitcnt vmcnt(24)
; DI unsigned pk2(float lo, float hi) { f32x2_t v; v[0] = lo; v[1] = hi; bf16x2_t b = __builtin_convertvector(v, bf16x2_t); return __builtin_bit_cast(unsigned, b); }
; DI float bflo(unsigned u) { return __uint_as_float(u << 16); }
; DI float bfhi(unsigned u) { return __uint_as_float(u & 0xffff0000u); }
; DI void diffpost_item(const Params& p, int l, int item) {
;     ...
;   for (int rr = 0; rr < 16; ++rr) {
;     const int t = item * 64 + wid * 16 + rr;
;     u32x4 a = *(const u32x4*)(D1 + (size_t)t * 512 + lane * 8), b = *(const u32x4*)(D2 + (size_t)t * 512 + lane * 8);
;     unsigned aw[4] = {a.x, a.y, a.z, a.w}, bw[4] = {b.x, b.y, b.z, b.w};
;     float o[8]; float ss = 0.f;
; #pragma unroll
;     for (int j = 0; j < 4; ++j) { o[2 * j] = bflo(aw[j]) - lam * bflo(bw[j]); o[2 * j + 1] = bfhi(aw[j]) - lam * bfhi(bw[j]); ss += o[2 * j] * o[2 * j] + o[2 * j + 1] * o[2 * j + 1]; }
;     ss += __shfl_xor(ss, 1); ss += __shfl_xor(ss, 2); ss += __shfl_xor(ss, 4); ss += __shfl_xor(ss, 8);
;     const float rs = rsqrtf(ss * (1.f / 128.f) + EPS) * (1.f - lambda_init);
;     u32x4 ov; ov.x = pk2(o[0] * rs * w0[0], o[1] * rs * w0[1]); ov.y = pk2(o[2] * rs * w0[2], o[3] * rs * w0[3]);
;     ov.z = pk2(o[4] * rs * w1[0], o[5] * rs * w1[1]); ov.w = pk2(o[6] * rs * w1[2], o[7] * rs * w1[3]);
;     *(u32x4*)(RA + (size_t)t * 1536 + lane * 8) = ov;
;   }
	v_mov_b32_e32 v22, v134
	v_mov_b32_e32 v23, v135
	v_mov_b32_e32 v24, v136
	v_mov_b32_e32 v25, v137
	v_mov_b32_e32 v26, v138
	v_mov_b32_e32 v27, v139
	v_mov_b32_e32 v28, v140
	v_mov_b32_e32 v29, v141
	v_add_u32_e32 v30, 6, v0
	v_lshlrev_b32_e32 v32, 16, v25
	v_and_b32_e32 v33, 0xffff0000, v25
	v_lshlrev_b32_e32 v34, 16, v29
	v_and_b32_e32 v35, 0xffff0000, v29
	v_pk_fma_f32 v[32:33], v[10:11], v[34:35], v[32:33] neg_lo:[1,0,0] neg_hi:[1,0,0]
	v_lshlrev_b32_e32 v34, 16, v24
	v_and_b32_e32 v35, 0xffff0000, v24
	v_lshlrev_b32_e32 v24, 16, v28
	v_and_b32_e32 v25, 0xffff0000, v28
	v_pk_fma_f32 v[24:25], v[10:11], v[24:25], v[34:35] neg_lo:[1,0,0] neg_hi:[1,0,0]
	v_mov_b32_e32 v28, v32
	v_mov_b32_e32 v29, v24
	v_pk_mul_f32 v[28:29], v[28:29], v[28:29]
	v_mov_b32_e32 v34, v33
	v_mov_b32_e32 v35, v25
	v_pk_fma_f32 v[28:29], v[34:35], v[34:35], v[28:29]
	v_lshlrev_b32_e32 v34, 16, v23
	v_and_b32_e32 v35, 0xffff0000, v23
	v_lshlrev_b32_e32 v36, 16, v27
	v_and_b32_e32 v37, 0xffff0000, v27
	v_pk_fma_f32 v[34:35], v[10:11], v[36:37], v[34:35] neg_lo:[1,0,0] neg_hi:[1,0,0]
	v_lshlrev_b32_e32 v36, 16, v22
	v_and_b32_e32 v37, 0xffff0000, v22
	v_lshlrev_b32_e32 v22, 16, v26
	v_and_b32_e32 v23, 0xffff0000, v26
	v_pk_fma_f32 v[22:23], v[10:11], v[22:23], v[36:37] neg_lo:[1,0,0] neg_hi:[1,0,0]
	v_mov_b32_e32 v27, v34
	v_mov_b32_e32 v26, v22
	v_pk_mul_f32 v[26:27], v[26:27], v[26:27]
	v_mov_b32_e32 v36, v23
	v_mov_b32_e32 v37, v35
	v_pk_fma_f32 v[26:27], v[36:37], v[36:37], v[26:27]
	s_nop 0
	v_add_f32_e32 v26, v26, v27
	v_add_f32_e32 v26, v29, v26
	v_add_f32_e32 v26, v28, v26
	s_nop 1
	v_add_f32_dpp v26, v26, v26 quad_perm:[1,0,3,2] row_mask:0xf bank_mask:0xf
	s_nop 1
	v_add_f32_dpp v26, v26, v26 quad_perm:[2,3,0,1] row_mask:0xf bank_mask:0xf
	s_nop 1
	v_add_f32_dpp v26, v26, v26 row_half_mirror row_mask:0xf bank_mask:0xf
	s_nop 1
	v_add_f32_dpp v26, v26, v26 row_mirror row_mask:0xf bank_mask:0xf
	v_fmamk_f32 v26, v26, 0x3c000000, v200
	v_cmp_gt_f32_e32 vcc, s58, v26
	v_mul_f32_e32 v27, 0x4b800000, v26
	s_nop 0
	v_cndmask_b32_e32 v26, v26, v27, vcc
	v_rsq_f32_e32 v26, v26
	s_nop 0
	v_mul_f32_e32 v27, 0x45800000, v26
	v_cndmask_b32_e32 v26, v26, v27, vcc
	v_mul_f32_e32 v26, v63, v26
	v_pk_mul_f32 v[22:23], v[22:23], v[26:27] op_sel_hi:[1,0]
	v_pk_mul_f32 v[28:29], v[34:35], v[26:27] op_sel_hi:[1,0]
	v_pk_mul_f32 v[24:25], v[24:25], v[26:27] op_sel_hi:[1,0]
	v_pk_mul_f32 v[26:27], v[32:33], v[26:27] op_sel_hi:[1,0]
	v_pk_mul_f32 v[22:23], v[2:3], v[22:23]
	v_pk_mul_f32 v[28:29], v[4:5], v[28:29]
	v_pk_mul_f32 v[24:25], v[6:7], v[24:25]
	v_pk_mul_f32 v[26:27], v[8:9], v[26:27]
	v_cvt_pk_bf16_f32 v22, v22, v23
	v_cvt_pk_bf16_f32 v23, v28, v29
	v_cvt_pk_bf16_f32 v24, v24, v25
	v_cvt_pk_bf16_f32 v25, v26, v27
	v_mad_i64_i32 v[26:27], s[18:19], v30, s57, v[16:17]
	global_store_dwordx4 v[26:27], v[22:25], off
	s_nop 1
	s_waitcnt vmcnt(23)
	v_mov_b32_e32 v22, v142
	v_mov_b32_e32 v23, v143
	v_mov_b32_e32 v24, v144
	v_mov_b32_e32 v25, v145
	v_mov_b32_e32 v26, v146
	v_mov_b32_e32 v27, v147
	v_mov_b32_e32 v28, v148
	v_mov_b32_e32 v29, v149
	v_add_u32_e32 v30, 7, v0
	v_lshlrev_b32_e32 v32, 16, v25
	v_and_b32_e32 v33, 0xffff0000, v25
	v_lshlrev_b32_e32 v34, 16, v29
	v_and_b32_e32 v35, 0xffff0000, v29
	v_pk_fma_f32 v[32:33], v[10:11], v[34:35], v[32:33] neg_lo:[1,0,0] neg_hi:[1,0,0]
	v_lshlrev_b32_e32 v34, 16, v24
	v_and_b32_e32 v35, 0xffff0000, v24
	v_lshlrev_b32_e32 v24, 16, v28
	v_and_b32_e32 v25, 0xffff0000, v28
	v_pk_fma_f32 v[24:25], v[10:11], v[24:25], v[34:35] neg_lo:[1,0,0] neg_hi:[1,0,0]
	v_mov_b32_e32 v28, v32
	v_mov_b32_e32 v29, v24
	v_pk_mul_f32 v[28:29], v[28:29], v[28:29]
	v_mov_b32_e32 v34, v33
	v_mov_b32_e32 v35, v25
	v_pk_fma_f32 v[28:29], v[34:35], v[34:35], v[28:29]
	v_lshlrev_b32_e32 v34, 16, v23
	v_and_b32_e32 v35, 0xffff0000, v23
	v_lshlrev_b32_e32 v36, 16, v27
	v_and_b32_e32 v37, 0xffff0000, v27
	v_pk_fma_f32 v[34:35], v[10:11], v[36:37], v[34:35] neg_lo:[1,0,0] neg_hi:[1,0,0]
	v_lshlrev_b32_e32 v36, 16, v22
	v_and_b32_e32 v37, 0xffff0000, v22
	v_lshlrev_b32_e32 v22, 16, v26
	v_and_b32_e32 v23, 0xffff0000, v26
	v_pk_fma_f32 v[22:23], v[10:11], v[22:23], v[36:37] neg_lo:[1,0,0] neg_hi:[1,0,0]
	v_mov_b32_e32 v27, v34
	v_mov_b32_e32 v26, v22
	v_pk_mul_f32 v[26:27], v[26:27], v[26:27]
	v_mov_b32_e32 v36, v23
	v_mov_b32_e32 v37, v35
	v_pk_fma_f32 v[26:27], v[36:37], v[36:37], v[26:27]
	s_nop 0
	v_add_f32_e32 v26, v26, v27
	v_add_f32_e32 v26, v29, v26
	v_add_f32_e32 v26, v28, v26
	s_nop 1
	v_add_f32_dpp v26, v26, v26 quad_perm:[1,0,3,2] row_mask:0xf bank_mask:0xf
	s_nop 1
	v_add_f32_dpp v26, v26, v26 quad_perm:[2,3,0,1] row_mask:0xf bank_mask:0xf
	s_nop 1
	v_add_f32_dpp v26, v26, v26 row_half_mirror row_mask:0xf bank_mask:0xf
	s_nop 1
	v_add_f32_dpp v26, v26, v26 row_mirror row_mask:0xf bank_mask:0xf
	v_fmamk_f32 v26, v26, 0x3c000000, v200
	v_cmp_gt_f32_e32 vcc, s58, v26
	v_mul_f32_e32 v27, 0x4b800000, v26
	s_nop 0
	v_cndmask_b32_e32 v26, v26, v27, vcc
	v_rsq_f32_e32 v26, v26
	s_nop 0
	v_mul_f32_e32 v27, 0x45800000, v26
	v_cndmask_b32_e32 v26, v26, v27, vcc
	v_mul_f32_e32 v26, v63, v26
	v_pk_mul_f32 v[22:23], v[22:23], v[26:27] op_sel_hi:[1,0]
	v_pk_mul_f32 v[28:29], v[34:35], v[26:27] op_sel_hi:[1,0]
	v_pk_mul_f32 v[24:25], v[24:25], v[26:27] op_sel_hi:[1,0]
	v_pk_mul_f32 v[26:27], v[32:33], v[26:27] op_sel_hi:[1,0]
	v_pk_mul_f32 v[22:23], v[2:3], v[22:23]
	v_pk_mul_f32 v[28:29], v[4:5], v[28:29]
	v_pk_mul_f32 v[24:25], v[6:7], v[24:25]
	v_pk_mul_f32 v[26:27], v[8:9], v[26:27]
	v_cvt_pk_bf16_f32 v22, v22, v23
	v_cvt_pk_bf16_f32 v23, v28, v29
	v_cvt_pk_bf16_f32 v24, v24, v25
	v_cvt_pk_bf16_f32 v25, v26, v27
	v_mad_i64_i32 v[26:27], s[18:19], v30, s57, v[16:17]
	global_store_dwordx4 v[26:27], v[22:25], off
	s_nop 1
	s_waitcnt vmcnt(22)
; DI unsigned pk2(float lo, float hi) { f32x2_t v; v[0] = lo; v[1] = hi; bf16x2_t b = __builtin_convertvector(v, bf16x2_t); return __builtin_bit_cast(unsigned, b); }
; DI float bflo(unsigned u) { return __uint_as_float(u << 16); }
; DI float bfhi(unsigned u) { return __uint_as_float(u & 0xffff0000u); }
; DI void diffpost_item(const Params& p, int l, int item) {
;     ...
;   for (int rr = 0; rr < 16; ++rr) {
;     const int t = item * 64 + wid * 16 + rr;
;     u32x4 a = *(const u32x4*)(D1 + (size_t)t * 512 + lane * 8), b = *(const u32x4*)(D2 + (size_t)t * 512 + lane * 8);
;     unsigned aw[4] = {a.x, a.y, a.z, a.w}, bw[4] = {b.x, b.y, b.z, b.w};
;     float o[8]; float ss = 0.f;
; #pragma unroll
;     for (int j = 0; j < 4; ++j) { o[2 * j] = bflo(aw[j]) - lam * bflo(bw[j]); o[2 * j + 1] = bfhi(aw[j]) - lam * bfhi(bw[j]); ss += o[2 * j] * o[2 * j] + o[2 * j + 1] * o[2 * j + 1]; }
;     ss += __shfl_xor(ss, 1); ss += __shfl_xor(ss, 2); ss += __shfl_xor(ss, 4); ss += __shfl_xor(ss, 8);
;     const float rs = rsqrtf(ss * (1.f / 128.f) + EPS) * (1.f - lambda_init);
;     u32x4 ov; ov.x = pk2(o[0] * rs * w0[0], o[1] * rs * w0[1]); ov.y = pk2(o[2] * rs * w0[2], o[3] * rs * w0[3]);
;     ov.z = pk2(o[4] * rs * w1[0], o[5] * rs * w1[1]); ov.w = pk2(o[6] * rs * w1[2], o[7] * rs * w1[3]);
;     *(u32x4*)(RA + (size_t)t * 1536 + lane * 8) = ov;
;   }
	v_mov_b32_e32 v22, v150
	v_mov_b32_e32 v23, v151
	v_mov_b32_e32 v24, v152
	v_mov_b32_e32 v25, v153
	v_mov_b32_e32 v26, v154
	v_mov_b32_e32 v27, v155
	v_mov_b32_e32 v28, v156
	v_mov_b32_e32 v29, v157
	v_add_u32_e32 v30, 8, v0
	v_lshlrev_b32_e32 v32, 16, v25
	v_and_b32_e32 v33, 0xffff0000, v25
	v_lshlrev_b32_e32 v34, 16, v29
	v_and_b32_e32 v35, 0xffff0000, v29
	v_pk_fma_f32 v[32:33], v[10:11], v[34:35], v[32:33] neg_lo:[1,0,0] neg_hi:[1,0,0]
	v_lshlrev_b32_e32 v34, 16, v24
	v_and_b32_e32 v35, 0xffff0000, v24
	v_lshlrev_b32_e32 v24, 16, v28
	v_and_b32_e32 v25, 0xffff0000, v28
	v_pk_fma_f32 v[24:25], v[10:11], v[24:25], v[34:35] neg_lo:[1,0,0] neg_hi:[1,0,0]
	v_mov_b32_e32 v28, v32
	v_mov_b32_e32 v29, v24
	v_pk_mul_f32 v[28:29], v[28:29], v[28:29]
	v_mov_b32_e32 v34, v33
	v_mov_b32_e32 v35, v25
	v_pk_fma_f32 v[28:29], v[34:35], v[34:35], v[28:29]
	v_lshlrev_b32_e32 v34, 16, v23
	v_and_b32_e32 v35, 0xffff0000, v23
	v_lshlrev_b32_e32 v36, 16, v27
	v_and_b32_e32 v37, 0xffff0000, v27
	v_pk_fma_f32 v[34:35], v[10:11], v[36:37], v[34:35] neg_lo:[1,0,0] neg_hi:[1,0,0]
	v_lshlrev_b32_e32 v36, 16, v22
	v_and_b32_e32 v37, 0xffff0000, v22
	v_lshlrev_b32_e32 v22, 16, v26
	v_and_b32_e32 v23, 0xffff0000, v26
	v_pk_fma_f32 v[22:23], v[10:11], v[22:23], v[36:37] neg_lo:[1,0,0] neg_hi:[1,0,0]
	v_mov_b32_e32 v27, v34
	v_mov_b32_e32 v26, v22
	v_pk_mul_f32 v[26:27], v[26:27], v[26:27]
	v_mov_b32_e32 v36, v23
	v_mov_b32_e32 v37, v35
	v_pk_fma_f32 v[26:27], v[36:37], v[36:37], v[26:27]
	s_nop 0
	v_add_f32_e32 v26, v26, v27
	v_add_f32_e32 v26, v29, v26
	v_add_f32_e32 v26, v28, v26
	s_nop 1
	v_add_f32_dpp v26, v26, v26 quad_perm:[1,0,3,2] row_mask:0xf bank_mask:0xf
	s_nop 1
	v_add_f32_dpp v26, v26, v26 quad_perm:[2,3,0,1] row_mask:0xf bank_mask:0xf
	s_nop 1
	v_add_f32_dpp v26, v26, v26 row_half_mirror row_mask:0xf bank_mask:0xf
	s_nop 1
	v_add_f32_dpp v26, v26, v26 row_mirror row_mask:0xf bank_mask:0xf
	v_fmamk_f32 v26, v26, 0x3c000000, v200
	v_cmp_gt_f32_e32 vcc, s58, v26
	v_mul_f32_e32 v27, 0x4b800000, v26
	s_nop 0
	v_cndmask_b32_e32 v26, v26, v27, vcc
	v_rsq_f32_e32 v26, v26
	s_nop 0
	v_mul_f32_e32 v27, 0x45800000, v26
	v_cndmask_b32_e32 v26, v26, v27, vcc
	v_mul_f32_e32 v26, v63, v26
	v_pk_mul_f32 v[22:23], v[22:23], v[26:27] op_sel_hi:[1,0]
	v_pk_mul_f32 v[28:29], v[34:35], v[26:27] op_sel_hi:[1,0]
	v_pk_mul_f32 v[24:25], v[24:25], v[26:27] op_sel_hi:[1,0]
	v_pk_mul_f32 v[26:27], v[32:33], v[26:27] op_sel_hi:[1,0]
	v_pk_mul_f32 v[22:23], v[2:3], v[22:23]
	v_pk_mul_f32 v[28:29], v[4:5], v[28:29]
	v_pk_mul_f32 v[24:25], v[6:7], v[24:25]
	v_pk_mul_f32 v[26:27], v[8:9], v[26:27]
	v_cvt_pk_bf16_f32 v22, v22, v23
	v_cvt_pk_bf16_f32 v23, v28, v29
	v_cvt_pk_bf16_f32 v24, v24, v25
	v_cvt_pk_bf16_f32 v25, v26, v27
	v_mad_i64_i32 v[26:27], s[18:19], v30, s57, v[16:17]
	global_store_dwordx4 v[26:27], v[22:25], off
	s_nop 1
	s_waitcnt vmcnt(21)
	v_mov_b32_e32 v22, v158
	v_mov_b32_e32 v23, v159
	v_mov_b32_e32 v24, v160
	v_mov_b32_e32 v25, v161
	v_mov_b32_e32 v26, v162
	v_mov_b32_e32 v27, v163
	v_mov_b32_e32 v28, v164
	v_mov_b32_e32 v29, v165
	v_add_u32_e32 v30, 9, v0
	v_lshlrev_b32_e32 v32, 16, v25
	v_and_b32_e32 v33, 0xffff0000, v25
	v_lshlrev_b32_e32 v34, 16, v29
	v_and_b32_e32 v35, 0xffff0000, v29
	v_pk_fma_f32 v[32:33], v[10:11], v[34:35], v[32:33] neg_lo:[1,0,0] neg_hi:[1,0,0]
	v_lshlrev_b32_e32 v34, 16, v24
	v_and_b32_e32 v35, 0xffff0000, v24
	v_lshlrev_b32_e32 v24, 16, v28
	v_and_b32_e32 v25, 0xffff0000, v28
	v_pk_fma_f32 v[24:25], v[10:11], v[24:25], v[34:35] neg_lo:[1,0,0] neg_hi:[1,0,0]
	v_mov_b32_e32 v28, v32
	v_mov_b32_e32 v29, v24
	v_pk_mul_f32 v[28:29], v[28:29], v[28:29]
	v_mov_b32_e32 v34, v33
	v_mov_b32_e32 v35, v25
	v_pk_fma_f32 v[28:29], v[34:35], v[34:35], v[28:29]
	v_lshlrev_b32_e32 v34, 16, v23
	v_and_b32_e32 v35, 0xffff0000, v23
	v_lshlrev_b32_e32 v36, 16, v27
	v_and_b32_e32 v37, 0xffff0000, v27
	v_pk_fma_f32 v[34:35], v[10:11], v[36:37], v[34:35] neg_lo:[1,0,0] neg_hi:[1,0,0]
	v_lshlrev_b32_e32 v36, 16, v22
	v_and_b32_e32 v37, 0xffff0000, v22
	v_lshlrev_b32_e32 v22, 16, v26
	v_and_b32_e32 v23, 0xffff0000, v26
	v_pk_fma_f32 v[22:23], v[10:11], v[22:23], v[36:37] neg_lo:[1,0,0] neg_hi:[1,0,0]
	v_mov_b32_e32 v27, v34
	v_mov_b32_e32 v26, v22
	v_pk_mul_f32 v[26:27], v[26:27], v[26:27]
	v_mov_b32_e32 v36, v23
	v_mov_b32_e32 v37, v35
	v_pk_fma_f32 v[26:27], v[36:37], v[36:37], v[26:27]
	s_nop 0
	v_add_f32_e32 v26, v26, v27
	v_add_f32_e32 v26, v29, v26
	v_add_f32_e32 v26, v28, v26
	s_nop 1
	v_add_f32_dpp v26, v26, v26 quad_perm:[1,0,3,2] row_mask:0xf bank_mask:0xf
	s_nop 1
	v_add_f32_dpp v26, v26, v26 quad_perm:[2,3,0,1] row_mask:0xf bank_mask:0xf
	s_nop 1
	v_add_f32_dpp v26, v26, v26 row_half_mirror row_mask:0xf bank_mask:0xf
	s_nop 1
	v_add_f32_dpp v26, v26, v26 row_mirror row_mask:0xf bank_mask:0xf
	v_fmamk_f32 v26, v26, 0x3c000000, v200
	v_cmp_gt_f32_e32 vcc, s58, v26
	v_mul_f32_e32 v27, 0x4b800000, v26
	s_nop 0
	v_cndmask_b32_e32 v26, v26, v27, vcc
	v_rsq_f32_e32 v26, v26
	s_nop 0
	v_mul_f32_e32 v27, 0x45800000, v26
	v_cndmask_b32_e32 v26, v26, v27, vcc
	v_mul_f32_e32 v26, v63, v26
	v_pk_mul_f32 v[22:23], v[22:23], v[26:27] op_sel_hi:[1,0]
	v_pk_mul_f32 v[28:29], v[34:35], v[26:27] op_sel_hi:[1,0]
	v_pk_mul_f32 v[24:25], v[24:25], v[26:27] op_sel_hi:[1,0]
	v_pk_mul_f32 v[26:27], v[32:33], v[26:27] op_sel_hi:[1,0]
	v_pk_mul_f32 v[22:23], v[2:3], v[22:23]
	v_pk_mul_f32 v[28:29], v[4:5], v[28:29]
	v_pk_mul_f32 v[24:25], v[6:7], v[24:25]
	v_pk_mul_f32 v[26:27], v[8:9], v[26:27]
	v_cvt_pk_bf16_f32 v22, v22, v23
	v_cvt_pk_bf16_f32 v23, v28, v29
	v_cvt_pk_bf16_f32 v24, v24, v25
	v_cvt_pk_bf16_f32 v25, v26, v27
	v_mad_i64_i32 v[26:27], s[18:19], v30, s57, v[16:17]
	global_store_dwordx4 v[26:27], v[22:25], off
	s_nop 1
	s_waitcnt vmcnt(20)
; DI unsigned pk2(float lo, float hi) { f32x2_t v; v[0] = lo; v[1] = hi; bf16x2_t b = __builtin_convertvector(v, bf16x2_t); return __builtin_bit_cast(unsigned, b); }
; DI float bflo(unsigned u) { return __uint_as_float(u << 16); }
; DI float bfhi(unsigned u) { return __uint_as_float(u & 0xffff0000u); }
; DI void diffpost_item(const Params& p, int l, int item) {
;     ...
;   for (int rr = 0; rr < 16; ++rr) {
;     const int t = item * 64 + wid * 16 + rr;
;     u32x4 a = *(const u32x4*)(D1 + (size_t)t * 512 + lane * 8), b = *(const u32x4*)(D2 + (size_t)t * 512 + lane * 8);
;     unsigned aw[4] = {a.x, a.y, a.z, a.w}, bw[4] = {b.x, b.y, b.z, b.w};
;     float o[8]; float ss = 0.f;
; #pragma unroll
;     for (int j = 0; j < 4; ++j) { o[2 * j] = bflo(aw[j]) - lam * bflo(bw[j]); o[2 * j + 1] = bfhi(aw[j]) - lam * bfhi(bw[j]); ss += o[2 * j] * o[2 * j] + o[2 * j + 1] * o[2 * j + 1]; }
;     ss += __shfl_xor(ss, 1); ss += __shfl_xor(ss, 2); ss += __shfl_xor(ss, 4); ss += __shfl_xor(ss, 8);
;     const float rs = rsqrtf(ss * (1.f / 128.f) + EPS) * (1.f - lambda_init);
;     u32x4 ov; ov.x = pk2(o[0] * rs * w0[0], o[1] * rs * w0[1]); ov.y = pk2(o[2] * rs * w0[2], o[3] * rs * w0[3]);
;     ov.z = pk2(o[4] * rs * w1[0], o[5] * rs * w1[1]); ov.w = pk2(o[6] * rs * w1[2], o[7] * rs * w1[3]);
;     *(u32x4*)(RA + (size_t)t * 1536 + lane * 8) = ov;
;   }
	v_mov_b32_e32 v22, v166
	v_mov_b32_e32 v23, v167
	v_mov_b32_e32 v24, v168
	v_mov_b32_e32 v25, v169
	v_mov_b32_e32 v26, v170
	v_mov_b32_e32 v27, v171
	v_mov_b32_e32 v28, v172
	v_mov_b32_e32 v29, v173
	v_add_u32_e32 v30, 10, v0
	v_lshlrev_b32_e32 v32, 16, v25
	v_and_b32_e32 v33, 0xffff0000, v25
	v_lshlrev_b32_e32 v34, 16, v29
	v_and_b32_e32 v35, 0xffff0000, v29
	v_pk_fma_f32 v[32:33], v[10:11], v[34:35], v[32:33] neg_lo:[1,0,0] neg_hi:[1,0,0]
	v_lshlrev_b32_e32 v34, 16, v24
	v_and_b32_e32 v35, 0xffff0000, v24
	v_lshlrev_b32_e32 v24, 16, v28
	v_and_b32_e32 v25, 0xffff0000, v28
	v_pk_fma_f32 v[24:25], v[10:11], v[24:25], v[34:35] neg_lo:[1,0,0] neg_hi:[1,0,0]
	v_mov_b32_e32 v28, v32
	v_mov_b32_e32 v29, v24
	v_pk_mul_f32 v[28:29], v[28:29], v[28:29]
	v_mov_b32_e32 v34, v33
	v_mov_b32_e32 v35, v25
	v_pk_fma_f32 v[28:29], v[34:35], v[34:35], v[28:29]
	v_lshlrev_b32_e32 v34, 16, v23
	v_and_b32_e32 v35, 0xffff0000, v23
	v_lshlrev_b32_e32 v36, 16, v27
	v_and_b32_e32 v37, 0xffff0000, v27
	v_pk_fma_f32 v[34:35], v[10:11], v[36:37], v[34:35] neg_lo:[1,0,0] neg_hi:[1,0,0]
	v_lshlrev_b32_e32 v36, 16, v22
	v_and_b32_e32 v37, 0xffff0000, v22
	v_lshlrev_b32_e32 v22, 16, v26
	v_and_b32_e32 v23, 0xffff0000, v26
	v_pk_fma_f32 v[22:23], v[10:11], v[22:23], v[36:37] neg_lo:[1,0,0] neg_hi:[1,0,0]
	v_mov_b32_e32 v27, v34
	v_mov_b32_e32 v26, v22
	v_pk_mul_f32 v[26:27], v[26:27], v[26:27]
	v_mov_b32_e32 v36, v23
	v_mov_b32_e32 v37, v35
	v_pk_fma_f32 v[26:27], v[36:37], v[36:37], v[26:27]
	s_nop 0
	v_add_f32_e32 v26, v26, v27
	v_add_f32_e32 v26, v29, v26
	v_add_f32_e32 v26, v28, v26
	s_nop 1
	v_add_f32_dpp v26, v26, v26 quad_perm:[1,0,3,2] row_mask:0xf bank_mask:0xf
	s_nop 1
	v_add_f32_dpp v26, v26, v26 quad_perm:[2,3,0,1] row_mask:0xf bank_mask:0xf
	s_nop 1
	v_add_f32_dpp v26, v26, v26 row_half_mirror row_mask:0xf bank_mask:0xf
	s_nop 1
	v_add_f32_dpp v26, v26, v26 row_mirror row_mask:0xf bank_mask:0xf
	v_fmamk_f32 v26, v26, 0x3c000000, v200
	v_cmp_gt_f32_e32 vcc, s58, v26
	v_mul_f32_e32 v27, 0x4b800000, v26
	s_nop 0
	v_cndmask_b32_e32 v26, v26, v27, vcc
	v_rsq_f32_e32 v26, v26
	s_nop 0
	v_mul_f32_e32 v27, 0x45800000, v26
	v_cndmask_b32_e32 v26, v26, v27, vcc
	v_mul_f32_e32 v26, v63, v26
	v_pk_mul_f32 v[22:23], v[22:23], v[26:27] op_sel_hi:[1,0]
	v_pk_mul_f32 v[28:29], v[34:35], v[26:27] op_sel_hi:[1,0]
	v_pk_mul_f32 v[24:25], v[24:25], v[26:27] op_sel_hi:[1,0]
	v_pk_mul_f32 v[26:27], v[32:33], v[26:27] op_sel_hi:[1,0]
	v_pk_mul_f32 v[22:23], v[2:3], v[22:23]
	v_pk_mul_f32 v[28:29], v[4:5], v[28:29]
	v_pk_mul_f32 v[24:25], v[6:7], v[24:25]
	v_pk_mul_f32 v[26:27], v[8:9], v[26:27]
	v_cvt_pk_bf16_f32 v22, v22, v23
	v_cvt_pk_bf16_f32 v23, v28, v29
	v_cvt_pk_bf16_f32 v24, v24, v25
	v_cvt_pk_bf16_f32 v25, v26, v27
	v_mad_i64_i32 v[26:27], s[18:19], v30, s57, v[16:17]
	global_store_dwordx4 v[26:27], v[22:25], off
	s_nop 1
	s_waitcnt vmcnt(19)
	v_mov_b32_e32 v22, v174
	v_mov_b32_e32 v23, v175
	v_mov_b32_e32 v24, v176
	v_mov_b32_e32 v25, v177
	v_mov_b32_e32 v26, v178
	v_mov_b32_e32 v27, v179
	v_mov_b32_e32 v28, v180
	v_mov_b32_e32 v29, v181
	v_add_u32_e32 v30, 11, v0
	v_lshlrev_b32_e32 v32, 16, v25
	v_and_b32_e32 v33, 0xffff0000, v25
	v_lshlrev_b32_e32 v34, 16, v29
	v_and_b32_e32 v35, 0xffff0000, v29
	v_pk_fma_f32 v[32:33], v[10:11], v[34:35], v[32:33] neg_lo:[1,0,0] neg_hi:[1,0,0]
	v_lshlrev_b32_e32 v34, 16, v24
	v_and_b32_e32 v35, 0xffff0000, v24
	v_lshlrev_b32_e32 v24, 16, v28
	v_and_b32_e32 v25, 0xffff0000, v28
	v_pk_fma_f32 v[24:25], v[10:11], v[24:25], v[34:35] neg_lo:[1,0,0] neg_hi:[1,0,0]
	v_mov_b32_e32 v28, v32
	v_mov_b32_e32 v29, v24
	v_pk_mul_f32 v[28:29], v[28:29], v[28:29]
	v_mov_b32_e32 v34, v33
	v_mov_b32_e32 v35, v25
	v_pk_fma_f32 v[28:29], v[34:35], v[34:35], v[28:29]
	v_lshlrev_b32_e32 v34, 16, v23
	v_and_b32_e32 v35, 0xffff0000, v23
	v_lshlrev_b32_e32 v36, 16, v27
	v_and_b32_e32 v37, 0xffff0000, v27
	v_pk_fma_f32 v[34:35], v[10:11], v[36:37], v[34:35] neg_lo:[1,0,0] neg_hi:[1,0,0]
	v_lshlrev_b32_e32 v36, 16, v22
	v_and_b32_e32 v37, 0xffff0000, v22
	v_lshlrev_b32_e32 v22, 16, v26
	v_and_b32_e32 v23, 0xffff0000, v26
	v_pk_fma_f32 v[22:23], v[10:11], v[22:23], v[36:37] neg_lo:[1,0,0] neg_hi:[1,0,0]
	v_mov_b32_e32 v27, v34
	v_mov_b32_e32 v26, v22
	v_pk_mul_f32 v[26:27], v[26:27], v[26:27]
	v_mov_b32_e32 v36, v23
	v_mov_b32_e32 v37, v35
	v_pk_fma_f32 v[26:27], v[36:37], v[36:37], v[26:27]
	s_nop 0
	v_add_f32_e32 v26, v26, v27
	v_add_f32_e32 v26, v29, v26
	v_add_f32_e32 v26, v28, v26
	s_nop 1
	v_add_f32_dpp v26, v26, v26 quad_perm:[1,0,3,2] row_mask:0xf bank_mask:0xf
	s_nop 1
	v_add_f32_dpp v26, v26, v26 quad_perm:[2,3,0,1] row_mask:0xf bank_mask:0xf
	s_nop 1
	v_add_f32_dpp v26, v26, v26 row_half_mirror row_mask:0xf bank_mask:0xf
	s_nop 1
	v_add_f32_dpp v26, v26, v26 row_mirror row_mask:0xf bank_mask:0xf
	v_fmamk_f32 v26, v26, 0x3c000000, v200
	v_cmp_gt_f32_e32 vcc, s58, v26
	v_mul_f32_e32 v27, 0x4b800000, v26
	s_nop 0
	v_cndmask_b32_e32 v26, v26, v27, vcc
	v_rsq_f32_e32 v26, v26
	s_nop 0
	v_mul_f32_e32 v27, 0x45800000, v26
	v_cndmask_b32_e32 v26, v26, v27, vcc
	v_mul_f32_e32 v26, v63, v26
	v_pk_mul_f32 v[22:23], v[22:23], v[26:27] op_sel_hi:[1,0]
	v_pk_mul_f32 v[28:29], v[34:35], v[26:27] op_sel_hi:[1,0]
	v_pk_mul_f32 v[24:25], v[24:25], v[26:27] op_sel_hi:[1,0]
	v_pk_mul_f32 v[26:27], v[32:33], v[26:27] op_sel_hi:[1,0]
	v_pk_mul_f32 v[22:23], v[2:3], v[22:23]
	v_pk_mul_f32 v[28:29], v[4:5], v[28:29]
	v_pk_mul_f32 v[24:25], v[6:7], v[24:25]
	v_pk_mul_f32 v[26:27], v[8:9], v[26:27]
	v_cvt_pk_bf16_f32 v22, v22, v23
	v_cvt_pk_bf16_f32 v23, v28, v29
	v_cvt_pk_bf16_f32 v24, v24, v25
	v_cvt_pk_bf16_f32 v25, v26, v27
	v_mad_i64_i32 v[26:27], s[18:19], v30, s57, v[16:17]
	global_store_dwordx4 v[26:27], v[22:25], off
	s_nop 1
	s_waitcnt vmcnt(18)
; DI unsigned pk2(float lo, float hi) { f32x2_t v; v[0] = lo; v[1] = hi; bf16x2_t b = __builtin_convertvector(v, bf16x2_t); return __builtin_bit_cast(unsigned, b); }
; DI float bflo(unsigned u) { return __uint_as_float(u << 16); }
; DI float bfhi(unsigned u) { return __uint_as_float(u & 0xffff0000u); }
; DI void diffpost_item(const Params& p, int l, int item) {
;     ...
;   for (int rr = 0; rr < 16; ++rr) {
;     const int t = item * 64 + wid * 16 + rr;
;     u32x4 a = *(const u32x4*)(D1 + (size_t)t * 512 + lane * 8), b = *(const u32x4*)(D2 + (size_t)t * 512 + lane * 8);
;     unsigned aw[4] = {a.x, a.y, a.z, a.w}, bw[4] = {b.x, b.y, b.z, b.w};
;     float o[8]; float ss = 0.f;
; #pragma unroll
;     for (int j = 0; j < 4; ++j) { o[2 * j] = bflo(aw[j]) - lam * bflo(bw[j]); o[2 * j + 1] = bfhi(aw[j]) - lam * bfhi(bw[j]); ss += o[2 * j] * o[2 * j] + o[2 * j + 1] * o[2 * j + 1]; }
;     ss += __shfl_xor(ss, 1); ss += __shfl_xor(ss, 2); ss += __shfl_xor(ss, 4); ss += __shfl_xor(ss, 8);
;     const float rs = rsqrtf(ss * (1.f / 128.f) + EPS) * (1.f - lambda_init);
;     u32x4 ov; ov.x = pk2(o[0] * rs * w0[0], o[1] * rs * w0[1]); ov.y = pk2(o[2] * rs * w0[2], o[3] * rs * w0[3]);
;     ov.z = pk2(o[4] * rs * w1[0], o[5] * rs * w1[1]); ov.w = pk2(o[6] * rs * w1[2], o[7] * rs * w1[3]);
;     *(u32x4*)(RA + (size_t)t * 1536 + lane * 8) = ov;
;   }
	v_mov_b32_e32 v22, v182
	v_mov_b32_e32 v23, v183
	v_mov_b32_e32 v24, v184
	v_mov_b32_e32 v25, v185
	v_mov_b32_e32 v26, v186
	v_mov_b32_e32 v27, v187
	v_mov_b32_e32 v28, v188
	v_mov_b32_e32 v29, v189
	v_add_u32_e32 v30, 12, v0
	v_lshlrev_b32_e32 v32, 16, v25
	v_and_b32_e32 v33, 0xffff0000, v25
	v_lshlrev_b32_e32 v34, 16, v29
	v_and_b32_e32 v35, 0xffff0000, v29
	v_pk_fma_f32 v[32:33], v[10:11], v[34:35], v[32:33] neg_lo:[1,0,0] neg_hi:[1,0,0]
	v_lshlrev_b32_e32 v34, 16, v24
	v_and_b32_e32 v35, 0xffff0000, v24
	v_lshlrev_b32_e32 v24, 16, v28
	v_and_b32_e32 v25, 0xffff0000, v28
	v_pk_fma_f32 v[24:25], v[10:11], v[24:25], v[34:35] neg_lo:[1,0,0] neg_hi:[1,0,0]
	v_mov_b32_e32 v28, v32
	v_mov_b32_e32 v29, v24
	v_pk_mul_f32 v[28:29], v[28:29], v[28:29]
	v_mov_b32_e32 v34, v33
	v_mov_b32_e32 v35, v25
	v_pk_fma_f32 v[28:29], v[34:35], v[34:35], v[28:29]
	v_lshlrev_b32_e32 v34, 16, v23
	v_and_b32_e32 v35, 0xffff0000, v23
	v_lshlrev_b32_e32 v36, 16, v27
	v_and_b32_e32 v37, 0xffff0000, v27
	v_pk_fma_f32 v[34:35], v[10:11], v[36:37], v[34:35] neg_lo:[1,0,0] neg_hi:[1,0,0]
	v_lshlrev_b32_e32 v36, 16, v22
	v_and_b32_e32 v37, 0xffff0000, v22
	v_lshlrev_b32_e32 v22, 16, v26
	v_and_b32_e32 v23, 0xffff0000, v26
	v_pk_fma_f32 v[22:23], v[10:11], v[22:23], v[36:37] neg_lo:[1,0,0] neg_hi:[1,0,0]
	v_mov_b32_e32 v27, v34
	v_mov_b32_e32 v26, v22
	v_pk_mul_f32 v[26:27], v[26:27], v[26:27]
	v_mov_b32_e32 v36, v23
	v_mov_b32_e32 v37, v35
	v_pk_fma_f32 v[26:27], v[36:37], v[36:37], v[26:27]
	s_nop 0
	v_add_f32_e32 v26, v26, v27
	v_add_f32_e32 v26, v29, v26
	v_add_f32_e32 v26, v28, v26
	s_nop 1
	v_add_f32_dpp v26, v26, v26 quad_perm:[1,0,3,2] row_mask:0xf bank_mask:0xf
	s_nop 1
	v_add_f32_dpp v26, v26, v26 quad_perm:[2,3,0,1] row_mask:0xf bank_mask:0xf
	s_nop 1
	v_add_f32_dpp v26, v26, v26 row_half_mirror row_mask:0xf bank_mask:0xf
	s_nop 1
	v_add_f32_dpp v26, v26, v26 row_mirror row_mask:0xf bank_mask:0xf
	v_fmamk_f32 v26, v26, 0x3c000000, v200
	v_cmp_gt_f32_e32 vcc, s58, v26
	v_mul_f32_e32 v27, 0x4b800000, v26
	s_nop 0
	v_cndmask_b32_e32 v26, v26, v27, vcc
	v_rsq_f32_e32 v26, v26
	s_nop 0
	v_mul_f32_e32 v27, 0x45800000, v26
	v_cndmask_b32_e32 v26, v26, v27, vcc
	v_mul_f32_e32 v26, v63, v26
	v_pk_mul_f32 v[22:23], v[22:23], v[26:27] op_sel_hi:[1,0]
	v_pk_mul_f32 v[28:29], v[34:35], v[26:27] op_sel_hi:[1,0]
	v_pk_mul_f32 v[24:25], v[24:25], v[26:27] op_sel_hi:[1,0]
	v_pk_mul_f32 v[26:27], v[32:33], v[26:27] op_sel_hi:[1,0]
	v_pk_mul_f32 v[22:23], v[2:3], v[22:23]
	v_pk_mul_f32 v[28:29], v[4:5], v[28:29]
	v_pk_mul_f32 v[24:25], v[6:7], v[24:25]
	v_pk_mul_f32 v[26:27], v[8:9], v[26:27]
	v_cvt_pk_bf16_f32 v22, v22, v23
	v_cvt_pk_bf16_f32 v23, v28, v29
	v_cvt_pk_bf16_f32 v24, v24, v25
	v_cvt_pk_bf16_f32 v25, v26, v27
	v_mad_i64_i32 v[26:27], s[18:19], v30, s57, v[16:17]
	global_store_dwordx4 v[26:27], v[22:25], off
	s_nop 1
	s_waitcnt vmcnt(17)
	v_mov_b32_e32 v22, v190
	v_mov_b32_e32 v23, v191
	v_mov_b32_e32 v24, v192
	v_mov_b32_e32 v25, v193
	v_mov_b32_e32 v26, v194
	v_mov_b32_e32 v27, v195
	v_mov_b32_e32 v28, v196
	v_mov_b32_e32 v29, v197
	v_add_u32_e32 v30, 13, v0
	v_lshlrev_b32_e32 v32, 16, v25
	v_and_b32_e32 v33, 0xffff0000, v25
	v_lshlrev_b32_e32 v34, 16, v29
	v_and_b32_e32 v35, 0xffff0000, v29
	v_pk_fma_f32 v[32:33], v[10:11], v[34:35], v[32:33] neg_lo:[1,0,0] neg_hi:[1,0,0]
	v_lshlrev_b32_e32 v34, 16, v24
	v_and_b32_e32 v35, 0xffff0000, v24
	v_lshlrev_b32_e32 v24, 16, v28
	v_and_b32_e32 v25, 0xffff0000, v28
	v_pk_fma_f32 v[24:25], v[10:11], v[24:25], v[34:35] neg_lo:[1,0,0] neg_hi:[1,0,0]
	v_mov_b32_e32 v28, v32
	v_mov_b32_e32 v29, v24
	v_pk_mul_f32 v[28:29], v[28:29], v[28:29]
	v_mov_b32_e32 v34, v33
	v_mov_b32_e32 v35, v25
	v_pk_fma_f32 v[28:29], v[34:35], v[34:35], v[28:29]
	v_lshlrev_b32_e32 v34, 16, v23
	v_and_b32_e32 v35, 0xffff0000, v23
	v_lshlrev_b32_e32 v36, 16, v27
	v_and_b32_e32 v37, 0xffff0000, v27
	v_pk_fma_f32 v[34:35], v[10:11], v[36:37], v[34:35] neg_lo:[1,0,0] neg_hi:[1,0,0]
	v_lshlrev_b32_e32 v36, 16, v22
	v_and_b32_e32 v37, 0xffff0000, v22
	v_lshlrev_b32_e32 v22, 16, v26
	v_and_b32_e32 v23, 0xffff0000, v26
	v_pk_fma_f32 v[22:23], v[10:11], v[22:23], v[36:37] neg_lo:[1,0,0] neg_hi:[1,0,0]
	v_mov_b32_e32 v27, v34
	v_mov_b32_e32 v26, v22
	v_pk_mul_f32 v[26:27], v[26:27], v[26:27]
	v_mov_b32_e32 v36, v23
	v_mov_b32_e32 v37, v35
	v_pk_fma_f32 v[26:27], v[36:37], v[36:37], v[26:27]
	s_nop 0
	v_add_f32_e32 v26, v26, v27
	v_add_f32_e32 v26, v29, v26
	v_add_f32_e32 v26, v28, v26
	s_nop 1
	v_add_f32_dpp v26, v26, v26 quad_perm:[1,0,3,2] row_mask:0xf bank_mask:0xf
	s_nop 1
	v_add_f32_dpp v26, v26, v26 quad_perm:[2,3,0,1] row_mask:0xf bank_mask:0xf
	s_nop 1
	v_add_f32_dpp v26, v26, v26 row_half_mirror row_mask:0xf bank_mask:0xf
	s_nop 1
	v_add_f32_dpp v26, v26, v26 row_mirror row_mask:0xf bank_mask:0xf
	v_fmamk_f32 v26, v26, 0x3c000000, v200
	v_cmp_gt_f32_e32 vcc, s58, v26
	v_mul_f32_e32 v27, 0x4b800000, v26
	s_nop 0
	v_cndmask_b32_e32 v26, v26, v27, vcc
	v_rsq_f32_e32 v26, v26
	s_nop 0
	v_mul_f32_e32 v27, 0x45800000, v26
	v_cndmask_b32_e32 v26, v26, v27, vcc
	v_mul_f32_e32 v26, v63, v26
	v_pk_mul_f32 v[22:23], v[22:23], v[26:27] op_sel_hi:[1,0]
	v_pk_mul_f32 v[28:29], v[34:35], v[26:27] op_sel_hi:[1,0]
	v_pk_mul_f32 v[24:25], v[24:25], v[26:27] op_sel_hi:[1,0]
	v_pk_mul_f32 v[26:27], v[32:33], v[26:27] op_sel_hi:[1,0]
	v_pk_mul_f32 v[22:23], v[2:3], v[22:23]
	v_pk_mul_f32 v[28:29], v[4:5], v[28:29]
	v_pk_mul_f32 v[24:25], v[6:7], v[24:25]
	v_pk_mul_f32 v[26:27], v[8:9], v[26:27]
	v_cvt_pk_bf16_f32 v22, v22, v23
	v_cvt_pk_bf16_f32 v23, v28, v29
	v_cvt_pk_bf16_f32 v24, v24, v25
	v_cvt_pk_bf16_f32 v25, v26, v27
	v_mad_i64_i32 v[26:27], s[18:19], v30, s57, v[16:17]
	global_store_dwordx4 v[26:27], v[22:25], off
	s_nop 1
	s_waitcnt vmcnt(15)
; DI unsigned pk2(float lo, float hi) { f32x2_t v; v[0] = lo; v[1] = hi; bf16x2_t b = __builtin_convertvector(v, bf16x2_t); return __builtin_bit_cast(unsigned, b); }
; DI float bflo(unsigned u) { return __uint_as_float(u << 16); }
; DI float bfhi(unsigned u) { return __uint_as_float(u & 0xffff0000u); }
; DI void diffpost_item(const Params& p, int l, int item) {
;     ...
;   for (int rr = 0; rr < 16; ++rr) {
;     const int t = item * 64 + wid * 16 + rr;
;     u32x4 a = *(const u32x4*)(D1 + (size_t)t * 512 + lane * 8), b = *(const u32x4*)(D2 + (size_t)t * 512 + lane * 8);
;     unsigned aw[4] = {a.x, a.y, a.z, a.w}, bw[4] = {b.x, b.y, b.z, b.w};
;     float o[8]; float ss = 0.f;
; #pragma unroll
;     for (int j = 0; j < 4; ++j) { o[2 * j] = bflo(aw[j]) - lam * bflo(bw[j]); o[2 * j + 1] = bfhi(aw[j]) - lam * bfhi(bw[j]); ss += o[2 * j] * o[2 * j] + o[2 * j + 1] * o[2 * j + 1]; }
;     ss += __shfl_xor(ss, 1); ss += __shfl_xor(ss, 2); ss += __shfl_xor(ss, 4); ss += __shfl_xor(ss, 8);
;     const float rs = rsqrtf(ss * (1.f / 128.f) + EPS) * (1.f - lambda_init);
;     u32x4 ov; ov.x = pk2(o[0] * rs * w0[0], o[1] * rs * w0[1]); ov.y = pk2(o[2] * rs * w0[2], o[3] * rs * w0[3]);
;     ov.z = pk2(o[4] * rs * w1[0], o[5] * rs * w1[1]); ov.w = pk2(o[6] * rs * w1[2], o[7] * rs * w1[3]);
;     *(u32x4*)(RA + (size_t)t * 1536 + lane * 8) = ov;
;   }
	v_mov_b32_e32 v22, v80
	v_mov_b32_e32 v23, v81
	v_mov_b32_e32 v24, v82
	v_mov_b32_e32 v25, v83
	v_mov_b32_e32 v26, v84
	v_mov_b32_e32 v27, v85
	v_mov_b32_e32 v28, v86
	v_mov_b32_e32 v29, v87
	v_add_u32_e32 v30, 14, v0
	v_lshlrev_b32_e32 v32, 16, v25
	v_and_b32_e32 v33, 0xffff0000, v25
	v_lshlrev_b32_e32 v34, 16, v29
	v_and_b32_e32 v35, 0xffff0000, v29
	v_pk_fma_f32 v[32:33], v[10:11], v[34:35], v[32:33] neg_lo:[1,0,0] neg_hi:[1,0,0]
	v_lshlrev_b32_e32 v34, 16, v24
	v_and_b32_e32 v35, 0xffff0000, v24
	v_lshlrev_b32_e32 v24, 16, v28
	v_and_b32_e32 v25, 0xffff0000, v28
	v_pk_fma_f32 v[24:25], v[10:11], v[24:25], v[34:35] neg_lo:[1,0,0] neg_hi:[1,0,0]
	v_mov_b32_e32 v28, v32
	v_mov_b32_e32 v29, v24
	v_pk_mul_f32 v[28:29], v[28:29], v[28:29]
	v_mov_b32_e32 v34, v33
	v_mov_b32_e32 v35, v25
	v_pk_fma_f32 v[28:29], v[34:35], v[34:35], v[28:29]
	v_lshlrev_b32_e32 v34, 16, v23
	v_and_b32_e32 v35, 0xffff0000, v23
	v_lshlrev_b32_e32 v36, 16, v27
	v_and_b32_e32 v37, 0xffff0000, v27
	v_pk_fma_f32 v[34:35], v[10:11], v[36:37], v[34:35] neg_lo:[1,0,0] neg_hi:[1,0,0]
	v_lshlrev_b32_e32 v36, 16, v22
	v_and_b32_e32 v37, 0xffff0000, v22
	v_lshlrev_b32_e32 v22, 16, v26
	v_and_b32_e32 v23, 0xffff0000, v26
	v_pk_fma_f32 v[22:23], v[10:11], v[22:23], v[36:37] neg_lo:[1,0,0] neg_hi:[1,0,0]
	v_mov_b32_e32 v27, v34
	v_mov_b32_e32 v26, v22
	v_pk_mul_f32 v[26:27], v[26:27], v[26:27]
	v_mov_b32_e32 v36, v23
	v_mov_b32_e32 v37, v35
	v_pk_fma_f32 v[26:27], v[36:37], v[36:37], v[26:27]
	s_nop 0
	v_add_f32_e32 v26, v26, v27
	v_add_f32_e32 v26, v29, v26
	v_add_f32_e32 v26, v28, v26
	s_nop 1
	v_add_f32_dpp v26, v26, v26 quad_perm:[1,0,3,2] row_mask:0xf bank_mask:0xf
	s_nop 1
	v_add_f32_dpp v26, v26, v26 quad_perm:[2,3,0,1] row_mask:0xf bank_mask:0xf
	s_nop 1
	v_add_f32_dpp v26, v26, v26 row_half_mirror row_mask:0xf bank_mask:0xf
	s_nop 1
	v_add_f32_dpp v26, v26, v26 row_mirror row_mask:0xf bank_mask:0xf
	v_fmamk_f32 v26, v26, 0x3c000000, v200
	v_cmp_gt_f32_e32 vcc, s58, v26
	v_mul_f32_e32 v27, 0x4b800000, v26
	s_nop 0
	v_cndmask_b32_e32 v26, v26, v27, vcc
	v_rsq_f32_e32 v26, v26
	s_nop 0
	v_mul_f32_e32 v27, 0x45800000, v26
	v_cndmask_b32_e32 v26, v26, v27, vcc
	v_mul_f32_e32 v26, v63, v26
	v_pk_mul_f32 v[22:23], v[22:23], v[26:27] op_sel_hi:[1,0]
	v_pk_mul_f32 v[28:29], v[34:35], v[26:27] op_sel_hi:[1,0]
	v_pk_mul_f32 v[24:25], v[24:25], v[26:27] op_sel_hi:[1,0]
	v_pk_mul_f32 v[26:27], v[32:33], v[26:27] op_sel_hi:[1,0]
	v_pk_mul_f32 v[22:23], v[2:3], v[22:23]
	v_pk_mul_f32 v[28:29], v[4:5], v[28:29]
	v_pk_mul_f32 v[24:25], v[6:7], v[24:25]
	v_pk_mul_f32 v[26:27], v[8:9], v[26:27]
	v_cvt_pk_bf16_f32 v22, v22, v23
	v_cvt_pk_bf16_f32 v23, v28, v29
	v_cvt_pk_bf16_f32 v24, v24, v25
	v_cvt_pk_bf16_f32 v25, v26, v27
	v_mad_i64_i32 v[26:27], s[18:19], v30, s57, v[16:17]
	global_store_dwordx4 v[26:27], v[22:25], off
	s_nop 1
	s_waitcnt vmcnt(13)
	v_mov_b32_e32 v22, v88
	v_mov_b32_e32 v23, v89
	v_mov_b32_e32 v24, v90
	v_mov_b32_e32 v25, v91
	v_mov_b32_e32 v26, v92
	v_mov_b32_e32 v27, v93
	v_mov_b32_e32 v28, v94
	v_mov_b32_e32 v29, v95
	v_add_u32_e32 v30, 15, v0
	v_lshlrev_b32_e32 v32, 16, v25
	v_and_b32_e32 v33, 0xffff0000, v25
	v_lshlrev_b32_e32 v34, 16, v29
	v_and_b32_e32 v35, 0xffff0000, v29
	v_pk_fma_f32 v[32:33], v[10:11], v[34:35], v[32:33] neg_lo:[1,0,0] neg_hi:[1,0,0]
	v_lshlrev_b32_e32 v34, 16, v24
	v_and_b32_e32 v35, 0xffff0000, v24
	v_lshlrev_b32_e32 v24, 16, v28
	v_and_b32_e32 v25, 0xffff0000, v28
	v_pk_fma_f32 v[24:25], v[10:11], v[24:25], v[34:35] neg_lo:[1,0,0] neg_hi:[1,0,0]
	v_mov_b32_e32 v28, v32
	v_mov_b32_e32 v29, v24
	v_pk_mul_f32 v[28:29], v[28:29], v[28:29]
	v_mov_b32_e32 v34, v33
	v_mov_b32_e32 v35, v25
	v_pk_fma_f32 v[28:29], v[34:35], v[34:35], v[28:29]
	v_lshlrev_b32_e32 v34, 16, v23
	v_and_b32_e32 v35, 0xffff0000, v23
	v_lshlrev_b32_e32 v36, 16, v27
	v_and_b32_e32 v37, 0xffff0000, v27
	v_pk_fma_f32 v[34:35], v[10:11], v[36:37], v[34:35] neg_lo:[1,0,0] neg_hi:[1,0,0]
	v_lshlrev_b32_e32 v36, 16, v22
	v_and_b32_e32 v37, 0xffff0000, v22
	v_lshlrev_b32_e32 v22, 16, v26
	v_and_b32_e32 v23, 0xffff0000, v26
	v_pk_fma_f32 v[22:23], v[10:11], v[22:23], v[36:37] neg_lo:[1,0,0] neg_hi:[1,0,0]
	v_mov_b32_e32 v27, v34
	v_mov_b32_e32 v26, v22
	v_pk_mul_f32 v[26:27], v[26:27], v[26:27]
	v_mov_b32_e32 v36, v23
	v_mov_b32_e32 v37, v35
	v_pk_fma_f32 v[26:27], v[36:37], v[36:37], v[26:27]
	s_nop 0
	v_add_f32_e32 v26, v26, v27
	v_add_f32_e32 v26, v29, v26
	v_add_f32_e32 v26, v28, v26
	s_nop 1
	v_add_f32_dpp v26, v26, v26 quad_perm:[1,0,3,2] row_mask:0xf bank_mask:0xf
	s_nop 1
	v_add_f32_dpp v26, v26, v26 quad_perm:[2,3,0,1] row_mask:0xf bank_mask:0xf
	s_nop 1
	v_add_f32_dpp v26, v26, v26 row_half_mirror row_mask:0xf bank_mask:0xf
	s_nop 1
	v_add_f32_dpp v26, v26, v26 row_mirror row_mask:0xf bank_mask:0xf
	v_fmamk_f32 v26, v26, 0x3c000000, v200
	v_cmp_gt_f32_e32 vcc, s58, v26
	v_mul_f32_e32 v27, 0x4b800000, v26
	s_nop 0
	v_cndmask_b32_e32 v26, v26, v27, vcc
	v_rsq_f32_e32 v26, v26
	s_nop 0
	v_mul_f32_e32 v27, 0x45800000, v26
	v_cndmask_b32_e32 v26, v26, v27, vcc
	v_mul_f32_e32 v26, v63, v26
	v_pk_mul_f32 v[22:23], v[22:23], v[26:27] op_sel_hi:[1,0]
	v_pk_mul_f32 v[28:29], v[34:35], v[26:27] op_sel_hi:[1,0]
	v_pk_mul_f32 v[24:25], v[24:25], v[26:27] op_sel_hi:[1,0]
	v_pk_mul_f32 v[26:27], v[32:33], v[26:27] op_sel_hi:[1,0]
	v_pk_mul_f32 v[22:23], v[2:3], v[22:23]
	v_pk_mul_f32 v[28:29], v[4:5], v[28:29]
	v_pk_mul_f32 v[24:25], v[6:7], v[24:25]
	v_pk_mul_f32 v[26:27], v[8:9], v[26:27]
	v_cvt_pk_bf16_f32 v22, v22, v23
	v_cvt_pk_bf16_f32 v23, v28, v29
	v_cvt_pk_bf16_f32 v24, v24, v25
	v_cvt_pk_bf16_f32 v25, v26, v27
	v_mad_i64_i32 v[26:27], s[18:19], v30, s57, v[16:17]
	global_store_dwordx4 v[26:27], v[22:25], off
	s_nop 1
	s_mov_b32 s17, 16
	s_branch .LBB0_305
; DI int otid() { int t = (int)__builtin_amdgcn_workitem_id_x(); asm volatile("" : "+v"(t)); return t; }
; DI f32x4 mfma16(bf16x8 a, bf16x8 b, f32x4 c) { return __builtin_amdgcn_mfma_f32_16x16x32_bf16(a, b, c, 0, 0, 0); }
; DI void gdnout_item(const Params& p, int l, int item, float* red  ) {
;   const int tid = otid(), lane = tid & 63, wid = tid >> 6, lr = lane & 15, lq = lane >> 4;
;   const int n = item >> 2, h = item & 3, t0 = n * 64;
;   const bf16_t* Qp = (const bf16_t*)(p.ws + OFF_RC + 16 * MiB) + (size_t)item * 8192;
;   const bf16_t* ATp = (const bf16_t*)(p.ws + OFF_ATT) + (size_t)item * 4096;
;   const float* GCp = (const float*)(p.ws + OFF_GC) + (size_t)item * 64;
;   const bf16x8* SN = (const bf16x8*)(p.ws + OFF_HB);
;   const bf16x8* VN = (const bf16x8*)(p.ws + OFF_CQ + 16 * MiB);
;   const bf16_t* RZ = (const bf16_t*)(p.ws + OFF_RZ);
;   bf16_t* OC = (bf16_t*)(p.ws + OFF_CQ + 32 * MiB);
;   f32x4 O[4][2];
; #pragma unroll
;   for (int mi = 0; mi < 4; ++mi) { O[mi][0] = (f32x4){0.f, 0.f, 0.f, 0.f}; O[mi][1] = (f32x4){0.f, 0.f, 0.f, 0.f}; }
; #pragma unroll
;   for (int s = 0; s < 4; ++s) {
;     bf16x8 b0 = SN[(((size_t)item * 8 + 2 * wid) * 4 + s) * 64 + lane], b1 = SN[(((size_t)item * 8 + 2 * wid + 1) * 4 + s) * 64 + lane];
; #pragma unroll
;     for (int mi = 0; mi < 4; ++mi) {
;       bf16x8 aq = *(const bf16x8*)(Qp + (mi * 16 + lr) * 128 + s * 32 + lq * 8);
;       O[mi][0] = mfma16(aq, b0, O[mi][0]); O[mi][1] = mfma16(aq, b1, O[mi][1]);
;     }
;   }
.LBB0_310:
	s_and_b64 vcc, exec, s[36:37]
	s_cbranch_vccz .LBB0_305
	s_ashr_i32 s31, s30, 31
	s_lshl_b64 s[38:39], s[30:31], 14
	s_lshl_b64 s[18:19], s[30:31], 13
	s_add_u32 s36, s5, s18
	v_mov_b32_e32 v65, v201
	s_addc_u32 s37, s6, s19
	s_lshl_b64 s[40:41], s[30:31], 8
	s_add_u32 s18, s9, s38
	v_ashrrev_i32_e32 v66, 6, v65
	s_addc_u32 s19, s10, s39
	v_lshlrev_b32_e32 v20, 1, v66
	s_lshl_b64 s[44:45], s[30:31], 15
	v_ashrrev_i32_e32 v21, 31, v20
	s_add_u32 s44, s7, s44
	v_and_b32_e32 v0, 63, v65
	v_and_b32_e32 v64, 15, v65
	v_lshlrev_b64 v[2:3], 12, v[20:21]
	s_addc_u32 s45, s8, s45
	v_and_b32_e32 v54, 48, v65
	v_mov_b32_e32 v55, v1
	v_lshl_add_u64 v[2:3], s[44:45], 0, v[2:3]
	v_lshlrev_b32_e32 v0, 4, v0
	v_lshl_add_u64 v[12:13], s[18:19], 0, v[54:55]
	v_lshlrev_b32_e32 v8, 8, v64
	v_mov_b32_e32 v9, v1
	v_lshl_add_u64 v[10:11], v[2:3], 0, v[0:1]
	v_lshl_add_u64 v[6:7], v[12:13], 0, v[8:9]
	global_load_dwordx4 v[22:25], v[10:11], off
	global_load_dwordx4 v[2:5], v[6:7], off
	v_add_co_u32_e32 v14, vcc, s59, v10
	v_lshlrev_b32_e32 v18, 7, v64
	s_nop 0
	v_addc_co_u32_e32 v15, vcc, 0, v11, vcc
	global_load_dwordx4 v[26:29], v[14:15], off
	v_or_b32_e32 v56, 0x1000, v18
	v_or_b32_e32 v58, 0x1800, v18
	s_mov_b64 s[18:19], 0x80
	s_add_u32 s40, s11, s40
	s_addc_u32 s41, s12, s41
	v_lshlrev_b64 v[20:21], 11, v[20:21]
	v_mov_b32_e32 v19, v1
	v_mov_b32_e32 v57, v1
	v_mov_b32_e32 v59, v1
	s_waitcnt vmcnt(1)
	v_mfma_f32_16x16x32_bf16 v[30:33], v[2:5], v[22:25], 0
	s_waitcnt vmcnt(0)
	v_mfma_f32_16x16x32_bf16 v[34:37], v[2:5], v[26:29], 0
	v_or_b32_e32 v2, 0x1000, v8
	v_mov_b32_e32 v3, v1
	v_lshl_add_u64 v[4:5], v[12:13], 0, v[2:3]
	global_load_dwordx4 v[38:41], v[4:5], off
	v_lshlrev_b32_e32 v4, 1, v56
	v_mov_b32_e32 v5, v1
	v_lshl_add_u64 v[8:9], v[12:13], 0, v[4:5]
	global_load_dwordx4 v[46:49], v[8:9], off
	v_lshlrev_b32_e32 v8, 1, v58
	v_mov_b32_e32 v9, v1
	v_lshl_add_u64 v[16:17], v[12:13], 0, v[8:9]
	global_load_dwordx4 v[68:71], v[16:17], off
	v_lshl_add_u64 v[16:17], v[12:13], 0, 64
	v_lshl_add_u64 v[60:61], v[16:17], 0, v[2:3]
	s_waitcnt vmcnt(2)
	v_mfma_f32_16x16x32_bf16 v[42:45], v[38:41], v[22:25], 0
	v_mfma_f32_16x16x32_bf16 v[38:41], v[38:41], v[26:29], 0
	s_waitcnt vmcnt(1)
	v_mfma_f32_16x16x32_bf16 v[50:53], v[46:49], v[22:25], 0
	v_mfma_f32_16x16x32_bf16 v[46:49], v[46:49], v[26:29], 0
	s_waitcnt vmcnt(0)
	v_mfma_f32_16x16x32_bf16 v[22:25], v[68:71], v[22:25], 0
	v_mfma_f32_16x16x32_bf16 v[26:29], v[68:71], v[26:29], 0
	global_load_dwordx4 v[68:71], v[10:11], off offset:1024
	global_load_dwordx4 v[72:75], v[14:15], off offset:1024
	global_load_dwordx4 v[76:79], v[6:7], off offset:64
	s_waitcnt vmcnt(0)
	v_mfma_f32_16x16x32_bf16 v[30:33], v[76:79], v[68:71], v[30:33]
	v_mfma_f32_16x16x32_bf16 v[34:37], v[76:79], v[72:75], v[34:37]
	global_load_dwordx4 v[76:79], v[60:61], off
	v_lshl_add_u64 v[60:61], v[16:17], 0, v[4:5]
	v_lshl_add_u64 v[16:17], v[16:17], 0, v[8:9]
	s_waitcnt vmcnt(0)
	v_mfma_f32_16x16x32_bf16 v[42:45], v[76:79], v[68:71], v[42:45]
	v_mfma_f32_16x16x32_bf16 v[38:41], v[76:79], v[72:75], v[38:41]
	global_load_dwordx4 v[76:79], v[60:61], off
	s_waitcnt vmcnt(0)
	v_mfma_f32_16x16x32_bf16 v[50:53], v[76:79], v[68:71], v[50:53]
	v_mfma_f32_16x16x32_bf16 v[46:49], v[76:79], v[72:75], v[46:49]
	global_load_dwordx4 v[76:79], v[16:17], off
	v_lshl_add_u64 v[16:17], v[12:13], 0, s[18:19]
	v_lshl_add_u64 v[60:61], v[16:17], 0, v[2:3]
	s_mov_b64 s[18:19], 0xc0
	s_waitcnt vmcnt(0)
	v_mfma_f32_16x16x32_bf16 v[22:25], v[76:79], v[68:71], v[22:25]
	v_mfma_f32_16x16x32_bf16 v[26:29], v[76:79], v[72:75], v[26:29]
	global_load_dwordx4 v[68:71], v[10:11], off offset:2048
	global_load_dwordx4 v[72:75], v[14:15], off offset:2048
	global_load_dwordx4 v[76:79], v[6:7], off offset:128
	s_waitcnt vmcnt(0)
	v_mfma_f32_16x16x32_bf16 v[30:33], v[76:79], v[68:71], v[30:33]
	v_mfma_f32_16x16x32_bf16 v[34:37], v[76:79], v[72:75], v[34:37]
	global_load_dwordx4 v[76:79], v[60:61], off
	v_lshl_add_u64 v[60:61], v[16:17], 0, v[4:5]
	v_lshl_add_u64 v[16:17], v[16:17], 0, v[8:9]
	s_waitcnt vmcnt(0)
	v_mfma_f32_16x16x32_bf16 v[42:45], v[76:79], v[68:71], v[42:45]
	v_mfma_f32_16x16x32_bf16 v[38:41], v[76:79], v[72:75], v[38:41]
	global_load_dwordx4 v[76:79], v[60:61], off
	v_lshl_add_u64 v[60:61], v[12:13], 0, s[18:19]
	v_lshl_add_u64 v[2:3], v[60:61], 0, v[2:3]
	s_add_u32 s18, s13, s38
	s_addc_u32 s19, s14, s39
	v_lshl_add_u64 v[20:21], s[18:19], 0, v[20:21]
	s_waitcnt vmcnt(0)
	v_mfma_f32_16x16x32_bf16 v[50:53], v[76:79], v[68:71], v[50:53]
	v_mfma_f32_16x16x32_bf16 v[46:49], v[76:79], v[72:75], v[46:49]
	global_load_dwordx4 v[76:79], v[16:17], off
	s_waitcnt vmcnt(0)
	v_mfma_f32_16x16x32_bf16 v[22:25], v[76:79], v[68:71], v[22:25]
	global_load_dwordx4 v[68:71], v[10:11], off offset:3072
	s_nop 0
	global_load_dwordx4 v[14:17], v[14:15], off offset:3072
	s_nop 0
	global_load_dwordx4 v[10:13], v[6:7], off offset:192
	v_mfma_f32_16x16x32_bf16 v[26:29], v[76:79], v[72:75], v[26:29]
	s_waitcnt vmcnt(0)
	v_mfma_f32_16x16x32_bf16 v[30:33], v[10:13], v[68:71], v[30:33]
	v_mfma_f32_16x16x32_bf16 v[10:13], v[10:13], v[14:17], v[34:37]
	s_nop 2
	global_load_dwordx4 v[34:37], v[2:3], off
	v_lshl_add_u64 v[2:3], v[60:61], 0, v[4:5]
	global_load_dwordx4 v[2:5], v[2:3], off
	s_waitcnt vmcnt(1)
	v_mfma_f32_16x16x32_bf16 v[42:45], v[34:37], v[68:71], v[42:45]
	v_mfma_f32_16x16x32_bf16 v[34:37], v[34:37], v[14:17], v[38:41]
	s_waitcnt vmcnt(0)
	v_mfma_f32_16x16x32_bf16 v[38:41], v[2:5], v[68:71], v[50:53]
	v_mfma_f32_16x16x32_bf16 v[46:49], v[2:5], v[14:17], v[46:49]
	v_lshl_add_u64 v[2:3], v[60:61], 0, v[8:9]
	global_load_dwordx4 v[2:5], v[2:3], off
	v_lshl_add_u64 v[60:61], s[36:37], 0, v[54:55]
	s_waitcnt vmcnt(0)
; DI f32x4 mfma16(bf16x8 a, bf16x8 b, f32x4 c) { return __builtin_amdgcn_mfma_f32_16x16x32_bf16(a, b, c, 0, 0, 0); }
; DI void gdnout_item(const Params& p, int l, int item, float* red  ) {
;     ...
; #pragma unroll
;   for (int mi = 0; mi < 4; ++mi) {
;     f32x4 g = *(const f32x4*)(GCp + mi * 16 + lq * 4);
; #pragma unroll
;     for (int r = 0; r < 4; ++r) { float e = __expf(g[r]); O[mi][0][r] *= e; O[mi][1][r] *= e; }
;   }
; #pragma unroll
;   for (int s2 = 0; s2 < 2; ++s2) {
;     bf16x8 b0 = VN[(((size_t)item * 8 + 2 * wid) * 2 + s2) * 64 + lane], b1 = VN[(((size_t)item * 8 + 2 * wid + 1) * 2 + s2) * 64 + lane];
; #pragma unroll
;     for (int mi = 0; mi < 4; ++mi) {
;       bf16x8 aa = *(const bf16x8*)(ATp + (mi * 16 + lr) * 64 + s2 * 32 + lq * 8);
;       O[mi][0] = mfma16(aa, b0, O[mi][0]); O[mi][1] = mfma16(aa, b1, O[mi][1]);
;     }
;   }
;   __syncthreads();
; #pragma unroll
;   for (int mi = 0; mi < 4; ++mi)
; #pragma unroll
;     for (int r = 0; r < 4; ++r) {
;       float ss = O[mi][0][r] * O[mi][0][r] + O[mi][1][r] * O[mi][1][r];
;       ss += __shfl_xor(ss, 1); ss += __shfl_xor(ss, 2); ss += __shfl_xor(ss, 4); ss += __shfl_xor(ss, 8);
;       if (lr == 0) red[wid * 64 + mi * 16 + lq * 4 + r] = ss;
;     }
	v_mfma_f32_16x16x32_bf16 v[22:25], v[2:5], v[68:71], v[22:25]
	v_lshl_add_u64 v[50:51], v[20:21], 0, v[0:1]
	v_lshl_add_u64 v[72:73], v[60:61], 0, v[18:19]
	v_xor_b32_e32 v0, 1, v227
	v_mfma_f32_16x16x32_bf16 v[26:29], v[2:5], v[14:17], v[26:29]
	global_load_dwordx4 v[2:5], v54, s[40:41]
	s_waitcnt vmcnt(0)
	v_mul_f32_e32 v2, 0x3fb8aa3b, v2
	v_exp_f32_e32 v6, v2
	v_mul_f32_e32 v2, 0x3fb8aa3b, v3
	v_exp_f32_e32 v7, v2
	v_mul_f32_e32 v2, 0x3fb8aa3b, v4
	v_exp_f32_e32 v8, v2
	v_mul_f32_e32 v2, 0x3fb8aa3b, v5
	v_exp_f32_e32 v9, v2
	v_pk_mul_f32 v[2:3], v[30:31], v[6:7]
	v_pk_mul_f32 v[6:7], v[10:11], v[6:7]
	v_pk_mul_f32 v[4:5], v[32:33], v[8:9]
	v_pk_mul_f32 v[8:9], v[12:13], v[8:9]
	global_load_dwordx4 v[10:13], v54, s[40:41] offset:64
	global_load_dwordx4 v[30:33], v54, s[40:41] offset:128
	s_waitcnt vmcnt(1)
	v_mul_f32_e32 v10, 0x3fb8aa3b, v10
	v_exp_f32_e32 v14, v10
	v_mul_f32_e32 v10, 0x3fb8aa3b, v11
	v_exp_f32_e32 v15, v10
	v_mul_f32_e32 v10, 0x3fb8aa3b, v12
	v_exp_f32_e32 v16, v10
	v_mul_f32_e32 v10, 0x3fb8aa3b, v13
	v_exp_f32_e32 v17, v10
	s_waitcnt vmcnt(0)
	v_mul_f32_e32 v30, 0x3fb8aa3b, v30
	v_pk_mul_f32 v[10:11], v[42:43], v[14:15]
	v_pk_mul_f32 v[14:15], v[34:35], v[14:15]
	v_exp_f32_e32 v34, v30
	v_mul_f32_e32 v30, 0x3fb8aa3b, v31
	v_exp_f32_e32 v35, v30
	v_mul_f32_e32 v30, 0x3fb8aa3b, v32
	v_pk_mul_f32 v[12:13], v[44:45], v[16:17]
	v_pk_mul_f32 v[16:17], v[36:37], v[16:17]
	v_exp_f32_e32 v36, v30
	v_mul_f32_e32 v30, 0x3fb8aa3b, v33
	v_exp_f32_e32 v37, v30
	v_pk_mul_f32 v[30:31], v[38:39], v[34:35]
	v_pk_mul_f32 v[34:35], v[46:47], v[34:35]
	v_pk_mul_f32 v[32:33], v[40:41], v[36:37]
	global_load_dwordx4 v[38:41], v54, s[40:41] offset:192
	v_pk_mul_f32 v[36:37], v[48:49], v[36:37]
	s_waitcnt vmcnt(0)
	v_mul_f32_e32 v38, 0x3fb8aa3b, v38
	v_mul_f32_e32 v39, 0x3fb8aa3b, v39
	v_mul_f32_e32 v40, 0x3fb8aa3b, v40
	v_mul_f32_e32 v41, 0x3fb8aa3b, v41
	v_exp_f32_e32 v38, v38
	v_exp_f32_e32 v39, v39
	v_exp_f32_e32 v40, v40
	v_exp_f32_e32 v41, v41
	v_pk_mul_f32 v[22:23], v[22:23], v[38:39]
	v_pk_mul_f32 v[26:27], v[26:27], v[38:39]
	v_pk_mul_f32 v[24:25], v[24:25], v[40:41]
	v_pk_mul_f32 v[28:29], v[28:29], v[40:41]
	global_load_dwordx4 v[38:41], v[50:51], off
	global_load_dwordx4 v[42:45], v[50:51], off offset:2048
	global_load_dwordx4 v[18:21], v[72:73], off
	s_waitcnt vmcnt(0)
	v_mfma_f32_16x16x32_bf16 v[68:71], v[18:21], v[38:41], v[2:5]
	v_mfma_f32_16x16x32_bf16 v[18:21], v[18:21], v[42:45], v[6:9]
	s_nop 2
	global_load_dwordx4 v[6:9], v[72:73], off offset:2048
	s_waitcnt vmcnt(0)
	v_mfma_f32_16x16x32_bf16 v[2:5], v[6:9], v[38:41], v[10:13]
	s_nop 2
	v_lshl_add_u64 v[10:11], v[60:61], 0, v[56:57]
	v_mfma_f32_16x16x32_bf16 v[6:9], v[6:9], v[42:45], v[14:17]
	s_nop 2
	global_load_dwordx4 v[14:17], v[10:11], off
	s_waitcnt vmcnt(0)
	v_mfma_f32_16x16x32_bf16 v[10:13], v[14:17], v[38:41], v[30:33]
	v_mfma_f32_16x16x32_bf16 v[34:37], v[14:17], v[42:45], v[34:37]
	v_lshl_add_u64 v[14:15], v[60:61], 0, v[58:59]
	global_load_dwordx4 v[14:17], v[14:15], off
	s_nop 0
	global_load_dwordx4 v[46:49], v[50:51], off offset:1024
	s_nop 0
	global_load_dwordx4 v[50:53], v[50:51], off offset:3072
	s_waitcnt vmcnt(2)
	v_mfma_f32_16x16x32_bf16 v[38:41], v[14:17], v[38:41], v[22:25]
	v_lshl_add_u64 v[60:61], v[60:61], 0, 64
	v_mfma_f32_16x16x32_bf16 v[42:45], v[14:17], v[42:45], v[26:29]
	global_load_dwordx4 v[14:17], v[72:73], off offset:64
	s_waitcnt vmcnt(0)
	v_mfma_f32_16x16x32_bf16 v[30:33], v[14:17], v[46:49], v[68:71]
	v_mfma_f32_16x16x32_bf16 v[26:29], v[14:17], v[50:53], v[18:21]
	global_load_dwordx4 v[14:17], v[72:73], off offset:2112
	s_waitcnt vmcnt(0)
	v_mfma_f32_16x16x32_bf16 v[22:25], v[14:17], v[46:49], v[2:5]
	s_nop 2
	v_lshl_add_u64 v[2:3], v[60:61], 0, v[56:57]
	global_load_dwordx4 v[2:5], v[2:3], off
	v_mfma_f32_16x16x32_bf16 v[18:21], v[14:17], v[50:53], v[6:9]
	s_waitcnt vmcnt(0)
	v_mfma_f32_16x16x32_bf16 v[14:17], v[2:5], v[46:49], v[10:13]
	v_mfma_f32_16x16x32_bf16 v[10:13], v[2:5], v[50:53], v[34:37]
	v_lshl_add_u64 v[2:3], v[60:61], 0, v[58:59]
	global_load_dwordx4 v[2:5], v[2:3], off
	s_nop 0
	v_and_b32_e32 v34, 64, v227
	v_add_u32_e32 v34, 64, v34
	v_cmp_lt_i32_e32 vcc, v0, v34
	s_waitcnt vmcnt(0)
	v_mfma_f32_16x16x32_bf16 v[6:9], v[2:5], v[46:49], v[38:41]
	v_cndmask_b32_e32 v0, v227, v0, vcc
	s_nop 1
	v_mul_f32_e32 v38, v26, v26
	v_lshlrev_b32_e32 v0, 2, v0
	v_fmac_f32_e32 v38, v30, v30
	s_nop 1
	v_add_f32_dpp v38, v38, v38 quad_perm:[1,0,3,2] row_mask:0xf bank_mask:0xf
	v_xor_b32_e32 v35, 2, v227
	v_cmp_lt_i32_e32 vcc, v35, v34
	v_xor_b32_e32 v36, 4, v227
	v_xor_b32_e32 v37, 8, v227
	v_cndmask_b32_e32 v35, v227, v35, vcc
	v_lshlrev_b32_e32 v35, 2, v35
	s_waitcnt lgkmcnt(0)
	s_nop 1
	v_add_f32_dpp v38, v38, v38 quad_perm:[2,3,0,1] row_mask:0xf bank_mask:0xf
	v_cmp_lt_i32_e32 vcc, v36, v34
	v_mfma_f32_16x16x32_bf16 v[2:5], v[2:5], v[50:53], v[42:45]
	s_barrier
	v_cndmask_b32_e32 v36, v227, v36, vcc
	v_lshlrev_b32_e32 v36, 2, v36
	s_waitcnt lgkmcnt(0)
	s_nop 1
	v_add_f32_dpp v38, v38, v38 row_half_mirror row_mask:0xf bank_mask:0xf
	v_cmp_lt_i32_e32 vcc, v37, v34
	s_waitcnt lgkmcnt(0)
	v_cndmask_b32_e32 v34, v227, v37, vcc
	v_lshlrev_b32_e32 v37, 2, v34
	s_nop 1
	v_add_f32_dpp v38, v38, v38 row_mirror row_mask:0xf bank_mask:0xf
	v_and_b32_e32 v34, 0x3fffffc0, v65
	v_cmp_eq_u32_e32 vcc, 0, v64
	v_lshlrev_b32_e32 v34, 2, v34
	s_and_saveexec_b64 s[36:37], vcc
	s_cbranch_execz .LBB0_313
	s_waitcnt lgkmcnt(0)
	v_add_u32_e32 v39, v34, v54
	ds_write_b32 v39, v38
; DI void gdnout_item(const Params& p, int l, int item, float* red  ) {
;     ...
; #pragma unroll
;   for (int mi = 0; mi < 4; ++mi)
; #pragma unroll
;     for (int r = 0; r < 4; ++r) {
;       float ss = O[mi][0][r] * O[mi][0][r] + O[mi][1][r] * O[mi][1][r];
;       ss += __shfl_xor(ss, 1); ss += __shfl_xor(ss, 2); ss += __shfl_xor(ss, 4); ss += __shfl_xor(ss, 8);
;       if (lr == 0) red[wid * 64 + mi * 16 + lq * 4 + r] = ss;
;     }
.LBB0_313:
	s_or_b64 exec, exec, s[36:37]
	v_mul_f32_e32 v38, v27, v27
	v_fmac_f32_e32 v38, v31, v31
	s_waitcnt lgkmcnt(0)
	s_nop 1
	v_add_f32_dpp v38, v38, v38 quad_perm:[1,0,3,2] row_mask:0xf bank_mask:0xf
	s_waitcnt lgkmcnt(0)
	s_nop 1
	v_add_f32_dpp v38, v38, v38 quad_perm:[2,3,0,1] row_mask:0xf bank_mask:0xf
	s_waitcnt lgkmcnt(0)
	s_nop 1
	v_add_f32_dpp v38, v38, v38 row_half_mirror row_mask:0xf bank_mask:0xf
	s_waitcnt lgkmcnt(0)
	s_nop 1
	v_add_f32_dpp v38, v38, v38 row_mirror row_mask:0xf bank_mask:0xf
	s_and_saveexec_b64 s[36:37], vcc
	s_cbranch_execz .LBB0_315
	s_waitcnt lgkmcnt(0)
	v_add_u32_e32 v39, v34, v54
	ds_write_b32 v39, v38 offset:4
.LBB0_315:
	s_or_b64 exec, exec, s[36:37]
	v_mul_f32_e32 v38, v28, v28
	v_fmac_f32_e32 v38, v32, v32
	s_waitcnt lgkmcnt(0)
	s_nop 1
	v_add_f32_dpp v38, v38, v38 quad_perm:[1,0,3,2] row_mask:0xf bank_mask:0xf
	s_waitcnt lgkmcnt(0)
	s_nop 1
	v_add_f32_dpp v38, v38, v38 quad_perm:[2,3,0,1] row_mask:0xf bank_mask:0xf
	s_waitcnt lgkmcnt(0)
	s_nop 1
	v_add_f32_dpp v38, v38, v38 row_half_mirror row_mask:0xf bank_mask:0xf
	s_waitcnt lgkmcnt(0)
	s_nop 1
	v_add_f32_dpp v38, v38, v38 row_mirror row_mask:0xf bank_mask:0xf
	s_and_saveexec_b64 s[36:37], vcc
	s_cbranch_execz .LBB0_317
	s_waitcnt lgkmcnt(0)
	v_add_u32_e32 v39, v34, v54
	ds_write_b32 v39, v38 offset:8
.LBB0_317:
	s_or_b64 exec, exec, s[36:37]
	v_mul_f32_e32 v38, v29, v29
	v_fmac_f32_e32 v38, v33, v33
	s_waitcnt lgkmcnt(0)
	s_nop 1
	v_add_f32_dpp v38, v38, v38 quad_perm:[1,0,3,2] row_mask:0xf bank_mask:0xf
	s_waitcnt lgkmcnt(0)
	s_nop 1
	v_add_f32_dpp v38, v38, v38 quad_perm:[2,3,0,1] row_mask:0xf bank_mask:0xf
	s_waitcnt lgkmcnt(0)
	s_nop 1
	v_add_f32_dpp v38, v38, v38 row_half_mirror row_mask:0xf bank_mask:0xf
	s_waitcnt lgkmcnt(0)
	s_nop 1
	v_add_f32_dpp v38, v38, v38 row_mirror row_mask:0xf bank_mask:0xf
	s_and_saveexec_b64 s[36:37], vcc
	s_cbranch_execz .LBB0_319
	s_waitcnt lgkmcnt(0)
	v_add_u32_e32 v39, v34, v54
	ds_write_b32 v39, v38 offset:12
.LBB0_319:
	s_or_b64 exec, exec, s[36:37]
	v_mul_f32_e32 v38, v18, v18
	v_fmac_f32_e32 v38, v22, v22
	s_waitcnt lgkmcnt(0)
	s_nop 1
	v_add_f32_dpp v38, v38, v38 quad_perm:[1,0,3,2] row_mask:0xf bank_mask:0xf
	s_waitcnt lgkmcnt(0)
	s_nop 1
	v_add_f32_dpp v38, v38, v38 quad_perm:[2,3,0,1] row_mask:0xf bank_mask:0xf
	s_waitcnt lgkmcnt(0)
	s_nop 1
	v_add_f32_dpp v38, v38, v38 row_half_mirror row_mask:0xf bank_mask:0xf
	s_waitcnt lgkmcnt(0)
	s_nop 1
	v_add_f32_dpp v38, v38, v38 row_mirror row_mask:0xf bank_mask:0xf
	s_and_saveexec_b64 s[36:37], vcc
	s_cbranch_execz .LBB0_321
	s_waitcnt lgkmcnt(0)
	v_add_u32_e32 v39, v34, v54
	ds_write_b32 v39, v38 offset:64
.LBB0_321:
	s_or_b64 exec, exec, s[36:37]
	v_mul_f32_e32 v38, v19, v19
	v_fmac_f32_e32 v38, v23, v23
	s_waitcnt lgkmcnt(0)
	s_nop 1
	v_add_f32_dpp v38, v38, v38 quad_perm:[1,0,3,2] row_mask:0xf bank_mask:0xf
	s_waitcnt lgkmcnt(0)
	s_nop 1
	v_add_f32_dpp v38, v38, v38 quad_perm:[2,3,0,1] row_mask:0xf bank_mask:0xf
	s_waitcnt lgkmcnt(0)
	s_nop 1
	v_add_f32_dpp v38, v38, v38 row_half_mirror row_mask:0xf bank_mask:0xf
	s_waitcnt lgkmcnt(0)
	s_nop 1
	v_add_f32_dpp v38, v38, v38 row_mirror row_mask:0xf bank_mask:0xf
	s_and_saveexec_b64 s[36:37], vcc
	s_cbranch_execz .LBB0_323
	s_waitcnt lgkmcnt(0)
	v_add_u32_e32 v39, v34, v54
	ds_write_b32 v39, v38 offset:68
.LBB0_323:
	s_or_b64 exec, exec, s[36:37]
	v_mul_f32_e32 v38, v20, v20
	v_fmac_f32_e32 v38, v24, v24
	s_waitcnt lgkmcnt(0)
	s_nop 1
	v_add_f32_dpp v38, v38, v38 quad_perm:[1,0,3,2] row_mask:0xf bank_mask:0xf
	s_waitcnt lgkmcnt(0)
	s_nop 1
	v_add_f32_dpp v38, v38, v38 quad_perm:[2,3,0,1] row_mask:0xf bank_mask:0xf
	s_waitcnt lgkmcnt(0)
	s_nop 1
	v_add_f32_dpp v38, v38, v38 row_half_mirror row_mask:0xf bank_mask:0xf
	s_waitcnt lgkmcnt(0)
	s_nop 1
	v_add_f32_dpp v38, v38, v38 row_mirror row_mask:0xf bank_mask:0xf
	s_and_saveexec_b64 s[36:37], vcc
	s_cbranch_execz .LBB0_325
	s_waitcnt lgkmcnt(0)
	v_add_u32_e32 v39, v34, v54
	ds_write_b32 v39, v38 offset:72
.LBB0_325:
	s_or_b64 exec, exec, s[36:37]
	v_mul_f32_e32 v38, v21, v21
	v_fmac_f32_e32 v38, v25, v25
	s_waitcnt lgkmcnt(0)
	s_nop 1
	v_add_f32_dpp v38, v38, v38 quad_perm:[1,0,3,2] row_mask:0xf bank_mask:0xf
	s_waitcnt lgkmcnt(0)
	s_nop 1
	v_add_f32_dpp v38, v38, v38 quad_perm:[2,3,0,1] row_mask:0xf bank_mask:0xf
	s_waitcnt lgkmcnt(0)
	s_nop 1
	v_add_f32_dpp v38, v38, v38 row_half_mirror row_mask:0xf bank_mask:0xf
	s_waitcnt lgkmcnt(0)
	s_nop 1
	v_add_f32_dpp v38, v38, v38 row_mirror row_mask:0xf bank_mask:0xf
	s_and_saveexec_b64 s[36:37], vcc
	s_cbranch_execz .LBB0_327
	s_waitcnt lgkmcnt(0)
	v_add_u32_e32 v39, v34, v54
	ds_write_b32 v39, v38 offset:76
; DI void gdnout_item(const Params& p, int l, int item, float* red  ) {
;     ...
; #pragma unroll
;   for (int mi = 0; mi < 4; ++mi)
; #pragma unroll
;     for (int r = 0; r < 4; ++r) {
;       float ss = O[mi][0][r] * O[mi][0][r] + O[mi][1][r] * O[mi][1][r];
;       ss += __shfl_xor(ss, 1); ss += __shfl_xor(ss, 2); ss += __shfl_xor(ss, 4); ss += __shfl_xor(ss, 8);
;       if (lr == 0) red[wid * 64 + mi * 16 + lq * 4 + r] = ss;
;     }
.LBB0_327:
	s_or_b64 exec, exec, s[36:37]
	v_mul_f32_e32 v38, v10, v10
	v_fmac_f32_e32 v38, v14, v14
	s_waitcnt lgkmcnt(0)
	s_nop 1
	v_add_f32_dpp v38, v38, v38 quad_perm:[1,0,3,2] row_mask:0xf bank_mask:0xf
	s_waitcnt lgkmcnt(0)
	s_nop 1
	v_add_f32_dpp v38, v38, v38 quad_perm:[2,3,0,1] row_mask:0xf bank_mask:0xf
	s_waitcnt lgkmcnt(0)
	s_nop 1
	v_add_f32_dpp v38, v38, v38 row_half_mirror row_mask:0xf bank_mask:0xf
	s_waitcnt lgkmcnt(0)
	s_nop 1
	v_add_f32_dpp v38, v38, v38 row_mirror row_mask:0xf bank_mask:0xf
	s_and_saveexec_b64 s[36:37], vcc
	s_cbranch_execz .LBB0_329
	s_waitcnt lgkmcnt(0)
	v_add_u32_e32 v39, v34, v54
	ds_write_b32 v39, v38 offset:128
.LBB0_329:
	s_or_b64 exec, exec, s[36:37]
	v_mul_f32_e32 v38, v11, v11
	v_fmac_f32_e32 v38, v15, v15
	s_waitcnt lgkmcnt(0)
	s_nop 1
	v_add_f32_dpp v38, v38, v38 quad_perm:[1,0,3,2] row_mask:0xf bank_mask:0xf
	s_waitcnt lgkmcnt(0)
	s_nop 1
	v_add_f32_dpp v38, v38, v38 quad_perm:[2,3,0,1] row_mask:0xf bank_mask:0xf
	s_waitcnt lgkmcnt(0)
	s_nop 1
	v_add_f32_dpp v38, v38, v38 row_half_mirror row_mask:0xf bank_mask:0xf
	s_waitcnt lgkmcnt(0)
	s_nop 1
	v_add_f32_dpp v38, v38, v38 row_mirror row_mask:0xf bank_mask:0xf
	s_and_saveexec_b64 s[36:37], vcc
	s_cbranch_execz .LBB0_331
	s_waitcnt lgkmcnt(0)
	v_add_u32_e32 v39, v34, v54
	ds_write_b32 v39, v38 offset:132
.LBB0_331:
	s_or_b64 exec, exec, s[36:37]
	v_mul_f32_e32 v38, v12, v12
	v_fmac_f32_e32 v38, v16, v16
	s_waitcnt lgkmcnt(0)
	s_nop 1
	v_add_f32_dpp v38, v38, v38 quad_perm:[1,0,3,2] row_mask:0xf bank_mask:0xf
	s_waitcnt lgkmcnt(0)
	s_nop 1
	v_add_f32_dpp v38, v38, v38 quad_perm:[2,3,0,1] row_mask:0xf bank_mask:0xf
	s_waitcnt lgkmcnt(0)
	s_nop 1
	v_add_f32_dpp v38, v38, v38 row_half_mirror row_mask:0xf bank_mask:0xf
	s_waitcnt lgkmcnt(0)
	s_nop 1
	v_add_f32_dpp v38, v38, v38 row_mirror row_mask:0xf bank_mask:0xf
	s_and_saveexec_b64 s[36:37], vcc
	s_cbranch_execz .LBB0_333
	s_waitcnt lgkmcnt(0)
	v_add_u32_e32 v39, v34, v54
	ds_write_b32 v39, v38 offset:136
.LBB0_333:
	s_or_b64 exec, exec, s[36:37]
	v_mul_f32_e32 v38, v13, v13
	v_fmac_f32_e32 v38, v17, v17
	s_waitcnt lgkmcnt(0)
	s_nop 1
	v_add_f32_dpp v38, v38, v38 quad_perm:[1,0,3,2] row_mask:0xf bank_mask:0xf
	s_waitcnt lgkmcnt(0)
	s_nop 1
	v_add_f32_dpp v38, v38, v38 quad_perm:[2,3,0,1] row_mask:0xf bank_mask:0xf
	s_waitcnt lgkmcnt(0)
	s_nop 1
	v_add_f32_dpp v38, v38, v38 row_half_mirror row_mask:0xf bank_mask:0xf
	s_waitcnt lgkmcnt(0)
	s_nop 1
	v_add_f32_dpp v38, v38, v38 row_mirror row_mask:0xf bank_mask:0xf
	s_and_saveexec_b64 s[36:37], vcc
	s_cbranch_execz .LBB0_335
	s_waitcnt lgkmcnt(0)
	v_add_u32_e32 v39, v34, v54
	ds_write_b32 v39, v38 offset:140
.LBB0_335:
	s_or_b64 exec, exec, s[36:37]
	v_mul_f32_e32 v38, v2, v2
	v_fmac_f32_e32 v38, v6, v6
	s_waitcnt lgkmcnt(0)
	s_nop 1
	v_add_f32_dpp v38, v38, v38 quad_perm:[1,0,3,2] row_mask:0xf bank_mask:0xf
	s_waitcnt lgkmcnt(0)
	s_nop 1
	v_add_f32_dpp v38, v38, v38 quad_perm:[2,3,0,1] row_mask:0xf bank_mask:0xf
	s_waitcnt lgkmcnt(0)
	s_nop 1
	v_add_f32_dpp v38, v38, v38 row_half_mirror row_mask:0xf bank_mask:0xf
	s_waitcnt lgkmcnt(0)
	s_nop 1
	v_add_f32_dpp v38, v38, v38 row_mirror row_mask:0xf bank_mask:0xf
	s_and_saveexec_b64 s[36:37], vcc
	s_cbranch_execz .LBB0_337
	s_waitcnt lgkmcnt(0)
	v_add_u32_e32 v39, v34, v54
	ds_write_b32 v39, v38 offset:192
.LBB0_337:
	s_or_b64 exec, exec, s[36:37]
	v_mul_f32_e32 v38, v3, v3
	v_fmac_f32_e32 v38, v7, v7
	s_waitcnt lgkmcnt(0)
	s_nop 1
	v_add_f32_dpp v38, v38, v38 quad_perm:[1,0,3,2] row_mask:0xf bank_mask:0xf
	s_waitcnt lgkmcnt(0)
	s_nop 1
	v_add_f32_dpp v38, v38, v38 quad_perm:[2,3,0,1] row_mask:0xf bank_mask:0xf
	s_waitcnt lgkmcnt(0)
	s_nop 1
	v_add_f32_dpp v38, v38, v38 row_half_mirror row_mask:0xf bank_mask:0xf
	s_waitcnt lgkmcnt(0)
	s_nop 1
	v_add_f32_dpp v38, v38, v38 row_mirror row_mask:0xf bank_mask:0xf
	s_and_saveexec_b64 s[36:37], vcc
	s_cbranch_execz .LBB0_339
	s_waitcnt lgkmcnt(0)
	v_add_u32_e32 v39, v34, v54
	ds_write_b32 v39, v38 offset:196
.LBB0_339:
	s_or_b64 exec, exec, s[36:37]
	v_mul_f32_e32 v38, v4, v4
	v_fmac_f32_e32 v38, v8, v8
	s_waitcnt lgkmcnt(0)
	s_nop 1
	v_add_f32_dpp v38, v38, v38 quad_perm:[1,0,3,2] row_mask:0xf bank_mask:0xf
	s_waitcnt lgkmcnt(0)
	s_nop 1
	v_add_f32_dpp v38, v38, v38 quad_perm:[2,3,0,1] row_mask:0xf bank_mask:0xf
	s_waitcnt lgkmcnt(0)
	s_nop 1
	v_add_f32_dpp v38, v38, v38 row_half_mirror row_mask:0xf bank_mask:0xf
	s_waitcnt lgkmcnt(0)
	s_nop 1
	v_add_f32_dpp v38, v38, v38 row_mirror row_mask:0xf bank_mask:0xf
	s_and_saveexec_b64 s[36:37], vcc
	s_cbranch_execz .LBB0_341
	s_waitcnt lgkmcnt(0)
	v_add_u32_e32 v39, v34, v54
	ds_write_b32 v39, v38 offset:200
.LBB0_341:
	s_or_b64 exec, exec, s[36:37]
	v_mul_f32_e32 v38, v5, v5
	v_fmac_f32_e32 v38, v9, v9
	s_nop 1
	v_add_f32_dpp v0, v38, v38 quad_perm:[1,0,3,2] row_mask:0xf bank_mask:0xf
	s_waitcnt lgkmcnt(0)
	s_nop 1
	v_add_f32_dpp v0, v0, v0 quad_perm:[2,3,0,1] row_mask:0xf bank_mask:0xf
	s_waitcnt lgkmcnt(0)
	s_nop 1
	v_add_f32_dpp v0, v0, v0 row_half_mirror row_mask:0xf bank_mask:0xf
	s_waitcnt lgkmcnt(0)
	s_nop 1
	v_add_f32_dpp v0, v0, v0 row_mirror row_mask:0xf bank_mask:0xf
	s_and_saveexec_b64 s[36:37], vcc
	s_cbranch_execz .LBB0_304
	s_waitcnt lgkmcnt(0)
	v_add_u32_e32 v34, v34, v54
	ds_write_b32 v34, v0 offset:204
	s_branch .LBB0_304

; DI void gdnprep_item(const Params& p, int item, unsigned char* ldsb) {
;     ...
;     for (int i = 1; i < 64; ++i) {
;       float a = x[i];
; #pragma unroll
;       for (int j4 = 0; j4 < (i + 3) / 4; ++j4) {
;         f32x4 Lv = *(const f32x4*)(Lm + i * 64 + j4 * 4);
; #pragma unroll
;         for (int e = 0; e < 4; ++e) if (j4 * 4 + e < i) a -= Lv[e] * x[j4 * 4 + e];
;       }
;       x[i] = a;
;       if ((i & 3) == 3) __builtin_amdgcn_sched_barrier(0);
;     }
.Lxinit_done:
.LBB0_833:
	s_or_b64 exec, exec, s[0:1]
	ds_read_b128 v[100:103], v1 offset:35072
	ds_read_b128 v[104:107], v1 offset:35328
	ds_read_b128 v[108:111], v1 offset:35584
	ds_read_b128 v[112:115], v1 offset:35840
	ds_read_b128 v[116:119], v1 offset:36096
	ds_read_b128 v[120:123], v1 offset:36352
	ds_read_b128 v[124:127], v1 offset:36112
	ds_read_b128 v[128:131], v1 offset:36368
	ds_read_b128 v[132:135], v1 offset:36608
	ds_read_b128 v[136:139], v1 offset:36864
	ds_read_b128 v[140:143], v1 offset:36624
	ds_read_b128 v[144:147], v1 offset:36880
	ds_read_b128 v[148:151], v1 offset:37120
	ds_read_b128 v[152:155], v1 offset:37376
	s_waitcnt lgkmcnt(13)
	v_fma_f32 v4, -v0, v100, v4
	ds_read_b128 v[100:103], v1 offset:37136
	s_waitcnt lgkmcnt(13)
	v_fma_f32 v5, -v0, v104, v5
	v_fma_f32 v5, -v105, v4, v5
	ds_read_b128 v[104:107], v1 offset:37392
	s_waitcnt lgkmcnt(13)
	v_fma_f32 v6, -v0, v108, v6
	s_waitcnt lgkmcnt(12)
	v_fma_f32 v7, -v0, v112, v7
	v_fma_f32 v6, -v109, v4, v6
	v_fma_f32 v7, -v4, v113, v7
	v_fma_f32 v6, -v110, v5, v6
	ds_read_b128 v[108:111], v1 offset:37152
	v_fma_f32 v7, -v114, v5, v7
	v_fma_f32 v7, -v115, v6, v7
	ds_read_b128 v[112:115], v1 offset:37408
	s_waitcnt lgkmcnt(13)
	v_fma_f32 v8, -v0, v116, v8
	s_waitcnt lgkmcnt(12)
	v_fma_f32 v9, -v0, v120, v9
	v_fma_f32 v8, -v4, v117, v8
	v_fma_f32 v9, -v4, v121, v9
	v_fma_f32 v8, -v5, v118, v8
	v_fma_f32 v9, -v5, v122, v9
	v_fma_f32 v8, -v119, v6, v8
	ds_read_b128 v[116:119], v1 offset:37632
	v_fma_f32 v9, -v6, v123, v9
	ds_read_b128 v[120:123], v1 offset:37888
	s_waitcnt lgkmcnt(13)
	v_fma_f32 v8, -v124, v7, v8
	ds_read_b128 v[124:127], v1 offset:37648
	s_waitcnt lgkmcnt(13)
	v_fma_f32 v9, -v128, v7, v9
	v_fma_f32 v9, -v129, v8, v9
	ds_read_b128 v[128:131], v1 offset:37904
	s_waitcnt lgkmcnt(13)
	v_fma_f32 v10, -v0, v132, v10
	s_waitcnt lgkmcnt(12)
	v_fma_f32 v11, -v0, v136, v11
	v_fma_f32 v10, -v4, v133, v10
	v_fma_f32 v11, -v4, v137, v11
	v_fma_f32 v10, -v5, v134, v10
	v_fma_f32 v11, -v5, v138, v11
	v_fma_f32 v10, -v6, v135, v10
	ds_read_b128 v[132:135], v1 offset:37664
	v_fma_f32 v11, -v6, v139, v11
	ds_read_b128 v[136:139], v1 offset:38144
	s_waitcnt lgkmcnt(13)
	v_fma_f32 v10, -v7, v140, v10
	s_waitcnt lgkmcnt(12)
	v_fma_f32 v11, -v7, v144, v11
	v_fma_f32 v10, -v141, v8, v10
	v_fma_f32 v11, -v8, v145, v11
	v_fma_f32 v10, -v142, v9, v10
	ds_read_b128 v[140:143], v1 offset:37920
	v_fma_f32 v11, -v146, v9, v11
	v_fma_f32 v11, -v147, v10, v11
	ds_read_b128 v[144:147], v1 offset:38160
	s_waitcnt lgkmcnt(13)
	v_fma_f32 v12, -v0, v148, v12
	s_waitcnt lgkmcnt(12)
	v_fma_f32 v13, -v0, v152, v13
	v_fma_f32 v12, -v4, v149, v12
	v_fma_f32 v13, -v4, v153, v13
	v_fma_f32 v12, -v5, v150, v12
	v_fma_f32 v13, -v5, v154, v13
	v_fma_f32 v12, -v6, v151, v12
	ds_read_b128 v[148:151], v1 offset:38400
	v_fma_f32 v13, -v6, v155, v13
	ds_read_b128 v[152:155], v1 offset:38176
	s_waitcnt lgkmcnt(13)
	v_fma_f32 v12, -v7, v100, v12
	s_waitcnt lgkmcnt(12)
	v_fma_f32 v13, -v7, v104, v13
	v_fma_f32 v12, -v8, v101, v12
	v_fma_f32 v13, -v8, v105, v13
	v_fma_f32 v12, -v9, v102, v12
	v_fma_f32 v13, -v9, v106, v13
	v_fma_f32 v12, -v103, v10, v12
	ds_read_b128 v[100:103], v1 offset:38416
	v_fma_f32 v13, -v10, v107, v13
	ds_read_b128 v[104:107], v1 offset:38192
	s_waitcnt lgkmcnt(13)
	v_fma_f32 v12, -v108, v11, v12
	ds_read_b128 v[108:111], v1 offset:38432
	s_waitcnt lgkmcnt(13)
	v_fma_f32 v13, -v112, v11, v13
	v_fma_f32 v13, -v113, v12, v13
	ds_read_b128 v[112:115], v1 offset:38448
	s_waitcnt lgkmcnt(13)
	v_fma_f32 v14, -v0, v116, v14
	s_waitcnt lgkmcnt(12)
	v_fma_f32 v15, -v0, v120, v15
	v_fma_f32 v14, -v4, v117, v14
	v_fma_f32 v15, -v4, v121, v15
	v_fma_f32 v14, -v5, v118, v14
	v_fma_f32 v15, -v5, v122, v15
	v_fma_f32 v14, -v6, v119, v14
	ds_read_b128 v[116:119], v1 offset:38656
	v_fma_f32 v15, -v6, v123, v15
	ds_read_b128 v[120:123], v1 offset:38912
	s_waitcnt lgkmcnt(13)
	v_fma_f32 v14, -v7, v124, v14
	s_waitcnt lgkmcnt(12)
	v_fma_f32 v15, -v7, v128, v15
	v_fma_f32 v14, -v8, v125, v14
	v_fma_f32 v15, -v8, v129, v15
	v_fma_f32 v14, -v9, v126, v14
	v_fma_f32 v15, -v9, v130, v15
	v_fma_f32 v14, -v10, v127, v14
	ds_read_b128 v[124:127], v1 offset:38672
	v_fma_f32 v15, -v10, v131, v15
	ds_read_b128 v[128:131], v1 offset:38928
	s_waitcnt lgkmcnt(13)
	v_fma_f32 v14, -v11, v132, v14
	v_fma_f32 v14, -v133, v12, v14
	v_fma_f32 v14, -v134, v13, v14
	ds_read_b128 v[132:135], v1 offset:38688
	s_waitcnt lgkmcnt(13)
	v_fma_f32 v16, -v0, v136, v16
	s_waitcnt lgkmcnt(12)
	v_fma_f32 v15, -v11, v140, v15
	v_fma_f32 v16, -v4, v137, v16
	v_fma_f32 v15, -v12, v141, v15
	v_fma_f32 v16, -v5, v138, v16
	v_fma_f32 v15, -v142, v13, v15
	v_fma_f32 v16, -v6, v139, v16
	ds_read_b128 v[136:139], v1 offset:38704
	v_fma_f32 v15, -v143, v14, v15
	ds_read_b128 v[140:143], v1 offset:39168
	s_waitcnt lgkmcnt(13)
	v_fma_f32 v16, -v7, v144, v16
	s_waitcnt lgkmcnt(12)
	v_fma_f32 v18, -v0, v148, v18
	v_fma_f32 v16, -v8, v145, v16
	v_fma_f32 v18, -v4, v149, v18
	v_fma_f32 v16, -v9, v146, v16
	v_fma_f32 v18, -v5, v150, v18
	v_fma_f32 v16, -v10, v147, v16
	ds_read_b128 v[144:147], v1 offset:38944
	v_fma_f32 v18, -v6, v151, v18
	ds_read_b128 v[148:151], v1 offset:39184
	s_waitcnt lgkmcnt(13)
	v_fma_f32 v16, -v11, v152, v16
	s_waitcnt lgkmcnt(12)
	v_fma_f32 v18, -v7, v100, v18
	v_fma_f32 v16, -v12, v153, v16
	v_fma_f32 v18, -v8, v101, v18
	v_fma_f32 v16, -v13, v154, v16
	v_fma_f32 v18, -v9, v102, v18
	v_fma_f32 v16, -v155, v14, v16
	ds_read_b128 v[152:155], v1 offset:38960
	v_fma_f32 v18, -v10, v103, v18
	ds_read_b128 v[100:103], v1 offset:39200
	s_waitcnt lgkmcnt(13)
	v_fma_f32 v16, -v104, v15, v16
	ds_read_b128 v[104:107], v1 offset:39424
	s_waitcnt lgkmcnt(13)
; DI void gdnprep_item(const Params& p, int item, unsigned char* ldsb) {
;     ...
;     for (int i = 1; i < 64; ++i) {
;       float a = x[i];
; #pragma unroll
;       for (int j4 = 0; j4 < (i + 3) / 4; ++j4) {
;         f32x4 Lv = *(const f32x4*)(Lm + i * 64 + j4 * 4);
; #pragma unroll
;         for (int e = 0; e < 4; ++e) if (j4 * 4 + e < i) a -= Lv[e] * x[j4 * 4 + e];
;       }
;       x[i] = a;
;       if ((i & 3) == 3) __builtin_amdgcn_sched_barrier(0);
;     }
	v_fma_f32 v18, -v11, v108, v18
	v_fma_f32 v18, -v12, v109, v18
	v_fma_f32 v18, -v13, v110, v18
	v_fma_f32 v18, -v14, v111, v18
	ds_read_b128 v[108:111], v1 offset:39216
	s_waitcnt lgkmcnt(13)
	v_fma_f32 v18, -v112, v15, v18
	v_fma_f32 v18, -v113, v16, v18
	ds_read_b128 v[112:115], v1 offset:39440
	s_waitcnt lgkmcnt(13)
	v_fma_f32 v19, -v0, v116, v19
	s_waitcnt lgkmcnt(12)
	v_fma_f32 v20, -v0, v120, v20
	v_fma_f32 v19, -v4, v117, v19
	v_fma_f32 v20, -v4, v121, v20
	v_fma_f32 v19, -v5, v118, v19
	v_fma_f32 v20, -v5, v122, v20
	v_fma_f32 v19, -v6, v119, v19
	ds_read_b128 v[116:119], v1 offset:39232
	v_fma_f32 v20, -v6, v123, v20
	ds_read_b128 v[120:123], v1 offset:39456
	s_waitcnt lgkmcnt(13)
	v_fma_f32 v19, -v7, v124, v19
	s_waitcnt lgkmcnt(12)
	v_fma_f32 v20, -v7, v128, v20
	v_fma_f32 v19, -v8, v125, v19
	v_fma_f32 v20, -v8, v129, v20
	v_fma_f32 v19, -v9, v126, v19
	v_fma_f32 v20, -v9, v130, v20
	v_fma_f32 v19, -v10, v127, v19
	ds_read_b128 v[124:127], v1 offset:39472
	v_fma_f32 v20, -v10, v131, v20
	ds_read_b128 v[128:131], v1 offset:39488
	s_waitcnt lgkmcnt(13)
	v_fma_f32 v19, -v11, v132, v19
	v_fma_f32 v19, -v12, v133, v19
	v_fma_f32 v19, -v13, v134, v19
	v_fma_f32 v19, -v14, v135, v19
	ds_read_b128 v[132:135], v1 offset:39680
	s_waitcnt lgkmcnt(13)
	v_fma_f32 v19, -v15, v136, v19
	v_fma_f32 v19, -v137, v16, v19
	v_fma_f32 v19, -v138, v18, v19
	ds_read_b128 v[136:139], v1 offset:39936
	s_waitcnt lgkmcnt(13)
	v_fma_f32 v22, -v0, v140, v22
	s_waitcnt lgkmcnt(12)
	v_fma_f32 v20, -v11, v144, v20
	v_fma_f32 v22, -v4, v141, v22
	v_fma_f32 v20, -v12, v145, v20
	v_fma_f32 v22, -v5, v142, v22
	v_fma_f32 v20, -v13, v146, v20
	v_fma_f32 v22, -v6, v143, v22
	ds_read_b128 v[140:143], v1 offset:39696
	v_fma_f32 v20, -v14, v147, v20
	ds_read_b128 v[144:147], v1 offset:39952
	s_waitcnt lgkmcnt(13)
	v_fma_f32 v22, -v7, v148, v22
	s_waitcnt lgkmcnt(12)
	v_fma_f32 v20, -v15, v152, v20
	v_fma_f32 v22, -v8, v149, v22
	v_fma_f32 v20, -v16, v153, v20
	v_fma_f32 v22, -v9, v150, v22
	v_fma_f32 v20, -v154, v18, v20
	v_fma_f32 v22, -v10, v151, v22
	ds_read_b128 v[148:151], v1 offset:39712
	v_fma_f32 v20, -v155, v19, v20
	ds_read_b128 v[152:155], v1 offset:39968
	s_waitcnt lgkmcnt(13)
	v_fma_f32 v22, -v11, v100, v22
	s_waitcnt lgkmcnt(12)
	v_fma_f32 v23, -v0, v104, v23
	v_fma_f32 v22, -v12, v101, v22
	v_fma_f32 v23, -v4, v105, v23
	v_fma_f32 v22, -v13, v102, v22
	v_fma_f32 v23, -v5, v106, v23
	v_fma_f32 v22, -v14, v103, v22
	ds_read_b128 v[100:103], v1 offset:39728
	v_fma_f32 v23, -v6, v107, v23
	ds_read_b128 v[104:107], v1 offset:39984
	s_waitcnt lgkmcnt(13)
	v_fma_f32 v22, -v15, v108, v22
	s_waitcnt lgkmcnt(12)
	v_fma_f32 v23, -v7, v112, v23
	v_fma_f32 v22, -v16, v109, v22
	v_fma_f32 v23, -v8, v113, v23
	v_fma_f32 v22, -v18, v110, v22
	v_fma_f32 v23, -v9, v114, v23
	v_fma_f32 v22, -v111, v19, v22
	ds_read_b128 v[108:111], v1 offset:39744
	v_fma_f32 v23, -v10, v115, v23
	ds_read_b128 v[112:115], v1 offset:40000
	s_waitcnt lgkmcnt(13)
	v_fma_f32 v22, -v116, v20, v22
	ds_read_b128 v[116:119], v1 offset:40192
	s_waitcnt lgkmcnt(13)
	v_fma_f32 v23, -v11, v120, v23
	v_fma_f32 v23, -v12, v121, v23
	v_fma_f32 v23, -v13, v122, v23
	v_fma_f32 v23, -v14, v123, v23
	ds_read_b128 v[120:123], v1 offset:40448
	s_waitcnt lgkmcnt(13)
	v_fma_f32 v23, -v15, v124, v23
	v_fma_f32 v23, -v16, v125, v23
	v_fma_f32 v23, -v18, v126, v23
	v_fma_f32 v23, -v19, v127, v23
	ds_read_b128 v[124:127], v1 offset:40208
	s_waitcnt lgkmcnt(13)
	v_fma_f32 v23, -v128, v20, v23
	v_fma_f32 v23, -v129, v22, v23
	ds_read_b128 v[128:131], v1 offset:40464
	s_waitcnt lgkmcnt(13)
	v_fma_f32 v24, -v0, v132, v24
	s_waitcnt lgkmcnt(12)
	v_fma_f32 v25, -v0, v136, v25
	v_fma_f32 v24, -v4, v133, v24
	v_fma_f32 v25, -v4, v137, v25
	v_fma_f32 v24, -v5, v134, v24
	v_fma_f32 v25, -v5, v138, v25
	v_fma_f32 v24, -v6, v135, v24
	ds_read_b128 v[132:135], v1 offset:40224
	v_fma_f32 v25, -v6, v139, v25
	ds_read_b128 v[136:139], v1 offset:40480
	s_waitcnt lgkmcnt(13)
	v_fma_f32 v24, -v7, v140, v24
	s_waitcnt lgkmcnt(12)
	v_fma_f32 v25, -v7, v144, v25
	v_fma_f32 v24, -v8, v141, v24
	v_fma_f32 v25, -v8, v145, v25
	v_fma_f32 v24, -v9, v142, v24
	v_fma_f32 v25, -v9, v146, v25
	v_fma_f32 v24, -v10, v143, v24
	ds_read_b128 v[140:143], v1 offset:40240
	v_fma_f32 v25, -v10, v147, v25
	ds_read_b128 v[144:147], v1 offset:40496
	s_waitcnt lgkmcnt(13)
	v_fma_f32 v24, -v11, v148, v24
	s_waitcnt lgkmcnt(12)
	v_fma_f32 v25, -v11, v152, v25
	v_fma_f32 v24, -v12, v149, v24
	v_fma_f32 v25, -v12, v153, v25
	v_fma_f32 v24, -v13, v150, v24
	v_fma_f32 v25, -v13, v154, v25
	v_fma_f32 v24, -v14, v151, v24
	ds_read_b128 v[148:151], v1 offset:40256
	v_fma_f32 v25, -v14, v155, v25
	ds_read_b128 v[152:155], v1 offset:40512
	s_waitcnt lgkmcnt(13)
	v_fma_f32 v24, -v15, v100, v24
	s_waitcnt lgkmcnt(12)
	v_fma_f32 v25, -v15, v104, v25
	v_fma_f32 v24, -v16, v101, v24
	v_fma_f32 v25, -v16, v105, v25
	v_fma_f32 v24, -v18, v102, v24
	v_fma_f32 v25, -v18, v106, v25
	v_fma_f32 v24, -v19, v103, v24
	ds_read_b128 v[100:103], v1 offset:40272
	v_fma_f32 v25, -v19, v107, v25
	ds_read_b128 v[104:107], v1 offset:40528
	s_waitcnt lgkmcnt(13)
	v_fma_f32 v24, -v20, v108, v24
	s_waitcnt lgkmcnt(12)
	v_fma_f32 v25, -v20, v112, v25
	v_fma_f32 v24, -v109, v22, v24
	v_fma_f32 v25, -v22, v113, v25
	v_fma_f32 v24, -v110, v23, v24
	ds_read_b128 v[108:111], v1 offset:40704
	v_fma_f32 v25, -v114, v23, v25
	v_fma_f32 v25, -v115, v24, v25
	ds_read_b128 v[112:115], v1 offset:40960
	s_waitcnt lgkmcnt(13)
	v_fma_f32 v27, -v0, v116, v27
	s_waitcnt lgkmcnt(12)
; DI void gdnprep_item(const Params& p, int item, unsigned char* ldsb) {
;     ...
;     for (int i = 1; i < 64; ++i) {
;       float a = x[i];
; #pragma unroll
;       for (int j4 = 0; j4 < (i + 3) / 4; ++j4) {
;         f32x4 Lv = *(const f32x4*)(Lm + i * 64 + j4 * 4);
; #pragma unroll
;         for (int e = 0; e < 4; ++e) if (j4 * 4 + e < i) a -= Lv[e] * x[j4 * 4 + e];
;       }
;       x[i] = a;
;       if ((i & 3) == 3) __builtin_amdgcn_sched_barrier(0);
;     }
	v_fma_f32 v28, -v0, v120, v28
	v_fma_f32 v27, -v4, v117, v27
	v_fma_f32 v28, -v4, v121, v28
	v_fma_f32 v27, -v5, v118, v27
	v_fma_f32 v28, -v5, v122, v28
	v_fma_f32 v27, -v6, v119, v27
	ds_read_b128 v[116:119], v1 offset:40720
	v_fma_f32 v28, -v6, v123, v28
	ds_read_b128 v[120:123], v1 offset:40976
	s_waitcnt lgkmcnt(13)
	v_fma_f32 v27, -v7, v124, v27
	s_waitcnt lgkmcnt(12)
	v_fma_f32 v28, -v7, v128, v28
	v_fma_f32 v27, -v8, v125, v27
	v_fma_f32 v28, -v8, v129, v28
	v_fma_f32 v27, -v9, v126, v27
	v_fma_f32 v28, -v9, v130, v28
	v_fma_f32 v27, -v10, v127, v27
	ds_read_b128 v[124:127], v1 offset:40736
	v_fma_f32 v28, -v10, v131, v28
	ds_read_b128 v[128:131], v1 offset:40992
	s_waitcnt lgkmcnt(13)
	v_fma_f32 v27, -v11, v132, v27
	s_waitcnt lgkmcnt(12)
	v_fma_f32 v28, -v11, v136, v28
	v_fma_f32 v27, -v12, v133, v27
	v_fma_f32 v28, -v12, v137, v28
	v_fma_f32 v27, -v13, v134, v27
	v_fma_f32 v28, -v13, v138, v28
	v_fma_f32 v27, -v14, v135, v27
	ds_read_b128 v[132:135], v1 offset:40752
	v_fma_f32 v28, -v14, v139, v28
	ds_read_b128 v[136:139], v1 offset:41008
	s_waitcnt lgkmcnt(13)
	v_fma_f32 v27, -v15, v140, v27
	s_waitcnt lgkmcnt(12)
	v_fma_f32 v28, -v15, v144, v28
	v_fma_f32 v27, -v16, v141, v27
	v_fma_f32 v28, -v16, v145, v28
	v_fma_f32 v27, -v18, v142, v27
	v_fma_f32 v28, -v18, v146, v28
	v_fma_f32 v27, -v19, v143, v27
	ds_read_b128 v[140:143], v1 offset:40768
	v_fma_f32 v28, -v19, v147, v28
	ds_read_b128 v[144:147], v1 offset:41024
	s_waitcnt lgkmcnt(13)
	v_fma_f32 v27, -v20, v148, v27
	s_waitcnt lgkmcnt(12)
	v_fma_f32 v28, -v20, v152, v28
	v_fma_f32 v27, -v22, v149, v27
	v_fma_f32 v28, -v22, v153, v28
	v_fma_f32 v27, -v23, v150, v27
	v_fma_f32 v28, -v23, v154, v28
	v_fma_f32 v27, -v151, v24, v27
	ds_read_b128 v[148:151], v1 offset:40784
	v_fma_f32 v28, -v24, v155, v28
	ds_read_b128 v[152:155], v1 offset:41040
	s_waitcnt lgkmcnt(13)
	v_fma_f32 v27, -v100, v25, v27
	ds_read_b128 v[100:103], v1 offset:41216
	s_waitcnt lgkmcnt(13)
	v_fma_f32 v28, -v104, v25, v28
	v_fma_f32 v28, -v105, v27, v28
	ds_read_b128 v[104:107], v1 offset:41472
	s_waitcnt lgkmcnt(13)
	v_fma_f32 v30, -v0, v108, v30
	s_waitcnt lgkmcnt(12)
	v_fma_f32 v31, -v0, v112, v31
	v_fma_f32 v30, -v4, v109, v30
	v_fma_f32 v31, -v4, v113, v31
	v_fma_f32 v30, -v5, v110, v30
	v_fma_f32 v31, -v5, v114, v31
	v_fma_f32 v30, -v6, v111, v30
	ds_read_b128 v[108:111], v1 offset:41232
	v_fma_f32 v31, -v6, v115, v31
	ds_read_b128 v[112:115], v1 offset:41488
	s_waitcnt lgkmcnt(13)
	v_fma_f32 v30, -v7, v116, v30
	s_waitcnt lgkmcnt(12)
	v_fma_f32 v31, -v7, v120, v31
	v_fma_f32 v30, -v8, v117, v30
	v_fma_f32 v31, -v8, v121, v31
	v_fma_f32 v30, -v9, v118, v30
	v_fma_f32 v31, -v9, v122, v31
	v_fma_f32 v30, -v10, v119, v30
	ds_read_b128 v[116:119], v1 offset:41248
	v_fma_f32 v31, -v10, v123, v31
	ds_read_b128 v[120:123], v1 offset:41504
	s_waitcnt lgkmcnt(13)
	v_fma_f32 v30, -v11, v124, v30
	s_waitcnt lgkmcnt(12)
	v_fma_f32 v31, -v11, v128, v31
	v_fma_f32 v30, -v12, v125, v30
	v_fma_f32 v31, -v12, v129, v31
	v_fma_f32 v30, -v13, v126, v30
	v_fma_f32 v31, -v13, v130, v31
	v_fma_f32 v30, -v14, v127, v30
	ds_read_b128 v[124:127], v1 offset:41264
	v_fma_f32 v31, -v14, v131, v31
	ds_read_b128 v[128:131], v1 offset:41520
	s_waitcnt lgkmcnt(13)
	v_fma_f32 v30, -v15, v132, v30
	s_waitcnt lgkmcnt(12)
	v_fma_f32 v31, -v15, v136, v31
	v_fma_f32 v30, -v16, v133, v30
	v_fma_f32 v31, -v16, v137, v31
	v_fma_f32 v30, -v18, v134, v30
	v_fma_f32 v31, -v18, v138, v31
	v_fma_f32 v30, -v19, v135, v30
	ds_read_b128 v[132:135], v1 offset:41280
	v_fma_f32 v31, -v19, v139, v31
	ds_read_b128 v[136:139], v1 offset:41536
	s_waitcnt lgkmcnt(13)
	v_fma_f32 v30, -v20, v140, v30
	s_waitcnt lgkmcnt(12)
	v_fma_f32 v31, -v20, v144, v31
	v_fma_f32 v30, -v22, v141, v30
	v_fma_f32 v31, -v22, v145, v31
	v_fma_f32 v30, -v23, v142, v30
	v_fma_f32 v31, -v23, v146, v31
	v_fma_f32 v30, -v24, v143, v30
	ds_read_b128 v[140:143], v1 offset:41296
	v_fma_f32 v31, -v24, v147, v31
	ds_read_b128 v[144:147], v1 offset:41552
	s_waitcnt lgkmcnt(13)
	v_fma_f32 v30, -v25, v148, v30
	s_waitcnt lgkmcnt(12)
	v_fma_f32 v31, -v25, v152, v31
	v_fma_f32 v30, -v149, v27, v30
	v_fma_f32 v31, -v27, v153, v31
	v_fma_f32 v30, -v150, v28, v30
	ds_read_b128 v[148:151], v1 offset:41312
	v_fma_f32 v31, -v154, v28, v31
	v_fma_f32 v31, -v155, v30, v31
	ds_read_b128 v[152:155], v1 offset:41568
	s_waitcnt lgkmcnt(13)
	v_fma_f32 v33, -v0, v100, v33
	s_waitcnt lgkmcnt(12)
	v_fma_f32 v34, -v0, v104, v34
	v_fma_f32 v33, -v4, v101, v33
	v_fma_f32 v34, -v4, v105, v34
	v_fma_f32 v33, -v5, v102, v33
	v_fma_f32 v34, -v5, v106, v34
	v_fma_f32 v33, -v6, v103, v33
	ds_read_b128 v[100:103], v1 offset:41728
	v_fma_f32 v34, -v6, v107, v34
	ds_read_b128 v[104:107], v1 offset:41984
	s_waitcnt lgkmcnt(13)
	v_fma_f32 v33, -v7, v108, v33
	s_waitcnt lgkmcnt(12)
	v_fma_f32 v34, -v7, v112, v34
	v_fma_f32 v33, -v8, v109, v33
	v_fma_f32 v34, -v8, v113, v34
	v_fma_f32 v33, -v9, v110, v33
	v_fma_f32 v34, -v9, v114, v34
	v_fma_f32 v33, -v10, v111, v33
	ds_read_b128 v[108:111], v1 offset:41744
	v_fma_f32 v34, -v10, v115, v34
	ds_read_b128 v[112:115], v1 offset:42000
	s_waitcnt lgkmcnt(13)
	v_fma_f32 v33, -v11, v116, v33
	s_waitcnt lgkmcnt(12)
	v_fma_f32 v34, -v11, v120, v34
	v_fma_f32 v33, -v12, v117, v33
	v_fma_f32 v34, -v12, v121, v34
	v_fma_f32 v33, -v13, v118, v33
	v_fma_f32 v34, -v13, v122, v34
	v_fma_f32 v33, -v14, v119, v33
	ds_read_b128 v[116:119], v1 offset:41760
	v_fma_f32 v34, -v14, v123, v34
	ds_read_b128 v[120:123], v1 offset:42016
	s_waitcnt lgkmcnt(13)
	v_fma_f32 v33, -v15, v124, v33
	s_waitcnt lgkmcnt(12)
; DI void gdnprep_item(const Params& p, int item, unsigned char* ldsb) {
;     ...
;     for (int i = 1; i < 64; ++i) {
;       float a = x[i];
; #pragma unroll
;       for (int j4 = 0; j4 < (i + 3) / 4; ++j4) {
;         f32x4 Lv = *(const f32x4*)(Lm + i * 64 + j4 * 4);
; #pragma unroll
;         for (int e = 0; e < 4; ++e) if (j4 * 4 + e < i) a -= Lv[e] * x[j4 * 4 + e];
;       }
;       x[i] = a;
;       if ((i & 3) == 3) __builtin_amdgcn_sched_barrier(0);
;     }
	v_fma_f32 v34, -v15, v128, v34
	v_fma_f32 v33, -v16, v125, v33
	v_fma_f32 v34, -v16, v129, v34
	v_fma_f32 v33, -v18, v126, v33
	v_fma_f32 v34, -v18, v130, v34
	v_fma_f32 v33, -v19, v127, v33
	ds_read_b128 v[124:127], v1 offset:41776
	v_fma_f32 v34, -v19, v131, v34
	ds_read_b128 v[128:131], v1 offset:42032
	s_waitcnt lgkmcnt(13)
	v_fma_f32 v33, -v20, v132, v33
	s_waitcnt lgkmcnt(12)
	v_fma_f32 v34, -v20, v136, v34
	v_fma_f32 v33, -v22, v133, v33
	v_fma_f32 v34, -v22, v137, v34
	v_fma_f32 v33, -v23, v134, v33
	v_fma_f32 v34, -v23, v138, v34
	v_fma_f32 v33, -v24, v135, v33
	ds_read_b128 v[132:135], v1 offset:41792
	v_fma_f32 v34, -v24, v139, v34
	ds_read_b128 v[136:139], v1 offset:42048
	s_waitcnt lgkmcnt(13)
	v_fma_f32 v33, -v25, v140, v33
	s_waitcnt lgkmcnt(12)
	v_fma_f32 v34, -v25, v144, v34
	v_fma_f32 v33, -v27, v141, v33
	v_fma_f32 v34, -v27, v145, v34
	v_fma_f32 v33, -v28, v142, v33
	v_fma_f32 v34, -v28, v146, v34
	v_fma_f32 v33, -v143, v30, v33
	ds_read_b128 v[140:143], v1 offset:41808
	v_fma_f32 v34, -v30, v147, v34
	ds_read_b128 v[144:147], v1 offset:42064
	s_waitcnt lgkmcnt(13)
	v_fma_f32 v33, -v148, v31, v33
	ds_read_b128 v[148:151], v1 offset:41824
	s_waitcnt lgkmcnt(13)
	v_fma_f32 v34, -v152, v31, v34
	v_fma_f32 v34, -v153, v33, v34
	ds_read_b128 v[152:155], v1 offset:42080
	s_waitcnt lgkmcnt(13)
	v_fma_f32 v36, -v0, v100, v36
	s_waitcnt lgkmcnt(12)
	v_fma_f32 v37, -v0, v104, v37
	v_fma_f32 v36, -v4, v101, v36
	v_fma_f32 v37, -v4, v105, v37
	v_fma_f32 v36, -v5, v102, v36
	v_fma_f32 v37, -v5, v106, v37
	v_fma_f32 v36, -v6, v103, v36
	ds_read_b128 v[100:103], v1 offset:42240
	v_fma_f32 v37, -v6, v107, v37
	ds_read_b128 v[104:107], v1 offset:42496
	s_waitcnt lgkmcnt(13)
	v_fma_f32 v36, -v7, v108, v36
	s_waitcnt lgkmcnt(12)
	v_fma_f32 v37, -v7, v112, v37
	v_fma_f32 v36, -v8, v109, v36
	v_fma_f32 v37, -v8, v113, v37
	v_fma_f32 v36, -v9, v110, v36
	v_fma_f32 v37, -v9, v114, v37
	v_fma_f32 v36, -v10, v111, v36
	ds_read_b128 v[108:111], v1 offset:42256
	v_fma_f32 v37, -v10, v115, v37
	ds_read_b128 v[112:115], v1 offset:42512
	s_waitcnt lgkmcnt(13)
	v_fma_f32 v36, -v11, v116, v36
	s_waitcnt lgkmcnt(12)
	v_fma_f32 v37, -v11, v120, v37
	v_fma_f32 v36, -v12, v117, v36
	v_fma_f32 v37, -v12, v121, v37
	v_fma_f32 v36, -v13, v118, v36
	v_fma_f32 v37, -v13, v122, v37
	v_fma_f32 v36, -v14, v119, v36
	ds_read_b128 v[116:119], v1 offset:42272
	v_fma_f32 v37, -v14, v123, v37
	ds_read_b128 v[120:123], v1 offset:42528
	s_waitcnt lgkmcnt(13)
	v_fma_f32 v36, -v15, v124, v36
	s_waitcnt lgkmcnt(12)
	v_fma_f32 v37, -v15, v128, v37
	v_fma_f32 v36, -v16, v125, v36
	v_fma_f32 v37, -v16, v129, v37
	v_fma_f32 v36, -v18, v126, v36
	v_fma_f32 v37, -v18, v130, v37
	v_fma_f32 v36, -v19, v127, v36
	ds_read_b128 v[124:127], v1 offset:42288
	v_fma_f32 v37, -v19, v131, v37
	ds_read_b128 v[128:131], v1 offset:42544
	s_waitcnt lgkmcnt(13)
	v_fma_f32 v36, -v20, v132, v36
	s_waitcnt lgkmcnt(12)
	v_fma_f32 v37, -v20, v136, v37
	v_fma_f32 v36, -v22, v133, v36
	v_fma_f32 v37, -v22, v137, v37
	v_fma_f32 v36, -v23, v134, v36
	v_fma_f32 v37, -v23, v138, v37
	v_fma_f32 v36, -v24, v135, v36
	ds_read_b128 v[132:135], v1 offset:42304
	v_fma_f32 v37, -v24, v139, v37
	ds_read_b128 v[136:139], v1 offset:42560
	s_waitcnt lgkmcnt(13)
	v_fma_f32 v36, -v25, v140, v36
	s_waitcnt lgkmcnt(12)
	v_fma_f32 v37, -v25, v144, v37
	v_fma_f32 v36, -v27, v141, v36
	v_fma_f32 v37, -v27, v145, v37
	v_fma_f32 v36, -v28, v142, v36
	v_fma_f32 v37, -v28, v146, v37
	v_fma_f32 v36, -v30, v143, v36
	ds_read_b128 v[140:143], v1 offset:42320
	v_fma_f32 v37, -v30, v147, v37
	ds_read_b128 v[144:147], v1 offset:42576
	s_waitcnt lgkmcnt(13)
	v_fma_f32 v36, -v31, v148, v36
	s_waitcnt lgkmcnt(12)
	v_fma_f32 v37, -v31, v152, v37
	v_fma_f32 v36, -v149, v33, v36
	v_fma_f32 v37, -v33, v153, v37
	v_fma_f32 v36, -v150, v34, v36
	ds_read_b128 v[148:151], v1 offset:42336
	v_fma_f32 v37, -v154, v34, v37
	v_fma_f32 v37, -v155, v36, v37
	ds_read_b128 v[152:155], v1 offset:42592
	s_waitcnt lgkmcnt(13)
	v_fma_f32 v39, -v0, v100, v39
	s_waitcnt lgkmcnt(12)
	v_fma_f32 v40, -v0, v104, v40
	v_fma_f32 v39, -v4, v101, v39
	v_fma_f32 v40, -v4, v105, v40
	v_fma_f32 v39, -v5, v102, v39
	v_fma_f32 v40, -v5, v106, v40
	v_fma_f32 v39, -v6, v103, v39
	ds_read_b128 v[100:103], v1 offset:42352
	v_fma_f32 v40, -v6, v107, v40
	ds_read_b128 v[104:107], v1 offset:42608
	s_waitcnt lgkmcnt(13)
	v_fma_f32 v39, -v7, v108, v39
	s_waitcnt lgkmcnt(12)
	v_fma_f32 v40, -v7, v112, v40
	v_fma_f32 v39, -v8, v109, v39
	v_fma_f32 v40, -v8, v113, v40
	v_fma_f32 v39, -v9, v110, v39
	v_fma_f32 v40, -v9, v114, v40
	v_fma_f32 v39, -v10, v111, v39
	ds_read_b128 v[108:111], v1 offset:42752
	v_fma_f32 v40, -v10, v115, v40
	ds_read_b128 v[112:115], v1 offset:43008
	s_waitcnt lgkmcnt(13)
	v_fma_f32 v39, -v11, v116, v39
	s_waitcnt lgkmcnt(12)
	v_fma_f32 v40, -v11, v120, v40
	v_fma_f32 v39, -v12, v117, v39
	v_fma_f32 v40, -v12, v121, v40
	v_fma_f32 v39, -v13, v118, v39
	v_fma_f32 v40, -v13, v122, v40
	v_fma_f32 v39, -v14, v119, v39
	ds_read_b128 v[116:119], v1 offset:42768
	v_fma_f32 v40, -v14, v123, v40
	ds_read_b128 v[120:123], v1 offset:43024
	s_waitcnt lgkmcnt(13)
	v_fma_f32 v39, -v15, v124, v39
	s_waitcnt lgkmcnt(12)
	v_fma_f32 v40, -v15, v128, v40
	v_fma_f32 v39, -v16, v125, v39
	v_fma_f32 v40, -v16, v129, v40
	v_fma_f32 v39, -v18, v126, v39
	v_fma_f32 v40, -v18, v130, v40
	v_fma_f32 v39, -v19, v127, v39
	ds_read_b128 v[124:127], v1 offset:42784
	v_fma_f32 v40, -v19, v131, v40
	ds_read_b128 v[128:131], v1 offset:43040
	s_waitcnt lgkmcnt(13)
	v_fma_f32 v39, -v20, v132, v39
	s_waitcnt lgkmcnt(12)
; DI void gdnprep_item(const Params& p, int item, unsigned char* ldsb) {
;     ...
;     for (int i = 1; i < 64; ++i) {
;       float a = x[i];
; #pragma unroll
;       for (int j4 = 0; j4 < (i + 3) / 4; ++j4) {
;         f32x4 Lv = *(const f32x4*)(Lm + i * 64 + j4 * 4);
; #pragma unroll
;         for (int e = 0; e < 4; ++e) if (j4 * 4 + e < i) a -= Lv[e] * x[j4 * 4 + e];
;       }
;       x[i] = a;
;       if ((i & 3) == 3) __builtin_amdgcn_sched_barrier(0);
;     }
	v_fma_f32 v40, -v20, v136, v40
	v_fma_f32 v39, -v22, v133, v39
	v_fma_f32 v40, -v22, v137, v40
	v_fma_f32 v39, -v23, v134, v39
	v_fma_f32 v40, -v23, v138, v40
	v_fma_f32 v39, -v24, v135, v39
	ds_read_b128 v[132:135], v1 offset:42800
	v_fma_f32 v40, -v24, v139, v40
	ds_read_b128 v[136:139], v1 offset:43056
	s_waitcnt lgkmcnt(13)
	v_fma_f32 v39, -v25, v140, v39
	s_waitcnt lgkmcnt(12)
	v_fma_f32 v40, -v25, v144, v40
	v_fma_f32 v39, -v27, v141, v39
	v_fma_f32 v40, -v27, v145, v40
	v_fma_f32 v39, -v28, v142, v39
	v_fma_f32 v40, -v28, v146, v40
	v_fma_f32 v39, -v30, v143, v39
	ds_read_b128 v[140:143], v1 offset:42816
	v_fma_f32 v40, -v30, v147, v40
	ds_read_b128 v[144:147], v1 offset:43072
	s_waitcnt lgkmcnt(13)
	v_fma_f32 v39, -v31, v148, v39
	s_waitcnt lgkmcnt(12)
	v_fma_f32 v40, -v31, v152, v40
	v_fma_f32 v39, -v33, v149, v39
	v_fma_f32 v40, -v33, v153, v40
	v_fma_f32 v39, -v34, v150, v39
	v_fma_f32 v40, -v34, v154, v40
	v_fma_f32 v39, -v151, v36, v39
	ds_read_b128 v[148:151], v1 offset:42832
	v_fma_f32 v40, -v36, v155, v40
	ds_read_b128 v[152:155], v1 offset:43088
	s_waitcnt lgkmcnt(13)
	v_fma_f32 v39, -v100, v37, v39
	ds_read_b128 v[100:103], v1 offset:42848
	s_waitcnt lgkmcnt(13)
	v_fma_f32 v40, -v104, v37, v40
	v_fma_f32 v40, -v105, v39, v40
	ds_read_b128 v[104:107], v1 offset:43104
	s_waitcnt lgkmcnt(13)
	v_fma_f32 v44, -v0, v108, v44
	s_waitcnt lgkmcnt(12)
	v_fma_f32 v46, -v0, v112, v46
	v_fma_f32 v44, -v4, v109, v44
	v_fma_f32 v46, -v4, v113, v46
	v_fma_f32 v44, -v5, v110, v44
	v_fma_f32 v46, -v5, v114, v46
	v_fma_f32 v44, -v6, v111, v44
	ds_read_b128 v[108:111], v1 offset:42864
	v_fma_f32 v46, -v6, v115, v46
	ds_read_b128 v[112:115], v1 offset:43120
	s_waitcnt lgkmcnt(13)
	v_fma_f32 v44, -v7, v116, v44
	s_waitcnt lgkmcnt(12)
	v_fma_f32 v46, -v7, v120, v46
	v_fma_f32 v44, -v8, v117, v44
	v_fma_f32 v46, -v8, v121, v46
	v_fma_f32 v44, -v9, v118, v44
	v_fma_f32 v46, -v9, v122, v46
	v_fma_f32 v44, -v10, v119, v44
	ds_read_b128 v[116:119], v1 offset:43264
	v_fma_f32 v46, -v10, v123, v46
	ds_read_b128 v[120:123], v1 offset:43520
	s_waitcnt lgkmcnt(13)
	v_fma_f32 v44, -v11, v124, v44
	s_waitcnt lgkmcnt(12)
	v_fma_f32 v46, -v11, v128, v46
	v_fma_f32 v44, -v12, v125, v44
	v_fma_f32 v46, -v12, v129, v46
	v_fma_f32 v44, -v13, v126, v44
	v_fma_f32 v46, -v13, v130, v46
	v_fma_f32 v44, -v14, v127, v44
	ds_read_b128 v[124:127], v1 offset:43280
	v_fma_f32 v46, -v14, v131, v46
	ds_read_b128 v[128:131], v1 offset:43536
	s_waitcnt lgkmcnt(13)
	v_fma_f32 v44, -v15, v132, v44
	s_waitcnt lgkmcnt(12)
	v_fma_f32 v46, -v15, v136, v46
	v_fma_f32 v44, -v16, v133, v44
	v_fma_f32 v46, -v16, v137, v46
	v_fma_f32 v44, -v18, v134, v44
	v_fma_f32 v46, -v18, v138, v46
	v_fma_f32 v44, -v19, v135, v44
	ds_read_b128 v[132:135], v1 offset:43296
	v_fma_f32 v46, -v19, v139, v46
	ds_read_b128 v[136:139], v1 offset:43552
	s_waitcnt lgkmcnt(13)
	v_fma_f32 v44, -v20, v140, v44
	s_waitcnt lgkmcnt(12)
	v_fma_f32 v46, -v20, v144, v46
	v_fma_f32 v44, -v22, v141, v44
	v_fma_f32 v46, -v22, v145, v46
	v_fma_f32 v44, -v23, v142, v44
	v_fma_f32 v46, -v23, v146, v46
	v_fma_f32 v44, -v24, v143, v44
	ds_read_b128 v[140:143], v1 offset:43312
	v_fma_f32 v46, -v24, v147, v46
	ds_read_b128 v[144:147], v1 offset:43568
	s_waitcnt lgkmcnt(13)
	v_fma_f32 v44, -v25, v148, v44
	s_waitcnt lgkmcnt(12)
	v_fma_f32 v46, -v25, v152, v46
	v_fma_f32 v44, -v27, v149, v44
	v_fma_f32 v46, -v27, v153, v46
	v_fma_f32 v44, -v28, v150, v44
	v_fma_f32 v46, -v28, v154, v46
	v_fma_f32 v44, -v30, v151, v44
	ds_read_b128 v[148:151], v1 offset:43328
	v_fma_f32 v46, -v30, v155, v46
	ds_read_b128 v[152:155], v1 offset:43584
	s_waitcnt lgkmcnt(13)
	v_fma_f32 v44, -v31, v100, v44
	s_waitcnt lgkmcnt(12)
	v_fma_f32 v46, -v31, v104, v46
	v_fma_f32 v44, -v33, v101, v44
	v_fma_f32 v46, -v33, v105, v46
	v_fma_f32 v44, -v34, v102, v44
	v_fma_f32 v46, -v34, v106, v46
	v_fma_f32 v44, -v36, v103, v44
	ds_read_b128 v[100:103], v1 offset:43344
	v_fma_f32 v46, -v36, v107, v46
	ds_read_b128 v[104:107], v1 offset:43600
	s_waitcnt lgkmcnt(13)
	v_fma_f32 v44, -v37, v108, v44
	s_waitcnt lgkmcnt(12)
	v_fma_f32 v46, -v37, v112, v46
	v_fma_f32 v44, -v109, v39, v44
	v_fma_f32 v46, -v39, v113, v46
	v_fma_f32 v44, -v110, v40, v44
	ds_read_b128 v[108:111], v1 offset:43360
	v_fma_f32 v46, -v114, v40, v46
	v_fma_f32 v46, -v115, v44, v46
	ds_read_b128 v[112:115], v1 offset:43616
	s_waitcnt lgkmcnt(13)
	v_fma_f32 v47, -v0, v116, v47
	s_waitcnt lgkmcnt(12)
	v_fma_f32 v49, -v0, v120, v49
	v_fma_f32 v47, -v4, v117, v47
	v_fma_f32 v49, -v4, v121, v49
	v_fma_f32 v47, -v5, v118, v47
	v_fma_f32 v49, -v5, v122, v49
	v_fma_f32 v47, -v6, v119, v47
	ds_read_b128 v[116:119], v1 offset:43376
	v_fma_f32 v49, -v6, v123, v49
	ds_read_b128 v[120:123], v1 offset:43632
	s_waitcnt lgkmcnt(13)
	v_fma_f32 v47, -v7, v124, v47
	s_waitcnt lgkmcnt(12)
	v_fma_f32 v49, -v7, v128, v49
	v_fma_f32 v47, -v8, v125, v47
	v_fma_f32 v49, -v8, v129, v49
	v_fma_f32 v47, -v9, v126, v47
	v_fma_f32 v49, -v9, v130, v49
	v_fma_f32 v47, -v10, v127, v47
	ds_read_b128 v[124:127], v1 offset:43392
	v_fma_f32 v49, -v10, v131, v49
	ds_read_b128 v[128:131], v1 offset:43648
	s_waitcnt lgkmcnt(13)
	v_fma_f32 v47, -v11, v132, v47
	s_waitcnt lgkmcnt(12)
	v_fma_f32 v49, -v11, v136, v49
	v_fma_f32 v47, -v12, v133, v47
	v_fma_f32 v49, -v12, v137, v49
	v_fma_f32 v47, -v13, v134, v47
	v_fma_f32 v49, -v13, v138, v49
	v_fma_f32 v47, -v14, v135, v47
	ds_read_b128 v[132:135], v1 offset:43776
	v_fma_f32 v49, -v14, v139, v49
	ds_read_b128 v[136:139], v1 offset:44032
	s_waitcnt lgkmcnt(13)
	v_fma_f32 v47, -v15, v140, v47
	s_waitcnt lgkmcnt(12)
; DI void gdnprep_item(const Params& p, int item, unsigned char* ldsb) {
;     ...
;     for (int i = 1; i < 64; ++i) {
;       float a = x[i];
; #pragma unroll
;       for (int j4 = 0; j4 < (i + 3) / 4; ++j4) {
;         f32x4 Lv = *(const f32x4*)(Lm + i * 64 + j4 * 4);
; #pragma unroll
;         for (int e = 0; e < 4; ++e) if (j4 * 4 + e < i) a -= Lv[e] * x[j4 * 4 + e];
;       }
;       x[i] = a;
;       if ((i & 3) == 3) __builtin_amdgcn_sched_barrier(0);
;     }
	v_fma_f32 v49, -v15, v144, v49
	v_fma_f32 v47, -v16, v141, v47
	v_fma_f32 v49, -v16, v145, v49
	v_fma_f32 v47, -v18, v142, v47
	v_fma_f32 v49, -v18, v146, v49
	v_fma_f32 v47, -v19, v143, v47
	ds_read_b128 v[140:143], v1 offset:43792
	v_fma_f32 v49, -v19, v147, v49
	ds_read_b128 v[144:147], v1 offset:44048
	s_waitcnt lgkmcnt(13)
	v_fma_f32 v47, -v20, v148, v47
	s_waitcnt lgkmcnt(12)
	v_fma_f32 v49, -v20, v152, v49
	v_fma_f32 v47, -v22, v149, v47
	v_fma_f32 v49, -v22, v153, v49
	v_fma_f32 v47, -v23, v150, v47
	v_fma_f32 v49, -v23, v154, v49
	v_fma_f32 v47, -v24, v151, v47
	ds_read_b128 v[148:151], v1 offset:43808
	v_fma_f32 v49, -v24, v155, v49
	ds_read_b128 v[152:155], v1 offset:44064
	s_waitcnt lgkmcnt(13)
	v_fma_f32 v47, -v25, v100, v47
	s_waitcnt lgkmcnt(12)
	v_fma_f32 v49, -v25, v104, v49
	v_fma_f32 v47, -v27, v101, v47
	v_fma_f32 v49, -v27, v105, v49
	v_fma_f32 v47, -v28, v102, v47
	v_fma_f32 v49, -v28, v106, v49
	v_fma_f32 v47, -v30, v103, v47
	ds_read_b128 v[100:103], v1 offset:43824
	v_fma_f32 v49, -v30, v107, v49
	ds_read_b128 v[104:107], v1 offset:44080
	s_waitcnt lgkmcnt(13)
	v_fma_f32 v47, -v31, v108, v47
	s_waitcnt lgkmcnt(12)
	v_fma_f32 v49, -v31, v112, v49
	v_fma_f32 v47, -v33, v109, v47
	v_fma_f32 v49, -v33, v113, v49
	v_fma_f32 v47, -v34, v110, v47
	v_fma_f32 v49, -v34, v114, v49
	v_fma_f32 v47, -v36, v111, v47
	ds_read_b128 v[108:111], v1 offset:43840
	v_fma_f32 v49, -v36, v115, v49
	ds_read_b128 v[112:115], v1 offset:44096
	s_waitcnt lgkmcnt(13)
	v_fma_f32 v47, -v37, v116, v47
	s_waitcnt lgkmcnt(12)
	v_fma_f32 v49, -v37, v120, v49
	v_fma_f32 v47, -v39, v117, v47
	v_fma_f32 v49, -v39, v121, v49
	v_fma_f32 v47, -v40, v118, v47
	v_fma_f32 v49, -v40, v122, v49
	v_fma_f32 v47, -v119, v44, v47
	ds_read_b128 v[116:119], v1 offset:43856
	v_fma_f32 v49, -v44, v123, v49
	ds_read_b128 v[120:123], v1 offset:44112
	s_waitcnt lgkmcnt(13)
	v_fma_f32 v47, -v124, v46, v47
	ds_read_b128 v[124:127], v1 offset:43872
	s_waitcnt lgkmcnt(13)
	v_fma_f32 v49, -v128, v46, v49
	v_fma_f32 v49, -v129, v47, v49
	ds_read_b128 v[128:131], v1 offset:44128
	s_waitcnt lgkmcnt(13)
	v_fma_f32 v51, -v0, v132, v51
	s_waitcnt lgkmcnt(12)
	v_fma_f32 v58, -v0, v136, v58
	v_fma_f32 v51, -v4, v133, v51
	v_fma_f32 v58, -v4, v137, v58
	v_fma_f32 v51, -v5, v134, v51
	v_fma_f32 v58, -v5, v138, v58
	v_fma_f32 v51, -v6, v135, v51
	ds_read_b128 v[132:135], v1 offset:43888
	v_fma_f32 v58, -v6, v139, v58
	ds_read_b128 v[136:139], v1 offset:44144
	s_waitcnt lgkmcnt(13)
	v_fma_f32 v51, -v7, v140, v51
	s_waitcnt lgkmcnt(12)
	v_fma_f32 v58, -v7, v144, v58
	v_fma_f32 v51, -v8, v141, v51
	v_fma_f32 v58, -v8, v145, v58
	v_fma_f32 v51, -v9, v142, v51
	v_fma_f32 v58, -v9, v146, v58
	v_fma_f32 v51, -v10, v143, v51
	ds_read_b128 v[140:143], v1 offset:43904
	v_fma_f32 v58, -v10, v147, v58
	ds_read_b128 v[144:147], v1 offset:44160
	s_waitcnt lgkmcnt(13)
	v_fma_f32 v51, -v11, v148, v51
	s_waitcnt lgkmcnt(12)
	v_fma_f32 v58, -v11, v152, v58
	v_fma_f32 v51, -v12, v149, v51
	v_fma_f32 v58, -v12, v153, v58
	v_fma_f32 v51, -v13, v150, v51
	v_fma_f32 v58, -v13, v154, v58
	v_fma_f32 v51, -v14, v151, v51
	ds_read_b128 v[148:151], v1 offset:44288
	v_fma_f32 v58, -v14, v155, v58
	ds_read_b128 v[152:155], v1 offset:44544
	s_waitcnt lgkmcnt(13)
	v_fma_f32 v51, -v15, v100, v51
	s_waitcnt lgkmcnt(12)
	v_fma_f32 v58, -v15, v104, v58
	v_fma_f32 v51, -v16, v101, v51
	v_fma_f32 v58, -v16, v105, v58
	v_fma_f32 v51, -v18, v102, v51
	v_fma_f32 v58, -v18, v106, v58
	v_fma_f32 v51, -v19, v103, v51
	ds_read_b128 v[100:103], v1 offset:44304
	v_fma_f32 v58, -v19, v107, v58
	ds_read_b128 v[104:107], v1 offset:44560
	s_waitcnt lgkmcnt(13)
	v_fma_f32 v51, -v20, v108, v51
	s_waitcnt lgkmcnt(12)
	v_fma_f32 v58, -v20, v112, v58
	v_fma_f32 v51, -v22, v109, v51
	v_fma_f32 v58, -v22, v113, v58
	v_fma_f32 v51, -v23, v110, v51
	v_fma_f32 v58, -v23, v114, v58
	v_fma_f32 v51, -v24, v111, v51
	ds_read_b128 v[108:111], v1 offset:44320
	v_fma_f32 v58, -v24, v115, v58
	ds_read_b128 v[112:115], v1 offset:44576
	s_waitcnt lgkmcnt(13)
	v_fma_f32 v51, -v25, v116, v51
	s_waitcnt lgkmcnt(12)
	v_fma_f32 v58, -v25, v120, v58
	v_fma_f32 v51, -v27, v117, v51
	v_fma_f32 v58, -v27, v121, v58
	v_fma_f32 v51, -v28, v118, v51
	v_fma_f32 v58, -v28, v122, v58
	v_fma_f32 v51, -v30, v119, v51
	ds_read_b128 v[116:119], v1 offset:44336
	v_fma_f32 v58, -v30, v123, v58
	ds_read_b128 v[120:123], v1 offset:44592
	s_waitcnt lgkmcnt(13)
	v_fma_f32 v51, -v31, v124, v51
	s_waitcnt lgkmcnt(12)
	v_fma_f32 v58, -v31, v128, v58
	v_fma_f32 v51, -v33, v125, v51
	v_fma_f32 v58, -v33, v129, v58
	v_fma_f32 v51, -v34, v126, v51
	v_fma_f32 v58, -v34, v130, v58
	v_fma_f32 v51, -v36, v127, v51
	ds_read_b128 v[124:127], v1 offset:44352
	v_fma_f32 v58, -v36, v131, v58
	ds_read_b128 v[128:131], v1 offset:44608
	s_waitcnt lgkmcnt(13)
	v_fma_f32 v51, -v37, v132, v51
	s_waitcnt lgkmcnt(12)
	v_fma_f32 v58, -v37, v136, v58
	v_fma_f32 v51, -v39, v133, v51
	v_fma_f32 v58, -v39, v137, v58
	v_fma_f32 v51, -v40, v134, v51
	v_fma_f32 v58, -v40, v138, v58
	v_fma_f32 v51, -v44, v135, v51
	ds_read_b128 v[132:135], v1 offset:44368
	v_fma_f32 v58, -v44, v139, v58
	ds_read_b128 v[136:139], v1 offset:44624
	s_waitcnt lgkmcnt(13)
	v_fma_f32 v51, -v46, v140, v51
	s_waitcnt lgkmcnt(12)
	v_fma_f32 v58, -v46, v144, v58
	v_fma_f32 v51, -v141, v47, v51
	v_fma_f32 v58, -v47, v145, v58
	v_fma_f32 v51, -v142, v49, v51
	ds_read_b128 v[140:143], v1 offset:44384
	v_fma_f32 v58, -v146, v49, v58
	v_fma_f32 v58, -v147, v51, v58
	ds_read_b128 v[144:147], v1 offset:44640
	s_waitcnt lgkmcnt(13)
	v_fma_f32 v59, -v0, v148, v59
	s_waitcnt lgkmcnt(12)
; DI void gdnprep_item(const Params& p, int item, unsigned char* ldsb) {
;     ...
;     for (int i = 1; i < 64; ++i) {
;       float a = x[i];
; #pragma unroll
;       for (int j4 = 0; j4 < (i + 3) / 4; ++j4) {
;         f32x4 Lv = *(const f32x4*)(Lm + i * 64 + j4 * 4);
; #pragma unroll
;         for (int e = 0; e < 4; ++e) if (j4 * 4 + e < i) a -= Lv[e] * x[j4 * 4 + e];
;       }
;       x[i] = a;
;       if ((i & 3) == 3) __builtin_amdgcn_sched_barrier(0);
;     }
	v_fma_f32 v61, -v0, v152, v61
	v_fma_f32 v59, -v4, v149, v59
	v_fma_f32 v61, -v4, v153, v61
	v_fma_f32 v59, -v5, v150, v59
	v_fma_f32 v61, -v5, v154, v61
	v_fma_f32 v59, -v6, v151, v59
	ds_read_b128 v[148:151], v1 offset:44400
	v_fma_f32 v61, -v6, v155, v61
	ds_read_b128 v[152:155], v1 offset:44656
	s_waitcnt lgkmcnt(13)
	v_fma_f32 v59, -v7, v100, v59
	s_waitcnt lgkmcnt(12)
	v_fma_f32 v61, -v7, v104, v61
	v_fma_f32 v59, -v8, v101, v59
	v_fma_f32 v61, -v8, v105, v61
	v_fma_f32 v59, -v9, v102, v59
	v_fma_f32 v61, -v9, v106, v61
	v_fma_f32 v59, -v10, v103, v59
	ds_read_b128 v[100:103], v1 offset:44416
	v_fma_f32 v61, -v10, v107, v61
	ds_read_b128 v[104:107], v1 offset:44672
	s_waitcnt lgkmcnt(13)
	v_fma_f32 v59, -v11, v108, v59
	s_waitcnt lgkmcnt(12)
	v_fma_f32 v61, -v11, v112, v61
	v_fma_f32 v59, -v12, v109, v59
	v_fma_f32 v61, -v12, v113, v61
	v_fma_f32 v59, -v13, v110, v59
	v_fma_f32 v61, -v13, v114, v61
	v_fma_f32 v59, -v14, v111, v59
	ds_read_b128 v[108:111], v1 offset:44432
	v_fma_f32 v61, -v14, v115, v61
	ds_read_b128 v[112:115], v1 offset:44688
	s_waitcnt lgkmcnt(13)
	v_fma_f32 v59, -v15, v116, v59
	s_waitcnt lgkmcnt(12)
	v_fma_f32 v61, -v15, v120, v61
	v_fma_f32 v59, -v16, v117, v59
	v_fma_f32 v61, -v16, v121, v61
	v_fma_f32 v59, -v18, v118, v59
	v_fma_f32 v61, -v18, v122, v61
	v_fma_f32 v59, -v19, v119, v59
	ds_read_b128 v[116:119], v1 offset:44800
	v_fma_f32 v61, -v19, v123, v61
	ds_read_b128 v[120:123], v1 offset:45056
	s_waitcnt lgkmcnt(13)
	v_fma_f32 v59, -v20, v124, v59
	s_waitcnt lgkmcnt(12)
	v_fma_f32 v61, -v20, v128, v61
	v_fma_f32 v59, -v22, v125, v59
	v_fma_f32 v61, -v22, v129, v61
	v_fma_f32 v59, -v23, v126, v59
	v_fma_f32 v61, -v23, v130, v61
	v_fma_f32 v59, -v24, v127, v59
	ds_read_b128 v[124:127], v1 offset:44816
	v_fma_f32 v61, -v24, v131, v61
	ds_read_b128 v[128:131], v1 offset:45072
	s_waitcnt lgkmcnt(13)
	v_fma_f32 v59, -v25, v132, v59
	s_waitcnt lgkmcnt(12)
	v_fma_f32 v61, -v25, v136, v61
	v_fma_f32 v59, -v27, v133, v59
	v_fma_f32 v61, -v27, v137, v61
	v_fma_f32 v59, -v28, v134, v59
	v_fma_f32 v61, -v28, v138, v61
	v_fma_f32 v59, -v30, v135, v59
	ds_read_b128 v[132:135], v1 offset:44832
	v_fma_f32 v61, -v30, v139, v61
	ds_read_b128 v[136:139], v1 offset:45088
	s_waitcnt lgkmcnt(13)
	v_fma_f32 v59, -v31, v140, v59
	s_waitcnt lgkmcnt(12)
	v_fma_f32 v61, -v31, v144, v61
	v_fma_f32 v59, -v33, v141, v59
	v_fma_f32 v61, -v33, v145, v61
	v_fma_f32 v59, -v34, v142, v59
	v_fma_f32 v61, -v34, v146, v61
	v_fma_f32 v59, -v36, v143, v59
	ds_read_b128 v[140:143], v1 offset:44848
	v_fma_f32 v61, -v36, v147, v61
	ds_read_b128 v[144:147], v1 offset:45104
	s_waitcnt lgkmcnt(13)
	v_fma_f32 v59, -v37, v148, v59
	s_waitcnt lgkmcnt(12)
	v_fma_f32 v61, -v37, v152, v61
	v_fma_f32 v59, -v39, v149, v59
	v_fma_f32 v61, -v39, v153, v61
	v_fma_f32 v59, -v40, v150, v59
	v_fma_f32 v61, -v40, v154, v61
	v_fma_f32 v59, -v44, v151, v59
	ds_read_b128 v[148:151], v1 offset:44864
	v_fma_f32 v61, -v44, v155, v61
	ds_read_b128 v[152:155], v1 offset:45120
	s_waitcnt lgkmcnt(13)
	v_fma_f32 v59, -v46, v100, v59
	s_waitcnt lgkmcnt(12)
	v_fma_f32 v61, -v46, v104, v61
	v_fma_f32 v59, -v47, v101, v59
	v_fma_f32 v61, -v47, v105, v61
	v_fma_f32 v59, -v49, v102, v59
	v_fma_f32 v61, -v49, v106, v61
	v_fma_f32 v59, -v103, v51, v59
	ds_read_b128 v[100:103], v1 offset:44880
	v_fma_f32 v61, -v51, v107, v61
	ds_read_b128 v[104:107], v1 offset:45136
	s_waitcnt lgkmcnt(13)
	v_fma_f32 v59, -v108, v58, v59
	ds_read_b128 v[108:111], v1 offset:44896
	s_waitcnt lgkmcnt(13)
	v_fma_f32 v61, -v112, v58, v61
	v_fma_f32 v61, -v113, v59, v61
	ds_read_b128 v[112:115], v1 offset:45152
	s_waitcnt lgkmcnt(13)
	v_fma_f32 v63, -v0, v116, v63
	s_waitcnt lgkmcnt(12)
	v_fma_f32 v65, -v0, v120, v65
	v_fma_f32 v63, -v4, v117, v63
	v_fma_f32 v65, -v4, v121, v65
	v_fma_f32 v63, -v5, v118, v63
	v_fma_f32 v65, -v5, v122, v65
	v_fma_f32 v63, -v6, v119, v63
	ds_read_b128 v[116:119], v1 offset:44912
	v_fma_f32 v65, -v6, v123, v65
	ds_read_b128 v[120:123], v1 offset:45168
	s_waitcnt lgkmcnt(13)
	v_fma_f32 v63, -v7, v124, v63
	s_waitcnt lgkmcnt(12)
	v_fma_f32 v65, -v7, v128, v65
	v_fma_f32 v63, -v8, v125, v63
	v_fma_f32 v65, -v8, v129, v65
	v_fma_f32 v63, -v9, v126, v63
	v_fma_f32 v65, -v9, v130, v65
	v_fma_f32 v63, -v10, v127, v63
	ds_read_b128 v[124:127], v1 offset:44928
	v_fma_f32 v65, -v10, v131, v65
	ds_read_b128 v[128:131], v1 offset:45184
	s_waitcnt lgkmcnt(13)
	v_fma_f32 v63, -v11, v132, v63
	s_waitcnt lgkmcnt(12)
	v_fma_f32 v65, -v11, v136, v65
	v_fma_f32 v63, -v12, v133, v63
	v_fma_f32 v65, -v12, v137, v65
	v_fma_f32 v63, -v13, v134, v63
	v_fma_f32 v65, -v13, v138, v65
	v_fma_f32 v63, -v14, v135, v63
	ds_read_b128 v[132:135], v1 offset:44944
	v_fma_f32 v65, -v14, v139, v65
	ds_read_b128 v[136:139], v1 offset:45200
	s_waitcnt lgkmcnt(13)
	v_fma_f32 v63, -v15, v140, v63
	s_waitcnt lgkmcnt(12)
	v_fma_f32 v65, -v15, v144, v65
	v_fma_f32 v63, -v16, v141, v63
	v_fma_f32 v65, -v16, v145, v65
	v_fma_f32 v63, -v18, v142, v63
	v_fma_f32 v65, -v18, v146, v65
	v_fma_f32 v63, -v19, v143, v63
	ds_read_b128 v[140:143], v1 offset:45312
	v_fma_f32 v65, -v19, v147, v65
	ds_read_b128 v[144:147], v1 offset:45568
	s_waitcnt lgkmcnt(13)
	v_fma_f32 v63, -v20, v148, v63
	s_waitcnt lgkmcnt(12)
	v_fma_f32 v65, -v20, v152, v65
	v_fma_f32 v63, -v22, v149, v63
	v_fma_f32 v65, -v22, v153, v65
	v_fma_f32 v63, -v23, v150, v63
	v_fma_f32 v65, -v23, v154, v65
	v_fma_f32 v63, -v24, v151, v63
	ds_read_b128 v[148:151], v1 offset:45328
	v_fma_f32 v65, -v24, v155, v65
	ds_read_b128 v[152:155], v1 offset:45584
	s_waitcnt lgkmcnt(13)
	v_fma_f32 v63, -v25, v100, v63
	s_waitcnt lgkmcnt(12)
; DI void gdnprep_item(const Params& p, int item, unsigned char* ldsb) {
;     ...
;     for (int i = 1; i < 64; ++i) {
;       float a = x[i];
; #pragma unroll
;       for (int j4 = 0; j4 < (i + 3) / 4; ++j4) {
;         f32x4 Lv = *(const f32x4*)(Lm + i * 64 + j4 * 4);
; #pragma unroll
;         for (int e = 0; e < 4; ++e) if (j4 * 4 + e < i) a -= Lv[e] * x[j4 * 4 + e];
;       }
;       x[i] = a;
;       if ((i & 3) == 3) __builtin_amdgcn_sched_barrier(0);
;     }
	v_fma_f32 v65, -v25, v104, v65
	v_fma_f32 v63, -v27, v101, v63
	v_fma_f32 v65, -v27, v105, v65
	v_fma_f32 v63, -v28, v102, v63
	v_fma_f32 v65, -v28, v106, v65
	v_fma_f32 v63, -v30, v103, v63
	ds_read_b128 v[100:103], v1 offset:45344
	v_fma_f32 v65, -v30, v107, v65
	ds_read_b128 v[104:107], v1 offset:45600
	s_waitcnt lgkmcnt(13)
	v_fma_f32 v63, -v31, v108, v63
	s_waitcnt lgkmcnt(12)
	v_fma_f32 v65, -v31, v112, v65
	v_fma_f32 v63, -v33, v109, v63
	v_fma_f32 v65, -v33, v113, v65
	v_fma_f32 v63, -v34, v110, v63
	v_fma_f32 v65, -v34, v114, v65
	v_fma_f32 v63, -v36, v111, v63
	ds_read_b128 v[108:111], v1 offset:45360
	v_fma_f32 v65, -v36, v115, v65
	ds_read_b128 v[112:115], v1 offset:45616
	s_waitcnt lgkmcnt(13)
	v_fma_f32 v63, -v37, v116, v63
	s_waitcnt lgkmcnt(12)
	v_fma_f32 v65, -v37, v120, v65
	v_fma_f32 v63, -v39, v117, v63
	v_fma_f32 v65, -v39, v121, v65
	v_fma_f32 v63, -v40, v118, v63
	v_fma_f32 v65, -v40, v122, v65
	v_fma_f32 v63, -v44, v119, v63
	ds_read_b128 v[116:119], v1 offset:45376
	v_fma_f32 v65, -v44, v123, v65
	ds_read_b128 v[120:123], v1 offset:45632
	s_waitcnt lgkmcnt(13)
	v_fma_f32 v63, -v46, v124, v63
	s_waitcnt lgkmcnt(12)
	v_fma_f32 v65, -v46, v128, v65
	v_fma_f32 v63, -v47, v125, v63
	v_fma_f32 v65, -v47, v129, v65
	v_fma_f32 v63, -v49, v126, v63
	v_fma_f32 v65, -v49, v130, v65
	v_fma_f32 v63, -v51, v127, v63
	ds_read_b128 v[124:127], v1 offset:45392
	v_fma_f32 v65, -v51, v131, v65
	ds_read_b128 v[128:131], v1 offset:45648
	s_waitcnt lgkmcnt(13)
	v_fma_f32 v63, -v58, v132, v63
	s_waitcnt lgkmcnt(12)
	v_fma_f32 v65, -v58, v136, v65
	v_fma_f32 v63, -v133, v59, v63
	v_fma_f32 v65, -v59, v137, v65
	v_fma_f32 v63, -v134, v61, v63
	ds_read_b128 v[132:135], v1 offset:45408
	v_fma_f32 v65, -v138, v61, v65
	v_fma_f32 v65, -v139, v63, v65
	ds_read_b128 v[136:139], v1 offset:45664
	s_waitcnt lgkmcnt(13)
	v_fma_f32 v67, -v0, v140, v67
	s_waitcnt lgkmcnt(12)
	v_fma_f32 v69, -v0, v144, v69
	v_fma_f32 v67, -v4, v141, v67
	v_fma_f32 v69, -v4, v145, v69
	v_fma_f32 v67, -v5, v142, v67
	v_fma_f32 v69, -v5, v146, v69
	v_fma_f32 v67, -v6, v143, v67
	ds_read_b128 v[140:143], v1 offset:45424
	v_fma_f32 v69, -v6, v147, v69
	ds_read_b128 v[144:147], v1 offset:45680
	s_waitcnt lgkmcnt(13)
	v_fma_f32 v67, -v7, v148, v67
	s_waitcnt lgkmcnt(12)
	v_fma_f32 v69, -v7, v152, v69
	v_fma_f32 v67, -v8, v149, v67
	v_fma_f32 v69, -v8, v153, v69
	v_fma_f32 v67, -v9, v150, v67
	v_fma_f32 v69, -v9, v154, v69
	v_fma_f32 v67, -v10, v151, v67
	ds_read_b128 v[148:151], v1 offset:45440
	v_fma_f32 v69, -v10, v155, v69
	ds_read_b128 v[152:155], v1 offset:45696
	s_waitcnt lgkmcnt(13)
	v_fma_f32 v67, -v11, v100, v67
	s_waitcnt lgkmcnt(12)
	v_fma_f32 v69, -v11, v104, v69
	v_fma_f32 v67, -v12, v101, v67
	v_fma_f32 v69, -v12, v105, v69
	v_fma_f32 v67, -v13, v102, v67
	v_fma_f32 v69, -v13, v106, v69
	v_fma_f32 v67, -v14, v103, v67
	ds_read_b128 v[100:103], v1 offset:45456
	v_fma_f32 v69, -v14, v107, v69
	ds_read_b128 v[104:107], v1 offset:45712
	s_waitcnt lgkmcnt(13)
	v_fma_f32 v67, -v15, v108, v67
	s_waitcnt lgkmcnt(12)
	v_fma_f32 v69, -v15, v112, v69
	v_fma_f32 v67, -v16, v109, v67
	v_fma_f32 v69, -v16, v113, v69
	v_fma_f32 v67, -v18, v110, v67
	v_fma_f32 v69, -v18, v114, v69
	v_fma_f32 v67, -v19, v111, v67
	ds_read_b128 v[108:111], v1 offset:45472
	v_fma_f32 v69, -v19, v115, v69
	ds_read_b128 v[112:115], v1 offset:45728
	s_waitcnt lgkmcnt(13)
	v_fma_f32 v67, -v20, v116, v67
	s_waitcnt lgkmcnt(12)
	v_fma_f32 v69, -v20, v120, v69
	v_fma_f32 v67, -v22, v117, v67
	v_fma_f32 v69, -v22, v121, v69
	v_fma_f32 v67, -v23, v118, v67
	v_fma_f32 v69, -v23, v122, v69
	v_fma_f32 v67, -v24, v119, v67
	ds_read_b128 v[116:119], v1 offset:45824
	v_fma_f32 v69, -v24, v123, v69
	ds_read_b128 v[120:123], v1 offset:46080
	s_waitcnt lgkmcnt(13)
	v_fma_f32 v67, -v25, v124, v67
	s_waitcnt lgkmcnt(12)
	v_fma_f32 v69, -v25, v128, v69
	v_fma_f32 v67, -v27, v125, v67
	v_fma_f32 v69, -v27, v129, v69
	v_fma_f32 v67, -v28, v126, v67
	v_fma_f32 v69, -v28, v130, v69
	v_fma_f32 v67, -v30, v127, v67
	ds_read_b128 v[124:127], v1 offset:45840
	v_fma_f32 v69, -v30, v131, v69
	ds_read_b128 v[128:131], v1 offset:46096
	s_waitcnt lgkmcnt(13)
	v_fma_f32 v67, -v31, v132, v67
	s_waitcnt lgkmcnt(12)
	v_fma_f32 v69, -v31, v136, v69
	v_fma_f32 v67, -v33, v133, v67
	v_fma_f32 v69, -v33, v137, v69
	v_fma_f32 v67, -v34, v134, v67
	v_fma_f32 v69, -v34, v138, v69
	v_fma_f32 v67, -v36, v135, v67
	ds_read_b128 v[132:135], v1 offset:45856
	v_fma_f32 v69, -v36, v139, v69
	ds_read_b128 v[136:139], v1 offset:46112
	s_waitcnt lgkmcnt(13)
	v_fma_f32 v67, -v37, v140, v67
	s_waitcnt lgkmcnt(12)
	v_fma_f32 v69, -v37, v144, v69
	v_fma_f32 v67, -v39, v141, v67
	v_fma_f32 v69, -v39, v145, v69
	v_fma_f32 v67, -v40, v142, v67
	v_fma_f32 v69, -v40, v146, v69
	v_fma_f32 v67, -v44, v143, v67
	ds_read_b128 v[140:143], v1 offset:45872
	v_fma_f32 v69, -v44, v147, v69
	ds_read_b128 v[144:147], v1 offset:46128
	s_waitcnt lgkmcnt(13)
	v_fma_f32 v67, -v46, v148, v67
	s_waitcnt lgkmcnt(12)
	v_fma_f32 v69, -v46, v152, v69
	v_fma_f32 v67, -v47, v149, v67
	v_fma_f32 v69, -v47, v153, v69
	v_fma_f32 v67, -v49, v150, v67
	v_fma_f32 v69, -v49, v154, v69
	v_fma_f32 v67, -v51, v151, v67
	ds_read_b128 v[148:151], v1 offset:45888
	v_fma_f32 v69, -v51, v155, v69
	ds_read_b128 v[152:155], v1 offset:46144
	s_waitcnt lgkmcnt(13)
	v_fma_f32 v67, -v58, v100, v67
	s_waitcnt lgkmcnt(12)
	v_fma_f32 v69, -v58, v104, v69
	v_fma_f32 v67, -v59, v101, v67
	v_fma_f32 v69, -v59, v105, v69
	v_fma_f32 v67, -v61, v102, v67
	v_fma_f32 v69, -v61, v106, v69
	v_fma_f32 v67, -v103, v63, v67
	ds_read_b128 v[100:103], v1 offset:45904
	v_fma_f32 v69, -v63, v107, v69
	ds_read_b128 v[104:107], v1 offset:46160
	s_waitcnt lgkmcnt(13)
; DI void gdnprep_item(const Params& p, int item, unsigned char* ldsb) {
;     ...
;     for (int i = 1; i < 64; ++i) {
;       float a = x[i];
; #pragma unroll
;       for (int j4 = 0; j4 < (i + 3) / 4; ++j4) {
;         f32x4 Lv = *(const f32x4*)(Lm + i * 64 + j4 * 4);
; #pragma unroll
;         for (int e = 0; e < 4; ++e) if (j4 * 4 + e < i) a -= Lv[e] * x[j4 * 4 + e];
;       }
;       x[i] = a;
;       if ((i & 3) == 3) __builtin_amdgcn_sched_barrier(0);
;     }
	v_fma_f32 v67, -v108, v65, v67
	ds_read_b128 v[108:111], v1 offset:45920
	s_waitcnt lgkmcnt(13)
	v_fma_f32 v69, -v112, v65, v69
	v_fma_f32 v69, -v113, v67, v69
	ds_read_b128 v[112:115], v1 offset:46176
	s_waitcnt lgkmcnt(13)
	v_fma_f32 v71, -v0, v116, v71
	s_waitcnt lgkmcnt(12)
	v_fma_f32 v73, -v0, v120, v73
	v_fma_f32 v71, -v4, v117, v71
	v_fma_f32 v73, -v4, v121, v73
	v_fma_f32 v71, -v5, v118, v71
	v_fma_f32 v73, -v5, v122, v73
	v_fma_f32 v71, -v6, v119, v71
	ds_read_b128 v[116:119], v1 offset:45936
	v_fma_f32 v73, -v6, v123, v73
	ds_read_b128 v[120:123], v1 offset:46192
	s_waitcnt lgkmcnt(13)
	v_fma_f32 v71, -v7, v124, v71
	s_waitcnt lgkmcnt(12)
	v_fma_f32 v73, -v7, v128, v73
	v_fma_f32 v71, -v8, v125, v71
	v_fma_f32 v73, -v8, v129, v73
	v_fma_f32 v71, -v9, v126, v71
	v_fma_f32 v73, -v9, v130, v73
	v_fma_f32 v71, -v10, v127, v71
	ds_read_b128 v[124:127], v1 offset:45952
	v_fma_f32 v73, -v10, v131, v73
	ds_read_b128 v[128:131], v1 offset:46208
	s_waitcnt lgkmcnt(13)
	v_fma_f32 v71, -v11, v132, v71
	s_waitcnt lgkmcnt(12)
	v_fma_f32 v73, -v11, v136, v73
	v_fma_f32 v71, -v12, v133, v71
	v_fma_f32 v73, -v12, v137, v73
	v_fma_f32 v71, -v13, v134, v71
	v_fma_f32 v73, -v13, v138, v73
	v_fma_f32 v71, -v14, v135, v71
	ds_read_b128 v[132:135], v1 offset:45968
	v_fma_f32 v73, -v14, v139, v73
	ds_read_b128 v[136:139], v1 offset:46224
	s_waitcnt lgkmcnt(13)
	v_fma_f32 v71, -v15, v140, v71
	s_waitcnt lgkmcnt(12)
	v_fma_f32 v73, -v15, v144, v73
	v_fma_f32 v71, -v16, v141, v71
	v_fma_f32 v73, -v16, v145, v73
	v_fma_f32 v71, -v18, v142, v71
	v_fma_f32 v73, -v18, v146, v73
	v_fma_f32 v71, -v19, v143, v71
	ds_read_b128 v[140:143], v1 offset:45984
	v_fma_f32 v73, -v19, v147, v73
	ds_read_b128 v[144:147], v1 offset:46240
	s_waitcnt lgkmcnt(13)
	v_fma_f32 v71, -v20, v148, v71
	s_waitcnt lgkmcnt(12)
	v_fma_f32 v73, -v20, v152, v73
	v_fma_f32 v71, -v22, v149, v71
	v_fma_f32 v73, -v22, v153, v73
	v_fma_f32 v71, -v23, v150, v71
	v_fma_f32 v73, -v23, v154, v73
	v_fma_f32 v71, -v24, v151, v71
	ds_read_b128 v[148:151], v1 offset:46336
	v_fma_f32 v73, -v24, v155, v73
	ds_read_b128 v[152:155], v1 offset:46592
	s_waitcnt lgkmcnt(13)
	v_fma_f32 v71, -v25, v100, v71
	s_waitcnt lgkmcnt(12)
	v_fma_f32 v73, -v25, v104, v73
	v_fma_f32 v71, -v27, v101, v71
	v_fma_f32 v73, -v27, v105, v73
	v_fma_f32 v71, -v28, v102, v71
	v_fma_f32 v73, -v28, v106, v73
	v_fma_f32 v71, -v30, v103, v71
	ds_read_b128 v[100:103], v1 offset:46352
	v_fma_f32 v73, -v30, v107, v73
	ds_read_b128 v[104:107], v1 offset:46608
	s_waitcnt lgkmcnt(13)
	v_fma_f32 v71, -v31, v108, v71
	s_waitcnt lgkmcnt(12)
	v_fma_f32 v73, -v31, v112, v73
	v_fma_f32 v71, -v33, v109, v71
	v_fma_f32 v73, -v33, v113, v73
	v_fma_f32 v71, -v34, v110, v71
	v_fma_f32 v73, -v34, v114, v73
	v_fma_f32 v71, -v36, v111, v71
	ds_read_b128 v[108:111], v1 offset:46368
	v_fma_f32 v73, -v36, v115, v73
	ds_read_b128 v[112:115], v1 offset:46624
	s_waitcnt lgkmcnt(13)
	v_fma_f32 v71, -v37, v116, v71
	s_waitcnt lgkmcnt(12)
	v_fma_f32 v73, -v37, v120, v73
	v_fma_f32 v71, -v39, v117, v71
	v_fma_f32 v73, -v39, v121, v73
	v_fma_f32 v71, -v40, v118, v71
	v_fma_f32 v73, -v40, v122, v73
	v_fma_f32 v71, -v44, v119, v71
	ds_read_b128 v[116:119], v1 offset:46384
	v_fma_f32 v73, -v44, v123, v73
	ds_read_b128 v[120:123], v1 offset:46640
	s_waitcnt lgkmcnt(13)
	v_fma_f32 v71, -v46, v124, v71
	s_waitcnt lgkmcnt(12)
	v_fma_f32 v73, -v46, v128, v73
	v_fma_f32 v71, -v47, v125, v71
	v_fma_f32 v73, -v47, v129, v73
	v_fma_f32 v71, -v49, v126, v71
	v_fma_f32 v73, -v49, v130, v73
	v_fma_f32 v71, -v51, v127, v71
	ds_read_b128 v[124:127], v1 offset:46400
	v_fma_f32 v73, -v51, v131, v73
	ds_read_b128 v[128:131], v1 offset:46656
	s_waitcnt lgkmcnt(13)
	v_fma_f32 v71, -v58, v132, v71
	s_waitcnt lgkmcnt(12)
	v_fma_f32 v73, -v58, v136, v73
	v_fma_f32 v71, -v59, v133, v71
	v_fma_f32 v73, -v59, v137, v73
	v_fma_f32 v71, -v61, v134, v71
	v_fma_f32 v73, -v61, v138, v73
	v_fma_f32 v71, -v63, v135, v71
	ds_read_b128 v[132:135], v1 offset:46416
	v_fma_f32 v73, -v63, v139, v73
	ds_read_b128 v[136:139], v1 offset:46672
	s_waitcnt lgkmcnt(13)
	v_fma_f32 v71, -v65, v140, v71
	s_waitcnt lgkmcnt(12)
	v_fma_f32 v73, -v65, v144, v73
	v_fma_f32 v71, -v141, v67, v71
	v_fma_f32 v73, -v67, v145, v73
	v_fma_f32 v71, -v142, v69, v71
	ds_read_b128 v[140:143], v1 offset:46432
	v_fma_f32 v73, -v146, v69, v73
	v_fma_f32 v73, -v147, v71, v73
	ds_read_b128 v[144:147], v1 offset:46688
	s_waitcnt lgkmcnt(13)
	v_fma_f32 v72, -v0, v148, v72
	s_waitcnt lgkmcnt(12)
	v_fma_f32 v70, -v0, v152, v70
	v_fma_f32 v72, -v4, v149, v72
	v_fma_f32 v70, -v4, v153, v70
	v_fma_f32 v72, -v5, v150, v72
	v_fma_f32 v70, -v5, v154, v70
	v_fma_f32 v72, -v6, v151, v72
	ds_read_b128 v[148:151], v1 offset:46448
	v_fma_f32 v70, -v6, v155, v70
	ds_read_b128 v[152:155], v1 offset:46704
	s_waitcnt lgkmcnt(13)
	v_fma_f32 v72, -v7, v100, v72
	s_waitcnt lgkmcnt(12)
	v_fma_f32 v70, -v7, v104, v70
	v_fma_f32 v72, -v8, v101, v72
	v_fma_f32 v70, -v8, v105, v70
	v_fma_f32 v72, -v9, v102, v72
	v_fma_f32 v70, -v9, v106, v70
	v_fma_f32 v72, -v10, v103, v72
	ds_read_b128 v[100:103], v1 offset:46464
	v_fma_f32 v70, -v10, v107, v70
	ds_read_b128 v[104:107], v1 offset:46720
	s_waitcnt lgkmcnt(13)
	v_fma_f32 v72, -v11, v108, v72
	s_waitcnt lgkmcnt(12)
	v_fma_f32 v70, -v11, v112, v70
	v_fma_f32 v72, -v12, v109, v72
	v_fma_f32 v70, -v12, v113, v70
	v_fma_f32 v72, -v13, v110, v72
	v_fma_f32 v70, -v13, v114, v70
	v_fma_f32 v72, -v14, v111, v72
	ds_read_b128 v[108:111], v1 offset:46480
	v_fma_f32 v70, -v14, v115, v70
	ds_read_b128 v[112:115], v1 offset:46736
	s_waitcnt lgkmcnt(13)
	v_fma_f32 v72, -v15, v116, v72
	s_waitcnt lgkmcnt(12)
; DI void gdnprep_item(const Params& p, int item, unsigned char* ldsb) {
;     ...
;     for (int i = 1; i < 64; ++i) {
;       float a = x[i];
; #pragma unroll
;       for (int j4 = 0; j4 < (i + 3) / 4; ++j4) {
;         f32x4 Lv = *(const f32x4*)(Lm + i * 64 + j4 * 4);
; #pragma unroll
;         for (int e = 0; e < 4; ++e) if (j4 * 4 + e < i) a -= Lv[e] * x[j4 * 4 + e];
;       }
;       x[i] = a;
;       if ((i & 3) == 3) __builtin_amdgcn_sched_barrier(0);
;     }
	v_fma_f32 v70, -v15, v120, v70
	v_fma_f32 v72, -v16, v117, v72
	v_fma_f32 v70, -v16, v121, v70
	v_fma_f32 v72, -v18, v118, v72
	v_fma_f32 v70, -v18, v122, v70
	v_fma_f32 v72, -v19, v119, v72
	ds_read_b128 v[116:119], v1 offset:46496
	v_fma_f32 v70, -v19, v123, v70
	ds_read_b128 v[120:123], v1 offset:46752
	s_waitcnt lgkmcnt(13)
	v_fma_f32 v72, -v20, v124, v72
	s_waitcnt lgkmcnt(12)
	v_fma_f32 v70, -v20, v128, v70
	v_fma_f32 v72, -v22, v125, v72
	v_fma_f32 v70, -v22, v129, v70
	v_fma_f32 v72, -v23, v126, v72
	v_fma_f32 v70, -v23, v130, v70
	v_fma_f32 v72, -v24, v127, v72
	ds_read_b128 v[124:127], v1 offset:46512
	v_fma_f32 v70, -v24, v131, v70
	ds_read_b128 v[128:131], v1 offset:46768
	s_waitcnt lgkmcnt(13)
	v_fma_f32 v72, -v25, v132, v72
	s_waitcnt lgkmcnt(12)
	v_fma_f32 v70, -v25, v136, v70
	v_fma_f32 v72, -v27, v133, v72
	v_fma_f32 v70, -v27, v137, v70
	v_fma_f32 v72, -v28, v134, v72
	v_fma_f32 v70, -v28, v138, v70
	v_fma_f32 v72, -v30, v135, v72
	ds_read_b128 v[132:135], v1 offset:46848
	v_fma_f32 v70, -v30, v139, v70
	ds_read_b128 v[136:139], v1 offset:47104
	s_waitcnt lgkmcnt(13)
	v_fma_f32 v72, -v31, v140, v72
	s_waitcnt lgkmcnt(12)
	v_fma_f32 v70, -v31, v144, v70
	v_fma_f32 v72, -v33, v141, v72
	v_fma_f32 v70, -v33, v145, v70
	v_fma_f32 v72, -v34, v142, v72
	v_fma_f32 v70, -v34, v146, v70
	v_fma_f32 v72, -v36, v143, v72
	ds_read_b128 v[140:143], v1 offset:46864
	v_fma_f32 v70, -v36, v147, v70
	ds_read_b128 v[144:147], v1 offset:47120
	s_waitcnt lgkmcnt(13)
	v_fma_f32 v72, -v37, v148, v72
	s_waitcnt lgkmcnt(12)
	v_fma_f32 v70, -v37, v152, v70
	v_fma_f32 v72, -v39, v149, v72
	v_fma_f32 v70, -v39, v153, v70
	v_fma_f32 v72, -v40, v150, v72
	v_fma_f32 v70, -v40, v154, v70
	v_fma_f32 v72, -v44, v151, v72
	ds_read_b128 v[148:151], v1 offset:46880
	v_fma_f32 v70, -v44, v155, v70
	ds_read_b128 v[152:155], v1 offset:47136
	s_waitcnt lgkmcnt(13)
	v_fma_f32 v72, -v46, v100, v72
	s_waitcnt lgkmcnt(12)
	v_fma_f32 v70, -v46, v104, v70
	v_fma_f32 v72, -v47, v101, v72
	v_fma_f32 v70, -v47, v105, v70
	v_fma_f32 v72, -v49, v102, v72
	v_fma_f32 v70, -v49, v106, v70
	v_fma_f32 v72, -v51, v103, v72
	ds_read_b128 v[100:103], v1 offset:46896
	v_fma_f32 v70, -v51, v107, v70
	ds_read_b128 v[104:107], v1 offset:47152
	s_waitcnt lgkmcnt(13)
	v_fma_f32 v72, -v58, v108, v72
	s_waitcnt lgkmcnt(12)
	v_fma_f32 v70, -v58, v112, v70
	v_fma_f32 v72, -v59, v109, v72
	v_fma_f32 v70, -v59, v113, v70
	v_fma_f32 v72, -v61, v110, v72
	v_fma_f32 v70, -v61, v114, v70
	v_fma_f32 v72, -v63, v111, v72
	ds_read_b128 v[108:111], v1 offset:46912
	v_fma_f32 v70, -v63, v115, v70
	ds_read_b128 v[112:115], v1 offset:47168
	s_waitcnt lgkmcnt(13)
	v_fma_f32 v72, -v65, v116, v72
	s_waitcnt lgkmcnt(12)
	v_fma_f32 v70, -v65, v120, v70
	v_fma_f32 v72, -v67, v117, v72
	v_fma_f32 v70, -v67, v121, v70
	v_fma_f32 v72, -v69, v118, v72
	v_fma_f32 v70, -v69, v122, v70
	v_fma_f32 v72, -v119, v71, v72
	ds_read_b128 v[116:119], v1 offset:46928
	v_fma_f32 v70, -v71, v123, v70
	ds_read_b128 v[120:123], v1 offset:47184
	s_waitcnt lgkmcnt(13)
	v_fma_f32 v72, -v124, v73, v72
	ds_read_b128 v[124:127], v1 offset:46944
	s_waitcnt lgkmcnt(13)
	v_fma_f32 v70, -v128, v73, v70
	v_fma_f32 v70, -v129, v72, v70
	ds_read_b128 v[128:131], v1 offset:47200
	s_waitcnt lgkmcnt(13)
	v_fma_f32 v68, -v0, v132, v68
	s_waitcnt lgkmcnt(12)
	v_fma_f32 v66, -v0, v136, v66
	v_fma_f32 v68, -v4, v133, v68
	v_fma_f32 v66, -v4, v137, v66
	v_fma_f32 v68, -v5, v134, v68
	v_fma_f32 v66, -v5, v138, v66
	v_fma_f32 v68, -v6, v135, v68
	ds_read_b128 v[132:135], v1 offset:46960
	v_fma_f32 v66, -v6, v139, v66
	ds_read_b128 v[136:139], v1 offset:47216
	s_waitcnt lgkmcnt(13)
	v_fma_f32 v68, -v7, v140, v68
	s_waitcnt lgkmcnt(12)
	v_fma_f32 v66, -v7, v144, v66
	v_fma_f32 v68, -v8, v141, v68
	v_fma_f32 v66, -v8, v145, v66
	v_fma_f32 v68, -v9, v142, v68
	v_fma_f32 v66, -v9, v146, v66
	v_fma_f32 v68, -v10, v143, v68
	ds_read_b128 v[140:143], v1 offset:46976
	v_fma_f32 v66, -v10, v147, v66
	ds_read_b128 v[144:147], v1 offset:47232
	s_waitcnt lgkmcnt(13)
	v_fma_f32 v68, -v11, v148, v68
	s_waitcnt lgkmcnt(12)
	v_fma_f32 v66, -v11, v152, v66
	v_fma_f32 v68, -v12, v149, v68
	v_fma_f32 v66, -v12, v153, v66
	v_fma_f32 v68, -v13, v150, v68
	v_fma_f32 v66, -v13, v154, v66
	v_fma_f32 v68, -v14, v151, v68
	ds_read_b128 v[148:151], v1 offset:46992
	v_fma_f32 v66, -v14, v155, v66
	ds_read_b128 v[152:155], v1 offset:47248
	s_waitcnt lgkmcnt(13)
	v_fma_f32 v68, -v15, v100, v68
	s_waitcnt lgkmcnt(12)
	v_fma_f32 v66, -v15, v104, v66
	v_fma_f32 v68, -v16, v101, v68
	v_fma_f32 v66, -v16, v105, v66
	v_fma_f32 v68, -v18, v102, v68
	v_fma_f32 v66, -v18, v106, v66
	v_fma_f32 v68, -v19, v103, v68
	ds_read_b128 v[100:103], v1 offset:47008
	v_fma_f32 v66, -v19, v107, v66
	ds_read_b128 v[104:107], v1 offset:47264
	s_waitcnt lgkmcnt(13)
	v_fma_f32 v68, -v20, v108, v68
	s_waitcnt lgkmcnt(12)
	v_fma_f32 v66, -v20, v112, v66
	v_fma_f32 v68, -v22, v109, v68
	v_fma_f32 v66, -v22, v113, v66
	v_fma_f32 v68, -v23, v110, v68
	v_fma_f32 v66, -v23, v114, v66
	v_fma_f32 v68, -v24, v111, v68
	ds_read_b128 v[108:111], v1 offset:47024
	v_fma_f32 v66, -v24, v115, v66
	ds_read_b128 v[112:115], v1 offset:47280
	s_waitcnt lgkmcnt(13)
	v_fma_f32 v68, -v25, v116, v68
	s_waitcnt lgkmcnt(12)
	v_fma_f32 v66, -v25, v120, v66
	v_fma_f32 v68, -v27, v117, v68
	v_fma_f32 v66, -v27, v121, v66
	v_fma_f32 v68, -v28, v118, v68
	v_fma_f32 v66, -v28, v122, v66
	v_fma_f32 v68, -v30, v119, v68
	ds_read_b128 v[116:119], v1 offset:47360
	v_fma_f32 v66, -v30, v123, v66
	ds_read_b128 v[120:123], v1 offset:47616
	s_waitcnt lgkmcnt(13)
	v_fma_f32 v68, -v31, v124, v68
	s_waitcnt lgkmcnt(12)
; DI void gdnprep_item(const Params& p, int item, unsigned char* ldsb) {
;     ...
;     for (int i = 1; i < 64; ++i) {
;       float a = x[i];
; #pragma unroll
;       for (int j4 = 0; j4 < (i + 3) / 4; ++j4) {
;         f32x4 Lv = *(const f32x4*)(Lm + i * 64 + j4 * 4);
; #pragma unroll
;         for (int e = 0; e < 4; ++e) if (j4 * 4 + e < i) a -= Lv[e] * x[j4 * 4 + e];
;       }
;       x[i] = a;
;       if ((i & 3) == 3) __builtin_amdgcn_sched_barrier(0);
;     }
	v_fma_f32 v66, -v31, v128, v66
	v_fma_f32 v68, -v33, v125, v68
	v_fma_f32 v66, -v33, v129, v66
	v_fma_f32 v68, -v34, v126, v68
	v_fma_f32 v66, -v34, v130, v66
	v_fma_f32 v68, -v36, v127, v68
	ds_read_b128 v[124:127], v1 offset:47376
	v_fma_f32 v66, -v36, v131, v66
	ds_read_b128 v[128:131], v1 offset:47632
	s_waitcnt lgkmcnt(13)
	v_fma_f32 v68, -v37, v132, v68
	s_waitcnt lgkmcnt(12)
	v_fma_f32 v66, -v37, v136, v66
	v_fma_f32 v68, -v39, v133, v68
	v_fma_f32 v66, -v39, v137, v66
	v_fma_f32 v68, -v40, v134, v68
	v_fma_f32 v66, -v40, v138, v66
	v_fma_f32 v68, -v44, v135, v68
	ds_read_b128 v[132:135], v1 offset:47392
	v_fma_f32 v66, -v44, v139, v66
	ds_read_b128 v[136:139], v1 offset:47648
	s_waitcnt lgkmcnt(13)
	v_fma_f32 v68, -v46, v140, v68
	s_waitcnt lgkmcnt(12)
	v_fma_f32 v66, -v46, v144, v66
	v_fma_f32 v68, -v47, v141, v68
	v_fma_f32 v66, -v47, v145, v66
	v_fma_f32 v68, -v49, v142, v68
	v_fma_f32 v66, -v49, v146, v66
	v_fma_f32 v68, -v51, v143, v68
	ds_read_b128 v[140:143], v1 offset:47408
	v_fma_f32 v66, -v51, v147, v66
	ds_read_b128 v[144:147], v1 offset:47664
	s_waitcnt lgkmcnt(13)
	v_fma_f32 v68, -v58, v148, v68
	s_waitcnt lgkmcnt(12)
	v_fma_f32 v66, -v58, v152, v66
	v_fma_f32 v68, -v59, v149, v68
	v_fma_f32 v66, -v59, v153, v66
	v_fma_f32 v68, -v61, v150, v68
	v_fma_f32 v66, -v61, v154, v66
	v_fma_f32 v68, -v63, v151, v68
	ds_read_b128 v[148:151], v1 offset:47424
	v_fma_f32 v66, -v63, v155, v66
	ds_read_b128 v[152:155], v1 offset:47680
	s_waitcnt lgkmcnt(13)
	v_fma_f32 v68, -v65, v100, v68
	s_waitcnt lgkmcnt(12)
	v_fma_f32 v66, -v65, v104, v66
	v_fma_f32 v68, -v67, v101, v68
	v_fma_f32 v66, -v67, v105, v66
	v_fma_f32 v68, -v69, v102, v68
	v_fma_f32 v66, -v69, v106, v66
	v_fma_f32 v68, -v71, v103, v68
	ds_read_b128 v[100:103], v1 offset:47440
	v_fma_f32 v66, -v71, v107, v66
	ds_read_b128 v[104:107], v1 offset:47696
	s_waitcnt lgkmcnt(13)
	v_fma_f32 v68, -v73, v108, v68
	s_waitcnt lgkmcnt(12)
	v_fma_f32 v66, -v73, v112, v66
	v_fma_f32 v68, -v109, v72, v68
	v_fma_f32 v66, -v72, v113, v66
	v_fma_f32 v68, -v110, v70, v68
	ds_read_b128 v[108:111], v1 offset:47456
	v_fma_f32 v66, -v114, v70, v66
	v_fma_f32 v66, -v115, v68, v66
	ds_read_b128 v[112:115], v1 offset:47712
	s_waitcnt lgkmcnt(13)
	v_fma_f32 v64, -v0, v116, v64
	s_waitcnt lgkmcnt(12)
	v_fma_f32 v62, -v0, v120, v62
	v_fma_f32 v64, -v4, v117, v64
	v_fma_f32 v62, -v4, v121, v62
	v_fma_f32 v64, -v5, v118, v64
	v_fma_f32 v62, -v5, v122, v62
	v_fma_f32 v64, -v6, v119, v64
	ds_read_b128 v[116:119], v1 offset:47472
	v_fma_f32 v62, -v6, v123, v62
	ds_read_b128 v[120:123], v1 offset:47728
	s_waitcnt lgkmcnt(13)
	v_fma_f32 v64, -v7, v124, v64
	s_waitcnt lgkmcnt(12)
	v_fma_f32 v62, -v7, v128, v62
	v_fma_f32 v64, -v8, v125, v64
	v_fma_f32 v62, -v8, v129, v62
	v_fma_f32 v64, -v9, v126, v64
	v_fma_f32 v62, -v9, v130, v62
	v_fma_f32 v64, -v10, v127, v64
	ds_read_b128 v[124:127], v1 offset:47488
	v_fma_f32 v62, -v10, v131, v62
	ds_read_b128 v[128:131], v1 offset:47744
	s_waitcnt lgkmcnt(13)
	v_fma_f32 v64, -v11, v132, v64
	s_waitcnt lgkmcnt(12)
	v_fma_f32 v62, -v11, v136, v62
	v_fma_f32 v64, -v12, v133, v64
	v_fma_f32 v62, -v12, v137, v62
	v_fma_f32 v64, -v13, v134, v64
	v_fma_f32 v62, -v13, v138, v62
	v_fma_f32 v64, -v14, v135, v64
	ds_read_b128 v[132:135], v1 offset:47504
	v_fma_f32 v62, -v14, v139, v62
	ds_read_b128 v[136:139], v1 offset:47760
	s_waitcnt lgkmcnt(13)
	v_fma_f32 v64, -v15, v140, v64
	s_waitcnt lgkmcnt(12)
	v_fma_f32 v62, -v15, v144, v62
	v_fma_f32 v64, -v16, v141, v64
	v_fma_f32 v62, -v16, v145, v62
	v_fma_f32 v64, -v18, v142, v64
	v_fma_f32 v62, -v18, v146, v62
	v_fma_f32 v64, -v19, v143, v64
	ds_read_b128 v[140:143], v1 offset:47520
	v_fma_f32 v62, -v19, v147, v62
	ds_read_b128 v[144:147], v1 offset:47776
	s_waitcnt lgkmcnt(13)
	v_fma_f32 v64, -v20, v148, v64
	s_waitcnt lgkmcnt(12)
	v_fma_f32 v62, -v20, v152, v62
	v_fma_f32 v64, -v22, v149, v64
	v_fma_f32 v62, -v22, v153, v62
	v_fma_f32 v64, -v23, v150, v64
	v_fma_f32 v62, -v23, v154, v62
	v_fma_f32 v64, -v24, v151, v64
	ds_read_b128 v[148:151], v1 offset:47536
	v_fma_f32 v62, -v24, v155, v62
	ds_read_b128 v[152:155], v1 offset:47792
	s_waitcnt lgkmcnt(13)
	v_fma_f32 v64, -v25, v100, v64
	s_waitcnt lgkmcnt(12)
	v_fma_f32 v62, -v25, v104, v62
	v_fma_f32 v64, -v27, v101, v64
	v_fma_f32 v62, -v27, v105, v62
	v_fma_f32 v64, -v28, v102, v64
	v_fma_f32 v62, -v28, v106, v62
	v_fma_f32 v64, -v30, v103, v64
	ds_read_b128 v[100:103], v1 offset:47552
	v_fma_f32 v62, -v30, v107, v62
	ds_read_b128 v[104:107], v1 offset:47808
	s_waitcnt lgkmcnt(13)
	v_fma_f32 v64, -v31, v108, v64
	s_waitcnt lgkmcnt(12)
	v_fma_f32 v62, -v31, v112, v62
	v_fma_f32 v64, -v33, v109, v64
	v_fma_f32 v62, -v33, v113, v62
	v_fma_f32 v64, -v34, v110, v64
	v_fma_f32 v62, -v34, v114, v62
	v_fma_f32 v64, -v36, v111, v64
	ds_read_b128 v[108:111], v1 offset:47872
	v_fma_f32 v62, -v36, v115, v62
	ds_read_b128 v[112:115], v1 offset:48128
	s_waitcnt lgkmcnt(13)
	v_fma_f32 v64, -v37, v116, v64
	s_waitcnt lgkmcnt(12)
	v_fma_f32 v62, -v37, v120, v62
	v_fma_f32 v64, -v39, v117, v64
	v_fma_f32 v62, -v39, v121, v62
	v_fma_f32 v64, -v40, v118, v64
	v_fma_f32 v62, -v40, v122, v62
	v_fma_f32 v64, -v44, v119, v64
	ds_read_b128 v[116:119], v1 offset:47888
	v_fma_f32 v62, -v44, v123, v62
	ds_read_b128 v[120:123], v1 offset:48144
	s_waitcnt lgkmcnt(13)
	v_fma_f32 v64, -v46, v124, v64
	s_waitcnt lgkmcnt(12)
	v_fma_f32 v62, -v46, v128, v62
	v_fma_f32 v64, -v47, v125, v64
	v_fma_f32 v62, -v47, v129, v62
	v_fma_f32 v64, -v49, v126, v64
	v_fma_f32 v62, -v49, v130, v62
	v_fma_f32 v64, -v51, v127, v64
	ds_read_b128 v[124:127], v1 offset:47904
	v_fma_f32 v62, -v51, v131, v62
	ds_read_b128 v[128:131], v1 offset:48160
	s_waitcnt lgkmcnt(13)
; DI void gdnprep_item(const Params& p, int item, unsigned char* ldsb) {
;     ...
;     for (int i = 1; i < 64; ++i) {
;       float a = x[i];
; #pragma unroll
;       for (int j4 = 0; j4 < (i + 3) / 4; ++j4) {
;         f32x4 Lv = *(const f32x4*)(Lm + i * 64 + j4 * 4);
; #pragma unroll
;         for (int e = 0; e < 4; ++e) if (j4 * 4 + e < i) a -= Lv[e] * x[j4 * 4 + e];
;       }
;       x[i] = a;
;       if ((i & 3) == 3) __builtin_amdgcn_sched_barrier(0);
;     }
	v_fma_f32 v64, -v58, v132, v64
	s_waitcnt lgkmcnt(12)
	v_fma_f32 v62, -v58, v136, v62
	v_fma_f32 v64, -v59, v133, v64
	v_fma_f32 v62, -v59, v137, v62
	v_fma_f32 v64, -v61, v134, v64
	v_fma_f32 v62, -v61, v138, v62
	v_fma_f32 v64, -v63, v135, v64
	ds_read_b128 v[132:135], v1 offset:47920
	v_fma_f32 v62, -v63, v139, v62
	ds_read_b128 v[136:139], v1 offset:48176
	s_waitcnt lgkmcnt(13)
	v_fma_f32 v64, -v65, v140, v64
	s_waitcnt lgkmcnt(12)
	v_fma_f32 v62, -v65, v144, v62
	v_fma_f32 v64, -v67, v141, v64
	v_fma_f32 v62, -v67, v145, v62
	v_fma_f32 v64, -v69, v142, v64
	v_fma_f32 v62, -v69, v146, v62
	v_fma_f32 v64, -v71, v143, v64
	ds_read_b128 v[140:143], v1 offset:47936
	v_fma_f32 v62, -v71, v147, v62
	ds_read_b128 v[144:147], v1 offset:48192
	s_waitcnt lgkmcnt(13)
	v_fma_f32 v64, -v73, v148, v64
	s_waitcnt lgkmcnt(12)
	v_fma_f32 v62, -v73, v152, v62
	v_fma_f32 v64, -v72, v149, v64
	v_fma_f32 v62, -v72, v153, v62
	v_fma_f32 v64, -v70, v150, v64
	v_fma_f32 v62, -v70, v154, v62
	v_fma_f32 v64, -v151, v68, v64
	ds_read_b128 v[148:151], v1 offset:47952
	v_fma_f32 v62, -v68, v155, v62
	ds_read_b128 v[152:155], v1 offset:48208
	s_waitcnt lgkmcnt(13)
	v_fma_f32 v64, -v100, v66, v64
	ds_read_b128 v[100:103], v1 offset:47968
	s_waitcnt lgkmcnt(13)
	v_fma_f32 v62, -v104, v66, v62
	v_fma_f32 v62, -v105, v64, v62
	ds_read_b128 v[104:107], v1 offset:48224
	s_waitcnt lgkmcnt(13)
	v_fma_f32 v60, -v0, v108, v60
	s_waitcnt lgkmcnt(12)
	v_fma_f32 v57, -v0, v112, v57
	v_fma_f32 v60, -v4, v109, v60
	v_fma_f32 v57, -v4, v113, v57
	v_fma_f32 v60, -v5, v110, v60
	v_fma_f32 v57, -v5, v114, v57
	v_fma_f32 v60, -v6, v111, v60
	ds_read_b128 v[108:111], v1 offset:47984
	v_fma_f32 v57, -v6, v115, v57
	ds_read_b128 v[112:115], v1 offset:48240
	s_waitcnt lgkmcnt(13)
	v_fma_f32 v60, -v7, v116, v60
	s_waitcnt lgkmcnt(12)
	v_fma_f32 v57, -v7, v120, v57
	v_fma_f32 v60, -v8, v117, v60
	v_fma_f32 v57, -v8, v121, v57
	v_fma_f32 v60, -v9, v118, v60
	v_fma_f32 v57, -v9, v122, v57
	v_fma_f32 v60, -v10, v119, v60
	ds_read_b128 v[116:119], v1 offset:48000
	v_fma_f32 v57, -v10, v123, v57
	ds_read_b128 v[120:123], v1 offset:48256
	s_waitcnt lgkmcnt(13)
	v_fma_f32 v60, -v11, v124, v60
	s_waitcnt lgkmcnt(12)
	v_fma_f32 v57, -v11, v128, v57
	v_fma_f32 v60, -v12, v125, v60
	v_fma_f32 v57, -v12, v129, v57
	v_fma_f32 v60, -v13, v126, v60
	v_fma_f32 v57, -v13, v130, v57
	v_fma_f32 v60, -v14, v127, v60
	ds_read_b128 v[124:127], v1 offset:48016
	v_fma_f32 v57, -v14, v131, v57
	ds_read_b128 v[128:131], v1 offset:48272
	s_waitcnt lgkmcnt(13)
	v_fma_f32 v60, -v15, v132, v60
	s_waitcnt lgkmcnt(12)
	v_fma_f32 v57, -v15, v136, v57
	v_fma_f32 v60, -v16, v133, v60
	v_fma_f32 v57, -v16, v137, v57
	v_fma_f32 v60, -v18, v134, v60
	v_fma_f32 v57, -v18, v138, v57
	v_fma_f32 v60, -v19, v135, v60
	ds_read_b128 v[132:135], v1 offset:48032
	v_fma_f32 v57, -v19, v139, v57
	ds_read_b128 v[136:139], v1 offset:48288
	s_waitcnt lgkmcnt(13)
	v_fma_f32 v60, -v20, v140, v60
	s_waitcnt lgkmcnt(12)
	v_fma_f32 v57, -v20, v144, v57
	v_fma_f32 v60, -v22, v141, v60
	v_fma_f32 v57, -v22, v145, v57
	v_fma_f32 v60, -v23, v142, v60
	v_fma_f32 v57, -v23, v146, v57
	v_fma_f32 v60, -v24, v143, v60
	ds_read_b128 v[140:143], v1 offset:48048
	v_fma_f32 v57, -v24, v147, v57
	ds_read_b128 v[144:147], v1 offset:48304
	s_waitcnt lgkmcnt(13)
	v_fma_f32 v60, -v25, v148, v60
	s_waitcnt lgkmcnt(12)
	v_fma_f32 v57, -v25, v152, v57
	v_fma_f32 v60, -v27, v149, v60
	v_fma_f32 v57, -v27, v153, v57
	v_fma_f32 v60, -v28, v150, v60
	v_fma_f32 v57, -v28, v154, v57
	v_fma_f32 v60, -v30, v151, v60
	ds_read_b128 v[148:151], v1 offset:48064
	v_fma_f32 v57, -v30, v155, v57
	ds_read_b128 v[152:155], v1 offset:48320
	s_waitcnt lgkmcnt(13)
	v_fma_f32 v60, -v31, v100, v60
	s_waitcnt lgkmcnt(12)
	v_fma_f32 v57, -v31, v104, v57
	v_fma_f32 v60, -v33, v101, v60
	v_fma_f32 v57, -v33, v105, v57
	v_fma_f32 v60, -v34, v102, v60
	v_fma_f32 v57, -v34, v106, v57
	v_fma_f32 v60, -v36, v103, v60
	ds_read_b128 v[100:103], v1 offset:48384
	v_fma_f32 v57, -v36, v107, v57
	ds_read_b128 v[104:107], v1 offset:48640
	s_waitcnt lgkmcnt(13)
	v_fma_f32 v60, -v37, v108, v60
	s_waitcnt lgkmcnt(12)
	v_fma_f32 v57, -v37, v112, v57
	v_fma_f32 v60, -v39, v109, v60
	v_fma_f32 v57, -v39, v113, v57
	v_fma_f32 v60, -v40, v110, v60
	v_fma_f32 v57, -v40, v114, v57
	v_fma_f32 v60, -v44, v111, v60
	ds_read_b128 v[108:111], v1 offset:48400
	v_fma_f32 v57, -v44, v115, v57
	ds_read_b128 v[112:115], v1 offset:48656
	s_waitcnt lgkmcnt(13)
	v_fma_f32 v60, -v46, v116, v60
	s_waitcnt lgkmcnt(12)
	v_fma_f32 v57, -v46, v120, v57
	v_fma_f32 v60, -v47, v117, v60
	v_fma_f32 v57, -v47, v121, v57
	v_fma_f32 v60, -v49, v118, v60
	v_fma_f32 v57, -v49, v122, v57
	v_fma_f32 v60, -v51, v119, v60
	ds_read_b128 v[116:119], v1 offset:48416
	v_fma_f32 v57, -v51, v123, v57
	ds_read_b128 v[120:123], v1 offset:48672
	s_waitcnt lgkmcnt(13)
	v_fma_f32 v60, -v58, v124, v60
	s_waitcnt lgkmcnt(12)
	v_fma_f32 v57, -v58, v128, v57
	v_fma_f32 v60, -v59, v125, v60
	v_fma_f32 v57, -v59, v129, v57
	v_fma_f32 v60, -v61, v126, v60
	v_fma_f32 v57, -v61, v130, v57
	v_fma_f32 v60, -v63, v127, v60
	ds_read_b128 v[124:127], v1 offset:48432
	v_fma_f32 v57, -v63, v131, v57
	ds_read_b128 v[128:131], v1 offset:48688
	s_waitcnt lgkmcnt(13)
	v_fma_f32 v60, -v65, v132, v60
	s_waitcnt lgkmcnt(12)
	v_fma_f32 v57, -v65, v136, v57
	v_fma_f32 v60, -v67, v133, v60
	v_fma_f32 v57, -v67, v137, v57
	v_fma_f32 v60, -v69, v134, v60
	v_fma_f32 v57, -v69, v138, v57
	v_fma_f32 v60, -v71, v135, v60
	ds_read_b128 v[132:135], v1 offset:48448
	v_fma_f32 v57, -v71, v139, v57
	ds_read_b128 v[136:139], v1 offset:48704
	s_waitcnt lgkmcnt(13)
; DI void gdnprep_item(const Params& p, int item, unsigned char* ldsb) {
;     ...
; #pragma unroll
;     for (int i = 1; i < 64; ++i) {
;       float a = x[i];
; #pragma unroll
;       for (int j4 = 0; j4 < (i + 3) / 4; ++j4) {
;         f32x4 Lv = *(const f32x4*)(Lm + i * 64 + j4 * 4);
; #pragma unroll
;         for (int e = 0; e < 4; ++e) if (j4 * 4 + e < i) a -= Lv[e] * x[j4 * 4 + e];
;       }
;       x[i] = a;
;       if ((i & 3) == 3) __builtin_amdgcn_sched_barrier(0);
;     }
	v_fma_f32 v60, -v73, v140, v60
	s_waitcnt lgkmcnt(12)
	v_fma_f32 v57, -v73, v144, v57
	v_fma_f32 v60, -v72, v141, v60
	v_fma_f32 v57, -v72, v145, v57
	v_fma_f32 v60, -v70, v142, v60
	v_fma_f32 v57, -v70, v146, v57
	v_fma_f32 v60, -v68, v143, v60
	ds_read_b128 v[140:143], v1 offset:48464
	v_fma_f32 v57, -v68, v147, v57
	ds_read_b128 v[144:147], v1 offset:48720
	s_waitcnt lgkmcnt(13)
	v_fma_f32 v60, -v66, v148, v60
	s_waitcnt lgkmcnt(12)
	v_fma_f32 v57, -v66, v152, v57
	v_fma_f32 v60, -v149, v64, v60
	v_fma_f32 v57, -v64, v153, v57
	v_fma_f32 v60, -v150, v62, v60
	ds_read_b128 v[148:151], v1 offset:48480
	v_fma_f32 v57, -v154, v62, v57
	v_fma_f32 v57, -v155, v60, v57
	ds_read_b128 v[152:155], v1 offset:48736
	s_waitcnt lgkmcnt(13)
	v_fma_f32 v50, -v0, v100, v50
	s_waitcnt lgkmcnt(12)
	v_fma_f32 v48, -v0, v104, v48
	v_fma_f32 v50, -v4, v101, v50
	v_fma_f32 v48, -v4, v105, v48
	v_fma_f32 v50, -v5, v102, v50
	v_fma_f32 v48, -v5, v106, v48
	v_fma_f32 v50, -v6, v103, v50
	ds_read_b128 v[100:103], v1 offset:48496
	v_fma_f32 v48, -v6, v107, v48
	ds_read_b128 v[104:107], v1 offset:48752
	s_waitcnt lgkmcnt(13)
	v_fma_f32 v50, -v7, v108, v50
	s_waitcnt lgkmcnt(12)
	v_fma_f32 v48, -v7, v112, v48
	v_fma_f32 v50, -v8, v109, v50
	v_fma_f32 v48, -v8, v113, v48
	v_fma_f32 v50, -v9, v110, v50
	v_fma_f32 v48, -v9, v114, v48
	v_fma_f32 v50, -v10, v111, v50
	ds_read_b128 v[108:111], v1 offset:48512
	v_fma_f32 v48, -v10, v115, v48
	ds_read_b128 v[112:115], v1 offset:48768
	s_waitcnt lgkmcnt(13)
	v_fma_f32 v50, -v11, v116, v50
	s_waitcnt lgkmcnt(12)
	v_fma_f32 v48, -v11, v120, v48
	v_fma_f32 v50, -v12, v117, v50
	v_fma_f32 v48, -v12, v121, v48
	v_fma_f32 v50, -v13, v118, v50
	v_fma_f32 v48, -v13, v122, v48
	v_fma_f32 v50, -v14, v119, v50
	ds_read_b128 v[116:119], v1 offset:48528
	v_fma_f32 v48, -v14, v123, v48
	ds_read_b128 v[120:123], v1 offset:48784
	s_waitcnt lgkmcnt(13)
	v_fma_f32 v50, -v15, v124, v50
	s_waitcnt lgkmcnt(12)
	v_fma_f32 v48, -v15, v128, v48
	v_fma_f32 v50, -v16, v125, v50
	v_fma_f32 v48, -v16, v129, v48
	v_fma_f32 v50, -v18, v126, v50
	v_fma_f32 v48, -v18, v130, v48
	v_fma_f32 v50, -v19, v127, v50
	ds_read_b128 v[124:127], v1 offset:48544
	v_fma_f32 v48, -v19, v131, v48
	ds_read_b128 v[128:131], v1 offset:48800
	s_waitcnt lgkmcnt(13)
	v_fma_f32 v50, -v20, v132, v50
	s_waitcnt lgkmcnt(12)
	v_fma_f32 v48, -v20, v136, v48
	v_fma_f32 v50, -v22, v133, v50
	v_fma_f32 v48, -v22, v137, v48
	v_fma_f32 v50, -v23, v134, v50
	v_fma_f32 v48, -v23, v138, v48
	v_fma_f32 v50, -v24, v135, v50
	ds_read_b128 v[132:135], v1 offset:48560
	v_fma_f32 v48, -v24, v139, v48
	ds_read_b128 v[136:139], v1 offset:48816
	s_waitcnt lgkmcnt(13)
	v_fma_f32 v50, -v25, v140, v50
	s_waitcnt lgkmcnt(12)
	v_fma_f32 v48, -v25, v144, v48
	v_fma_f32 v50, -v27, v141, v50
	v_fma_f32 v48, -v27, v145, v48
	v_fma_f32 v50, -v28, v142, v50
	v_fma_f32 v48, -v28, v146, v48
	v_fma_f32 v50, -v30, v143, v50
	ds_read_b128 v[140:143], v1 offset:48576
	v_fma_f32 v48, -v30, v147, v48
	ds_read_b128 v[144:147], v1 offset:48832
	s_waitcnt lgkmcnt(13)
	v_fma_f32 v50, -v31, v148, v50
	s_waitcnt lgkmcnt(12)
	v_fma_f32 v48, -v31, v152, v48
	v_fma_f32 v50, -v33, v149, v50
	v_fma_f32 v48, -v33, v153, v48
	v_fma_f32 v50, -v34, v150, v50
	v_fma_f32 v48, -v34, v154, v48
	v_fma_f32 v50, -v36, v151, v50
	ds_read_b128 v[148:151], v1 offset:48592
	v_fma_f32 v48, -v36, v155, v48
	ds_read_b128 v[152:155], v1 offset:48848
	s_waitcnt lgkmcnt(13)
	v_fma_f32 v50, -v37, v100, v50
	s_waitcnt lgkmcnt(12)
	v_fma_f32 v48, -v37, v104, v48
	v_fma_f32 v50, -v39, v101, v50
	v_fma_f32 v48, -v39, v105, v48
	v_fma_f32 v50, -v40, v102, v50
	v_fma_f32 v48, -v40, v106, v48
	v_fma_f32 v50, -v44, v103, v50
	ds_read_b128 v[100:103], v1 offset:48896
	v_fma_f32 v48, -v44, v107, v48
	ds_read_b128 v[104:107], v1 offset:49152
	s_waitcnt lgkmcnt(13)
	v_fma_f32 v50, -v46, v108, v50
	s_waitcnt lgkmcnt(12)
	v_fma_f32 v48, -v46, v112, v48
	v_fma_f32 v50, -v47, v109, v50
	v_fma_f32 v48, -v47, v113, v48
	v_fma_f32 v50, -v49, v110, v50
	v_fma_f32 v48, -v49, v114, v48
	v_fma_f32 v50, -v51, v111, v50
	ds_read_b128 v[108:111], v1 offset:48912
	v_fma_f32 v48, -v51, v115, v48
	ds_read_b128 v[112:115], v1 offset:49168
	s_waitcnt lgkmcnt(13)
	v_fma_f32 v50, -v58, v116, v50
	s_waitcnt lgkmcnt(12)
	v_fma_f32 v48, -v58, v120, v48
	v_fma_f32 v50, -v59, v117, v50
	v_fma_f32 v48, -v59, v121, v48
	v_fma_f32 v50, -v61, v118, v50
	v_fma_f32 v48, -v61, v122, v48
	v_fma_f32 v50, -v63, v119, v50
	ds_read_b128 v[116:119], v1 offset:48928
	v_fma_f32 v48, -v63, v123, v48
	ds_read_b128 v[120:123], v1 offset:49184
	s_waitcnt lgkmcnt(13)
	v_fma_f32 v50, -v65, v124, v50
	s_waitcnt lgkmcnt(12)
	v_fma_f32 v48, -v65, v128, v48
	v_fma_f32 v50, -v67, v125, v50
	v_fma_f32 v48, -v67, v129, v48
	v_fma_f32 v50, -v69, v126, v50
	v_fma_f32 v48, -v69, v130, v48
	v_fma_f32 v50, -v71, v127, v50
	ds_read_b128 v[124:127], v1 offset:48944
	v_fma_f32 v48, -v71, v131, v48
	ds_read_b128 v[128:131], v1 offset:49200
	s_waitcnt lgkmcnt(13)
	v_fma_f32 v50, -v73, v132, v50
	s_waitcnt lgkmcnt(12)
	v_fma_f32 v48, -v73, v136, v48
	v_fma_f32 v50, -v72, v133, v50
	v_fma_f32 v48, -v72, v137, v48
	v_fma_f32 v50, -v70, v134, v50
	v_fma_f32 v48, -v70, v138, v48
	v_fma_f32 v50, -v68, v135, v50
	ds_read_b128 v[132:135], v1 offset:48960
	v_fma_f32 v48, -v68, v139, v48
	ds_read_b128 v[136:139], v1 offset:49216
	s_waitcnt lgkmcnt(13)
	v_fma_f32 v50, -v66, v140, v50
	s_waitcnt lgkmcnt(12)
	v_fma_f32 v48, -v66, v144, v48
	v_fma_f32 v50, -v64, v141, v50
	v_fma_f32 v48, -v64, v145, v48
	v_fma_f32 v50, -v62, v142, v50
	v_fma_f32 v48, -v62, v146, v48
	v_fma_f32 v50, -v143, v60, v50
	ds_read_b128 v[140:143], v1 offset:48976
	v_fma_f32 v48, -v60, v147, v48
	ds_read_b128 v[144:147], v1 offset:49232
	s_waitcnt lgkmcnt(13)
; DI void gdnprep_item(const Params& p, int item, unsigned char* ldsb) {
;     ...
; #pragma unroll
;     for (int i = 1; i < 64; ++i) {
;       float a = x[i];
; #pragma unroll
;       for (int j4 = 0; j4 < (i + 3) / 4; ++j4) {
;         f32x4 Lv = *(const f32x4*)(Lm + i * 64 + j4 * 4);
; #pragma unroll
;         for (int e = 0; e < 4; ++e) if (j4 * 4 + e < i) a -= Lv[e] * x[j4 * 4 + e];
;       }
;       x[i] = a;
;       if ((i & 3) == 3) __builtin_amdgcn_sched_barrier(0);
;     }
	v_fma_f32 v50, -v148, v57, v50
	ds_read_b128 v[148:151], v1 offset:48992
	s_waitcnt lgkmcnt(13)
	v_fma_f32 v48, -v152, v57, v48
	v_fma_f32 v48, -v153, v50, v48
	ds_read_b128 v[152:155], v1 offset:49248
	s_waitcnt lgkmcnt(13)
	v_fma_f32 v45, -v0, v100, v45
	s_waitcnt lgkmcnt(12)
	v_fma_f32 v41, -v0, v104, v41
	v_fma_f32 v45, -v4, v101, v45
	v_fma_f32 v41, -v4, v105, v41
	v_fma_f32 v45, -v5, v102, v45
	v_fma_f32 v41, -v5, v106, v41
	v_fma_f32 v45, -v6, v103, v45
	ds_read_b128 v[100:103], v1 offset:49008
	v_fma_f32 v41, -v6, v107, v41
	ds_read_b128 v[104:107], v1 offset:49264
	s_waitcnt lgkmcnt(13)
	v_fma_f32 v45, -v7, v108, v45
	s_waitcnt lgkmcnt(12)
	v_fma_f32 v41, -v7, v112, v41
	v_fma_f32 v45, -v8, v109, v45
	v_fma_f32 v41, -v8, v113, v41
	v_fma_f32 v45, -v9, v110, v45
	v_fma_f32 v41, -v9, v114, v41
	v_fma_f32 v45, -v10, v111, v45
	ds_read_b128 v[108:111], v1 offset:49024
	v_fma_f32 v41, -v10, v115, v41
	ds_read_b128 v[112:115], v1 offset:49280
	s_waitcnt lgkmcnt(13)
	v_fma_f32 v45, -v11, v116, v45
	s_waitcnt lgkmcnt(12)
	v_fma_f32 v41, -v11, v120, v41
	v_fma_f32 v45, -v12, v117, v45
	v_fma_f32 v41, -v12, v121, v41
	v_fma_f32 v45, -v13, v118, v45
	v_fma_f32 v41, -v13, v122, v41
	v_fma_f32 v45, -v14, v119, v45
	ds_read_b128 v[116:119], v1 offset:49040
	v_fma_f32 v41, -v14, v123, v41
	ds_read_b128 v[120:123], v1 offset:49296
	s_waitcnt lgkmcnt(13)
	v_fma_f32 v45, -v15, v124, v45
	s_waitcnt lgkmcnt(12)
	v_fma_f32 v41, -v15, v128, v41
	v_fma_f32 v45, -v16, v125, v45
	v_fma_f32 v41, -v16, v129, v41
	v_fma_f32 v45, -v18, v126, v45
	v_fma_f32 v41, -v18, v130, v41
	v_fma_f32 v45, -v19, v127, v45
	ds_read_b128 v[124:127], v1 offset:49056
	v_fma_f32 v41, -v19, v131, v41
	ds_read_b128 v[128:131], v1 offset:49312
	s_waitcnt lgkmcnt(13)
	v_fma_f32 v45, -v20, v132, v45
	s_waitcnt lgkmcnt(12)
	v_fma_f32 v41, -v20, v136, v41
	v_fma_f32 v45, -v22, v133, v45
	v_fma_f32 v41, -v22, v137, v41
	v_fma_f32 v45, -v23, v134, v45
	v_fma_f32 v41, -v23, v138, v41
	v_fma_f32 v45, -v24, v135, v45
	ds_read_b128 v[132:135], v1 offset:49072
	v_fma_f32 v41, -v24, v139, v41
	ds_read_b128 v[136:139], v1 offset:49328
	s_waitcnt lgkmcnt(13)
	v_fma_f32 v45, -v25, v140, v45
	s_waitcnt lgkmcnt(12)
	v_fma_f32 v41, -v25, v144, v41
	v_fma_f32 v45, -v27, v141, v45
	v_fma_f32 v41, -v27, v145, v41
	v_fma_f32 v45, -v28, v142, v45
	v_fma_f32 v41, -v28, v146, v41
	v_fma_f32 v45, -v30, v143, v45
	ds_read_b128 v[140:143], v1 offset:49088
	v_fma_f32 v41, -v30, v147, v41
	ds_read_b128 v[144:147], v1 offset:49344
	s_waitcnt lgkmcnt(13)
	v_fma_f32 v45, -v31, v148, v45
	s_waitcnt lgkmcnt(12)
	v_fma_f32 v41, -v31, v152, v41
	v_fma_f32 v45, -v33, v149, v45
	v_fma_f32 v41, -v33, v153, v41
	v_fma_f32 v45, -v34, v150, v45
	v_fma_f32 v41, -v34, v154, v41
	v_fma_f32 v45, -v36, v151, v45
	ds_read_b128 v[148:151], v1 offset:49104
	v_fma_f32 v41, -v36, v155, v41
	ds_read_b128 v[152:155], v1 offset:49360
	s_waitcnt lgkmcnt(13)
	v_fma_f32 v45, -v37, v100, v45
	s_waitcnt lgkmcnt(12)
	v_fma_f32 v41, -v37, v104, v41
	v_fma_f32 v45, -v39, v101, v45
	v_fma_f32 v41, -v39, v105, v41
	v_fma_f32 v45, -v40, v102, v45
	v_fma_f32 v41, -v40, v106, v41
	v_fma_f32 v45, -v44, v103, v45
	ds_read_b128 v[100:103], v1 offset:49408
	v_fma_f32 v41, -v44, v107, v41
	ds_read_b128 v[104:107], v1 offset:49664
	s_waitcnt lgkmcnt(13)
	v_fma_f32 v45, -v46, v108, v45
	s_waitcnt lgkmcnt(12)
	v_fma_f32 v41, -v46, v112, v41
	v_fma_f32 v45, -v47, v109, v45
	v_fma_f32 v41, -v47, v113, v41
	v_fma_f32 v45, -v49, v110, v45
	v_fma_f32 v41, -v49, v114, v41
	v_fma_f32 v45, -v51, v111, v45
	ds_read_b128 v[108:111], v1 offset:49424
	v_fma_f32 v41, -v51, v115, v41
	ds_read_b128 v[112:115], v1 offset:49680
	s_waitcnt lgkmcnt(13)
	v_fma_f32 v45, -v58, v116, v45
	s_waitcnt lgkmcnt(12)
	v_fma_f32 v41, -v58, v120, v41
	v_fma_f32 v45, -v59, v117, v45
	v_fma_f32 v41, -v59, v121, v41
	v_fma_f32 v45, -v61, v118, v45
	v_fma_f32 v41, -v61, v122, v41
	v_fma_f32 v45, -v63, v119, v45
	ds_read_b128 v[116:119], v1 offset:49440
	v_fma_f32 v41, -v63, v123, v41
	ds_read_b128 v[120:123], v1 offset:49696
	s_waitcnt lgkmcnt(13)
	v_fma_f32 v45, -v65, v124, v45
	s_waitcnt lgkmcnt(12)
	v_fma_f32 v41, -v65, v128, v41
	v_fma_f32 v45, -v67, v125, v45
	v_fma_f32 v41, -v67, v129, v41
	v_fma_f32 v45, -v69, v126, v45
	v_fma_f32 v41, -v69, v130, v41
	v_fma_f32 v45, -v71, v127, v45
	ds_read_b128 v[124:127], v1 offset:49456
	v_fma_f32 v41, -v71, v131, v41
	ds_read_b128 v[128:131], v1 offset:49712
	s_waitcnt lgkmcnt(13)
	v_fma_f32 v45, -v73, v132, v45
	s_waitcnt lgkmcnt(12)
	v_fma_f32 v41, -v73, v136, v41
	v_fma_f32 v45, -v72, v133, v45
	v_fma_f32 v41, -v72, v137, v41
	v_fma_f32 v45, -v70, v134, v45
	v_fma_f32 v41, -v70, v138, v41
	v_fma_f32 v45, -v68, v135, v45
	ds_read_b128 v[132:135], v1 offset:49472
	v_fma_f32 v41, -v68, v139, v41
	ds_read_b128 v[136:139], v1 offset:49728
	s_waitcnt lgkmcnt(13)
	v_fma_f32 v45, -v66, v140, v45
	s_waitcnt lgkmcnt(12)
	v_fma_f32 v41, -v66, v144, v41
	v_fma_f32 v45, -v64, v141, v45
	v_fma_f32 v41, -v64, v145, v41
	v_fma_f32 v45, -v62, v142, v45
	v_fma_f32 v41, -v62, v146, v41
	v_fma_f32 v45, -v60, v143, v45
	ds_read_b128 v[140:143], v1 offset:49488
	v_fma_f32 v41, -v60, v147, v41
	ds_read_b128 v[144:147], v1 offset:49744
	s_waitcnt lgkmcnt(13)
	v_fma_f32 v45, -v57, v148, v45
	s_waitcnt lgkmcnt(12)
	v_fma_f32 v41, -v57, v152, v41
	v_fma_f32 v45, -v149, v50, v45
	v_fma_f32 v41, -v50, v153, v41
	v_fma_f32 v45, -v150, v48, v45
	ds_read_b128 v[148:151], v1 offset:49504
	v_fma_f32 v41, -v154, v48, v41
	v_fma_f32 v41, -v155, v45, v41
	ds_read_b128 v[152:155], v1 offset:49760
	s_waitcnt lgkmcnt(13)
	v_fma_f32 v38, -v0, v100, v38
	s_waitcnt lgkmcnt(12)
; DI void gdnprep_item(const Params& p, int item, unsigned char* ldsb) {
;     ...
; #pragma unroll
;     for (int i = 1; i < 64; ++i) {
;       float a = x[i];
; #pragma unroll
;       for (int j4 = 0; j4 < (i + 3) / 4; ++j4) {
;         f32x4 Lv = *(const f32x4*)(Lm + i * 64 + j4 * 4);
; #pragma unroll
;         for (int e = 0; e < 4; ++e) if (j4 * 4 + e < i) a -= Lv[e] * x[j4 * 4 + e];
;       }
;       x[i] = a;
;       if ((i & 3) == 3) __builtin_amdgcn_sched_barrier(0);
;     }
	v_fma_f32 v35, -v0, v104, v35
	v_fma_f32 v38, -v4, v101, v38
	v_fma_f32 v35, -v4, v105, v35
	v_fma_f32 v38, -v5, v102, v38
	v_fma_f32 v35, -v5, v106, v35
	v_fma_f32 v38, -v6, v103, v38
	ds_read_b128 v[100:103], v1 offset:49520
	v_fma_f32 v35, -v6, v107, v35
	ds_read_b128 v[104:107], v1 offset:49776
	s_waitcnt lgkmcnt(13)
	v_fma_f32 v38, -v7, v108, v38
	s_waitcnt lgkmcnt(12)
	v_fma_f32 v35, -v7, v112, v35
	v_fma_f32 v38, -v8, v109, v38
	v_fma_f32 v35, -v8, v113, v35
	v_fma_f32 v38, -v9, v110, v38
	v_fma_f32 v35, -v9, v114, v35
	v_fma_f32 v38, -v10, v111, v38
	ds_read_b128 v[108:111], v1 offset:49536
	v_fma_f32 v35, -v10, v115, v35
	ds_read_b128 v[112:115], v1 offset:49792
	s_waitcnt lgkmcnt(13)
	v_fma_f32 v38, -v11, v116, v38
	s_waitcnt lgkmcnt(12)
	v_fma_f32 v35, -v11, v120, v35
	v_fma_f32 v38, -v12, v117, v38
	v_fma_f32 v35, -v12, v121, v35
	v_fma_f32 v38, -v13, v118, v38
	v_fma_f32 v35, -v13, v122, v35
	v_fma_f32 v38, -v14, v119, v38
	ds_read_b128 v[116:119], v1 offset:49552
	v_fma_f32 v35, -v14, v123, v35
	ds_read_b128 v[120:123], v1 offset:49808
	s_waitcnt lgkmcnt(13)
	v_fma_f32 v38, -v15, v124, v38
	s_waitcnt lgkmcnt(12)
	v_fma_f32 v35, -v15, v128, v35
	v_fma_f32 v38, -v16, v125, v38
	v_fma_f32 v35, -v16, v129, v35
	v_fma_f32 v38, -v18, v126, v38
	v_fma_f32 v35, -v18, v130, v35
	v_fma_f32 v38, -v19, v127, v38
	ds_read_b128 v[124:127], v1 offset:49568
	v_fma_f32 v35, -v19, v131, v35
	ds_read_b128 v[128:131], v1 offset:49824
	s_waitcnt lgkmcnt(13)
	v_fma_f32 v38, -v20, v132, v38
	s_waitcnt lgkmcnt(12)
	v_fma_f32 v35, -v20, v136, v35
	v_fma_f32 v38, -v22, v133, v38
	v_fma_f32 v35, -v22, v137, v35
	v_fma_f32 v38, -v23, v134, v38
	v_fma_f32 v35, -v23, v138, v35
	v_fma_f32 v38, -v24, v135, v38
	ds_read_b128 v[132:135], v1 offset:49584
	v_fma_f32 v35, -v24, v139, v35
	ds_read_b128 v[136:139], v1 offset:49840
	s_waitcnt lgkmcnt(13)
	v_fma_f32 v38, -v25, v140, v38
	s_waitcnt lgkmcnt(12)
	v_fma_f32 v35, -v25, v144, v35
	v_fma_f32 v38, -v27, v141, v38
	v_fma_f32 v35, -v27, v145, v35
	v_fma_f32 v38, -v28, v142, v38
	v_fma_f32 v35, -v28, v146, v35
	v_fma_f32 v38, -v30, v143, v38
	ds_read_b128 v[140:143], v1 offset:49600
	v_fma_f32 v35, -v30, v147, v35
	ds_read_b128 v[144:147], v1 offset:49856
	s_waitcnt lgkmcnt(13)
	v_fma_f32 v38, -v31, v148, v38
	s_waitcnt lgkmcnt(12)
	v_fma_f32 v35, -v31, v152, v35
	v_fma_f32 v38, -v33, v149, v38
	v_fma_f32 v35, -v33, v153, v35
	v_fma_f32 v38, -v34, v150, v38
	v_fma_f32 v35, -v34, v154, v35
	v_fma_f32 v38, -v36, v151, v38
	ds_read_b128 v[148:151], v1 offset:49616
	v_fma_f32 v35, -v36, v155, v35
	ds_read_b128 v[152:155], v1 offset:49872
	s_waitcnt lgkmcnt(13)
	v_fma_f32 v38, -v37, v100, v38
	s_waitcnt lgkmcnt(12)
	v_fma_f32 v35, -v37, v104, v35
	v_fma_f32 v38, -v39, v101, v38
	v_fma_f32 v35, -v39, v105, v35
	v_fma_f32 v38, -v40, v102, v38
	v_fma_f32 v35, -v40, v106, v35
	v_fma_f32 v38, -v44, v103, v38
	ds_read_b128 v[100:103], v1 offset:49632
	v_fma_f32 v35, -v44, v107, v35
	ds_read_b128 v[104:107], v1 offset:49888
	s_waitcnt lgkmcnt(13)
	v_fma_f32 v38, -v46, v108, v38
	s_waitcnt lgkmcnt(12)
	v_fma_f32 v35, -v46, v112, v35
	v_fma_f32 v38, -v47, v109, v38
	v_fma_f32 v35, -v47, v113, v35
	v_fma_f32 v38, -v49, v110, v38
	v_fma_f32 v35, -v49, v114, v35
	v_fma_f32 v38, -v51, v111, v38
	ds_read_b128 v[108:111], v1 offset:49920
	v_fma_f32 v35, -v51, v115, v35
	ds_read_b128 v[112:115], v1 offset:50176
	s_waitcnt lgkmcnt(13)
	v_fma_f32 v38, -v58, v116, v38
	s_waitcnt lgkmcnt(12)
	v_fma_f32 v35, -v58, v120, v35
	v_fma_f32 v38, -v59, v117, v38
	v_fma_f32 v35, -v59, v121, v35
	v_fma_f32 v38, -v61, v118, v38
	v_fma_f32 v35, -v61, v122, v35
	v_fma_f32 v38, -v63, v119, v38
	ds_read_b128 v[116:119], v1 offset:49936
	v_fma_f32 v35, -v63, v123, v35
	ds_read_b128 v[120:123], v1 offset:50192
	s_waitcnt lgkmcnt(13)
	v_fma_f32 v38, -v65, v124, v38
	s_waitcnt lgkmcnt(12)
	v_fma_f32 v35, -v65, v128, v35
	v_fma_f32 v38, -v67, v125, v38
	v_fma_f32 v35, -v67, v129, v35
	v_fma_f32 v38, -v69, v126, v38
	v_fma_f32 v35, -v69, v130, v35
	v_fma_f32 v38, -v71, v127, v38
	ds_read_b128 v[124:127], v1 offset:49952
	v_fma_f32 v35, -v71, v131, v35
	ds_read_b128 v[128:131], v1 offset:50208
	s_waitcnt lgkmcnt(13)
	v_fma_f32 v38, -v73, v132, v38
	s_waitcnt lgkmcnt(12)
	v_fma_f32 v35, -v73, v136, v35
	v_fma_f32 v38, -v72, v133, v38
	v_fma_f32 v35, -v72, v137, v35
	v_fma_f32 v38, -v70, v134, v38
	v_fma_f32 v35, -v70, v138, v35
	v_fma_f32 v38, -v68, v135, v38
	ds_read_b128 v[132:135], v1 offset:49968
	v_fma_f32 v35, -v68, v139, v35
	ds_read_b128 v[136:139], v1 offset:50224
	s_waitcnt lgkmcnt(13)
	v_fma_f32 v38, -v66, v140, v38
	s_waitcnt lgkmcnt(12)
	v_fma_f32 v35, -v66, v144, v35
	v_fma_f32 v38, -v64, v141, v38
	v_fma_f32 v35, -v64, v145, v35
	v_fma_f32 v38, -v62, v142, v38
	v_fma_f32 v35, -v62, v146, v35
	v_fma_f32 v38, -v60, v143, v38
	ds_read_b128 v[140:143], v1 offset:49984
	v_fma_f32 v35, -v60, v147, v35
	ds_read_b128 v[144:147], v1 offset:50240
	s_waitcnt lgkmcnt(13)
	v_fma_f32 v38, -v57, v148, v38
	s_waitcnt lgkmcnt(12)
	v_fma_f32 v35, -v57, v152, v35
	v_fma_f32 v38, -v50, v149, v38
	v_fma_f32 v35, -v50, v153, v35
	v_fma_f32 v38, -v48, v150, v38
	v_fma_f32 v35, -v48, v154, v35
	v_fma_f32 v38, -v151, v45, v38
	ds_read_b128 v[148:151], v1 offset:50000
	v_fma_f32 v35, -v45, v155, v35
	ds_read_b128 v[152:155], v1 offset:50256
	s_waitcnt lgkmcnt(13)
	v_fma_f32 v38, -v100, v41, v38
	ds_read_b128 v[100:103], v1 offset:50016
	s_waitcnt lgkmcnt(13)
	v_fma_f32 v35, -v104, v41, v35
	v_fma_f32 v35, -v105, v38, v35
	ds_read_b128 v[104:107], v1 offset:50272
	s_waitcnt lgkmcnt(13)
	v_fma_f32 v32, -v0, v108, v32
	s_waitcnt lgkmcnt(12)
; DI void gdnprep_item(const Params& p, int item, unsigned char* ldsb) {
;     ...
; #pragma unroll
;     for (int i = 1; i < 64; ++i) {
;       float a = x[i];
; #pragma unroll
;       for (int j4 = 0; j4 < (i + 3) / 4; ++j4) {
;         f32x4 Lv = *(const f32x4*)(Lm + i * 64 + j4 * 4);
; #pragma unroll
;         for (int e = 0; e < 4; ++e) if (j4 * 4 + e < i) a -= Lv[e] * x[j4 * 4 + e];
;       }
;       x[i] = a;
;       if ((i & 3) == 3) __builtin_amdgcn_sched_barrier(0);
;     }
	v_fma_f32 v29, -v0, v112, v29
	v_fma_f32 v32, -v4, v109, v32
	v_fma_f32 v29, -v4, v113, v29
	v_fma_f32 v32, -v5, v110, v32
	v_fma_f32 v29, -v5, v114, v29
	v_fma_f32 v32, -v6, v111, v32
	ds_read_b128 v[108:111], v1 offset:50032
	v_fma_f32 v29, -v6, v115, v29
	ds_read_b128 v[112:115], v1 offset:50288
	s_waitcnt lgkmcnt(13)
	v_fma_f32 v32, -v7, v116, v32
	s_waitcnt lgkmcnt(12)
	v_fma_f32 v29, -v7, v120, v29
	v_fma_f32 v32, -v8, v117, v32
	v_fma_f32 v29, -v8, v121, v29
	v_fma_f32 v32, -v9, v118, v32
	v_fma_f32 v29, -v9, v122, v29
	v_fma_f32 v32, -v10, v119, v32
	ds_read_b128 v[116:119], v1 offset:50048
	v_fma_f32 v29, -v10, v123, v29
	ds_read_b128 v[120:123], v1 offset:50304
	s_waitcnt lgkmcnt(13)
	v_fma_f32 v32, -v11, v124, v32
	s_waitcnt lgkmcnt(12)
	v_fma_f32 v29, -v11, v128, v29
	v_fma_f32 v32, -v12, v125, v32
	v_fma_f32 v29, -v12, v129, v29
	v_fma_f32 v32, -v13, v126, v32
	v_fma_f32 v29, -v13, v130, v29
	v_fma_f32 v32, -v14, v127, v32
	ds_read_b128 v[124:127], v1 offset:50064
	v_fma_f32 v29, -v14, v131, v29
	ds_read_b128 v[128:131], v1 offset:50320
	s_waitcnt lgkmcnt(13)
	v_fma_f32 v32, -v15, v132, v32
	s_waitcnt lgkmcnt(12)
	v_fma_f32 v29, -v15, v136, v29
	v_fma_f32 v32, -v16, v133, v32
	v_fma_f32 v29, -v16, v137, v29
	v_fma_f32 v32, -v18, v134, v32
	v_fma_f32 v29, -v18, v138, v29
	v_fma_f32 v32, -v19, v135, v32
	ds_read_b128 v[132:135], v1 offset:50080
	v_fma_f32 v29, -v19, v139, v29
	ds_read_b128 v[136:139], v1 offset:50336
	s_waitcnt lgkmcnt(13)
	v_fma_f32 v32, -v20, v140, v32
	s_waitcnt lgkmcnt(12)
	v_fma_f32 v29, -v20, v144, v29
	v_fma_f32 v32, -v22, v141, v32
	v_fma_f32 v29, -v22, v145, v29
	v_fma_f32 v32, -v23, v142, v32
	v_fma_f32 v29, -v23, v146, v29
	v_fma_f32 v32, -v24, v143, v32
	ds_read_b128 v[140:143], v1 offset:50096
	v_fma_f32 v29, -v24, v147, v29
	ds_read_b128 v[144:147], v1 offset:50352
	s_waitcnt lgkmcnt(13)
	v_fma_f32 v32, -v25, v148, v32
	s_waitcnt lgkmcnt(12)
	v_fma_f32 v29, -v25, v152, v29
	v_fma_f32 v32, -v27, v149, v32
	v_fma_f32 v29, -v27, v153, v29
	v_fma_f32 v32, -v28, v150, v32
	v_fma_f32 v29, -v28, v154, v29
	v_fma_f32 v32, -v30, v151, v32
	ds_read_b128 v[148:151], v1 offset:50112
	v_fma_f32 v29, -v30, v155, v29
	ds_read_b128 v[152:155], v1 offset:50368
	s_waitcnt lgkmcnt(13)
	v_fma_f32 v32, -v31, v100, v32
	s_waitcnt lgkmcnt(12)
	v_fma_f32 v29, -v31, v104, v29
	v_fma_f32 v32, -v33, v101, v32
	v_fma_f32 v29, -v33, v105, v29
	v_fma_f32 v32, -v34, v102, v32
	v_fma_f32 v29, -v34, v106, v29
	v_fma_f32 v32, -v36, v103, v32
	ds_read_b128 v[100:103], v1 offset:50128
	v_fma_f32 v29, -v36, v107, v29
	ds_read_b128 v[104:107], v1 offset:50384
	s_waitcnt lgkmcnt(13)
	v_fma_f32 v32, -v37, v108, v32
	s_waitcnt lgkmcnt(12)
	v_fma_f32 v29, -v37, v112, v29
	v_fma_f32 v32, -v39, v109, v32
	v_fma_f32 v29, -v39, v113, v29
	v_fma_f32 v32, -v40, v110, v32
	v_fma_f32 v29, -v40, v114, v29
	v_fma_f32 v32, -v44, v111, v32
	ds_read_b128 v[108:111], v1 offset:50144
	v_fma_f32 v29, -v44, v115, v29
	ds_read_b128 v[112:115], v1 offset:50400
	s_waitcnt lgkmcnt(13)
	v_fma_f32 v32, -v46, v116, v32
	s_waitcnt lgkmcnt(12)
	v_fma_f32 v29, -v46, v120, v29
	v_fma_f32 v32, -v47, v117, v32
	v_fma_f32 v29, -v47, v121, v29
	v_fma_f32 v32, -v49, v118, v32
	v_fma_f32 v29, -v49, v122, v29
	v_fma_f32 v32, -v51, v119, v32
	ds_read_b128 v[116:119], v1 offset:50432
	v_fma_f32 v29, -v51, v123, v29
	ds_read_b128 v[120:123], v1 offset:50688
	s_waitcnt lgkmcnt(13)
	v_fma_f32 v32, -v58, v124, v32
	s_waitcnt lgkmcnt(12)
	v_fma_f32 v29, -v58, v128, v29
	v_fma_f32 v32, -v59, v125, v32
	v_fma_f32 v29, -v59, v129, v29
	v_fma_f32 v32, -v61, v126, v32
	v_fma_f32 v29, -v61, v130, v29
	v_fma_f32 v32, -v63, v127, v32
	ds_read_b128 v[124:127], v1 offset:50448
	v_fma_f32 v29, -v63, v131, v29
	ds_read_b128 v[128:131], v1 offset:50704
	s_waitcnt lgkmcnt(13)
	v_fma_f32 v32, -v65, v132, v32
	s_waitcnt lgkmcnt(12)
	v_fma_f32 v29, -v65, v136, v29
	v_fma_f32 v32, -v67, v133, v32
	v_fma_f32 v29, -v67, v137, v29
	v_fma_f32 v32, -v69, v134, v32
	v_fma_f32 v29, -v69, v138, v29
	v_fma_f32 v32, -v71, v135, v32
	ds_read_b128 v[132:135], v1 offset:50464
	v_fma_f32 v29, -v71, v139, v29
	ds_read_b128 v[136:139], v1 offset:50720
	s_waitcnt lgkmcnt(13)
	v_fma_f32 v32, -v73, v140, v32
	s_waitcnt lgkmcnt(12)
	v_fma_f32 v29, -v73, v144, v29
	v_fma_f32 v32, -v72, v141, v32
	v_fma_f32 v29, -v72, v145, v29
	v_fma_f32 v32, -v70, v142, v32
	v_fma_f32 v29, -v70, v146, v29
	v_fma_f32 v32, -v68, v143, v32
	ds_read_b128 v[140:143], v1 offset:50480
	v_fma_f32 v29, -v68, v147, v29
	ds_read_b128 v[144:147], v1 offset:50736
	s_waitcnt lgkmcnt(13)
	v_fma_f32 v32, -v66, v148, v32
	s_waitcnt lgkmcnt(12)
	v_fma_f32 v29, -v66, v152, v29
	v_fma_f32 v32, -v64, v149, v32
	v_fma_f32 v29, -v64, v153, v29
	v_fma_f32 v32, -v62, v150, v32
	v_fma_f32 v29, -v62, v154, v29
	v_fma_f32 v32, -v60, v151, v32
	ds_read_b128 v[148:151], v1 offset:50496
	v_fma_f32 v29, -v60, v155, v29
	ds_read_b128 v[152:155], v1 offset:50752
	s_waitcnt lgkmcnt(13)
	v_fma_f32 v32, -v57, v100, v32
	s_waitcnt lgkmcnt(12)
	v_fma_f32 v29, -v57, v104, v29
	v_fma_f32 v32, -v50, v101, v32
	v_fma_f32 v29, -v50, v105, v29
	v_fma_f32 v32, -v48, v102, v32
	v_fma_f32 v29, -v48, v106, v29
	v_fma_f32 v32, -v45, v103, v32
	ds_read_b128 v[100:103], v1 offset:50512
	v_fma_f32 v29, -v45, v107, v29
	ds_read_b128 v[104:107], v1 offset:50768
	s_waitcnt lgkmcnt(13)
	v_fma_f32 v32, -v41, v108, v32
	s_waitcnt lgkmcnt(12)
	v_fma_f32 v29, -v41, v112, v29
	v_fma_f32 v32, -v109, v38, v32
	v_fma_f32 v29, -v38, v113, v29
	v_fma_f32 v32, -v110, v35, v32
	ds_read_b128 v[108:111], v1 offset:50528
	v_fma_f32 v29, -v114, v35, v29
	v_fma_f32 v29, -v115, v32, v29
	ds_read_b128 v[112:115], v1 offset:50784
	s_waitcnt lgkmcnt(13)
; DI void gdnprep_item(const Params& p, int item, unsigned char* ldsb) {
;     ...
; #pragma unroll
;     for (int i = 1; i < 64; ++i) {
;       float a = x[i];
; #pragma unroll
;       for (int j4 = 0; j4 < (i + 3) / 4; ++j4) {
;         f32x4 Lv = *(const f32x4*)(Lm + i * 64 + j4 * 4);
; #pragma unroll
;         for (int e = 0; e < 4; ++e) if (j4 * 4 + e < i) a -= Lv[e] * x[j4 * 4 + e];
;       }
;       x[i] = a;
;       if ((i & 3) == 3) __builtin_amdgcn_sched_barrier(0);
;     }
	v_fma_f32 v26, -v0, v116, v26
	s_waitcnt lgkmcnt(12)
	v_fma_f32 v21, -v0, v120, v21
	v_fma_f32 v26, -v4, v117, v26
	v_fma_f32 v21, -v4, v121, v21
	v_fma_f32 v26, -v5, v118, v26
	v_fma_f32 v21, -v5, v122, v21
	v_fma_f32 v26, -v6, v119, v26
	ds_read_b128 v[116:119], v1 offset:50544
	v_fma_f32 v21, -v6, v123, v21
	ds_read_b128 v[120:123], v1 offset:50800
	s_waitcnt lgkmcnt(13)
	v_fma_f32 v26, -v7, v124, v26
	s_waitcnt lgkmcnt(12)
	v_fma_f32 v21, -v7, v128, v21
	v_fma_f32 v26, -v8, v125, v26
	v_fma_f32 v21, -v8, v129, v21
	v_fma_f32 v26, -v9, v126, v26
	v_fma_f32 v21, -v9, v130, v21
	v_fma_f32 v26, -v10, v127, v26
	ds_read_b128 v[124:127], v1 offset:50560
	v_fma_f32 v21, -v10, v131, v21
	ds_read_b128 v[128:131], v1 offset:50816
	s_waitcnt lgkmcnt(13)
	v_fma_f32 v26, -v11, v132, v26
	s_waitcnt lgkmcnt(12)
	v_fma_f32 v21, -v11, v136, v21
	v_fma_f32 v26, -v12, v133, v26
	v_fma_f32 v21, -v12, v137, v21
	v_fma_f32 v26, -v13, v134, v26
	v_fma_f32 v21, -v13, v138, v21
	v_fma_f32 v26, -v14, v135, v26
	ds_read_b128 v[132:135], v1 offset:50576
	v_fma_f32 v21, -v14, v139, v21
	ds_read_b128 v[136:139], v1 offset:50832
	s_waitcnt lgkmcnt(13)
	v_fma_f32 v26, -v15, v140, v26
	s_waitcnt lgkmcnt(12)
	v_fma_f32 v21, -v15, v144, v21
	v_fma_f32 v26, -v16, v141, v26
	v_fma_f32 v21, -v16, v145, v21
	v_fma_f32 v26, -v18, v142, v26
	v_fma_f32 v21, -v18, v146, v21
	v_fma_f32 v26, -v19, v143, v26
	ds_read_b128 v[140:143], v1 offset:50592
	v_fma_f32 v21, -v19, v147, v21
	ds_read_b128 v[144:147], v1 offset:50848
	s_waitcnt lgkmcnt(13)
	v_fma_f32 v26, -v20, v148, v26
	s_waitcnt lgkmcnt(12)
	v_fma_f32 v21, -v20, v152, v21
	v_fma_f32 v26, -v22, v149, v26
	v_fma_f32 v21, -v22, v153, v21
	v_fma_f32 v26, -v23, v150, v26
	v_fma_f32 v21, -v23, v154, v21
	v_fma_f32 v26, -v24, v151, v26
	ds_read_b128 v[148:151], v1 offset:50608
	v_fma_f32 v21, -v24, v155, v21
	ds_read_b128 v[152:155], v1 offset:50864
	s_waitcnt lgkmcnt(13)
	v_fma_f32 v26, -v25, v100, v26
	s_waitcnt lgkmcnt(12)
	v_fma_f32 v21, -v25, v104, v21
	v_fma_f32 v26, -v27, v101, v26
	v_fma_f32 v21, -v27, v105, v21
	v_fma_f32 v26, -v28, v102, v26
	v_fma_f32 v21, -v28, v106, v21
	v_fma_f32 v26, -v30, v103, v26
	ds_read_b128 v[100:103], v1 offset:50624
	v_fma_f32 v21, -v30, v107, v21
	ds_read_b128 v[104:107], v1 offset:50880
	s_waitcnt lgkmcnt(13)
	v_fma_f32 v26, -v31, v108, v26
	s_waitcnt lgkmcnt(12)
	v_fma_f32 v21, -v31, v112, v21
	v_fma_f32 v26, -v33, v109, v26
	v_fma_f32 v21, -v33, v113, v21
	v_fma_f32 v26, -v34, v110, v26
	v_fma_f32 v21, -v34, v114, v21
	v_fma_f32 v26, -v36, v111, v26
	ds_read_b128 v[108:111], v1 offset:50640
	v_fma_f32 v21, -v36, v115, v21
	ds_read_b128 v[112:115], v1 offset:50896
	s_waitcnt lgkmcnt(13)
	v_fma_f32 v26, -v37, v116, v26
	s_waitcnt lgkmcnt(12)
	v_fma_f32 v21, -v37, v120, v21
	v_fma_f32 v26, -v39, v117, v26
	v_fma_f32 v21, -v39, v121, v21
	v_fma_f32 v26, -v40, v118, v26
	v_fma_f32 v21, -v40, v122, v21
	v_fma_f32 v26, -v44, v119, v26
	ds_read_b128 v[116:119], v1 offset:50656
	v_fma_f32 v21, -v44, v123, v21
	ds_read_b128 v[120:123], v1 offset:50912
	s_waitcnt lgkmcnt(13)
	v_fma_f32 v26, -v46, v124, v26
	s_waitcnt lgkmcnt(12)
	v_fma_f32 v21, -v46, v128, v21
	v_fma_f32 v26, -v47, v125, v26
	v_fma_f32 v21, -v47, v129, v21
	v_fma_f32 v26, -v49, v126, v26
	v_fma_f32 v21, -v49, v130, v21
	v_fma_f32 v26, -v51, v127, v26
	ds_read_b128 v[124:127], v1 offset:50672
	v_fma_f32 v21, -v51, v131, v21
	ds_read_b128 v[128:131], v1 offset:50928
	s_waitcnt lgkmcnt(13)
	v_fma_f32 v26, -v58, v132, v26
	s_waitcnt lgkmcnt(12)
	v_fma_f32 v21, -v58, v136, v21
	v_fma_f32 v26, -v59, v133, v26
	v_fma_f32 v21, -v59, v137, v21
	v_fma_f32 v26, -v61, v134, v26
	v_fma_f32 v21, -v61, v138, v21
	v_fma_f32 v26, -v63, v135, v26
	ds_read_b128 v[132:135], v1 offset:50944
	v_fma_f32 v21, -v63, v139, v21
	ds_read_b128 v[136:139], v1 offset:50960
	s_waitcnt lgkmcnt(13)
	v_fma_f32 v26, -v65, v140, v26
	s_waitcnt lgkmcnt(12)
	v_fma_f32 v21, -v65, v144, v21
	v_fma_f32 v26, -v67, v141, v26
	v_fma_f32 v21, -v67, v145, v21
	v_fma_f32 v26, -v69, v142, v26
	v_fma_f32 v21, -v69, v146, v21
	v_fma_f32 v26, -v71, v143, v26
	ds_read_b128 v[140:143], v1 offset:50976
	v_fma_f32 v21, -v71, v147, v21
	ds_read_b128 v[144:147], v1 offset:50992
	s_waitcnt lgkmcnt(13)
	v_fma_f32 v26, -v73, v148, v26
	s_waitcnt lgkmcnt(12)
	v_fma_f32 v21, -v73, v152, v21
	v_fma_f32 v26, -v72, v149, v26
	v_fma_f32 v21, -v72, v153, v21
	v_fma_f32 v26, -v70, v150, v26
	v_fma_f32 v21, -v70, v154, v21
	v_fma_f32 v26, -v68, v151, v26
	ds_read_b128 v[148:151], v1 offset:51008
	v_fma_f32 v21, -v68, v155, v21
	ds_read_b128 v[152:155], v1 offset:51024
	s_waitcnt lgkmcnt(13)
	v_fma_f32 v26, -v66, v100, v26
	s_waitcnt lgkmcnt(12)
	v_fma_f32 v21, -v66, v104, v21
	v_fma_f32 v26, -v64, v101, v26
	v_fma_f32 v21, -v64, v105, v21
	v_fma_f32 v26, -v62, v102, v26
	v_fma_f32 v21, -v62, v106, v21
	v_fma_f32 v26, -v60, v103, v26
	ds_read_b128 v[100:103], v1 offset:51040
	v_fma_f32 v21, -v60, v107, v21
	ds_read_b128 v[104:107], v1 offset:51056
	s_waitcnt lgkmcnt(13)
	v_fma_f32 v26, -v57, v108, v26
	s_waitcnt lgkmcnt(12)
; DI void gdnprep_item(const Params& p, int item, unsigned char* ldsb) {
;     ...
; #pragma unroll
;     for (int i = 1; i < 64; ++i) {
;       float a = x[i];
; #pragma unroll
;       for (int j4 = 0; j4 < (i + 3) / 4; ++j4) {
;         f32x4 Lv = *(const f32x4*)(Lm + i * 64 + j4 * 4);
; #pragma unroll
;         for (int e = 0; e < 4; ++e) if (j4 * 4 + e < i) a -= Lv[e] * x[j4 * 4 + e];
;       }
;       x[i] = a;
;       if ((i & 3) == 3) __builtin_amdgcn_sched_barrier(0);
;     }
;     if (!isw) {
; #pragma unroll
;       for (int i8 = 0; i8 < 8; ++i8)
;         *(bf16x8*)(UTp + c * 64 + i8 * 8) = pack8(x[i8 * 8], x[i8 * 8 + 1], x[i8 * 8 + 2], x[i8 * 8 + 3], x[i8 * 8 + 4], x[i8 * 8 + 5], x[i8 * 8 + 6], x[i8 * 8 + 7]);
	v_fma_f32 v21, -v57, v112, v21
	v_fma_f32 v26, -v50, v109, v26
	v_fma_f32 v21, -v50, v113, v21
	v_fma_f32 v26, -v48, v110, v26
	v_fma_f32 v21, -v48, v114, v21
	v_fma_f32 v26, -v45, v111, v26
	ds_read_b128 v[108:111], v1 offset:51072
	v_fma_f32 v21, -v45, v115, v21
	ds_read_b128 v[112:115], v1 offset:51088
	s_waitcnt lgkmcnt(13)
	v_fma_f32 v26, -v41, v116, v26
	s_waitcnt lgkmcnt(12)
	v_fma_f32 v21, -v41, v120, v21
	v_fma_f32 v26, -v38, v117, v26
	v_fma_f32 v21, -v38, v121, v21
	v_fma_f32 v26, -v35, v118, v26
	v_fma_f32 v21, -v35, v122, v21
	v_fma_f32 v26, -v119, v32, v26
	ds_read_b128 v[116:119], v1 offset:51104
	v_fma_f32 v21, -v32, v123, v21
	ds_read_b128 v[120:123], v1 offset:51120
	s_waitcnt lgkmcnt(13)
	v_fma_f32 v26, -v124, v29, v26
	ds_read_b128 v[124:127], v1 offset:51136
	s_waitcnt lgkmcnt(13)
	v_fma_f32 v21, -v128, v29, v21
	s_waitcnt lgkmcnt(12)
	v_fma_f32 v17, -v0, v132, v17
	v_fma_f32 v74, -v129, v26, v21
	ds_read_b128 v[128:131], v1 offset:51152
	v_fma_f32 v17, -v4, v133, v17
	v_fma_f32 v17, -v5, v134, v17
	v_fma_f32 v17, -v6, v135, v17
	ds_read_b128 v[132:135], v1 offset:51168
	s_waitcnt lgkmcnt(13)
	v_fma_f32 v17, -v7, v136, v17
	v_fma_f32 v17, -v8, v137, v17
	v_fma_f32 v17, -v9, v138, v17
	v_fma_f32 v17, -v10, v139, v17
	ds_read_b128 v[136:139], v1 offset:51184
	s_waitcnt lgkmcnt(13)
	v_fma_f32 v17, -v11, v140, v17
	v_fma_f32 v17, -v12, v141, v17
	v_fma_f32 v17, -v13, v142, v17
	v_fma_f32 v17, -v14, v143, v17
	s_waitcnt lgkmcnt(12)
	v_fma_f32 v17, -v15, v144, v17
	v_fma_f32 v17, -v16, v145, v17
	v_fma_f32 v17, -v18, v146, v17
	v_fma_f32 v17, -v19, v147, v17
	s_waitcnt lgkmcnt(11)
	v_fma_f32 v17, -v20, v148, v17
	v_fma_f32 v17, -v22, v149, v17
	v_fma_f32 v17, -v23, v150, v17
	v_fma_f32 v17, -v24, v151, v17
	s_waitcnt lgkmcnt(10)
	v_fma_f32 v17, -v25, v152, v17
	v_fma_f32 v17, -v27, v153, v17
	v_fma_f32 v17, -v28, v154, v17
	v_fma_f32 v17, -v30, v155, v17
	s_waitcnt lgkmcnt(9)
	v_fma_f32 v17, -v31, v100, v17
	v_fma_f32 v17, -v33, v101, v17
	v_fma_f32 v17, -v34, v102, v17
	v_fma_f32 v17, -v36, v103, v17
	s_waitcnt lgkmcnt(8)
	v_fma_f32 v17, -v37, v104, v17
	v_fma_f32 v17, -v39, v105, v17
	v_fma_f32 v17, -v40, v106, v17
	v_fma_f32 v17, -v44, v107, v17
	s_waitcnt lgkmcnt(7)
	v_fma_f32 v17, -v46, v108, v17
	v_fma_f32 v17, -v47, v109, v17
	v_fma_f32 v17, -v49, v110, v17
	v_fma_f32 v17, -v51, v111, v17
	s_waitcnt lgkmcnt(6)
	v_fma_f32 v17, -v58, v112, v17
	v_fma_f32 v17, -v59, v113, v17
	v_fma_f32 v17, -v61, v114, v17
	v_fma_f32 v17, -v63, v115, v17
	s_waitcnt lgkmcnt(5)
	v_fma_f32 v17, -v65, v116, v17
	v_fma_f32 v17, -v67, v117, v17
	v_fma_f32 v17, -v69, v118, v17
	v_fma_f32 v17, -v71, v119, v17
	s_waitcnt lgkmcnt(4)
	v_fma_f32 v17, -v73, v120, v17
	v_fma_f32 v17, -v72, v121, v17
	v_fma_f32 v17, -v70, v122, v17
	v_fma_f32 v17, -v68, v123, v17
	s_waitcnt lgkmcnt(3)
	v_fma_f32 v17, -v66, v124, v17
	v_fma_f32 v17, -v64, v125, v17
	v_fma_f32 v17, -v62, v126, v17
	v_fma_f32 v17, -v60, v127, v17
	s_waitcnt lgkmcnt(2)
	v_fma_f32 v17, -v57, v128, v17
	v_fma_f32 v17, -v50, v129, v17
	v_fma_f32 v17, -v48, v130, v17
	v_fma_f32 v17, -v45, v131, v17
	s_waitcnt lgkmcnt(1)
	v_fma_f32 v17, -v41, v132, v17
	v_fma_f32 v17, -v38, v133, v17
	v_fma_f32 v17, -v35, v134, v17
	v_fma_f32 v17, -v32, v135, v17
	s_waitcnt lgkmcnt(0)
	v_fma_f32 v17, -v29, v136, v17
	v_fma_f32 v17, -v137, v26, v17
	v_fma_f32 v75, -v138, v74, v17
	v_lshlrev_b32_e32 v17, 1, v42
	v_lshrrev_b32_e32 v77, 2, v42
	v_and_b32_e32 v21, 0x60, v42
	v_and_b32_e32 v76, 24, v17
	v_and_b32_e32 v77, 4, v77
	s_and_saveexec_b64 s[0:1], vcc
	s_xor_b64 s[0:1], exec, s[0:1]
	s_cbranch_execz .LBB0_835
	s_lshl_b64 s[4:5], s[38:39], 1
	s_add_u32 s4, s74, s4
	s_addc_u32 s5, s75, s5
	v_lshlrev_b32_e32 v3, 7, v3
	v_cvt_pk_bf16_f32 v4, v0, v4
	v_cvt_pk_bf16_f32 v5, v5, v6
	v_cvt_pk_bf16_f32 v6, v7, v8
	v_cvt_pk_bf16_f32 v7, v9, v10
	global_store_dwordx4 v3, v[4:7], s[4:5]
	v_and_b32_e32 v21, 0x60, v42
	v_or3_b32 v17, v77, v76, v56
	v_cvt_pk_bf16_f32 v4, v11, v12
	v_cvt_pk_bf16_f32 v5, v13, v14
	v_cvt_pk_bf16_f32 v6, v15, v16
	v_cvt_pk_bf16_f32 v7, v18, v19
	global_store_dwordx4 v3, v[4:7], s[4:5] offset:16
	s_nop 1
	v_cvt_pk_bf16_f32 v4, v20, v22
	v_cvt_pk_bf16_f32 v5, v23, v24
	v_cvt_pk_bf16_f32 v6, v25, v27
	v_cvt_pk_bf16_f32 v7, v28, v30
	global_store_dwordx4 v3, v[4:7], s[4:5] offset:32
	s_nop 1
	v_cvt_pk_bf16_f32 v4, v31, v33
	v_cvt_pk_bf16_f32 v5, v34, v36
	v_cvt_pk_bf16_f32 v6, v37, v39
	v_cvt_pk_bf16_f32 v7, v40, v44
	global_store_dwordx4 v3, v[4:7], s[4:5] offset:48
	s_nop 1
	v_cvt_pk_bf16_f32 v4, v46, v47
	v_cvt_pk_bf16_f32 v5, v49, v51
	v_cvt_pk_bf16_f32 v6, v58, v59
	v_cvt_pk_bf16_f32 v7, v61, v63
	global_store_dwordx4 v3, v[4:7], s[4:5] offset:64
	s_nop 1
	v_cvt_pk_bf16_f32 v4, v65, v67
	v_cvt_pk_bf16_f32 v5, v69, v71
	v_cvt_pk_bf16_f32 v6, v73, v72
	v_cvt_pk_bf16_f32 v7, v70, v68
	global_store_dwordx4 v3, v[4:7], s[4:5] offset:80
	s_nop 1
	v_cvt_pk_bf16_f32 v4, v66, v64
	v_cvt_pk_bf16_f32 v5, v62, v60
	v_cvt_pk_bf16_f32 v6, v57, v50
	v_cvt_pk_bf16_f32 v7, v48, v45
	global_store_dwordx4 v3, v[4:7], s[4:5] offset:96
	s_nop 1
	v_cvt_pk_bf16_f32 v4, v41, v38
	v_cvt_pk_bf16_f32 v5, v35, v32
	v_cvt_pk_bf16_f32 v6, v29, v26
	v_cvt_pk_bf16_f32 v7, v74, v75
	global_store_dwordx4 v3, v[4:7], s[4:5] offset:112
